# GEMM K-loops: s_setprio raise issued in front of the pre-cluster barrier and the drop behind the post-cluster barrier (both off the compute hand-off path)
# baseline (speedup 1.0000x reference)
; #define PG8_STAGE(bufoff, gbase, voff) do { _Pragma("unroll") for (int _i = 0; _i < 2; ++_i) \
;         __builtin_amdgcn_global_load_lds((const unsigned*)((const char*)(gbase) + (voff)[_i]), (LAS unsigned*)(lds + (bufoff) + ldsw + _i * 8192), 16, 0, 0); } while (0)
; #define PG8_STAGEB(bufoff, gbase, perm) do { _Pragma("unroll") for (int _i = 0; _i < 2; ++_i) \
;         __builtin_amdgcn_global_load_lds((const unsigned*)((const char*)(gbase) + ((BSEL && (perm)) ? voffBp[_i] : voffB[_i])), (LAS unsigned*)(lds + (bufoff) + ldsw + _i * 8192), 16, 0, 0); } while (0)
; #define PG8_LDA(dst, b, h) do { _Pragma("unroll") for (int m = 0; m < 4; ++m) _Pragma("unroll") for (int k = 0; k < 2; ++k) dst[m][k] = *(const LAS bf16x8*)(lds + PG8_SA(b, h) + aoff + m * 2048 + k * 1024); } while (0)
; #define PG8_LDB(dst, b, h) do { _Pragma("unroll") for (int n = 0; n < 2; ++n) _Pragma("unroll") for (int k = 0; k < 2; ++k) dst[n][k] = *(const LAS bf16x8*)(lds + PG8_SB(b, h) + boff + n * 2048 + k * 1024); } while (0)
; #define PG8_WAIT_V(n) asm volatile("s_waitcnt vmcnt(" #n ")" ::: "memory")
; #define PG8_WAIT_L(n) asm volatile("s_waitcnt lgkmcnt(" #n ")" ::: "memory")
; #define PG8_BAR __builtin_amdgcn_s_barrier()
; #define PG8_SCHED __builtin_amdgcn_sched_barrier(0)
; template <class Epi, bool BSEL = false>
; __device__ __forceinline__ void gemm_phase(LAS unsigned char* lds, const Gemm g, const Order& S, const Epi& E, const int tid) {
;     ...
;         for (int t = 0; t < nt; t += 2) {
;             const bool last = (t == nt - 2);
;             const char* a1 = cA + (size_t)(t + 1) * kstep;
;             const char* a2 = last ? nA : cA + (size_t)(t + 2) * kstep; const char* b2 = last ? nB : cB + (size_t)(t + 2) * kstep;
;             const char* a3 = a2 + kstep; const char* b3 = b2 + kstep;
;             const bool p2 = last ? nP : cP; const size_t h2 = last ? nhB : chB;
;             PG8_LDB(B0, 0, 0); PG8_LDB(B1, 0, 1); PG8_SCHED; PG8_LDA(At, 0, 0); PG8_STAGE(PG8_SA(1, 1), a1 + hstepA, voffA);
;             PG8_WAIT_V(8); PG8_WAIT_L(0); PG8_BAR; PG8_MMA(0, 0, At, B0); PG8_MMA(0, 1, At, B1); PG8_BAR; PG8_SCHED;
;             PG8_LDA(At, 0, 1); PG8_STAGEB(PG8_SB(0, 0), b2, p2); PG8_STAGEB(PG8_SB(0, 1), b2 + h2, p2); PG8_STAGE(PG8_SA(0, 0), a2, voffA);
;             PG8_WAIT_V(8); PG8_WAIT_L(0); PG8_BAR; PG8_MMA(1, 0, At, B0); PG8_MMA(1, 1, At, B1); PG8_BAR; PG8_SCHED;
.LBB0_324:
	v_add_u32_e32 v162, s45, v147
	v_add_u32_e32 v178, s46, v147
	s_add_u32 s2, s8, s38
	ds_read_b128 v[150:153], v162
	ds_read_b128 v[154:157], v162 offset:1024
	ds_read_b128 v[158:161], v162 offset:2048
	ds_read_b128 v[162:165], v162 offset:3072
	ds_read_b128 v[166:169], v178
	ds_read_b128 v[170:173], v178 offset:1024
	ds_read_b128 v[174:177], v178 offset:2048
	ds_read_b128 v[178:181], v178 offset:3072
	s_addc_u32 s3, s9, s39
	s_add_u32 s2, s2, 0x100
	s_addc_u32 s3, s3, 0
	s_add_u32 s57, s25, s38
	s_addc_u32 s58, s51, s39
	s_cmpk_eq_i32 s38, 0x700
	s_cselect_b32 s35, s52, s3
	s_cselect_b32 s34, s53, s2
	s_cselect_b32 s3, s54, s58
	s_cselect_b32 s2, s55, s57
	v_lshl_add_u64 v[198:199], v[142:143], 0, s[38:39]
	s_add_i32 m0, s7, 0xc000
	ds_read_b128 v[182:185], v149
	ds_read_b128 v[186:189], v149 offset:1024
	ds_read_b128 v[190:193], v149 offset:2048
	ds_read_b128 v[194:197], v149 offset:3072
	ds_read_b128 v[202:205], v149 offset:4096
	ds_read_b128 v[206:209], v149 offset:5120
	ds_read_b128 v[210:213], v149 offset:6144
	ds_read_b128 v[214:217], v149 offset:7168
	global_load_lds_dwordx4 v[198:199], off
	v_lshl_add_u64 v[198:199], v[144:145], 0, s[38:39]
	s_add_i32 m0, s7, 0xe000
	s_nop 0
	global_load_lds_dwordx4 v[198:199], off
	s_waitcnt vmcnt(8)
	s_waitcnt lgkmcnt(0)
	s_setprio 1
	s_barrier
	v_mfma_f32_16x16x32_bf16 v[124:127], v[150:153], v[182:185], v[124:127]
	v_mfma_f32_16x16x32_bf16 v[120:123], v[158:161], v[182:185], v[120:123]
	v_mfma_f32_16x16x32_bf16 v[116:119], v[150:153], v[190:193], v[116:119]
	v_mfma_f32_16x16x32_bf16 v[112:115], v[158:161], v[190:193], v[112:115]
	v_mfma_f32_16x16x32_bf16 v[108:111], v[150:153], v[202:205], v[108:111]
	v_mfma_f32_16x16x32_bf16 v[104:107], v[158:161], v[202:205], v[104:107]
	v_mfma_f32_16x16x32_bf16 v[100:103], v[150:153], v[210:213], v[100:103]
	v_mfma_f32_16x16x32_bf16 v[96:99], v[158:161], v[210:213], v[96:99]
	v_mfma_f32_16x16x32_bf16 v[124:127], v[154:157], v[186:189], v[124:127]
	v_mfma_f32_16x16x32_bf16 v[120:123], v[162:165], v[186:189], v[120:123]
	v_mfma_f32_16x16x32_bf16 v[116:119], v[154:157], v[194:197], v[116:119]
	v_mfma_f32_16x16x32_bf16 v[112:115], v[162:165], v[194:197], v[112:115]
	v_mfma_f32_16x16x32_bf16 v[108:111], v[154:157], v[206:209], v[108:111]
	v_mfma_f32_16x16x32_bf16 v[104:107], v[162:165], v[206:209], v[104:107]
	v_mfma_f32_16x16x32_bf16 v[100:103], v[154:157], v[214:217], v[100:103]
	v_mfma_f32_16x16x32_bf16 v[96:99], v[162:165], v[214:217], v[96:99]
	v_mfma_f32_16x16x32_bf16 v[92:95], v[166:169], v[182:185], v[92:95]
	v_mfma_f32_16x16x32_bf16 v[88:91], v[174:177], v[182:185], v[88:91]
	v_mfma_f32_16x16x32_bf16 v[84:87], v[166:169], v[190:193], v[84:87]
	v_mfma_f32_16x16x32_bf16 v[80:83], v[174:177], v[190:193], v[80:83]
	v_mfma_f32_16x16x32_bf16 v[76:79], v[166:169], v[202:205], v[76:79]
	v_mfma_f32_16x16x32_bf16 v[72:75], v[174:177], v[202:205], v[72:75]
	v_mfma_f32_16x16x32_bf16 v[68:71], v[166:169], v[210:213], v[68:71]
	v_mfma_f32_16x16x32_bf16 v[64:67], v[174:177], v[210:213], v[64:67]
	v_mfma_f32_16x16x32_bf16 v[92:95], v[170:173], v[186:189], v[92:95]
	v_mfma_f32_16x16x32_bf16 v[88:91], v[178:181], v[186:189], v[88:91]
	v_mfma_f32_16x16x32_bf16 v[84:87], v[170:173], v[194:197], v[84:87]
	v_mfma_f32_16x16x32_bf16 v[80:83], v[178:181], v[194:197], v[80:83]
	v_mfma_f32_16x16x32_bf16 v[76:79], v[170:173], v[206:209], v[76:79]
	v_mfma_f32_16x16x32_bf16 v[72:75], v[178:181], v[206:209], v[72:75]
	v_mfma_f32_16x16x32_bf16 v[68:71], v[170:173], v[214:217], v[68:71]
	v_mfma_f32_16x16x32_bf16 v[64:67], v[178:181], v[214:217], v[64:67]
	s_barrier
	s_setprio 0
	s_add_i32 s57, s45, s12
	v_lshl_add_u64 v[198:199], s[2:3], 0, v[132:133]
	s_mov_b32 m0, s57
	ds_read_b128 v[182:185], v149 offset:16384
	ds_read_b128 v[186:189], v149 offset:17408
	ds_read_b128 v[190:193], v149 offset:18432
	ds_read_b128 v[194:197], v149 offset:19456
	ds_read_b128 v[202:205], v149 offset:20480
	ds_read_b128 v[206:209], v149 offset:21504
	ds_read_b128 v[210:213], v149 offset:22528
	ds_read_b128 v[214:217], v149 offset:23552
	global_load_lds_dwordx4 v[198:199], off
	s_add_i32 m0, s57, 0x2000
	s_add_u32 s58, s2, 0x40000
	v_lshl_add_u64 v[218:219], s[2:3], 0, v[128:129]
	s_addc_u32 s59, s3, 0
	s_add_i32 s57, s46, s12
	global_load_lds_dwordx4 v[218:219], off
	v_lshl_add_u64 v[220:221], s[58:59], 0, v[132:133]
	s_mov_b32 m0, s57
	v_lshl_add_u64 v[222:223], s[34:35], 0, v[130:131]
	global_load_lds_dwordx4 v[220:221], off
	v_lshl_add_u64 v[220:221], s[58:59], 0, v[128:129]
	s_add_i32 m0, s57, 0x2000
	s_nop 0
	global_load_lds_dwordx4 v[220:221], off
	v_lshl_add_u64 v[220:221], s[34:35], 0, v[134:135]
	s_mov_b32 m0, s7
	s_nop 0
	global_load_lds_dwordx4 v[220:221], off
	s_mov_b32 m0, s15
	s_nop 0
	global_load_lds_dwordx4 v[222:223], off
	s_waitcnt vmcnt(8)
	s_waitcnt lgkmcnt(0)
	s_setprio 1
	s_barrier
; #define PG8_STAGE(bufoff, gbase, voff) do { _Pragma("unroll") for (int _i = 0; _i < 2; ++_i) \
;         __builtin_amdgcn_global_load_lds((const unsigned*)((const char*)(gbase) + (voff)[_i]), (LAS unsigned*)(lds + (bufoff) + ldsw + _i * 8192), 16, 0, 0); } while (0)
; #define PG8_LDA(dst, b, h) do { _Pragma("unroll") for (int m = 0; m < 4; ++m) _Pragma("unroll") for (int k = 0; k < 2; ++k) dst[m][k] = *(const LAS bf16x8*)(lds + PG8_SA(b, h) + aoff + m * 2048 + k * 1024); } while (0)
; #define PG8_LDB(dst, b, h) do { _Pragma("unroll") for (int n = 0; n < 2; ++n) _Pragma("unroll") for (int k = 0; k < 2; ++k) dst[n][k] = *(const LAS bf16x8*)(lds + PG8_SB(b, h) + boff + n * 2048 + k * 1024); } while (0)
; #define PG8_MMA(ai, bj, At, Bt) do { __builtin_amdgcn_s_setprio(1); _Pragma("unroll") for (int m = 0; m < 4; ++m) _Pragma("unroll") for (int n = 0; n < 2; ++n) _Pragma("unroll") for (int k = 0; k < 2; ++k) \
;         acc[ai][bj][m][n] = __builtin_amdgcn_mfma_f32_16x16x32_bf16(Bt[n][k], At[m][k], acc[ai][bj][m][n], 0, 0, 0); __builtin_amdgcn_s_setprio(0); } while (0)
; #define PG8_WAIT_V(n) asm volatile("s_waitcnt vmcnt(" #n ")" ::: "memory")
; #define PG8_WAIT_L(n) asm volatile("s_waitcnt lgkmcnt(" #n ")" ::: "memory")
; #define PG8_BAR __builtin_amdgcn_s_barrier()
; #define PG8_SCHED __builtin_amdgcn_sched_barrier(0)
; template <class Epi, bool BSEL = false>
; __device__ __forceinline__ void gemm_phase(LAS unsigned char* lds, const Gemm g, const Order& S, const Epi& E, const int tid) {
;     ...
;             PG8_WAIT_V(8); PG8_WAIT_L(0); PG8_BAR; PG8_MMA(1, 0, At, B0); PG8_MMA(1, 1, At, B1); PG8_BAR; PG8_SCHED;
;             PG8_LDB(B0, 1, 0); PG8_LDB(B1, 1, 1); PG8_SCHED; PG8_LDA(At, 1, 0); PG8_STAGE(PG8_SA(0, 1), a2 + hstepA, voffA);
;             PG8_WAIT_V(8); PG8_WAIT_L(0); PG8_BAR; PG8_MMA(0, 0, At, B0); PG8_MMA(0, 1, At, B1); PG8_BAR; PG8_SCHED;
	v_mfma_f32_16x16x32_bf16 v[60:63], v[150:153], v[182:185], v[60:63]
	v_mfma_f32_16x16x32_bf16 v[56:59], v[158:161], v[182:185], v[56:59]
	v_mfma_f32_16x16x32_bf16 v[52:55], v[150:153], v[190:193], v[52:55]
	v_mfma_f32_16x16x32_bf16 v[48:51], v[158:161], v[190:193], v[48:51]
	v_mfma_f32_16x16x32_bf16 v[44:47], v[150:153], v[202:205], v[44:47]
	v_mfma_f32_16x16x32_bf16 v[40:43], v[158:161], v[202:205], v[40:43]
	v_mfma_f32_16x16x32_bf16 v[36:39], v[150:153], v[210:213], v[36:39]
	v_mfma_f32_16x16x32_bf16 v[32:35], v[158:161], v[210:213], v[32:35]
	v_mfma_f32_16x16x32_bf16 v[60:63], v[154:157], v[186:189], v[60:63]
	v_mfma_f32_16x16x32_bf16 v[56:59], v[162:165], v[186:189], v[56:59]
	v_mfma_f32_16x16x32_bf16 v[52:55], v[154:157], v[194:197], v[52:55]
	v_mfma_f32_16x16x32_bf16 v[48:51], v[162:165], v[194:197], v[48:51]
	v_mfma_f32_16x16x32_bf16 v[44:47], v[154:157], v[206:209], v[44:47]
	v_mfma_f32_16x16x32_bf16 v[40:43], v[162:165], v[206:209], v[40:43]
	v_mfma_f32_16x16x32_bf16 v[36:39], v[154:157], v[214:217], v[36:39]
	v_mfma_f32_16x16x32_bf16 v[32:35], v[162:165], v[214:217], v[32:35]
	v_mfma_f32_16x16x32_bf16 v[28:31], v[166:169], v[182:185], v[28:31]
	v_mfma_f32_16x16x32_bf16 v[24:27], v[174:177], v[182:185], v[24:27]
	v_mfma_f32_16x16x32_bf16 v[20:23], v[166:169], v[190:193], v[20:23]
	v_mfma_f32_16x16x32_bf16 v[16:19], v[174:177], v[190:193], v[16:19]
	v_mfma_f32_16x16x32_bf16 v[12:15], v[166:169], v[202:205], v[12:15]
	v_mfma_f32_16x16x32_bf16 v[8:11], v[174:177], v[202:205], v[8:11]
	v_mfma_f32_16x16x32_bf16 v[4:7], v[166:169], v[210:213], v[4:7]
	v_mfma_f32_16x16x32_bf16 v[0:3], v[174:177], v[210:213], v[0:3]
	v_mfma_f32_16x16x32_bf16 v[28:31], v[170:173], v[186:189], v[28:31]
	v_mfma_f32_16x16x32_bf16 v[24:27], v[178:181], v[186:189], v[24:27]
	v_mfma_f32_16x16x32_bf16 v[20:23], v[170:173], v[194:197], v[20:23]
	v_mfma_f32_16x16x32_bf16 v[16:19], v[178:181], v[194:197], v[16:19]
	v_mfma_f32_16x16x32_bf16 v[12:15], v[170:173], v[206:209], v[12:15]
	v_mfma_f32_16x16x32_bf16 v[8:11], v[178:181], v[206:209], v[8:11]
	v_mfma_f32_16x16x32_bf16 v[4:7], v[170:173], v[214:217], v[4:7]
	v_mfma_f32_16x16x32_bf16 v[0:3], v[178:181], v[214:217], v[0:3]
	s_barrier
	s_setprio 0
	s_add_i32 s57, 0, 0x18000
	s_add_i32 s58, 0, 0x1c000
	v_add_u32_e32 v162, s57, v147
	v_add_u32_e32 v178, s58, v147
	ds_read_b128 v[150:153], v162
	ds_read_b128 v[154:157], v162 offset:1024
	ds_read_b128 v[158:161], v162 offset:2048
	ds_read_b128 v[162:165], v162 offset:3072
	ds_read_b128 v[166:169], v178
	ds_read_b128 v[170:173], v178 offset:1024
	ds_read_b128 v[174:177], v178 offset:2048
	ds_read_b128 v[178:181], v178 offset:3072
	s_add_u32 s34, s34, 0x40000
	s_addc_u32 s35, s35, 0
	s_mov_b32 m0, s40
	v_lshl_add_u64 v[224:225], s[34:35], 0, v[134:135]
	ds_read_b128 v[182:185], v149 offset:32768
	ds_read_b128 v[186:189], v149 offset:33792
	ds_read_b128 v[190:193], v149 offset:34816
	ds_read_b128 v[194:197], v149 offset:35840
	ds_read_b128 v[202:205], v149 offset:36864
	ds_read_b128 v[206:209], v149 offset:37888
	ds_read_b128 v[210:213], v149 offset:38912
	ds_read_b128 v[214:217], v149 offset:39936
	global_load_lds_dwordx4 v[224:225], off
	v_lshl_add_u64 v[224:225], s[34:35], 0, v[130:131]
	s_mov_b32 m0, s41
	s_nop 0
	global_load_lds_dwordx4 v[224:225], off
	s_waitcnt vmcnt(8)
	s_waitcnt lgkmcnt(0)
	s_setprio 1
	s_barrier
	v_mfma_f32_16x16x32_bf16 v[124:127], v[150:153], v[182:185], v[124:127]
	v_mfma_f32_16x16x32_bf16 v[120:123], v[158:161], v[182:185], v[120:123]
	v_mfma_f32_16x16x32_bf16 v[116:119], v[150:153], v[190:193], v[116:119]
	v_mfma_f32_16x16x32_bf16 v[112:115], v[158:161], v[190:193], v[112:115]
	v_mfma_f32_16x16x32_bf16 v[108:111], v[150:153], v[202:205], v[108:111]
	v_mfma_f32_16x16x32_bf16 v[104:107], v[158:161], v[202:205], v[104:107]
	v_mfma_f32_16x16x32_bf16 v[100:103], v[150:153], v[210:213], v[100:103]
	v_mfma_f32_16x16x32_bf16 v[96:99], v[158:161], v[210:213], v[96:99]
	v_mfma_f32_16x16x32_bf16 v[124:127], v[154:157], v[186:189], v[124:127]
	v_mfma_f32_16x16x32_bf16 v[120:123], v[162:165], v[186:189], v[120:123]
	v_mfma_f32_16x16x32_bf16 v[116:119], v[154:157], v[194:197], v[116:119]
	v_mfma_f32_16x16x32_bf16 v[112:115], v[162:165], v[194:197], v[112:115]
	v_mfma_f32_16x16x32_bf16 v[108:111], v[154:157], v[206:209], v[108:111]
	v_mfma_f32_16x16x32_bf16 v[104:107], v[162:165], v[206:209], v[104:107]
	v_mfma_f32_16x16x32_bf16 v[100:103], v[154:157], v[214:217], v[100:103]
	v_mfma_f32_16x16x32_bf16 v[96:99], v[162:165], v[214:217], v[96:99]
	v_mfma_f32_16x16x32_bf16 v[92:95], v[166:169], v[182:185], v[92:95]
	v_mfma_f32_16x16x32_bf16 v[88:91], v[174:177], v[182:185], v[88:91]
	v_mfma_f32_16x16x32_bf16 v[84:87], v[166:169], v[190:193], v[84:87]
	v_mfma_f32_16x16x32_bf16 v[80:83], v[174:177], v[190:193], v[80:83]
	v_mfma_f32_16x16x32_bf16 v[76:79], v[166:169], v[202:205], v[76:79]
	v_mfma_f32_16x16x32_bf16 v[72:75], v[174:177], v[202:205], v[72:75]
	v_mfma_f32_16x16x32_bf16 v[68:71], v[166:169], v[210:213], v[68:71]
	v_mfma_f32_16x16x32_bf16 v[64:67], v[174:177], v[210:213], v[64:67]
	v_mfma_f32_16x16x32_bf16 v[92:95], v[170:173], v[186:189], v[92:95]
	v_mfma_f32_16x16x32_bf16 v[88:91], v[178:181], v[186:189], v[88:91]
	v_mfma_f32_16x16x32_bf16 v[84:87], v[170:173], v[194:197], v[84:87]
	v_mfma_f32_16x16x32_bf16 v[80:83], v[178:181], v[194:197], v[80:83]
	v_mfma_f32_16x16x32_bf16 v[76:79], v[170:173], v[206:209], v[76:79]
	v_mfma_f32_16x16x32_bf16 v[72:75], v[178:181], v[206:209], v[72:75]
	v_mfma_f32_16x16x32_bf16 v[68:71], v[170:173], v[214:217], v[68:71]
	v_mfma_f32_16x16x32_bf16 v[64:67], v[178:181], v[214:217], v[64:67]
	s_barrier
; #define PG8_STAGE(bufoff, gbase, voff) do { _Pragma("unroll") for (int _i = 0; _i < 2; ++_i) \
;         __builtin_amdgcn_global_load_lds((const unsigned*)((const char*)(gbase) + (voff)[_i]), (LAS unsigned*)(lds + (bufoff) + ldsw + _i * 8192), 16, 0, 0); } while (0)
; #define PG8_STAGEB(bufoff, gbase, perm) do { _Pragma("unroll") for (int _i = 0; _i < 2; ++_i) \
;         __builtin_amdgcn_global_load_lds((const unsigned*)((const char*)(gbase) + ((BSEL && (perm)) ? voffBp[_i] : voffB[_i])), (LAS unsigned*)(lds + (bufoff) + ldsw + _i * 8192), 16, 0, 0); } while (0)
; #define PG8_LDA(dst, b, h) do { _Pragma("unroll") for (int m = 0; m < 4; ++m) _Pragma("unroll") for (int k = 0; k < 2; ++k) dst[m][k] = *(const LAS bf16x8*)(lds + PG8_SA(b, h) + aoff + m * 2048 + k * 1024); } while (0)
; #define PG8_MMA(ai, bj, At, Bt) do { __builtin_amdgcn_s_setprio(1); _Pragma("unroll") for (int m = 0; m < 4; ++m) _Pragma("unroll") for (int n = 0; n < 2; ++n) _Pragma("unroll") for (int k = 0; k < 2; ++k) \
;         acc[ai][bj][m][n] = __builtin_amdgcn_mfma_f32_16x16x32_bf16(Bt[n][k], At[m][k], acc[ai][bj][m][n], 0, 0, 0); __builtin_amdgcn_s_setprio(0); } while (0)
; #define PG8_WAIT_V(n) asm volatile("s_waitcnt vmcnt(" #n ")" ::: "memory")
; #define PG8_WAIT_L(n) asm volatile("s_waitcnt lgkmcnt(" #n ")" ::: "memory")
; #define PG8_BAR __builtin_amdgcn_s_barrier()
; #define PG8_SCHED __builtin_amdgcn_sched_barrier(0)
; template <class Epi, bool BSEL = false>
; __device__ __forceinline__ void gemm_phase(LAS unsigned char* lds, const Gemm g, const Order& S, const Epi& E, const int tid) {
;     ...
;             PG8_LDA(At, 1, 1); PG8_STAGEB(PG8_SB(1, 0), b3, p2); PG8_STAGEB(PG8_SB(1, 1), b3 + h2, p2); PG8_STAGE(PG8_SA(1, 0), a3, voffA);
;             PG8_WAIT_V(8); PG8_WAIT_L(0); PG8_BAR; PG8_MMA(1, 0, At, B0); PG8_MMA(1, 1, At, B1); PG8_BAR; PG8_SCHED;
;         }
;         if constexpr (ALIGN_EPI) { if (wr == 0) PG8_BAR; }
	s_setprio 0
	s_add_i32 s34, s57, s12
	v_lshl_add_u64 v[198:199], v[198:199], 0, s[20:21]
	s_mov_b32 m0, s34
	ds_read_b128 v[182:185], v149 offset:49152
	ds_read_b128 v[186:189], v149 offset:50176
	ds_read_b128 v[190:193], v149 offset:51200
	ds_read_b128 v[194:197], v149 offset:52224
	ds_read_b128 v[202:205], v149 offset:53248
	ds_read_b128 v[206:209], v149 offset:54272
	ds_read_b128 v[210:213], v149 offset:55296
	ds_read_b128 v[214:217], v149 offset:56320
	global_load_lds_dwordx4 v[198:199], off
	s_add_i32 m0, s34, 0x2000
	s_add_u32 s2, s2, 0x40080
	v_lshl_add_u64 v[198:199], v[218:219], 0, s[20:21]
	s_addc_u32 s3, s3, 0
	s_add_i32 s34, s58, s12
	global_load_lds_dwordx4 v[198:199], off
	v_lshl_add_u64 v[198:199], s[2:3], 0, v[132:133]
	s_mov_b32 m0, s34
	s_nop 0
	global_load_lds_dwordx4 v[198:199], off
	v_lshl_add_u64 v[198:199], s[2:3], 0, v[128:129]
	s_add_i32 m0, s34, 0x2000
	s_nop 0
	global_load_lds_dwordx4 v[198:199], off
	v_lshl_add_u64 v[198:199], v[220:221], 0, s[20:21]
	s_mov_b32 m0, s43
	s_nop 0
	global_load_lds_dwordx4 v[198:199], off
	v_lshl_add_u64 v[198:199], v[222:223], 0, s[20:21]
	s_mov_b32 m0, s44
	s_nop 0
	global_load_lds_dwordx4 v[198:199], off
	s_waitcnt vmcnt(8)
	s_waitcnt lgkmcnt(0)
	s_setprio 1
	s_barrier
	v_mfma_f32_16x16x32_bf16 v[60:63], v[150:153], v[182:185], v[60:63]
	v_mfma_f32_16x16x32_bf16 v[56:59], v[158:161], v[182:185], v[56:59]
	v_mfma_f32_16x16x32_bf16 v[52:55], v[150:153], v[190:193], v[52:55]
	v_mfma_f32_16x16x32_bf16 v[48:51], v[158:161], v[190:193], v[48:51]
	v_mfma_f32_16x16x32_bf16 v[44:47], v[150:153], v[202:205], v[44:47]
	v_mfma_f32_16x16x32_bf16 v[40:43], v[158:161], v[202:205], v[40:43]
	v_mfma_f32_16x16x32_bf16 v[36:39], v[150:153], v[210:213], v[36:39]
	v_mfma_f32_16x16x32_bf16 v[32:35], v[158:161], v[210:213], v[32:35]
	v_mfma_f32_16x16x32_bf16 v[60:63], v[154:157], v[186:189], v[60:63]
	v_mfma_f32_16x16x32_bf16 v[56:59], v[162:165], v[186:189], v[56:59]
	v_mfma_f32_16x16x32_bf16 v[52:55], v[154:157], v[194:197], v[52:55]
	v_mfma_f32_16x16x32_bf16 v[48:51], v[162:165], v[194:197], v[48:51]
	v_mfma_f32_16x16x32_bf16 v[44:47], v[154:157], v[206:209], v[44:47]
	v_mfma_f32_16x16x32_bf16 v[40:43], v[162:165], v[206:209], v[40:43]
	v_mfma_f32_16x16x32_bf16 v[36:39], v[154:157], v[214:217], v[36:39]
	v_mfma_f32_16x16x32_bf16 v[32:35], v[162:165], v[214:217], v[32:35]
	v_mfma_f32_16x16x32_bf16 v[28:31], v[166:169], v[182:185], v[28:31]
	v_mfma_f32_16x16x32_bf16 v[24:27], v[174:177], v[182:185], v[24:27]
	v_mfma_f32_16x16x32_bf16 v[20:23], v[166:169], v[190:193], v[20:23]
	v_mfma_f32_16x16x32_bf16 v[16:19], v[174:177], v[190:193], v[16:19]
	v_mfma_f32_16x16x32_bf16 v[12:15], v[166:169], v[202:205], v[12:15]
	v_mfma_f32_16x16x32_bf16 v[8:11], v[174:177], v[202:205], v[8:11]
	v_mfma_f32_16x16x32_bf16 v[4:7], v[166:169], v[210:213], v[4:7]
	v_mfma_f32_16x16x32_bf16 v[0:3], v[174:177], v[210:213], v[0:3]
	v_mfma_f32_16x16x32_bf16 v[28:31], v[170:173], v[186:189], v[28:31]
	v_mfma_f32_16x16x32_bf16 v[24:27], v[178:181], v[186:189], v[24:27]
	v_mfma_f32_16x16x32_bf16 v[20:23], v[170:173], v[194:197], v[20:23]
	v_mfma_f32_16x16x32_bf16 v[16:19], v[178:181], v[194:197], v[16:19]
	v_mfma_f32_16x16x32_bf16 v[12:15], v[170:173], v[206:209], v[12:15]
	v_mfma_f32_16x16x32_bf16 v[8:11], v[178:181], v[206:209], v[8:11]
	v_mfma_f32_16x16x32_bf16 v[4:7], v[170:173], v[214:217], v[4:7]
	v_mfma_f32_16x16x32_bf16 v[0:3], v[178:181], v[214:217], v[0:3]
	s_barrier
	s_setprio 0
	s_add_i32 s56, s56, 2
	s_add_u32 s38, s38, 0x100
	s_addc_u32 s39, s39, 0
	s_cmp_gt_u32 s56, 13
	s_cbranch_scc0 .LBB0_324
	s_and_b64 vcc, exec, s[22:23]
	s_cbranch_vccz .LBB0_327
	s_barrier

; #define PG8_STAGE(bufoff, gbase, voff) do { _Pragma("unroll") for (int _i = 0; _i < 2; ++_i) \
;         __builtin_amdgcn_global_load_lds((const unsigned*)((const char*)(gbase) + (voff)[_i]), (LAS unsigned*)(lds + (bufoff) + ldsw + _i * 8192), 16, 0, 0); } while (0)
; #define PG8_STAGEB(bufoff, gbase, perm) do { _Pragma("unroll") for (int _i = 0; _i < 2; ++_i) \
;         __builtin_amdgcn_global_load_lds((const unsigned*)((const char*)(gbase) + ((BSEL && (perm)) ? voffBp[_i] : voffB[_i])), (LAS unsigned*)(lds + (bufoff) + ldsw + _i * 8192), 16, 0, 0); } while (0)
; #define PG8_LDA(dst, b, h) do { _Pragma("unroll") for (int m = 0; m < 4; ++m) _Pragma("unroll") for (int k = 0; k < 2; ++k) dst[m][k] = *(const LAS bf16x8*)(lds + PG8_SA(b, h) + aoff + m * 2048 + k * 1024); } while (0)
; #define PG8_LDB(dst, b, h) do { _Pragma("unroll") for (int n = 0; n < 2; ++n) _Pragma("unroll") for (int k = 0; k < 2; ++k) dst[n][k] = *(const LAS bf16x8*)(lds + PG8_SB(b, h) + boff + n * 2048 + k * 1024); } while (0)
; #define PG8_MMA(ai, bj, At, Bt) do { __builtin_amdgcn_s_setprio(1); _Pragma("unroll") for (int m = 0; m < 4; ++m) _Pragma("unroll") for (int n = 0; n < 2; ++n) _Pragma("unroll") for (int k = 0; k < 2; ++k) \
;         acc[ai][bj][m][n] = __builtin_amdgcn_mfma_f32_16x16x32_bf16(Bt[n][k], At[m][k], acc[ai][bj][m][n], 0, 0, 0); __builtin_amdgcn_s_setprio(0); } while (0)
; template <class Epi, bool BSEL = false>
; __device__ __forceinline__ void gemm_phase(LAS unsigned char* lds, const Gemm g, const Order& S, const Epi& E, const int tid) {
;     ...
;         for (int t = 0; t < nt; t += 2) {
;             const bool last = (t == nt - 2);
;             const char* a1 = cA + (size_t)(t + 1) * kstep;
;             const char* a2 = last ? nA : cA + (size_t)(t + 2) * kstep; const char* b2 = last ? nB : cB + (size_t)(t + 2) * kstep;
;             const char* a3 = a2 + kstep; const char* b3 = b2 + kstep;
;             const bool p2 = last ? nP : cP; const size_t h2 = last ? nhB : chB;
;             PG8_LDB(B0, 0, 0); PG8_LDB(B1, 0, 1); PG8_SCHED; PG8_LDA(At, 0, 0); PG8_STAGE(PG8_SA(1, 1), a1 + hstepA, voffA);
;             PG8_WAIT_V(8); PG8_WAIT_L(0); PG8_BAR; PG8_MMA(0, 0, At, B0); PG8_MMA(0, 1, At, B1); PG8_BAR; PG8_SCHED;
;             PG8_LDA(At, 0, 1); PG8_STAGEB(PG8_SB(0, 0), b2, p2); PG8_STAGEB(PG8_SB(0, 1), b2 + h2, p2); PG8_STAGE(PG8_SA(0, 0), a2, voffA);
.LBB0_417:
	v_add_u32_e32 v167, s55, v156
	v_add_u32_e32 v201, s56, v156
	ds_read_b128 v[140:143], v167
	ds_read_b128 v[144:147], v167 offset:1024
	ds_read_b128 v[148:151], v167 offset:2048
	ds_read_b128 v[152:155], v167 offset:3072
	ds_read_b128 v[168:171], v201
	ds_read_b128 v[172:175], v201 offset:1024
	ds_read_b128 v[190:193], v201 offset:2048
	ds_read_b128 v[194:197], v201 offset:3072
	s_and_b64 s[2:3], s[46:47], exec
	s_cselect_b32 s45, s41, s5
	s_cselect_b32 s44, s40, s4
	s_cselect_b32 s3, s43, s23
	s_cselect_b32 s2, s42, s22
	s_add_u32 s64, s4, 0xb0080
	s_addc_u32 s65, s5, 0
	s_add_i32 s68, s1, 0xc000
	v_lshl_add_u64 v[176:177], s[64:65], 0, v[130:131]
	s_mov_b32 m0, s68
	s_add_i32 s39, s1, 0xe000
	ds_read_b128 v[202:205], v166
	ds_read_b128 v[206:209], v166 offset:1024
	ds_read_b128 v[210:213], v166 offset:2048
	ds_read_b128 v[214:217], v166 offset:3072
	ds_read_b128 v[218:221], v166 offset:4096
	ds_read_b128 v[222:225], v166 offset:5120
	ds_read_b128 v[226:229], v166 offset:6144
	ds_read_b128 v[230:233], v166 offset:7168
	global_load_lds_dwordx4 v[176:177], off
	v_lshl_add_u64 v[176:177], s[64:65], 0, v[134:135]
	s_mov_b32 m0, s39
	s_nop 0
	global_load_lds_dwordx4 v[176:177], off
	s_waitcnt vmcnt(8)
	s_waitcnt lgkmcnt(0)
	s_setprio 1
	s_barrier
	v_mfma_f32_16x16x32_bf16 v[124:127], v[140:143], v[202:205], v[124:127]
	v_mfma_f32_16x16x32_bf16 v[120:123], v[148:151], v[202:205], v[120:123]
	v_mfma_f32_16x16x32_bf16 v[116:119], v[140:143], v[210:213], v[116:119]
	v_mfma_f32_16x16x32_bf16 v[112:115], v[148:151], v[210:213], v[112:115]
	v_mfma_f32_16x16x32_bf16 v[108:111], v[140:143], v[218:221], v[108:111]
	v_mfma_f32_16x16x32_bf16 v[104:107], v[148:151], v[218:221], v[104:107]
	v_mfma_f32_16x16x32_bf16 v[100:103], v[140:143], v[226:229], v[100:103]
	v_mfma_f32_16x16x32_bf16 v[96:99], v[148:151], v[226:229], v[96:99]
	v_mfma_f32_16x16x32_bf16 v[124:127], v[144:147], v[206:209], v[124:127]
	v_mfma_f32_16x16x32_bf16 v[120:123], v[152:155], v[206:209], v[120:123]
	v_mfma_f32_16x16x32_bf16 v[116:119], v[144:147], v[214:217], v[116:119]
	v_mfma_f32_16x16x32_bf16 v[112:115], v[152:155], v[214:217], v[112:115]
	v_mfma_f32_16x16x32_bf16 v[108:111], v[144:147], v[222:225], v[108:111]
	v_mfma_f32_16x16x32_bf16 v[104:107], v[152:155], v[222:225], v[104:107]
	v_mfma_f32_16x16x32_bf16 v[100:103], v[144:147], v[230:233], v[100:103]
	v_mfma_f32_16x16x32_bf16 v[96:99], v[152:155], v[230:233], v[96:99]
	v_mfma_f32_16x16x32_bf16 v[92:95], v[168:171], v[202:205], v[92:95]
	v_mfma_f32_16x16x32_bf16 v[88:91], v[190:193], v[202:205], v[88:91]
	v_mfma_f32_16x16x32_bf16 v[84:87], v[168:171], v[210:213], v[84:87]
	v_mfma_f32_16x16x32_bf16 v[80:83], v[190:193], v[210:213], v[80:83]
	v_mfma_f32_16x16x32_bf16 v[76:79], v[168:171], v[218:221], v[76:79]
	v_mfma_f32_16x16x32_bf16 v[72:75], v[190:193], v[218:221], v[72:75]
	v_mfma_f32_16x16x32_bf16 v[68:71], v[168:171], v[226:229], v[68:71]
	v_mfma_f32_16x16x32_bf16 v[64:67], v[190:193], v[226:229], v[64:67]
	v_mfma_f32_16x16x32_bf16 v[92:95], v[172:175], v[206:209], v[92:95]
	v_mfma_f32_16x16x32_bf16 v[88:91], v[194:197], v[206:209], v[88:91]
	v_mfma_f32_16x16x32_bf16 v[84:87], v[172:175], v[214:217], v[84:87]
	v_mfma_f32_16x16x32_bf16 v[80:83], v[194:197], v[214:217], v[80:83]
	v_mfma_f32_16x16x32_bf16 v[76:79], v[172:175], v[222:225], v[76:79]
	v_mfma_f32_16x16x32_bf16 v[72:75], v[194:197], v[222:225], v[72:75]
	v_mfma_f32_16x16x32_bf16 v[68:71], v[172:175], v[230:233], v[68:71]
	v_mfma_f32_16x16x32_bf16 v[64:67], v[194:197], v[230:233], v[64:67]
	s_barrier
	s_setprio 0
	v_lshl_add_u64 v[176:177], s[22:23], 0, v[132:133]
	s_add_i32 s66, s55, s20
	v_lshl_add_u64 v[198:199], v[176:177], 0, s[34:35]
	s_mov_b32 m0, s66
	s_add_i32 s63, s66, 0x2000
	ds_read_b128 v[202:205], v166 offset:16384
	ds_read_b128 v[206:209], v166 offset:17408
	ds_read_b128 v[210:213], v166 offset:18432
	ds_read_b128 v[214:217], v166 offset:19456
	ds_read_b128 v[218:221], v166 offset:20480
	ds_read_b128 v[222:225], v166 offset:21504
	ds_read_b128 v[226:229], v166 offset:22528
	ds_read_b128 v[230:233], v166 offset:23552
	global_load_lds_dwordx4 v[198:199], off
	v_lshl_add_u64 v[198:199], s[22:23], 0, v[136:137]
	s_add_u32 s70, s22, 0xb0100
	v_lshl_add_u64 v[234:235], v[198:199], 0, s[34:35]
	s_mov_b32 m0, s63
	s_addc_u32 s71, s23, 0
	s_add_i32 s64, s56, s20
	global_load_lds_dwordx4 v[234:235], off
	v_lshl_add_u64 v[234:235], s[70:71], 0, v[132:133]
	s_mov_b32 m0, s64
	s_add_i32 s65, s64, 0x2000
	global_load_lds_dwordx4 v[234:235], off
	v_lshl_add_u64 v[234:235], s[70:71], 0, v[136:137]
	s_mov_b32 m0, s65
	s_nop 0
	global_load_lds_dwordx4 v[234:235], off
	v_lshl_add_u64 v[234:235], s[4:5], 0, v[130:131]
	v_lshl_add_u64 v[236:237], v[234:235], 0, s[34:35]
	s_mov_b32 m0, s1
	s_nop 0
	global_load_lds_dwordx4 v[236:237], off
	v_lshl_add_u64 v[236:237], s[4:5], 0, v[134:135]
	v_lshl_add_u64 v[238:239], v[236:237], 0, s[34:35]
	s_mov_b32 m0, s49
	s_nop 0
	global_load_lds_dwordx4 v[238:239], off
	s_waitcnt vmcnt(8)
	s_waitcnt lgkmcnt(0)
	s_setprio 1
	s_barrier
; #define PG8_STAGE(bufoff, gbase, voff) do { _Pragma("unroll") for (int _i = 0; _i < 2; ++_i) \
;         __builtin_amdgcn_global_load_lds((const unsigned*)((const char*)(gbase) + (voff)[_i]), (LAS unsigned*)(lds + (bufoff) + ldsw + _i * 8192), 16, 0, 0); } while (0)
; #define PG8_LDA(dst, b, h) do { _Pragma("unroll") for (int m = 0; m < 4; ++m) _Pragma("unroll") for (int k = 0; k < 2; ++k) dst[m][k] = *(const LAS bf16x8*)(lds + PG8_SA(b, h) + aoff + m * 2048 + k * 1024); } while (0)
; #define PG8_LDB(dst, b, h) do { _Pragma("unroll") for (int n = 0; n < 2; ++n) _Pragma("unroll") for (int k = 0; k < 2; ++k) dst[n][k] = *(const LAS bf16x8*)(lds + PG8_SB(b, h) + boff + n * 2048 + k * 1024); } while (0)
; #define PG8_MMA(ai, bj, At, Bt) do { __builtin_amdgcn_s_setprio(1); _Pragma("unroll") for (int m = 0; m < 4; ++m) _Pragma("unroll") for (int n = 0; n < 2; ++n) _Pragma("unroll") for (int k = 0; k < 2; ++k) \
;         acc[ai][bj][m][n] = __builtin_amdgcn_mfma_f32_16x16x32_bf16(Bt[n][k], At[m][k], acc[ai][bj][m][n], 0, 0, 0); __builtin_amdgcn_s_setprio(0); } while (0)
; #define PG8_WAIT_V(n) asm volatile("s_waitcnt vmcnt(" #n ")" ::: "memory")
; #define PG8_WAIT_L(n) asm volatile("s_waitcnt lgkmcnt(" #n ")" ::: "memory")
; #define PG8_BAR __builtin_amdgcn_s_barrier()
; #define PG8_SCHED __builtin_amdgcn_sched_barrier(0)
; template <class Epi, bool BSEL = false>
; __device__ __forceinline__ void gemm_phase(LAS unsigned char* lds, const Gemm g, const Order& S, const Epi& E, const int tid) {
;     ...
;             PG8_WAIT_V(8); PG8_WAIT_L(0); PG8_BAR; PG8_MMA(1, 0, At, B0); PG8_MMA(1, 1, At, B1); PG8_BAR; PG8_SCHED;
;             PG8_LDB(B0, 1, 0); PG8_LDB(B1, 1, 1); PG8_SCHED; PG8_LDA(At, 1, 0); PG8_STAGE(PG8_SA(0, 1), a2 + hstepA, voffA);
;             PG8_WAIT_V(8); PG8_WAIT_L(0); PG8_BAR; PG8_MMA(0, 0, At, B0); PG8_MMA(0, 1, At, B1); PG8_BAR; PG8_SCHED;
	v_mfma_f32_16x16x32_bf16 v[60:63], v[140:143], v[202:205], v[60:63]
	v_mfma_f32_16x16x32_bf16 v[56:59], v[148:151], v[202:205], v[56:59]
	v_mfma_f32_16x16x32_bf16 v[52:55], v[140:143], v[210:213], v[52:55]
	v_mfma_f32_16x16x32_bf16 v[48:51], v[148:151], v[210:213], v[48:51]
	v_mfma_f32_16x16x32_bf16 v[44:47], v[140:143], v[218:221], v[44:47]
	v_mfma_f32_16x16x32_bf16 v[40:43], v[148:151], v[218:221], v[40:43]
	v_mfma_f32_16x16x32_bf16 v[36:39], v[140:143], v[226:229], v[36:39]
	v_mfma_f32_16x16x32_bf16 v[32:35], v[148:151], v[226:229], v[32:35]
	v_mfma_f32_16x16x32_bf16 v[60:63], v[144:147], v[206:209], v[60:63]
	v_mfma_f32_16x16x32_bf16 v[56:59], v[152:155], v[206:209], v[56:59]
	v_mfma_f32_16x16x32_bf16 v[52:55], v[144:147], v[214:217], v[52:55]
	v_mfma_f32_16x16x32_bf16 v[48:51], v[152:155], v[214:217], v[48:51]
	v_mfma_f32_16x16x32_bf16 v[44:47], v[144:147], v[222:225], v[44:47]
	v_mfma_f32_16x16x32_bf16 v[40:43], v[152:155], v[222:225], v[40:43]
	v_mfma_f32_16x16x32_bf16 v[36:39], v[144:147], v[230:233], v[36:39]
	v_mfma_f32_16x16x32_bf16 v[32:35], v[152:155], v[230:233], v[32:35]
	v_mfma_f32_16x16x32_bf16 v[28:31], v[168:171], v[202:205], v[28:31]
	v_mfma_f32_16x16x32_bf16 v[24:27], v[190:193], v[202:205], v[24:27]
	v_mfma_f32_16x16x32_bf16 v[20:23], v[168:171], v[210:213], v[20:23]
	v_mfma_f32_16x16x32_bf16 v[16:19], v[190:193], v[210:213], v[16:19]
	v_mfma_f32_16x16x32_bf16 v[12:15], v[168:171], v[218:221], v[12:15]
	v_mfma_f32_16x16x32_bf16 v[8:11], v[190:193], v[218:221], v[8:11]
	v_mfma_f32_16x16x32_bf16 v[4:7], v[168:171], v[226:229], v[4:7]
	v_mfma_f32_16x16x32_bf16 v[0:3], v[190:193], v[226:229], v[0:3]
	v_mfma_f32_16x16x32_bf16 v[28:31], v[172:175], v[206:209], v[28:31]
	v_mfma_f32_16x16x32_bf16 v[24:27], v[194:197], v[206:209], v[24:27]
	v_mfma_f32_16x16x32_bf16 v[20:23], v[172:175], v[214:217], v[20:23]
	v_mfma_f32_16x16x32_bf16 v[16:19], v[194:197], v[214:217], v[16:19]
	v_mfma_f32_16x16x32_bf16 v[12:15], v[172:175], v[222:225], v[12:15]
	v_mfma_f32_16x16x32_bf16 v[8:11], v[194:197], v[222:225], v[8:11]
	v_mfma_f32_16x16x32_bf16 v[4:7], v[172:175], v[230:233], v[4:7]
	v_mfma_f32_16x16x32_bf16 v[0:3], v[194:197], v[230:233], v[0:3]
	s_barrier
	s_setprio 0
	s_add_i32 s67, 0, 0x18000
	s_add_i32 s69, 0, 0x1c000
	v_add_u32_e32 v240, s67, v156
	v_add_u32_e32 v241, s69, v156
	ds_read_b128 v[140:143], v240
	ds_read_b128 v[144:147], v240 offset:1024
	ds_read_b128 v[148:151], v240 offset:2048
	ds_read_b128 v[152:155], v240 offset:3072
	ds_read_b128 v[168:171], v241
	ds_read_b128 v[172:175], v241 offset:1024
	ds_read_b128 v[190:193], v241 offset:2048
	ds_read_b128 v[194:197], v241 offset:3072
	s_add_u32 s70, s4, 0xb0100
	s_addc_u32 s71, s5, 0
	s_mov_b32 m0, s50
	v_lshl_add_u64 v[238:239], s[70:71], 0, v[130:131]
	ds_read_b128 v[202:205], v166 offset:32768
	ds_read_b128 v[206:209], v166 offset:33792
	ds_read_b128 v[210:213], v166 offset:34816
	ds_read_b128 v[214:217], v166 offset:35840
	ds_read_b128 v[218:221], v166 offset:36864
	ds_read_b128 v[222:225], v166 offset:37888
	ds_read_b128 v[226:229], v166 offset:38912
	ds_read_b128 v[230:233], v166 offset:39936
	global_load_lds_dwordx4 v[238:239], off
	v_lshl_add_u64 v[238:239], s[70:71], 0, v[134:135]
	s_mov_b32 m0, s51
	s_nop 0
	global_load_lds_dwordx4 v[238:239], off
	s_waitcnt vmcnt(8)
	s_waitcnt lgkmcnt(0)
	s_setprio 1
	s_barrier
	v_mfma_f32_16x16x32_bf16 v[124:127], v[140:143], v[202:205], v[124:127]
	v_mfma_f32_16x16x32_bf16 v[120:123], v[148:151], v[202:205], v[120:123]
	v_mfma_f32_16x16x32_bf16 v[116:119], v[140:143], v[210:213], v[116:119]
	v_mfma_f32_16x16x32_bf16 v[112:115], v[148:151], v[210:213], v[112:115]
	v_mfma_f32_16x16x32_bf16 v[108:111], v[140:143], v[218:221], v[108:111]
	v_mfma_f32_16x16x32_bf16 v[104:107], v[148:151], v[218:221], v[104:107]
	v_mfma_f32_16x16x32_bf16 v[100:103], v[140:143], v[226:229], v[100:103]
	v_mfma_f32_16x16x32_bf16 v[96:99], v[148:151], v[226:229], v[96:99]
	v_mfma_f32_16x16x32_bf16 v[124:127], v[144:147], v[206:209], v[124:127]
	v_mfma_f32_16x16x32_bf16 v[120:123], v[152:155], v[206:209], v[120:123]
	v_mfma_f32_16x16x32_bf16 v[116:119], v[144:147], v[214:217], v[116:119]
	v_mfma_f32_16x16x32_bf16 v[112:115], v[152:155], v[214:217], v[112:115]
	v_mfma_f32_16x16x32_bf16 v[108:111], v[144:147], v[222:225], v[108:111]
	v_mfma_f32_16x16x32_bf16 v[104:107], v[152:155], v[222:225], v[104:107]
	v_mfma_f32_16x16x32_bf16 v[100:103], v[144:147], v[230:233], v[100:103]
	v_mfma_f32_16x16x32_bf16 v[96:99], v[152:155], v[230:233], v[96:99]
	v_mfma_f32_16x16x32_bf16 v[92:95], v[168:171], v[202:205], v[92:95]
	v_mfma_f32_16x16x32_bf16 v[88:91], v[190:193], v[202:205], v[88:91]
	v_mfma_f32_16x16x32_bf16 v[84:87], v[168:171], v[210:213], v[84:87]
	v_mfma_f32_16x16x32_bf16 v[80:83], v[190:193], v[210:213], v[80:83]
	v_mfma_f32_16x16x32_bf16 v[76:79], v[168:171], v[218:221], v[76:79]
	v_mfma_f32_16x16x32_bf16 v[72:75], v[190:193], v[218:221], v[72:75]
	v_mfma_f32_16x16x32_bf16 v[68:71], v[168:171], v[226:229], v[68:71]
	v_mfma_f32_16x16x32_bf16 v[64:67], v[190:193], v[226:229], v[64:67]
	v_mfma_f32_16x16x32_bf16 v[92:95], v[172:175], v[206:209], v[92:95]
	v_mfma_f32_16x16x32_bf16 v[88:91], v[194:197], v[206:209], v[88:91]
	v_mfma_f32_16x16x32_bf16 v[84:87], v[172:175], v[214:217], v[84:87]
	v_mfma_f32_16x16x32_bf16 v[80:83], v[194:197], v[214:217], v[80:83]
	v_mfma_f32_16x16x32_bf16 v[76:79], v[172:175], v[222:225], v[76:79]
	v_mfma_f32_16x16x32_bf16 v[72:75], v[194:197], v[222:225], v[72:75]
	v_mfma_f32_16x16x32_bf16 v[68:71], v[172:175], v[230:233], v[68:71]
	v_mfma_f32_16x16x32_bf16 v[64:67], v[194:197], v[230:233], v[64:67]
	s_barrier
; #define PG8_STAGE(bufoff, gbase, voff) do { _Pragma("unroll") for (int _i = 0; _i < 2; ++_i) \
;         __builtin_amdgcn_global_load_lds((const unsigned*)((const char*)(gbase) + (voff)[_i]), (LAS unsigned*)(lds + (bufoff) + ldsw + _i * 8192), 16, 0, 0); } while (0)
; #define PG8_STAGEB(bufoff, gbase, perm) do { _Pragma("unroll") for (int _i = 0; _i < 2; ++_i) \
;         __builtin_amdgcn_global_load_lds((const unsigned*)((const char*)(gbase) + ((BSEL && (perm)) ? voffBp[_i] : voffB[_i])), (LAS unsigned*)(lds + (bufoff) + ldsw + _i * 8192), 16, 0, 0); } while (0)
; #define PG8_LDA(dst, b, h) do { _Pragma("unroll") for (int m = 0; m < 4; ++m) _Pragma("unroll") for (int k = 0; k < 2; ++k) dst[m][k] = *(const LAS bf16x8*)(lds + PG8_SA(b, h) + aoff + m * 2048 + k * 1024); } while (0)
; #define PG8_LDB(dst, b, h) do { _Pragma("unroll") for (int n = 0; n < 2; ++n) _Pragma("unroll") for (int k = 0; k < 2; ++k) dst[n][k] = *(const LAS bf16x8*)(lds + PG8_SB(b, h) + boff + n * 2048 + k * 1024); } while (0)
; #define PG8_MMA(ai, bj, At, Bt) do { __builtin_amdgcn_s_setprio(1); _Pragma("unroll") for (int m = 0; m < 4; ++m) _Pragma("unroll") for (int n = 0; n < 2; ++n) _Pragma("unroll") for (int k = 0; k < 2; ++k) \
;         acc[ai][bj][m][n] = __builtin_amdgcn_mfma_f32_16x16x32_bf16(Bt[n][k], At[m][k], acc[ai][bj][m][n], 0, 0, 0); __builtin_amdgcn_s_setprio(0); } while (0)
; #define PG8_WAIT_V(n) asm volatile("s_waitcnt vmcnt(" #n ")" ::: "memory")
; #define PG8_WAIT_L(n) asm volatile("s_waitcnt lgkmcnt(" #n ")" ::: "memory")
; #define PG8_BAR __builtin_amdgcn_s_barrier()
; #define PG8_SCHED __builtin_amdgcn_sched_barrier(0)
; template <class Epi, bool BSEL = false>
; __device__ __forceinline__ void gemm_phase(LAS unsigned char* lds, const Gemm g, const Order& S, const Epi& E, const int tid) {
;     ...
;             PG8_LDB(B0, 0, 0); PG8_LDB(B1, 0, 1); PG8_SCHED; PG8_LDA(At, 0, 0); PG8_STAGE(PG8_SA(1, 1), a1 + hstepA, voffA);
;             PG8_WAIT_V(8); PG8_WAIT_L(0); PG8_BAR; PG8_MMA(0, 0, At, B0); PG8_MMA(0, 1, At, B1); PG8_BAR; PG8_SCHED;
;     ...
;             PG8_LDA(At, 1, 1); PG8_STAGEB(PG8_SB(1, 0), b3, p2); PG8_STAGEB(PG8_SB(1, 1), b3 + h2, p2); PG8_STAGE(PG8_SA(1, 0), a3, voffA);
;             PG8_WAIT_V(8); PG8_WAIT_L(0); PG8_BAR; PG8_MMA(1, 0, At, B0); PG8_MMA(1, 1, At, B1); PG8_BAR; PG8_SCHED;
	s_setprio 0
	s_add_i32 s71, s67, s20
	s_add_i32 s67, s71, 0x2000
	v_lshl_add_u64 v[176:177], v[176:177], 0, s[36:37]
	s_mov_b32 m0, s71
	s_add_u32 s72, s22, 0xb0180
	ds_read_b128 v[202:205], v166 offset:49152
	ds_read_b128 v[206:209], v166 offset:50176
	ds_read_b128 v[210:213], v166 offset:51200
	ds_read_b128 v[214:217], v166 offset:52224
	ds_read_b128 v[218:221], v166 offset:53248
	ds_read_b128 v[222:225], v166 offset:54272
	ds_read_b128 v[226:229], v166 offset:55296
	ds_read_b128 v[230:233], v166 offset:56320
	global_load_lds_dwordx4 v[176:177], off
	v_lshl_add_u64 v[176:177], v[198:199], 0, s[36:37]
	s_mov_b32 m0, s67
	s_addc_u32 s73, s23, 0
	s_add_i32 s69, s69, s20
	global_load_lds_dwordx4 v[176:177], off
	v_lshl_add_u64 v[176:177], s[72:73], 0, v[132:133]
	s_mov_b32 m0, s69
	s_add_i32 s70, s69, 0x2000
	global_load_lds_dwordx4 v[176:177], off
	v_lshl_add_u64 v[176:177], s[72:73], 0, v[136:137]
	s_mov_b32 m0, s70
	s_nop 0
	global_load_lds_dwordx4 v[176:177], off
	v_lshl_add_u64 v[176:177], v[234:235], 0, s[36:37]
	s_mov_b32 m0, s53
	s_nop 0
	global_load_lds_dwordx4 v[176:177], off
	v_lshl_add_u64 v[176:177], v[236:237], 0, s[36:37]
	s_mov_b32 m0, s54
	s_nop 0
	global_load_lds_dwordx4 v[176:177], off
	s_waitcnt vmcnt(8)
	s_waitcnt lgkmcnt(0)
	s_setprio 1
	s_barrier
	v_mfma_f32_16x16x32_bf16 v[60:63], v[140:143], v[202:205], v[60:63]
	v_mfma_f32_16x16x32_bf16 v[56:59], v[148:151], v[202:205], v[56:59]
	v_mfma_f32_16x16x32_bf16 v[52:55], v[140:143], v[210:213], v[52:55]
	v_mfma_f32_16x16x32_bf16 v[48:51], v[148:151], v[210:213], v[48:51]
	v_mfma_f32_16x16x32_bf16 v[44:47], v[140:143], v[218:221], v[44:47]
	v_mfma_f32_16x16x32_bf16 v[40:43], v[148:151], v[218:221], v[40:43]
	v_mfma_f32_16x16x32_bf16 v[36:39], v[140:143], v[226:229], v[36:39]
	v_mfma_f32_16x16x32_bf16 v[32:35], v[148:151], v[226:229], v[32:35]
	v_mfma_f32_16x16x32_bf16 v[60:63], v[144:147], v[206:209], v[60:63]
	v_mfma_f32_16x16x32_bf16 v[56:59], v[152:155], v[206:209], v[56:59]
	v_mfma_f32_16x16x32_bf16 v[52:55], v[144:147], v[214:217], v[52:55]
	v_mfma_f32_16x16x32_bf16 v[48:51], v[152:155], v[214:217], v[48:51]
	v_mfma_f32_16x16x32_bf16 v[44:47], v[144:147], v[222:225], v[44:47]
	v_mfma_f32_16x16x32_bf16 v[40:43], v[152:155], v[222:225], v[40:43]
	v_mfma_f32_16x16x32_bf16 v[36:39], v[144:147], v[230:233], v[36:39]
	v_mfma_f32_16x16x32_bf16 v[32:35], v[152:155], v[230:233], v[32:35]
	v_mfma_f32_16x16x32_bf16 v[28:31], v[168:171], v[202:205], v[28:31]
	v_mfma_f32_16x16x32_bf16 v[24:27], v[190:193], v[202:205], v[24:27]
	v_mfma_f32_16x16x32_bf16 v[20:23], v[168:171], v[210:213], v[20:23]
	v_mfma_f32_16x16x32_bf16 v[16:19], v[190:193], v[210:213], v[16:19]
	v_mfma_f32_16x16x32_bf16 v[12:15], v[168:171], v[218:221], v[12:15]
	v_mfma_f32_16x16x32_bf16 v[8:11], v[190:193], v[218:221], v[8:11]
	v_mfma_f32_16x16x32_bf16 v[4:7], v[168:171], v[226:229], v[4:7]
	v_mfma_f32_16x16x32_bf16 v[0:3], v[190:193], v[226:229], v[0:3]
	v_mfma_f32_16x16x32_bf16 v[28:31], v[172:175], v[206:209], v[28:31]
	v_mfma_f32_16x16x32_bf16 v[24:27], v[194:197], v[206:209], v[24:27]
	v_mfma_f32_16x16x32_bf16 v[20:23], v[172:175], v[214:217], v[20:23]
	v_mfma_f32_16x16x32_bf16 v[16:19], v[194:197], v[214:217], v[16:19]
	v_mfma_f32_16x16x32_bf16 v[12:15], v[172:175], v[222:225], v[12:15]
	v_mfma_f32_16x16x32_bf16 v[8:11], v[194:197], v[222:225], v[8:11]
	v_mfma_f32_16x16x32_bf16 v[4:7], v[172:175], v[230:233], v[4:7]
	v_mfma_f32_16x16x32_bf16 v[0:3], v[194:197], v[230:233], v[0:3]
	s_barrier
	s_setprio 0
	ds_read_b128 v[140:143], v167
	ds_read_b128 v[144:147], v167 offset:1024
	ds_read_b128 v[148:151], v167 offset:2048
	ds_read_b128 v[152:155], v167 offset:3072
	ds_read_b128 v[168:171], v201
	ds_read_b128 v[172:175], v201 offset:1024
	ds_read_b128 v[190:193], v201 offset:2048
	ds_read_b128 v[194:197], v201 offset:3072
	s_add_u32 s72, s4, 0xb0180
	s_addc_u32 s73, s5, 0
	s_mov_b32 m0, s68
	v_lshl_add_u64 v[176:177], s[72:73], 0, v[130:131]
	ds_read_b128 v[202:205], v166
	ds_read_b128 v[206:209], v166 offset:1024
	ds_read_b128 v[210:213], v166 offset:2048
	ds_read_b128 v[214:217], v166 offset:3072
	ds_read_b128 v[218:221], v166 offset:4096
	ds_read_b128 v[222:225], v166 offset:5120
	ds_read_b128 v[226:229], v166 offset:6144
	ds_read_b128 v[230:233], v166 offset:7168
	global_load_lds_dwordx4 v[176:177], off
	v_lshl_add_u64 v[176:177], s[72:73], 0, v[134:135]
	s_mov_b32 m0, s39
	s_nop 0
	global_load_lds_dwordx4 v[176:177], off
	s_waitcnt vmcnt(8)
	s_waitcnt lgkmcnt(0)
	s_setprio 1
	s_barrier
; #define PG8_STAGE(bufoff, gbase, voff) do { _Pragma("unroll") for (int _i = 0; _i < 2; ++_i) \
;         __builtin_amdgcn_global_load_lds((const unsigned*)((const char*)(gbase) + (voff)[_i]), (LAS unsigned*)(lds + (bufoff) + ldsw + _i * 8192), 16, 0, 0); } while (0)
; #define PG8_STAGEB(bufoff, gbase, perm) do { _Pragma("unroll") for (int _i = 0; _i < 2; ++_i) \
;         __builtin_amdgcn_global_load_lds((const unsigned*)((const char*)(gbase) + ((BSEL && (perm)) ? voffBp[_i] : voffB[_i])), (LAS unsigned*)(lds + (bufoff) + ldsw + _i * 8192), 16, 0, 0); } while (0)
; #define PG8_LDA(dst, b, h) do { _Pragma("unroll") for (int m = 0; m < 4; ++m) _Pragma("unroll") for (int k = 0; k < 2; ++k) dst[m][k] = *(const LAS bf16x8*)(lds + PG8_SA(b, h) + aoff + m * 2048 + k * 1024); } while (0)
; #define PG8_MMA(ai, bj, At, Bt) do { __builtin_amdgcn_s_setprio(1); _Pragma("unroll") for (int m = 0; m < 4; ++m) _Pragma("unroll") for (int n = 0; n < 2; ++n) _Pragma("unroll") for (int k = 0; k < 2; ++k) \
;         acc[ai][bj][m][n] = __builtin_amdgcn_mfma_f32_16x16x32_bf16(Bt[n][k], At[m][k], acc[ai][bj][m][n], 0, 0, 0); __builtin_amdgcn_s_setprio(0); } while (0)
; #define PG8_WAIT_V(n) asm volatile("s_waitcnt vmcnt(" #n ")" ::: "memory")
; #define PG8_WAIT_L(n) asm volatile("s_waitcnt lgkmcnt(" #n ")" ::: "memory")
; #define PG8_BAR __builtin_amdgcn_s_barrier()
; #define PG8_SCHED __builtin_amdgcn_sched_barrier(0)
; template <class Epi, bool BSEL = false>
; __device__ __forceinline__ void gemm_phase(LAS unsigned char* lds, const Gemm g, const Order& S, const Epi& E, const int tid) {
;     ...
;             PG8_WAIT_V(8); PG8_WAIT_L(0); PG8_BAR; PG8_MMA(0, 0, At, B0); PG8_MMA(0, 1, At, B1); PG8_BAR; PG8_SCHED;
;             PG8_LDA(At, 0, 1); PG8_STAGEB(PG8_SB(0, 0), b2, p2); PG8_STAGEB(PG8_SB(0, 1), b2 + h2, p2); PG8_STAGE(PG8_SA(0, 0), a2, voffA);
;             PG8_WAIT_V(8); PG8_WAIT_L(0); PG8_BAR; PG8_MMA(1, 0, At, B0); PG8_MMA(1, 1, At, B1); PG8_BAR; PG8_SCHED;
	v_mfma_f32_16x16x32_bf16 v[124:127], v[140:143], v[202:205], v[124:127]
	v_mfma_f32_16x16x32_bf16 v[120:123], v[148:151], v[202:205], v[120:123]
	v_mfma_f32_16x16x32_bf16 v[116:119], v[140:143], v[210:213], v[116:119]
	v_mfma_f32_16x16x32_bf16 v[112:115], v[148:151], v[210:213], v[112:115]
	v_mfma_f32_16x16x32_bf16 v[108:111], v[140:143], v[218:221], v[108:111]
	v_mfma_f32_16x16x32_bf16 v[104:107], v[148:151], v[218:221], v[104:107]
	v_mfma_f32_16x16x32_bf16 v[100:103], v[140:143], v[226:229], v[100:103]
	v_mfma_f32_16x16x32_bf16 v[96:99], v[148:151], v[226:229], v[96:99]
	v_mfma_f32_16x16x32_bf16 v[124:127], v[144:147], v[206:209], v[124:127]
	v_mfma_f32_16x16x32_bf16 v[120:123], v[152:155], v[206:209], v[120:123]
	v_mfma_f32_16x16x32_bf16 v[116:119], v[144:147], v[214:217], v[116:119]
	v_mfma_f32_16x16x32_bf16 v[112:115], v[152:155], v[214:217], v[112:115]
	v_mfma_f32_16x16x32_bf16 v[108:111], v[144:147], v[222:225], v[108:111]
	v_mfma_f32_16x16x32_bf16 v[104:107], v[152:155], v[222:225], v[104:107]
	v_mfma_f32_16x16x32_bf16 v[100:103], v[144:147], v[230:233], v[100:103]
	v_mfma_f32_16x16x32_bf16 v[96:99], v[152:155], v[230:233], v[96:99]
	v_mfma_f32_16x16x32_bf16 v[92:95], v[168:171], v[202:205], v[92:95]
	v_mfma_f32_16x16x32_bf16 v[88:91], v[190:193], v[202:205], v[88:91]
	v_mfma_f32_16x16x32_bf16 v[84:87], v[168:171], v[210:213], v[84:87]
	v_mfma_f32_16x16x32_bf16 v[80:83], v[190:193], v[210:213], v[80:83]
	v_mfma_f32_16x16x32_bf16 v[76:79], v[168:171], v[218:221], v[76:79]
	v_mfma_f32_16x16x32_bf16 v[72:75], v[190:193], v[218:221], v[72:75]
	v_mfma_f32_16x16x32_bf16 v[68:71], v[168:171], v[226:229], v[68:71]
	v_mfma_f32_16x16x32_bf16 v[64:67], v[190:193], v[226:229], v[64:67]
	v_mfma_f32_16x16x32_bf16 v[92:95], v[172:175], v[206:209], v[92:95]
	v_mfma_f32_16x16x32_bf16 v[88:91], v[194:197], v[206:209], v[88:91]
	v_mfma_f32_16x16x32_bf16 v[84:87], v[172:175], v[214:217], v[84:87]
	v_mfma_f32_16x16x32_bf16 v[80:83], v[194:197], v[214:217], v[80:83]
	v_mfma_f32_16x16x32_bf16 v[76:79], v[172:175], v[222:225], v[76:79]
	v_mfma_f32_16x16x32_bf16 v[72:75], v[194:197], v[222:225], v[72:75]
	v_mfma_f32_16x16x32_bf16 v[68:71], v[172:175], v[230:233], v[68:71]
	v_mfma_f32_16x16x32_bf16 v[64:67], v[194:197], v[230:233], v[64:67]
	s_barrier
	s_setprio 0
	s_mov_b32 m0, s66
	v_lshl_add_u64 v[176:177], s[2:3], 0, v[132:133]
	s_add_u32 s72, s2, 0xb0000
	ds_read_b128 v[202:205], v166 offset:16384
	ds_read_b128 v[206:209], v166 offset:17408
	ds_read_b128 v[210:213], v166 offset:18432
	ds_read_b128 v[214:217], v166 offset:19456
	ds_read_b128 v[218:221], v166 offset:20480
	ds_read_b128 v[222:225], v166 offset:21504
	ds_read_b128 v[226:229], v166 offset:22528
	ds_read_b128 v[230:233], v166 offset:23552
	global_load_lds_dwordx4 v[176:177], off
	v_lshl_add_u64 v[198:199], s[2:3], 0, v[136:137]
	s_mov_b32 m0, s63
	s_addc_u32 s73, s3, 0
	global_load_lds_dwordx4 v[198:199], off
	v_lshl_add_u64 v[234:235], s[72:73], 0, v[132:133]
	s_mov_b32 m0, s64
	v_lshl_add_u64 v[236:237], s[44:45], 0, v[134:135]
	global_load_lds_dwordx4 v[234:235], off
	v_lshl_add_u64 v[234:235], s[72:73], 0, v[136:137]
	s_mov_b32 m0, s65
	s_nop 0
	global_load_lds_dwordx4 v[234:235], off
	v_lshl_add_u64 v[234:235], s[44:45], 0, v[130:131]
	s_mov_b32 m0, s1
	s_nop 0
	global_load_lds_dwordx4 v[234:235], off
	s_mov_b32 m0, s49
	s_nop 0
	global_load_lds_dwordx4 v[236:237], off
	s_waitcnt vmcnt(8)
	s_waitcnt lgkmcnt(0)
	s_setprio 1
	s_barrier
	v_mfma_f32_16x16x32_bf16 v[60:63], v[140:143], v[202:205], v[60:63]
	v_mfma_f32_16x16x32_bf16 v[56:59], v[148:151], v[202:205], v[56:59]
	v_mfma_f32_16x16x32_bf16 v[52:55], v[140:143], v[210:213], v[52:55]
	v_mfma_f32_16x16x32_bf16 v[48:51], v[148:151], v[210:213], v[48:51]
	v_mfma_f32_16x16x32_bf16 v[44:47], v[140:143], v[218:221], v[44:47]
	v_mfma_f32_16x16x32_bf16 v[40:43], v[148:151], v[218:221], v[40:43]
	v_mfma_f32_16x16x32_bf16 v[36:39], v[140:143], v[226:229], v[36:39]
	v_mfma_f32_16x16x32_bf16 v[32:35], v[148:151], v[226:229], v[32:35]
	v_mfma_f32_16x16x32_bf16 v[60:63], v[144:147], v[206:209], v[60:63]
	v_mfma_f32_16x16x32_bf16 v[56:59], v[152:155], v[206:209], v[56:59]
	v_mfma_f32_16x16x32_bf16 v[52:55], v[144:147], v[214:217], v[52:55]
	v_mfma_f32_16x16x32_bf16 v[48:51], v[152:155], v[214:217], v[48:51]
	v_mfma_f32_16x16x32_bf16 v[44:47], v[144:147], v[222:225], v[44:47]
	v_mfma_f32_16x16x32_bf16 v[40:43], v[152:155], v[222:225], v[40:43]
	v_mfma_f32_16x16x32_bf16 v[36:39], v[144:147], v[230:233], v[36:39]
	v_mfma_f32_16x16x32_bf16 v[32:35], v[152:155], v[230:233], v[32:35]
	v_mfma_f32_16x16x32_bf16 v[28:31], v[168:171], v[202:205], v[28:31]
	v_mfma_f32_16x16x32_bf16 v[24:27], v[190:193], v[202:205], v[24:27]
	v_mfma_f32_16x16x32_bf16 v[20:23], v[168:171], v[210:213], v[20:23]
	v_mfma_f32_16x16x32_bf16 v[16:19], v[190:193], v[210:213], v[16:19]
	v_mfma_f32_16x16x32_bf16 v[12:15], v[168:171], v[218:221], v[12:15]
	v_mfma_f32_16x16x32_bf16 v[8:11], v[190:193], v[218:221], v[8:11]
	v_mfma_f32_16x16x32_bf16 v[4:7], v[168:171], v[226:229], v[4:7]
	v_mfma_f32_16x16x32_bf16 v[0:3], v[190:193], v[226:229], v[0:3]
	v_mfma_f32_16x16x32_bf16 v[28:31], v[172:175], v[206:209], v[28:31]
	v_mfma_f32_16x16x32_bf16 v[24:27], v[194:197], v[206:209], v[24:27]
	v_mfma_f32_16x16x32_bf16 v[20:23], v[172:175], v[214:217], v[20:23]
	v_mfma_f32_16x16x32_bf16 v[16:19], v[194:197], v[214:217], v[16:19]
	v_mfma_f32_16x16x32_bf16 v[12:15], v[172:175], v[222:225], v[12:15]
	v_mfma_f32_16x16x32_bf16 v[8:11], v[194:197], v[222:225], v[8:11]
	v_mfma_f32_16x16x32_bf16 v[4:7], v[172:175], v[230:233], v[4:7]
	v_mfma_f32_16x16x32_bf16 v[0:3], v[194:197], v[230:233], v[0:3]
	s_barrier
; #define PG8_STAGE(bufoff, gbase, voff) do { _Pragma("unroll") for (int _i = 0; _i < 2; ++_i) \
;         __builtin_amdgcn_global_load_lds((const unsigned*)((const char*)(gbase) + (voff)[_i]), (LAS unsigned*)(lds + (bufoff) + ldsw + _i * 8192), 16, 0, 0); } while (0)
; #define PG8_STAGEB(bufoff, gbase, perm) do { _Pragma("unroll") for (int _i = 0; _i < 2; ++_i) \
;         __builtin_amdgcn_global_load_lds((const unsigned*)((const char*)(gbase) + ((BSEL && (perm)) ? voffBp[_i] : voffB[_i])), (LAS unsigned*)(lds + (bufoff) + ldsw + _i * 8192), 16, 0, 0); } while (0)
; #define PG8_LDA(dst, b, h) do { _Pragma("unroll") for (int m = 0; m < 4; ++m) _Pragma("unroll") for (int k = 0; k < 2; ++k) dst[m][k] = *(const LAS bf16x8*)(lds + PG8_SA(b, h) + aoff + m * 2048 + k * 1024); } while (0)
; #define PG8_LDB(dst, b, h) do { _Pragma("unroll") for (int n = 0; n < 2; ++n) _Pragma("unroll") for (int k = 0; k < 2; ++k) dst[n][k] = *(const LAS bf16x8*)(lds + PG8_SB(b, h) + boff + n * 2048 + k * 1024); } while (0)
; #define PG8_MMA(ai, bj, At, Bt) do { __builtin_amdgcn_s_setprio(1); _Pragma("unroll") for (int m = 0; m < 4; ++m) _Pragma("unroll") for (int n = 0; n < 2; ++n) _Pragma("unroll") for (int k = 0; k < 2; ++k) \
;         acc[ai][bj][m][n] = __builtin_amdgcn_mfma_f32_16x16x32_bf16(Bt[n][k], At[m][k], acc[ai][bj][m][n], 0, 0, 0); __builtin_amdgcn_s_setprio(0); } while (0)
; #define PG8_WAIT_V(n) asm volatile("s_waitcnt vmcnt(" #n ")" ::: "memory")
; #define PG8_WAIT_L(n) asm volatile("s_waitcnt lgkmcnt(" #n ")" ::: "memory")
; #define PG8_BAR __builtin_amdgcn_s_barrier()
; #define PG8_SCHED __builtin_amdgcn_sched_barrier(0)
; template <class Epi, bool BSEL = false>
; __device__ __forceinline__ void gemm_phase(LAS unsigned char* lds, const Gemm g, const Order& S, const Epi& E, const int tid) {
;     ...
;             PG8_LDB(B0, 1, 0); PG8_LDB(B1, 1, 1); PG8_SCHED; PG8_LDA(At, 1, 0); PG8_STAGE(PG8_SA(0, 1), a2 + hstepA, voffA);
;             PG8_WAIT_V(8); PG8_WAIT_L(0); PG8_BAR; PG8_MMA(0, 0, At, B0); PG8_MMA(0, 1, At, B1); PG8_BAR; PG8_SCHED;
;             PG8_LDA(At, 1, 1); PG8_STAGEB(PG8_SB(1, 0), b3, p2); PG8_STAGEB(PG8_SB(1, 1), b3 + h2, p2); PG8_STAGE(PG8_SA(1, 0), a3, voffA);
;             PG8_WAIT_V(8); PG8_WAIT_L(0); PG8_BAR; PG8_MMA(1, 0, At, B0); PG8_MMA(1, 1, At, B1); PG8_BAR; PG8_SCHED;
;         }
;         if constexpr (ALIGN_EPI) { if (wr == 0) PG8_BAR; }
	s_setprio 0
	ds_read_b128 v[140:143], v240
	ds_read_b128 v[144:147], v240 offset:1024
	ds_read_b128 v[148:151], v240 offset:2048
	ds_read_b128 v[152:155], v240 offset:3072
	ds_read_b128 v[168:171], v241
	ds_read_b128 v[172:175], v241 offset:1024
	ds_read_b128 v[190:193], v241 offset:2048
	ds_read_b128 v[194:197], v241 offset:3072
	s_add_u32 s44, s44, 0xb0000
	s_addc_u32 s45, s45, 0
	s_mov_b32 m0, s50
	v_lshl_add_u64 v[238:239], s[44:45], 0, v[130:131]
	ds_read_b128 v[202:205], v166 offset:32768
	ds_read_b128 v[206:209], v166 offset:33792
	ds_read_b128 v[210:213], v166 offset:34816
	ds_read_b128 v[214:217], v166 offset:35840
	ds_read_b128 v[218:221], v166 offset:36864
	ds_read_b128 v[222:225], v166 offset:37888
	ds_read_b128 v[226:229], v166 offset:38912
	ds_read_b128 v[230:233], v166 offset:39936
	global_load_lds_dwordx4 v[238:239], off
	v_lshl_add_u64 v[238:239], s[44:45], 0, v[134:135]
	s_mov_b32 m0, s51
	s_nop 0
	global_load_lds_dwordx4 v[238:239], off
	s_waitcnt vmcnt(8)
	s_waitcnt lgkmcnt(0)
	s_setprio 1
	s_barrier
	v_mfma_f32_16x16x32_bf16 v[124:127], v[140:143], v[202:205], v[124:127]
	v_mfma_f32_16x16x32_bf16 v[120:123], v[148:151], v[202:205], v[120:123]
	v_mfma_f32_16x16x32_bf16 v[116:119], v[140:143], v[210:213], v[116:119]
	v_mfma_f32_16x16x32_bf16 v[112:115], v[148:151], v[210:213], v[112:115]
	v_mfma_f32_16x16x32_bf16 v[108:111], v[140:143], v[218:221], v[108:111]
	v_mfma_f32_16x16x32_bf16 v[104:107], v[148:151], v[218:221], v[104:107]
	v_mfma_f32_16x16x32_bf16 v[100:103], v[140:143], v[226:229], v[100:103]
	v_mfma_f32_16x16x32_bf16 v[96:99], v[148:151], v[226:229], v[96:99]
	v_mfma_f32_16x16x32_bf16 v[124:127], v[144:147], v[206:209], v[124:127]
	v_mfma_f32_16x16x32_bf16 v[120:123], v[152:155], v[206:209], v[120:123]
	v_mfma_f32_16x16x32_bf16 v[116:119], v[144:147], v[214:217], v[116:119]
	v_mfma_f32_16x16x32_bf16 v[112:115], v[152:155], v[214:217], v[112:115]
	v_mfma_f32_16x16x32_bf16 v[108:111], v[144:147], v[222:225], v[108:111]
	v_mfma_f32_16x16x32_bf16 v[104:107], v[152:155], v[222:225], v[104:107]
	v_mfma_f32_16x16x32_bf16 v[100:103], v[144:147], v[230:233], v[100:103]
	v_mfma_f32_16x16x32_bf16 v[96:99], v[152:155], v[230:233], v[96:99]
	v_mfma_f32_16x16x32_bf16 v[92:95], v[168:171], v[202:205], v[92:95]
	v_mfma_f32_16x16x32_bf16 v[88:91], v[190:193], v[202:205], v[88:91]
	v_mfma_f32_16x16x32_bf16 v[84:87], v[168:171], v[210:213], v[84:87]
	v_mfma_f32_16x16x32_bf16 v[80:83], v[190:193], v[210:213], v[80:83]
	v_mfma_f32_16x16x32_bf16 v[76:79], v[168:171], v[218:221], v[76:79]
	v_mfma_f32_16x16x32_bf16 v[72:75], v[190:193], v[218:221], v[72:75]
	v_mfma_f32_16x16x32_bf16 v[68:71], v[168:171], v[226:229], v[68:71]
	v_mfma_f32_16x16x32_bf16 v[64:67], v[190:193], v[226:229], v[64:67]
	v_mfma_f32_16x16x32_bf16 v[92:95], v[172:175], v[206:209], v[92:95]
	v_mfma_f32_16x16x32_bf16 v[88:91], v[194:197], v[206:209], v[88:91]
	v_mfma_f32_16x16x32_bf16 v[84:87], v[172:175], v[214:217], v[84:87]
	v_mfma_f32_16x16x32_bf16 v[80:83], v[194:197], v[214:217], v[80:83]
	v_mfma_f32_16x16x32_bf16 v[76:79], v[172:175], v[222:225], v[76:79]
	v_mfma_f32_16x16x32_bf16 v[72:75], v[194:197], v[222:225], v[72:75]
	v_mfma_f32_16x16x32_bf16 v[68:71], v[172:175], v[230:233], v[68:71]
	v_mfma_f32_16x16x32_bf16 v[64:67], v[194:197], v[230:233], v[64:67]
	s_barrier
	s_setprio 0
	s_mov_b32 m0, s71
	v_lshl_add_u64 v[176:177], v[176:177], 0, s[26:27]
	s_add_u32 s2, s2, 0xb0080
	ds_read_b128 v[202:205], v166 offset:49152
	ds_read_b128 v[206:209], v166 offset:50176
	ds_read_b128 v[210:213], v166 offset:51200
	ds_read_b128 v[214:217], v166 offset:52224
	ds_read_b128 v[218:221], v166 offset:53248
	ds_read_b128 v[222:225], v166 offset:54272
	ds_read_b128 v[226:229], v166 offset:55296
	ds_read_b128 v[230:233], v166 offset:56320
	global_load_lds_dwordx4 v[176:177], off
	v_lshl_add_u64 v[176:177], v[198:199], 0, s[26:27]
	s_mov_b32 m0, s67
	s_addc_u32 s3, s3, 0
	global_load_lds_dwordx4 v[176:177], off
	v_lshl_add_u64 v[176:177], s[2:3], 0, v[132:133]
	s_mov_b32 m0, s69
	s_nop 0
	global_load_lds_dwordx4 v[176:177], off
	v_lshl_add_u64 v[176:177], s[2:3], 0, v[136:137]
	s_mov_b32 m0, s70
	s_nop 0
	global_load_lds_dwordx4 v[176:177], off
	v_lshl_add_u64 v[176:177], v[234:235], 0, s[26:27]
	s_mov_b32 m0, s53
	s_nop 0
	global_load_lds_dwordx4 v[176:177], off
	v_lshl_add_u64 v[176:177], v[236:237], 0, s[26:27]
	s_mov_b32 m0, s54
	s_nop 0
	global_load_lds_dwordx4 v[176:177], off
	s_waitcnt vmcnt(8)
	s_waitcnt lgkmcnt(0)
	s_setprio 1
	s_barrier
	v_mfma_f32_16x16x32_bf16 v[60:63], v[140:143], v[202:205], v[60:63]
	v_mfma_f32_16x16x32_bf16 v[56:59], v[148:151], v[202:205], v[56:59]
	v_mfma_f32_16x16x32_bf16 v[52:55], v[140:143], v[210:213], v[52:55]
	v_mfma_f32_16x16x32_bf16 v[48:51], v[148:151], v[210:213], v[48:51]
	v_mfma_f32_16x16x32_bf16 v[44:47], v[140:143], v[218:221], v[44:47]
	v_mfma_f32_16x16x32_bf16 v[40:43], v[148:151], v[218:221], v[40:43]
	v_mfma_f32_16x16x32_bf16 v[36:39], v[140:143], v[226:229], v[36:39]
	v_mfma_f32_16x16x32_bf16 v[32:35], v[148:151], v[226:229], v[32:35]
	v_mfma_f32_16x16x32_bf16 v[60:63], v[144:147], v[206:209], v[60:63]
	v_mfma_f32_16x16x32_bf16 v[56:59], v[152:155], v[206:209], v[56:59]
	v_mfma_f32_16x16x32_bf16 v[52:55], v[144:147], v[214:217], v[52:55]
	v_mfma_f32_16x16x32_bf16 v[48:51], v[152:155], v[214:217], v[48:51]
	v_mfma_f32_16x16x32_bf16 v[44:47], v[144:147], v[222:225], v[44:47]
	v_mfma_f32_16x16x32_bf16 v[40:43], v[152:155], v[222:225], v[40:43]
	v_mfma_f32_16x16x32_bf16 v[36:39], v[144:147], v[230:233], v[36:39]
	v_mfma_f32_16x16x32_bf16 v[32:35], v[152:155], v[230:233], v[32:35]
	v_mfma_f32_16x16x32_bf16 v[28:31], v[168:171], v[202:205], v[28:31]
	v_mfma_f32_16x16x32_bf16 v[24:27], v[190:193], v[202:205], v[24:27]
	v_mfma_f32_16x16x32_bf16 v[20:23], v[168:171], v[210:213], v[20:23]
	v_mfma_f32_16x16x32_bf16 v[16:19], v[190:193], v[210:213], v[16:19]
	v_mfma_f32_16x16x32_bf16 v[12:15], v[168:171], v[218:221], v[12:15]
	v_mfma_f32_16x16x32_bf16 v[8:11], v[190:193], v[218:221], v[8:11]
	v_mfma_f32_16x16x32_bf16 v[4:7], v[168:171], v[226:229], v[4:7]
	v_mfma_f32_16x16x32_bf16 v[0:3], v[190:193], v[226:229], v[0:3]
	v_mfma_f32_16x16x32_bf16 v[28:31], v[172:175], v[206:209], v[28:31]
	v_mfma_f32_16x16x32_bf16 v[24:27], v[194:197], v[206:209], v[24:27]
	v_mfma_f32_16x16x32_bf16 v[20:23], v[172:175], v[214:217], v[20:23]
	v_mfma_f32_16x16x32_bf16 v[16:19], v[194:197], v[214:217], v[16:19]
	v_mfma_f32_16x16x32_bf16 v[12:15], v[172:175], v[222:225], v[12:15]
	v_mfma_f32_16x16x32_bf16 v[8:11], v[194:197], v[222:225], v[8:11]
	v_mfma_f32_16x16x32_bf16 v[4:7], v[172:175], v[230:233], v[4:7]
	v_mfma_f32_16x16x32_bf16 v[0:3], v[194:197], v[230:233], v[0:3]
	s_barrier
	s_setprio 0
	s_andn2_b64 vcc, exec, s[28:29]
	s_cbranch_vccnz .LBB0_419
	s_barrier

; #define PG8_STAGE(bufoff, gbase, voff) do { _Pragma("unroll") for (int _i = 0; _i < 2; ++_i) \
;         __builtin_amdgcn_global_load_lds((const unsigned*)((const char*)(gbase) + (voff)[_i]), (LAS unsigned*)(lds + (bufoff) + ldsw + _i * 8192), 16, 0, 0); } while (0)
; #define PG8_STAGEB(bufoff, gbase, perm) do { _Pragma("unroll") for (int _i = 0; _i < 2; ++_i) \
;         __builtin_amdgcn_global_load_lds((const unsigned*)((const char*)(gbase) + ((BSEL && (perm)) ? voffBp[_i] : voffB[_i])), (LAS unsigned*)(lds + (bufoff) + ldsw + _i * 8192), 16, 0, 0); } while (0)
; #define PG8_LDA(dst, b, h) do { _Pragma("unroll") for (int m = 0; m < 4; ++m) _Pragma("unroll") for (int k = 0; k < 2; ++k) dst[m][k] = *(const LAS bf16x8*)(lds + PG8_SA(b, h) + aoff + m * 2048 + k * 1024); } while (0)
; #define PG8_LDB(dst, b, h) do { _Pragma("unroll") for (int n = 0; n < 2; ++n) _Pragma("unroll") for (int k = 0; k < 2; ++k) dst[n][k] = *(const LAS bf16x8*)(lds + PG8_SB(b, h) + boff + n * 2048 + k * 1024); } while (0)
; #define PG8_WAIT_V(n) asm volatile("s_waitcnt vmcnt(" #n ")" ::: "memory")
; #define PG8_WAIT_L(n) asm volatile("s_waitcnt lgkmcnt(" #n ")" ::: "memory")
; #define PG8_BAR __builtin_amdgcn_s_barrier()
; #define PG8_SCHED __builtin_amdgcn_sched_barrier(0)
; template <class Epi, bool BSEL = false>
; __device__ __forceinline__ void gemm_phase(LAS unsigned char* lds, const Gemm g, const Order& S, const Epi& E, const int tid) {
;     ...
;         for (int t = 0; t < nt; t += 2) {
;             const bool last = (t == nt - 2);
;             const char* a1 = cA + (size_t)(t + 1) * kstep;
;             const char* a2 = last ? nA : cA + (size_t)(t + 2) * kstep; const char* b2 = last ? nB : cB + (size_t)(t + 2) * kstep;
;             const char* a3 = a2 + kstep; const char* b3 = b2 + kstep;
;             const bool p2 = last ? nP : cP; const size_t h2 = last ? nhB : chB;
;             PG8_LDB(B0, 0, 0); PG8_LDB(B1, 0, 1); PG8_SCHED; PG8_LDA(At, 0, 0); PG8_STAGE(PG8_SA(1, 1), a1 + hstepA, voffA);
;             PG8_WAIT_V(8); PG8_WAIT_L(0); PG8_BAR; PG8_MMA(0, 0, At, B0); PG8_MMA(0, 1, At, B1); PG8_BAR; PG8_SCHED;
;             PG8_LDA(At, 0, 1); PG8_STAGEB(PG8_SB(0, 0), b2, p2); PG8_STAGEB(PG8_SB(0, 1), b2 + h2, p2); PG8_STAGE(PG8_SA(0, 0), a2, voffA);
;             PG8_WAIT_V(8); PG8_WAIT_L(0); PG8_BAR; PG8_MMA(1, 0, At, B0); PG8_MMA(1, 1, At, B1); PG8_BAR; PG8_SCHED;
.LBB0_440:
	v_add_u32_e32 v176, s46, v133
	ds_read_b128 v[164:167], v176
	ds_read_b128 v[168:171], v176 offset:1024
	ds_read_b128 v[172:175], v176 offset:2048
	ds_read_b128 v[192:195], v176 offset:3072
	v_add_u32_e32 v176, s47, v133
	s_add_u32 s36, s10, s2
	ds_read_b128 v[196:199], v176
	ds_read_b128 v[202:205], v176 offset:1024
	ds_read_b128 v[206:209], v176 offset:2048
	ds_read_b128 v[210:213], v176 offset:3072
	s_addc_u32 s37, s11, s3
	s_add_u32 s36, s36, 0x100
	s_addc_u32 s37, s37, 0
	s_add_u32 s58, s1, s2
	s_addc_u32 s59, s52, s3
	s_cmpk_eq_i32 s2, 0x1500
	s_cselect_b32 s41, s53, s37
	s_cselect_b32 s40, s54, s36
	s_cselect_b32 s37, s55, s59
	s_cselect_b32 s36, s56, s58
	v_lshl_add_u64 v[176:177], v[160:161], 0, s[2:3]
	s_add_i32 m0, s15, 0xc000
	ds_read_b128 v[214:217], v190
	ds_read_b128 v[218:221], v190 offset:1024
	ds_read_b128 v[222:225], v190 offset:2048
	ds_read_b128 v[226:229], v190 offset:3072
	ds_read_b128 v[230:233], v190 offset:4096
	ds_read_b128 v[234:237], v190 offset:5120
	ds_read_b128 v[238:241], v190 offset:6144
	ds_read_b128 v[242:245], v190 offset:7168
	global_load_lds_dwordx4 v[176:177], off
	v_lshl_add_u64 v[176:177], v[162:163], 0, s[2:3]
	s_add_i32 m0, s15, 0xe000
	s_nop 0
	global_load_lds_dwordx4 v[176:177], off
	s_waitcnt vmcnt(8)
	s_waitcnt lgkmcnt(0)
	s_setprio 1
	s_barrier
	v_mfma_f32_16x16x32_bf16 v[124:127], v[164:167], v[214:217], v[124:127]
	v_mfma_f32_16x16x32_bf16 v[120:123], v[172:175], v[214:217], v[120:123]
	v_mfma_f32_16x16x32_bf16 v[116:119], v[164:167], v[222:225], v[116:119]
	v_mfma_f32_16x16x32_bf16 v[112:115], v[172:175], v[222:225], v[112:115]
	v_mfma_f32_16x16x32_bf16 v[108:111], v[164:167], v[230:233], v[108:111]
	v_mfma_f32_16x16x32_bf16 v[104:107], v[172:175], v[230:233], v[104:107]
	v_mfma_f32_16x16x32_bf16 v[100:103], v[164:167], v[238:241], v[100:103]
	v_mfma_f32_16x16x32_bf16 v[96:99], v[172:175], v[238:241], v[96:99]
	v_mfma_f32_16x16x32_bf16 v[124:127], v[168:171], v[218:221], v[124:127]
	v_mfma_f32_16x16x32_bf16 v[120:123], v[192:195], v[218:221], v[120:123]
	v_mfma_f32_16x16x32_bf16 v[116:119], v[168:171], v[226:229], v[116:119]
	v_mfma_f32_16x16x32_bf16 v[112:115], v[192:195], v[226:229], v[112:115]
	v_mfma_f32_16x16x32_bf16 v[108:111], v[168:171], v[234:237], v[108:111]
	v_mfma_f32_16x16x32_bf16 v[104:107], v[192:195], v[234:237], v[104:107]
	v_mfma_f32_16x16x32_bf16 v[100:103], v[168:171], v[242:245], v[100:103]
	v_mfma_f32_16x16x32_bf16 v[96:99], v[192:195], v[242:245], v[96:99]
	v_mfma_f32_16x16x32_bf16 v[92:95], v[196:199], v[214:217], v[92:95]
	v_mfma_f32_16x16x32_bf16 v[88:91], v[206:209], v[214:217], v[88:91]
	v_mfma_f32_16x16x32_bf16 v[84:87], v[196:199], v[222:225], v[84:87]
	v_mfma_f32_16x16x32_bf16 v[80:83], v[206:209], v[222:225], v[80:83]
	v_mfma_f32_16x16x32_bf16 v[76:79], v[196:199], v[230:233], v[76:79]
	v_mfma_f32_16x16x32_bf16 v[72:75], v[206:209], v[230:233], v[72:75]
	v_mfma_f32_16x16x32_bf16 v[68:71], v[196:199], v[238:241], v[68:71]
	v_mfma_f32_16x16x32_bf16 v[64:67], v[206:209], v[238:241], v[64:67]
	v_mfma_f32_16x16x32_bf16 v[92:95], v[202:205], v[218:221], v[92:95]
	v_mfma_f32_16x16x32_bf16 v[88:91], v[210:213], v[218:221], v[88:91]
	v_mfma_f32_16x16x32_bf16 v[84:87], v[202:205], v[226:229], v[84:87]
	v_mfma_f32_16x16x32_bf16 v[80:83], v[210:213], v[226:229], v[80:83]
	v_mfma_f32_16x16x32_bf16 v[76:79], v[202:205], v[234:237], v[76:79]
	v_mfma_f32_16x16x32_bf16 v[72:75], v[210:213], v[234:237], v[72:75]
	v_mfma_f32_16x16x32_bf16 v[68:71], v[202:205], v[242:245], v[68:71]
	v_mfma_f32_16x16x32_bf16 v[64:67], v[210:213], v[242:245], v[64:67]
	s_barrier
	s_setprio 0
	s_add_i32 s58, s46, s14
	v_lshl_add_u64 v[176:177], s[36:37], 0, v[130:131]
	s_mov_b32 m0, s58
	ds_read_b128 v[214:217], v190 offset:16384
	ds_read_b128 v[218:221], v190 offset:17408
	ds_read_b128 v[222:225], v190 offset:18432
	ds_read_b128 v[226:229], v190 offset:19456
	ds_read_b128 v[230:233], v190 offset:20480
	ds_read_b128 v[234:237], v190 offset:21504
	ds_read_b128 v[238:241], v190 offset:22528
	ds_read_b128 v[242:245], v190 offset:23552
	global_load_lds_dwordx4 v[176:177], off
	s_add_i32 m0, s58, 0x2000
	s_add_u32 s58, s36, 0xb0000
	v_lshl_add_u64 v[246:247], s[36:37], 0, v[134:135]
	s_addc_u32 s59, s37, 0
	s_add_i32 s62, s47, s14
	global_load_lds_dwordx4 v[246:247], off
	v_lshl_add_u64 v[248:249], s[58:59], 0, v[130:131]
	s_mov_b32 m0, s62
	v_lshl_add_u64 v[250:251], s[40:41], 0, v[134:135]
	global_load_lds_dwordx4 v[248:249], off
	v_lshl_add_u64 v[248:249], s[58:59], 0, v[134:135]
	s_add_i32 m0, s62, 0x2000
	s_nop 0
	global_load_lds_dwordx4 v[248:249], off
	v_lshl_add_u64 v[248:249], s[40:41], 0, v[130:131]
	s_mov_b32 m0, s15
	s_nop 0
	global_load_lds_dwordx4 v[248:249], off
	s_mov_b32 m0, s20
	s_nop 0
	global_load_lds_dwordx4 v[250:251], off
	s_waitcnt vmcnt(8)
	s_waitcnt lgkmcnt(0)
	s_setprio 1
	s_barrier
; #define PG8_STAGE(bufoff, gbase, voff) do { _Pragma("unroll") for (int _i = 0; _i < 2; ++_i) \
;         __builtin_amdgcn_global_load_lds((const unsigned*)((const char*)(gbase) + (voff)[_i]), (LAS unsigned*)(lds + (bufoff) + ldsw + _i * 8192), 16, 0, 0); } while (0)
; #define PG8_STAGEB(bufoff, gbase, perm) do { _Pragma("unroll") for (int _i = 0; _i < 2; ++_i) \
;         __builtin_amdgcn_global_load_lds((const unsigned*)((const char*)(gbase) + ((BSEL && (perm)) ? voffBp[_i] : voffB[_i])), (LAS unsigned*)(lds + (bufoff) + ldsw + _i * 8192), 16, 0, 0); } while (0)
; #define PG8_LDA(dst, b, h) do { _Pragma("unroll") for (int m = 0; m < 4; ++m) _Pragma("unroll") for (int k = 0; k < 2; ++k) dst[m][k] = *(const LAS bf16x8*)(lds + PG8_SA(b, h) + aoff + m * 2048 + k * 1024); } while (0)
; #define PG8_LDB(dst, b, h) do { _Pragma("unroll") for (int n = 0; n < 2; ++n) _Pragma("unroll") for (int k = 0; k < 2; ++k) dst[n][k] = *(const LAS bf16x8*)(lds + PG8_SB(b, h) + boff + n * 2048 + k * 1024); } while (0)
; #define PG8_MMA(ai, bj, At, Bt) do { __builtin_amdgcn_s_setprio(1); _Pragma("unroll") for (int m = 0; m < 4; ++m) _Pragma("unroll") for (int n = 0; n < 2; ++n) _Pragma("unroll") for (int k = 0; k < 2; ++k) \
;         acc[ai][bj][m][n] = __builtin_amdgcn_mfma_f32_16x16x32_bf16(Bt[n][k], At[m][k], acc[ai][bj][m][n], 0, 0, 0); __builtin_amdgcn_s_setprio(0); } while (0)
; #define PG8_WAIT_V(n) asm volatile("s_waitcnt vmcnt(" #n ")" ::: "memory")
; template <class Epi, bool BSEL = false>
; __device__ __forceinline__ void gemm_phase(LAS unsigned char* lds, const Gemm g, const Order& S, const Epi& E, const int tid) {
;     ...
;             PG8_LDB(B0, 0, 0); PG8_LDB(B1, 0, 1); PG8_SCHED; PG8_LDA(At, 0, 0); PG8_STAGE(PG8_SA(1, 1), a1 + hstepA, voffA);
;             PG8_WAIT_V(8); PG8_WAIT_L(0); PG8_BAR; PG8_MMA(0, 0, At, B0); PG8_MMA(0, 1, At, B1); PG8_BAR; PG8_SCHED;
;             PG8_LDA(At, 0, 1); PG8_STAGEB(PG8_SB(0, 0), b2, p2); PG8_STAGEB(PG8_SB(0, 1), b2 + h2, p2); PG8_STAGE(PG8_SA(0, 0), a2, voffA);
;             PG8_WAIT_V(8); PG8_WAIT_L(0); PG8_BAR; PG8_MMA(1, 0, At, B0); PG8_MMA(1, 1, At, B1); PG8_BAR; PG8_SCHED;
;             PG8_LDB(B0, 1, 0); PG8_LDB(B1, 1, 1); PG8_SCHED; PG8_LDA(At, 1, 0); PG8_STAGE(PG8_SA(0, 1), a2 + hstepA, voffA);
;             PG8_WAIT_V(8); PG8_WAIT_L(0); PG8_BAR; PG8_MMA(0, 0, At, B0); PG8_MMA(0, 1, At, B1); PG8_BAR; PG8_SCHED;
	v_mfma_f32_16x16x32_bf16 v[60:63], v[164:167], v[214:217], v[60:63]
	v_mfma_f32_16x16x32_bf16 v[56:59], v[172:175], v[214:217], v[56:59]
	v_mfma_f32_16x16x32_bf16 v[52:55], v[164:167], v[222:225], v[52:55]
	v_mfma_f32_16x16x32_bf16 v[48:51], v[172:175], v[222:225], v[48:51]
	v_mfma_f32_16x16x32_bf16 v[44:47], v[164:167], v[230:233], v[44:47]
	v_mfma_f32_16x16x32_bf16 v[40:43], v[172:175], v[230:233], v[40:43]
	v_mfma_f32_16x16x32_bf16 v[36:39], v[164:167], v[238:241], v[36:39]
	v_mfma_f32_16x16x32_bf16 v[32:35], v[172:175], v[238:241], v[32:35]
	v_mfma_f32_16x16x32_bf16 v[60:63], v[168:171], v[218:221], v[60:63]
	v_mfma_f32_16x16x32_bf16 v[56:59], v[192:195], v[218:221], v[56:59]
	v_mfma_f32_16x16x32_bf16 v[52:55], v[168:171], v[226:229], v[52:55]
	v_mfma_f32_16x16x32_bf16 v[48:51], v[192:195], v[226:229], v[48:51]
	v_mfma_f32_16x16x32_bf16 v[44:47], v[168:171], v[234:237], v[44:47]
	v_mfma_f32_16x16x32_bf16 v[40:43], v[192:195], v[234:237], v[40:43]
	v_mfma_f32_16x16x32_bf16 v[36:39], v[168:171], v[242:245], v[36:39]
	v_mfma_f32_16x16x32_bf16 v[32:35], v[192:195], v[242:245], v[32:35]
	v_mfma_f32_16x16x32_bf16 v[28:31], v[196:199], v[214:217], v[28:31]
	v_mfma_f32_16x16x32_bf16 v[24:27], v[206:209], v[214:217], v[24:27]
	v_mfma_f32_16x16x32_bf16 v[20:23], v[196:199], v[222:225], v[20:23]
	v_mfma_f32_16x16x32_bf16 v[16:19], v[206:209], v[222:225], v[16:19]
	v_mfma_f32_16x16x32_bf16 v[12:15], v[196:199], v[230:233], v[12:15]
	v_mfma_f32_16x16x32_bf16 v[8:11], v[206:209], v[230:233], v[8:11]
	v_mfma_f32_16x16x32_bf16 v[4:7], v[196:199], v[238:241], v[4:7]
	v_mfma_f32_16x16x32_bf16 v[0:3], v[206:209], v[238:241], v[0:3]
	v_mfma_f32_16x16x32_bf16 v[28:31], v[202:205], v[218:221], v[28:31]
	v_mfma_f32_16x16x32_bf16 v[24:27], v[210:213], v[218:221], v[24:27]
	v_mfma_f32_16x16x32_bf16 v[20:23], v[202:205], v[226:229], v[20:23]
	v_mfma_f32_16x16x32_bf16 v[16:19], v[210:213], v[226:229], v[16:19]
	v_mfma_f32_16x16x32_bf16 v[12:15], v[202:205], v[234:237], v[12:15]
	v_mfma_f32_16x16x32_bf16 v[8:11], v[210:213], v[234:237], v[8:11]
	v_mfma_f32_16x16x32_bf16 v[4:7], v[202:205], v[242:245], v[4:7]
	v_mfma_f32_16x16x32_bf16 v[0:3], v[210:213], v[242:245], v[0:3]
	s_barrier
	s_setprio 0
	s_add_i32 s58, 0, 0x18000
	v_add_u32_e32 v191, s58, v133
	s_add_i32 s59, 0, 0x1c000
	ds_read_b128 v[164:167], v191
	ds_read_b128 v[168:171], v191 offset:1024
	ds_read_b128 v[172:175], v191 offset:2048
	ds_read_b128 v[192:195], v191 offset:3072
	v_add_u32_e32 v191, s59, v133
	ds_read_b128 v[196:199], v191
	ds_read_b128 v[202:205], v191 offset:1024
	ds_read_b128 v[206:209], v191 offset:2048
	ds_read_b128 v[210:213], v191 offset:3072
	s_add_u32 s40, s40, 0xb0000
	s_addc_u32 s41, s41, 0
	s_mov_b32 m0, s21
	v_lshl_add_u64 v[252:253], s[40:41], 0, v[130:131]
	ds_read_b128 v[214:217], v190 offset:32768
	ds_read_b128 v[218:221], v190 offset:33792
	ds_read_b128 v[222:225], v190 offset:34816
	ds_read_b128 v[226:229], v190 offset:35840
	ds_read_b128 v[230:233], v190 offset:36864
	ds_read_b128 v[234:237], v190 offset:37888
	ds_read_b128 v[238:241], v190 offset:38912
	ds_read_b128 v[242:245], v190 offset:39936
	global_load_lds_dwordx4 v[252:253], off
	v_lshl_add_u64 v[252:253], s[40:41], 0, v[134:135]
	s_mov_b32 m0, s42
	s_nop 0
	global_load_lds_dwordx4 v[252:253], off
	s_waitcnt vmcnt(8)
	s_waitcnt lgkmcnt(0)
	s_setprio 1
	s_barrier
	v_mfma_f32_16x16x32_bf16 v[124:127], v[164:167], v[214:217], v[124:127]
	v_mfma_f32_16x16x32_bf16 v[120:123], v[172:175], v[214:217], v[120:123]
	v_mfma_f32_16x16x32_bf16 v[116:119], v[164:167], v[222:225], v[116:119]
	v_mfma_f32_16x16x32_bf16 v[112:115], v[172:175], v[222:225], v[112:115]
	v_mfma_f32_16x16x32_bf16 v[108:111], v[164:167], v[230:233], v[108:111]
	v_mfma_f32_16x16x32_bf16 v[104:107], v[172:175], v[230:233], v[104:107]
	v_mfma_f32_16x16x32_bf16 v[100:103], v[164:167], v[238:241], v[100:103]
	v_mfma_f32_16x16x32_bf16 v[96:99], v[172:175], v[238:241], v[96:99]
	v_mfma_f32_16x16x32_bf16 v[124:127], v[168:171], v[218:221], v[124:127]
	v_mfma_f32_16x16x32_bf16 v[120:123], v[192:195], v[218:221], v[120:123]
	v_mfma_f32_16x16x32_bf16 v[116:119], v[168:171], v[226:229], v[116:119]
	v_mfma_f32_16x16x32_bf16 v[112:115], v[192:195], v[226:229], v[112:115]
	v_mfma_f32_16x16x32_bf16 v[108:111], v[168:171], v[234:237], v[108:111]
	v_mfma_f32_16x16x32_bf16 v[104:107], v[192:195], v[234:237], v[104:107]
	v_mfma_f32_16x16x32_bf16 v[100:103], v[168:171], v[242:245], v[100:103]
	v_mfma_f32_16x16x32_bf16 v[96:99], v[192:195], v[242:245], v[96:99]
	v_mfma_f32_16x16x32_bf16 v[92:95], v[196:199], v[214:217], v[92:95]
	v_mfma_f32_16x16x32_bf16 v[88:91], v[206:209], v[214:217], v[88:91]
	v_mfma_f32_16x16x32_bf16 v[84:87], v[196:199], v[222:225], v[84:87]
	v_mfma_f32_16x16x32_bf16 v[80:83], v[206:209], v[222:225], v[80:83]
	v_mfma_f32_16x16x32_bf16 v[76:79], v[196:199], v[230:233], v[76:79]
	v_mfma_f32_16x16x32_bf16 v[72:75], v[206:209], v[230:233], v[72:75]
	v_mfma_f32_16x16x32_bf16 v[68:71], v[196:199], v[238:241], v[68:71]
	v_mfma_f32_16x16x32_bf16 v[64:67], v[206:209], v[238:241], v[64:67]
	v_mfma_f32_16x16x32_bf16 v[92:95], v[202:205], v[218:221], v[92:95]
	v_mfma_f32_16x16x32_bf16 v[88:91], v[210:213], v[218:221], v[88:91]
	v_mfma_f32_16x16x32_bf16 v[84:87], v[202:205], v[226:229], v[84:87]
	v_mfma_f32_16x16x32_bf16 v[80:83], v[210:213], v[226:229], v[80:83]
	v_mfma_f32_16x16x32_bf16 v[76:79], v[202:205], v[234:237], v[76:79]
	v_mfma_f32_16x16x32_bf16 v[72:75], v[210:213], v[234:237], v[72:75]
	v_mfma_f32_16x16x32_bf16 v[68:71], v[202:205], v[242:245], v[68:71]
	v_mfma_f32_16x16x32_bf16 v[64:67], v[210:213], v[242:245], v[64:67]
	s_barrier
; #define PG8_STAGE(bufoff, gbase, voff) do { _Pragma("unroll") for (int _i = 0; _i < 2; ++_i) \
;         __builtin_amdgcn_global_load_lds((const unsigned*)((const char*)(gbase) + (voff)[_i]), (LAS unsigned*)(lds + (bufoff) + ldsw + _i * 8192), 16, 0, 0); } while (0)
; #define PG8_STAGEB(bufoff, gbase, perm) do { _Pragma("unroll") for (int _i = 0; _i < 2; ++_i) \
;         __builtin_amdgcn_global_load_lds((const unsigned*)((const char*)(gbase) + ((BSEL && (perm)) ? voffBp[_i] : voffB[_i])), (LAS unsigned*)(lds + (bufoff) + ldsw + _i * 8192), 16, 0, 0); } while (0)
; #define PG8_LDA(dst, b, h) do { _Pragma("unroll") for (int m = 0; m < 4; ++m) _Pragma("unroll") for (int k = 0; k < 2; ++k) dst[m][k] = *(const LAS bf16x8*)(lds + PG8_SA(b, h) + aoff + m * 2048 + k * 1024); } while (0)
; #define PG8_MMA(ai, bj, At, Bt) do { __builtin_amdgcn_s_setprio(1); _Pragma("unroll") for (int m = 0; m < 4; ++m) _Pragma("unroll") for (int n = 0; n < 2; ++n) _Pragma("unroll") for (int k = 0; k < 2; ++k) \
;         acc[ai][bj][m][n] = __builtin_amdgcn_mfma_f32_16x16x32_bf16(Bt[n][k], At[m][k], acc[ai][bj][m][n], 0, 0, 0); __builtin_amdgcn_s_setprio(0); } while (0)
; #define PG8_WAIT_V(n) asm volatile("s_waitcnt vmcnt(" #n ")" ::: "memory")
; #define PG8_WAIT_L(n) asm volatile("s_waitcnt lgkmcnt(" #n ")" ::: "memory")
; #define PG8_BAR __builtin_amdgcn_s_barrier()
; #define PG8_SCHED __builtin_amdgcn_sched_barrier(0)
; template <class Epi, bool BSEL = false>
; __device__ __forceinline__ void gemm_phase(LAS unsigned char* lds, const Gemm g, const Order& S, const Epi& E, const int tid) {
;     ...
;             PG8_LDA(At, 1, 1); PG8_STAGEB(PG8_SB(1, 0), b3, p2); PG8_STAGEB(PG8_SB(1, 1), b3 + h2, p2); PG8_STAGE(PG8_SA(1, 0), a3, voffA);
;             PG8_WAIT_V(8); PG8_WAIT_L(0); PG8_BAR; PG8_MMA(1, 0, At, B0); PG8_MMA(1, 1, At, B1); PG8_BAR; PG8_SCHED;
;         }
;         if constexpr (ALIGN_EPI) { if (wr == 0) PG8_BAR; }
	s_setprio 0
	s_add_i32 s40, s58, s14
	v_lshl_add_u64 v[176:177], v[176:177], 0, s[24:25]
	s_mov_b32 m0, s40
	ds_read_b128 v[214:217], v190 offset:49152
	ds_read_b128 v[218:221], v190 offset:50176
	ds_read_b128 v[222:225], v190 offset:51200
	ds_read_b128 v[226:229], v190 offset:52224
	ds_read_b128 v[230:233], v190 offset:53248
	ds_read_b128 v[234:237], v190 offset:54272
	ds_read_b128 v[238:241], v190 offset:55296
	ds_read_b128 v[242:245], v190 offset:56320
	global_load_lds_dwordx4 v[176:177], off
	s_add_i32 m0, s40, 0x2000
	s_add_u32 s36, s36, 0xb0080
	v_lshl_add_u64 v[176:177], v[246:247], 0, s[24:25]
	s_addc_u32 s37, s37, 0
	s_add_i32 s40, s59, s14
	global_load_lds_dwordx4 v[176:177], off
	v_lshl_add_u64 v[176:177], s[36:37], 0, v[130:131]
	s_mov_b32 m0, s40
	s_nop 0
	global_load_lds_dwordx4 v[176:177], off
	v_lshl_add_u64 v[176:177], s[36:37], 0, v[134:135]
	s_add_i32 m0, s40, 0x2000
	s_nop 0
	global_load_lds_dwordx4 v[176:177], off
	v_lshl_add_u64 v[176:177], v[248:249], 0, s[24:25]
	s_mov_b32 m0, s44
	s_nop 0
	global_load_lds_dwordx4 v[176:177], off
	v_lshl_add_u64 v[176:177], v[250:251], 0, s[24:25]
	s_mov_b32 m0, s45
	s_nop 0
	global_load_lds_dwordx4 v[176:177], off
	s_waitcnt vmcnt(8)
	s_waitcnt lgkmcnt(0)
	s_setprio 1
	s_barrier
	v_mfma_f32_16x16x32_bf16 v[60:63], v[164:167], v[214:217], v[60:63]
	v_mfma_f32_16x16x32_bf16 v[56:59], v[172:175], v[214:217], v[56:59]
	v_mfma_f32_16x16x32_bf16 v[52:55], v[164:167], v[222:225], v[52:55]
	v_mfma_f32_16x16x32_bf16 v[48:51], v[172:175], v[222:225], v[48:51]
	v_mfma_f32_16x16x32_bf16 v[44:47], v[164:167], v[230:233], v[44:47]
	v_mfma_f32_16x16x32_bf16 v[40:43], v[172:175], v[230:233], v[40:43]
	v_mfma_f32_16x16x32_bf16 v[36:39], v[164:167], v[238:241], v[36:39]
	v_mfma_f32_16x16x32_bf16 v[32:35], v[172:175], v[238:241], v[32:35]
	v_mfma_f32_16x16x32_bf16 v[60:63], v[168:171], v[218:221], v[60:63]
	v_mfma_f32_16x16x32_bf16 v[56:59], v[192:195], v[218:221], v[56:59]
	v_mfma_f32_16x16x32_bf16 v[52:55], v[168:171], v[226:229], v[52:55]
	v_mfma_f32_16x16x32_bf16 v[48:51], v[192:195], v[226:229], v[48:51]
	v_mfma_f32_16x16x32_bf16 v[44:47], v[168:171], v[234:237], v[44:47]
	v_mfma_f32_16x16x32_bf16 v[40:43], v[192:195], v[234:237], v[40:43]
	v_mfma_f32_16x16x32_bf16 v[36:39], v[168:171], v[242:245], v[36:39]
	v_mfma_f32_16x16x32_bf16 v[32:35], v[192:195], v[242:245], v[32:35]
	v_mfma_f32_16x16x32_bf16 v[28:31], v[196:199], v[214:217], v[28:31]
	v_mfma_f32_16x16x32_bf16 v[24:27], v[206:209], v[214:217], v[24:27]
	v_mfma_f32_16x16x32_bf16 v[20:23], v[196:199], v[222:225], v[20:23]
	v_mfma_f32_16x16x32_bf16 v[16:19], v[206:209], v[222:225], v[16:19]
	v_mfma_f32_16x16x32_bf16 v[12:15], v[196:199], v[230:233], v[12:15]
	v_mfma_f32_16x16x32_bf16 v[8:11], v[206:209], v[230:233], v[8:11]
	v_mfma_f32_16x16x32_bf16 v[4:7], v[196:199], v[238:241], v[4:7]
	v_mfma_f32_16x16x32_bf16 v[0:3], v[206:209], v[238:241], v[0:3]
	v_mfma_f32_16x16x32_bf16 v[28:31], v[202:205], v[218:221], v[28:31]
	v_mfma_f32_16x16x32_bf16 v[24:27], v[210:213], v[218:221], v[24:27]
	v_mfma_f32_16x16x32_bf16 v[20:23], v[202:205], v[226:229], v[20:23]
	v_mfma_f32_16x16x32_bf16 v[16:19], v[210:213], v[226:229], v[16:19]
	v_mfma_f32_16x16x32_bf16 v[12:15], v[202:205], v[234:237], v[12:15]
	v_mfma_f32_16x16x32_bf16 v[8:11], v[210:213], v[234:237], v[8:11]
	v_mfma_f32_16x16x32_bf16 v[4:7], v[202:205], v[242:245], v[4:7]
	v_mfma_f32_16x16x32_bf16 v[0:3], v[210:213], v[242:245], v[0:3]
	s_barrier
	s_setprio 0
	s_add_i32 s57, s57, 2
	s_add_u32 s2, s2, 0x100
	s_addc_u32 s3, s3, 0
	s_cmp_gt_u32 s57, 41
	s_cbranch_scc0 .LBB0_440
	s_and_b64 vcc, exec, s[26:27]
	s_cbranch_vccz .LBB0_443
	s_barrier

; #define PG8_STAGE(bufoff, gbase, voff) do { _Pragma("unroll") for (int _i = 0; _i < 2; ++_i) \
;         __builtin_amdgcn_global_load_lds((const unsigned*)((const char*)(gbase) + (voff)[_i]), (LAS unsigned*)(lds + (bufoff) + ldsw + _i * 8192), 16, 0, 0); } while (0)
; #define PG8_STAGEB(bufoff, gbase, perm) do { _Pragma("unroll") for (int _i = 0; _i < 2; ++_i) \
;         __builtin_amdgcn_global_load_lds((const unsigned*)((const char*)(gbase) + ((BSEL && (perm)) ? voffBp[_i] : voffB[_i])), (LAS unsigned*)(lds + (bufoff) + ldsw + _i * 8192), 16, 0, 0); } while (0)
; #define PG8_LDA(dst, b, h) do { _Pragma("unroll") for (int m = 0; m < 4; ++m) _Pragma("unroll") for (int k = 0; k < 2; ++k) dst[m][k] = *(const LAS bf16x8*)(lds + PG8_SA(b, h) + aoff + m * 2048 + k * 1024); } while (0)
; #define PG8_LDB(dst, b, h) do { _Pragma("unroll") for (int n = 0; n < 2; ++n) _Pragma("unroll") for (int k = 0; k < 2; ++k) dst[n][k] = *(const LAS bf16x8*)(lds + PG8_SB(b, h) + boff + n * 2048 + k * 1024); } while (0)
; #define PG8_MMA(ai, bj, At, Bt) do { __builtin_amdgcn_s_setprio(1); _Pragma("unroll") for (int m = 0; m < 4; ++m) _Pragma("unroll") for (int n = 0; n < 2; ++n) _Pragma("unroll") for (int k = 0; k < 2; ++k) \
;         acc[ai][bj][m][n] = __builtin_amdgcn_mfma_f32_16x16x32_bf16(Bt[n][k], At[m][k], acc[ai][bj][m][n], 0, 0, 0); __builtin_amdgcn_s_setprio(0); } while (0)
; #define PG8_WAIT_V(n) asm volatile("s_waitcnt vmcnt(" #n ")" ::: "memory")
; #define PG8_WAIT_L(n) asm volatile("s_waitcnt lgkmcnt(" #n ")" ::: "memory")
; #define PG8_BAR __builtin_amdgcn_s_barrier()
; #define PG8_SCHED __builtin_amdgcn_sched_barrier(0)
; template <class Epi, bool BSEL = false>
; __device__ __forceinline__ void gemm_phase(LAS unsigned char* lds, const Gemm g, const Order& S, const Epi& E, const int tid) {
;     ...
;             PG8_LDB(B0, 0, 0); PG8_LDB(B1, 0, 1); PG8_SCHED; PG8_LDA(At, 0, 0); PG8_STAGE(PG8_SA(1, 1), a1 + hstepA, voffA);
;             PG8_WAIT_V(8); PG8_WAIT_L(0); PG8_BAR; PG8_MMA(0, 0, At, B0); PG8_MMA(0, 1, At, B1); PG8_BAR; PG8_SCHED;
;             PG8_LDA(At, 0, 1); PG8_STAGEB(PG8_SB(0, 0), b2, p2); PG8_STAGEB(PG8_SB(0, 1), b2 + h2, p2); PG8_STAGE(PG8_SA(0, 0), a2, voffA);
;             PG8_WAIT_V(8); PG8_WAIT_L(0); PG8_BAR; PG8_MMA(1, 0, At, B0); PG8_MMA(1, 1, At, B1); PG8_BAR; PG8_SCHED;
.LBB0_472:
	v_add_u32_e32 v164, s52, v139
	v_add_u32_e32 v176, s53, v139
	s_add_u32 s46, s26, s44
	ds_read_b128 v[152:155], v164
	ds_read_b128 v[156:159], v164 offset:1024
	ds_read_b128 v[160:163], v164 offset:2048
	ds_read_b128 v[164:167], v164 offset:3072
	ds_read_b128 v[168:171], v176
	ds_read_b128 v[172:175], v176 offset:1024
	ds_read_b128 v[180:183], v176 offset:2048
	ds_read_b128 v[184:187], v176 offset:3072
	s_addc_u32 s47, s27, s45
	s_add_u32 s46, s46, 0x100
	s_addc_u32 s47, s47, 0
	s_add_u32 s65, s41, s44
	s_addc_u32 s66, s57, s45
	s_cmpk_eq_i32 s44, 0x1500
	s_cselect_b32 s49, s58, s47
	s_cselect_b32 s48, s59, s46
	s_cselect_b32 s47, s62, s66
	s_cselect_b32 s46, s63, s65
	v_lshl_add_u64 v[176:177], v[146:147], 0, s[44:45]
	s_add_i32 m0, s20, 0xc000
	ds_read_b128 v[188:191], v151
	ds_read_b128 v[192:195], v151 offset:1024
	ds_read_b128 v[196:199], v151 offset:2048
	ds_read_b128 v[202:205], v151 offset:3072
	ds_read_b128 v[206:209], v151 offset:4096
	ds_read_b128 v[210:213], v151 offset:5120
	ds_read_b128 v[214:217], v151 offset:6144
	ds_read_b128 v[218:221], v151 offset:7168
	global_load_lds_dwordx4 v[176:177], off
	v_lshl_add_u64 v[176:177], v[148:149], 0, s[44:45]
	s_add_i32 m0, s20, 0xe000
	s_nop 0
	global_load_lds_dwordx4 v[176:177], off
	s_waitcnt vmcnt(8)
	s_waitcnt lgkmcnt(0)
	s_setprio 1
	s_barrier
	v_mfma_f32_16x16x32_bf16 v[124:127], v[152:155], v[188:191], v[124:127]
	v_mfma_f32_16x16x32_bf16 v[120:123], v[160:163], v[188:191], v[120:123]
	v_mfma_f32_16x16x32_bf16 v[108:111], v[152:155], v[196:199], v[108:111]
	v_mfma_f32_16x16x32_bf16 v[104:107], v[160:163], v[196:199], v[104:107]
	v_mfma_f32_16x16x32_bf16 v[92:95], v[152:155], v[206:209], v[92:95]
	v_mfma_f32_16x16x32_bf16 v[88:91], v[160:163], v[206:209], v[88:91]
	v_mfma_f32_16x16x32_bf16 v[76:79], v[152:155], v[214:217], v[76:79]
	v_mfma_f32_16x16x32_bf16 v[72:75], v[160:163], v[214:217], v[72:75]
	v_mfma_f32_16x16x32_bf16 v[124:127], v[156:159], v[192:195], v[124:127]
	v_mfma_f32_16x16x32_bf16 v[120:123], v[164:167], v[192:195], v[120:123]
	v_mfma_f32_16x16x32_bf16 v[108:111], v[156:159], v[202:205], v[108:111]
	v_mfma_f32_16x16x32_bf16 v[104:107], v[164:167], v[202:205], v[104:107]
	v_mfma_f32_16x16x32_bf16 v[92:95], v[156:159], v[210:213], v[92:95]
	v_mfma_f32_16x16x32_bf16 v[88:91], v[164:167], v[210:213], v[88:91]
	v_mfma_f32_16x16x32_bf16 v[76:79], v[156:159], v[218:221], v[76:79]
	v_mfma_f32_16x16x32_bf16 v[72:75], v[164:167], v[218:221], v[72:75]
	v_mfma_f32_16x16x32_bf16 v[116:119], v[168:171], v[188:191], v[116:119]
	v_mfma_f32_16x16x32_bf16 v[112:115], v[180:183], v[188:191], v[112:115]
	v_mfma_f32_16x16x32_bf16 v[100:103], v[168:171], v[196:199], v[100:103]
	v_mfma_f32_16x16x32_bf16 v[96:99], v[180:183], v[196:199], v[96:99]
	v_mfma_f32_16x16x32_bf16 v[84:87], v[168:171], v[206:209], v[84:87]
	v_mfma_f32_16x16x32_bf16 v[80:83], v[180:183], v[206:209], v[80:83]
	v_mfma_f32_16x16x32_bf16 v[68:71], v[168:171], v[214:217], v[68:71]
	v_mfma_f32_16x16x32_bf16 v[64:67], v[180:183], v[214:217], v[64:67]
	v_mfma_f32_16x16x32_bf16 v[116:119], v[172:175], v[192:195], v[116:119]
	v_mfma_f32_16x16x32_bf16 v[112:115], v[184:187], v[192:195], v[112:115]
	v_mfma_f32_16x16x32_bf16 v[100:103], v[172:175], v[202:205], v[100:103]
	v_mfma_f32_16x16x32_bf16 v[96:99], v[184:187], v[202:205], v[96:99]
	v_mfma_f32_16x16x32_bf16 v[84:87], v[172:175], v[210:213], v[84:87]
	v_mfma_f32_16x16x32_bf16 v[80:83], v[184:187], v[210:213], v[80:83]
	v_mfma_f32_16x16x32_bf16 v[68:71], v[172:175], v[218:221], v[68:71]
	v_mfma_f32_16x16x32_bf16 v[64:67], v[184:187], v[218:221], v[64:67]
	s_barrier
	s_setprio 0
	s_add_i32 s65, s52, s15
	v_lshl_add_u64 v[176:177], s[46:47], 0, v[132:133]
	s_mov_b32 m0, s65
	ds_read_b128 v[188:191], v151 offset:16384
	ds_read_b128 v[192:195], v151 offset:17408
	ds_read_b128 v[196:199], v151 offset:18432
	ds_read_b128 v[202:205], v151 offset:19456
	ds_read_b128 v[206:209], v151 offset:20480
	ds_read_b128 v[210:213], v151 offset:21504
	ds_read_b128 v[214:217], v151 offset:22528
	ds_read_b128 v[218:221], v151 offset:23552
	global_load_lds_dwordx4 v[176:177], off
	s_add_i32 m0, s65, 0x2000
	s_add_u32 s66, s46, 0xb0000
	v_lshl_add_u64 v[222:223], s[46:47], 0, v[136:137]
	s_addc_u32 s67, s47, 0
	s_add_i32 s65, s53, s15
	global_load_lds_dwordx4 v[222:223], off
	v_lshl_add_u64 v[224:225], s[66:67], 0, v[132:133]
	s_mov_b32 m0, s65
	v_lshl_add_u64 v[226:227], s[48:49], 0, v[134:135]
	global_load_lds_dwordx4 v[224:225], off
	v_lshl_add_u64 v[224:225], s[66:67], 0, v[136:137]
	s_add_i32 m0, s65, 0x2000
	s_nop 0
	global_load_lds_dwordx4 v[224:225], off
	v_lshl_add_u64 v[224:225], s[48:49], 0, v[130:131]
	s_mov_b32 m0, s20
	s_nop 0
	global_load_lds_dwordx4 v[224:225], off
	s_mov_b32 m0, s21
	s_nop 0
	global_load_lds_dwordx4 v[226:227], off
	s_waitcnt vmcnt(8)
	s_waitcnt lgkmcnt(0)
	s_setprio 1
	s_barrier
; #define PG8_STAGE(bufoff, gbase, voff) do { _Pragma("unroll") for (int _i = 0; _i < 2; ++_i) \
;         __builtin_amdgcn_global_load_lds((const unsigned*)((const char*)(gbase) + (voff)[_i]), (LAS unsigned*)(lds + (bufoff) + ldsw + _i * 8192), 16, 0, 0); } while (0)
; #define PG8_LDA(dst, b, h) do { _Pragma("unroll") for (int m = 0; m < 4; ++m) _Pragma("unroll") for (int k = 0; k < 2; ++k) dst[m][k] = *(const LAS bf16x8*)(lds + PG8_SA(b, h) + aoff + m * 2048 + k * 1024); } while (0)
; #define PG8_LDB(dst, b, h) do { _Pragma("unroll") for (int n = 0; n < 2; ++n) _Pragma("unroll") for (int k = 0; k < 2; ++k) dst[n][k] = *(const LAS bf16x8*)(lds + PG8_SB(b, h) + boff + n * 2048 + k * 1024); } while (0)
; #define PG8_MMA(ai, bj, At, Bt) do { __builtin_amdgcn_s_setprio(1); _Pragma("unroll") for (int m = 0; m < 4; ++m) _Pragma("unroll") for (int n = 0; n < 2; ++n) _Pragma("unroll") for (int k = 0; k < 2; ++k) \
;         acc[ai][bj][m][n] = __builtin_amdgcn_mfma_f32_16x16x32_bf16(Bt[n][k], At[m][k], acc[ai][bj][m][n], 0, 0, 0); __builtin_amdgcn_s_setprio(0); } while (0)
; #define PG8_WAIT_V(n) asm volatile("s_waitcnt vmcnt(" #n ")" ::: "memory")
; #define PG8_WAIT_L(n) asm volatile("s_waitcnt lgkmcnt(" #n ")" ::: "memory")
; #define PG8_BAR __builtin_amdgcn_s_barrier()
; #define PG8_SCHED __builtin_amdgcn_sched_barrier(0)
; template <class Epi, bool BSEL = false>
; __device__ __forceinline__ void gemm_phase(LAS unsigned char* lds, const Gemm g, const Order& S, const Epi& E, const int tid) {
;     ...
;             PG8_WAIT_V(8); PG8_WAIT_L(0); PG8_BAR; PG8_MMA(1, 0, At, B0); PG8_MMA(1, 1, At, B1); PG8_BAR; PG8_SCHED;
;             PG8_LDB(B0, 1, 0); PG8_LDB(B1, 1, 1); PG8_SCHED; PG8_LDA(At, 1, 0); PG8_STAGE(PG8_SA(0, 1), a2 + hstepA, voffA);
;             PG8_WAIT_V(8); PG8_WAIT_L(0); PG8_BAR; PG8_MMA(0, 0, At, B0); PG8_MMA(0, 1, At, B1); PG8_BAR; PG8_SCHED;
	v_mfma_f32_16x16x32_bf16 v[60:63], v[152:155], v[188:191], v[60:63]
	v_mfma_f32_16x16x32_bf16 v[56:59], v[160:163], v[188:191], v[56:59]
	v_mfma_f32_16x16x32_bf16 v[44:47], v[152:155], v[196:199], v[44:47]
	v_mfma_f32_16x16x32_bf16 v[40:43], v[160:163], v[196:199], v[40:43]
	v_mfma_f32_16x16x32_bf16 v[28:31], v[152:155], v[206:209], v[28:31]
	v_mfma_f32_16x16x32_bf16 v[24:27], v[160:163], v[206:209], v[24:27]
	v_mfma_f32_16x16x32_bf16 v[12:15], v[152:155], v[214:217], v[12:15]
	v_mfma_f32_16x16x32_bf16 v[8:11], v[160:163], v[214:217], v[8:11]
	v_mfma_f32_16x16x32_bf16 v[60:63], v[156:159], v[192:195], v[60:63]
	v_mfma_f32_16x16x32_bf16 v[56:59], v[164:167], v[192:195], v[56:59]
	v_mfma_f32_16x16x32_bf16 v[44:47], v[156:159], v[202:205], v[44:47]
	v_mfma_f32_16x16x32_bf16 v[40:43], v[164:167], v[202:205], v[40:43]
	v_mfma_f32_16x16x32_bf16 v[28:31], v[156:159], v[210:213], v[28:31]
	v_mfma_f32_16x16x32_bf16 v[24:27], v[164:167], v[210:213], v[24:27]
	v_mfma_f32_16x16x32_bf16 v[12:15], v[156:159], v[218:221], v[12:15]
	v_mfma_f32_16x16x32_bf16 v[8:11], v[164:167], v[218:221], v[8:11]
	v_mfma_f32_16x16x32_bf16 v[52:55], v[168:171], v[188:191], v[52:55]
	v_mfma_f32_16x16x32_bf16 v[48:51], v[180:183], v[188:191], v[48:51]
	v_mfma_f32_16x16x32_bf16 v[36:39], v[168:171], v[196:199], v[36:39]
	v_mfma_f32_16x16x32_bf16 v[32:35], v[180:183], v[196:199], v[32:35]
	v_mfma_f32_16x16x32_bf16 v[20:23], v[168:171], v[206:209], v[20:23]
	v_mfma_f32_16x16x32_bf16 v[16:19], v[180:183], v[206:209], v[16:19]
	v_mfma_f32_16x16x32_bf16 v[4:7], v[168:171], v[214:217], v[4:7]
	v_mfma_f32_16x16x32_bf16 v[0:3], v[180:183], v[214:217], v[0:3]
	v_mfma_f32_16x16x32_bf16 v[52:55], v[172:175], v[192:195], v[52:55]
	v_mfma_f32_16x16x32_bf16 v[48:51], v[184:187], v[192:195], v[48:51]
	v_mfma_f32_16x16x32_bf16 v[36:39], v[172:175], v[202:205], v[36:39]
	v_mfma_f32_16x16x32_bf16 v[32:35], v[184:187], v[202:205], v[32:35]
	v_mfma_f32_16x16x32_bf16 v[20:23], v[172:175], v[210:213], v[20:23]
	v_mfma_f32_16x16x32_bf16 v[16:19], v[184:187], v[210:213], v[16:19]
	v_mfma_f32_16x16x32_bf16 v[4:7], v[172:175], v[218:221], v[4:7]
	v_mfma_f32_16x16x32_bf16 v[0:3], v[184:187], v[218:221], v[0:3]
	s_barrier
	s_setprio 0
	s_add_i32 s65, 0, 0x18000
	s_add_i32 s66, 0, 0x1c000
	v_add_u32_e32 v164, s65, v139
	v_add_u32_e32 v179, s66, v139
	ds_read_b128 v[152:155], v164
	ds_read_b128 v[156:159], v164 offset:1024
	ds_read_b128 v[160:163], v164 offset:2048
	ds_read_b128 v[164:167], v164 offset:3072
	ds_read_b128 v[168:171], v179
	ds_read_b128 v[172:175], v179 offset:1024
	ds_read_b128 v[180:183], v179 offset:2048
	ds_read_b128 v[184:187], v179 offset:3072
	s_add_u32 s48, s48, 0xb0000
	s_addc_u32 s49, s49, 0
	s_mov_b32 m0, s23
	v_lshl_add_u64 v[228:229], s[48:49], 0, v[130:131]
	ds_read_b128 v[188:191], v151 offset:32768
	ds_read_b128 v[192:195], v151 offset:33792
	ds_read_b128 v[196:199], v151 offset:34816
	ds_read_b128 v[202:205], v151 offset:35840
	ds_read_b128 v[206:209], v151 offset:36864
	ds_read_b128 v[210:213], v151 offset:37888
	ds_read_b128 v[214:217], v151 offset:38912
	ds_read_b128 v[218:221], v151 offset:39936
	global_load_lds_dwordx4 v[228:229], off
	v_lshl_add_u64 v[228:229], s[48:49], 0, v[134:135]
	s_mov_b32 m0, s25
	s_nop 0
	global_load_lds_dwordx4 v[228:229], off
	s_waitcnt vmcnt(8)
	s_waitcnt lgkmcnt(0)
	s_setprio 1
	s_barrier
	v_mfma_f32_16x16x32_bf16 v[124:127], v[152:155], v[188:191], v[124:127]
	v_mfma_f32_16x16x32_bf16 v[120:123], v[160:163], v[188:191], v[120:123]
	v_mfma_f32_16x16x32_bf16 v[108:111], v[152:155], v[196:199], v[108:111]
	v_mfma_f32_16x16x32_bf16 v[104:107], v[160:163], v[196:199], v[104:107]
	v_mfma_f32_16x16x32_bf16 v[92:95], v[152:155], v[206:209], v[92:95]
	v_mfma_f32_16x16x32_bf16 v[88:91], v[160:163], v[206:209], v[88:91]
	v_mfma_f32_16x16x32_bf16 v[76:79], v[152:155], v[214:217], v[76:79]
	v_mfma_f32_16x16x32_bf16 v[72:75], v[160:163], v[214:217], v[72:75]
	v_mfma_f32_16x16x32_bf16 v[124:127], v[156:159], v[192:195], v[124:127]
	v_mfma_f32_16x16x32_bf16 v[120:123], v[164:167], v[192:195], v[120:123]
	v_mfma_f32_16x16x32_bf16 v[108:111], v[156:159], v[202:205], v[108:111]
	v_mfma_f32_16x16x32_bf16 v[104:107], v[164:167], v[202:205], v[104:107]
	v_mfma_f32_16x16x32_bf16 v[92:95], v[156:159], v[210:213], v[92:95]
	v_mfma_f32_16x16x32_bf16 v[88:91], v[164:167], v[210:213], v[88:91]
	v_mfma_f32_16x16x32_bf16 v[76:79], v[156:159], v[218:221], v[76:79]
	v_mfma_f32_16x16x32_bf16 v[72:75], v[164:167], v[218:221], v[72:75]
	v_mfma_f32_16x16x32_bf16 v[116:119], v[168:171], v[188:191], v[116:119]
	v_mfma_f32_16x16x32_bf16 v[112:115], v[180:183], v[188:191], v[112:115]
	v_mfma_f32_16x16x32_bf16 v[100:103], v[168:171], v[196:199], v[100:103]
	v_mfma_f32_16x16x32_bf16 v[96:99], v[180:183], v[196:199], v[96:99]
	v_mfma_f32_16x16x32_bf16 v[84:87], v[168:171], v[206:209], v[84:87]
	v_mfma_f32_16x16x32_bf16 v[80:83], v[180:183], v[206:209], v[80:83]
	v_mfma_f32_16x16x32_bf16 v[68:71], v[168:171], v[214:217], v[68:71]
	v_mfma_f32_16x16x32_bf16 v[64:67], v[180:183], v[214:217], v[64:67]
	v_mfma_f32_16x16x32_bf16 v[116:119], v[172:175], v[192:195], v[116:119]
	v_mfma_f32_16x16x32_bf16 v[112:115], v[184:187], v[192:195], v[112:115]
	v_mfma_f32_16x16x32_bf16 v[100:103], v[172:175], v[202:205], v[100:103]
	v_mfma_f32_16x16x32_bf16 v[96:99], v[184:187], v[202:205], v[96:99]
	v_mfma_f32_16x16x32_bf16 v[84:87], v[172:175], v[210:213], v[84:87]
	v_mfma_f32_16x16x32_bf16 v[80:83], v[184:187], v[210:213], v[80:83]
	v_mfma_f32_16x16x32_bf16 v[68:71], v[172:175], v[218:221], v[68:71]
	v_mfma_f32_16x16x32_bf16 v[64:67], v[184:187], v[218:221], v[64:67]
	s_barrier
; #define PG8_STAGE(bufoff, gbase, voff) do { _Pragma("unroll") for (int _i = 0; _i < 2; ++_i) \
;         __builtin_amdgcn_global_load_lds((const unsigned*)((const char*)(gbase) + (voff)[_i]), (LAS unsigned*)(lds + (bufoff) + ldsw + _i * 8192), 16, 0, 0); } while (0)
; #define PG8_STAGEB(bufoff, gbase, perm) do { _Pragma("unroll") for (int _i = 0; _i < 2; ++_i) \
;         __builtin_amdgcn_global_load_lds((const unsigned*)((const char*)(gbase) + ((BSEL && (perm)) ? voffBp[_i] : voffB[_i])), (LAS unsigned*)(lds + (bufoff) + ldsw + _i * 8192), 16, 0, 0); } while (0)
; #define PG8_LDA(dst, b, h) do { _Pragma("unroll") for (int m = 0; m < 4; ++m) _Pragma("unroll") for (int k = 0; k < 2; ++k) dst[m][k] = *(const LAS bf16x8*)(lds + PG8_SA(b, h) + aoff + m * 2048 + k * 1024); } while (0)
; #define PG8_MMA(ai, bj, At, Bt) do { __builtin_amdgcn_s_setprio(1); _Pragma("unroll") for (int m = 0; m < 4; ++m) _Pragma("unroll") for (int n = 0; n < 2; ++n) _Pragma("unroll") for (int k = 0; k < 2; ++k) \
;         acc[ai][bj][m][n] = __builtin_amdgcn_mfma_f32_16x16x32_bf16(Bt[n][k], At[m][k], acc[ai][bj][m][n], 0, 0, 0); __builtin_amdgcn_s_setprio(0); } while (0)
; #define PG8_WAIT_V(n) asm volatile("s_waitcnt vmcnt(" #n ")" ::: "memory")
; #define PG8_WAIT_L(n) asm volatile("s_waitcnt lgkmcnt(" #n ")" ::: "memory")
; #define PG8_BAR __builtin_amdgcn_s_barrier()
; #define PG8_SCHED __builtin_amdgcn_sched_barrier(0)
; template <class Epi, bool BSEL = false>
; __device__ __forceinline__ void gemm_phase(LAS unsigned char* lds, const Gemm g, const Order& S, const Epi& E, const int tid) {
;     ...
;             PG8_LDA(At, 1, 1); PG8_STAGEB(PG8_SB(1, 0), b3, p2); PG8_STAGEB(PG8_SB(1, 1), b3 + h2, p2); PG8_STAGE(PG8_SA(1, 0), a3, voffA);
;             PG8_WAIT_V(8); PG8_WAIT_L(0); PG8_BAR; PG8_MMA(1, 0, At, B0); PG8_MMA(1, 1, At, B1); PG8_BAR; PG8_SCHED;
;         }
;         if constexpr (ALIGN_EPI) { if (wr == 0) PG8_BAR; }
	s_setprio 0
	s_add_i32 s48, s65, s15
	v_lshl_add_u64 v[176:177], v[176:177], 0, s[30:31]
	s_mov_b32 m0, s48
	ds_read_b128 v[188:191], v151 offset:49152
	ds_read_b128 v[192:195], v151 offset:50176
	ds_read_b128 v[196:199], v151 offset:51200
	ds_read_b128 v[202:205], v151 offset:52224
	ds_read_b128 v[206:209], v151 offset:53248
	ds_read_b128 v[210:213], v151 offset:54272
	ds_read_b128 v[214:217], v151 offset:55296
	ds_read_b128 v[218:221], v151 offset:56320
	global_load_lds_dwordx4 v[176:177], off
	s_add_i32 m0, s48, 0x2000
	s_add_u32 s46, s46, 0xb0080
	v_lshl_add_u64 v[176:177], v[222:223], 0, s[30:31]
	s_addc_u32 s47, s47, 0
	s_add_i32 s48, s66, s15
	global_load_lds_dwordx4 v[176:177], off
	v_lshl_add_u64 v[176:177], s[46:47], 0, v[132:133]
	s_mov_b32 m0, s48
	s_nop 0
	global_load_lds_dwordx4 v[176:177], off
	v_lshl_add_u64 v[176:177], s[46:47], 0, v[136:137]
	s_add_i32 m0, s48, 0x2000
	s_nop 0
	global_load_lds_dwordx4 v[176:177], off
	v_lshl_add_u64 v[176:177], v[224:225], 0, s[30:31]
	s_mov_b32 m0, s50
	s_nop 0
	global_load_lds_dwordx4 v[176:177], off
	v_lshl_add_u64 v[176:177], v[226:227], 0, s[30:31]
	s_mov_b32 m0, s51
	s_nop 0
	global_load_lds_dwordx4 v[176:177], off
	s_waitcnt vmcnt(8)
	s_waitcnt lgkmcnt(0)
	s_setprio 1
	s_barrier
	v_mfma_f32_16x16x32_bf16 v[60:63], v[152:155], v[188:191], v[60:63]
	v_mfma_f32_16x16x32_bf16 v[56:59], v[160:163], v[188:191], v[56:59]
	v_mfma_f32_16x16x32_bf16 v[44:47], v[152:155], v[196:199], v[44:47]
	v_mfma_f32_16x16x32_bf16 v[40:43], v[160:163], v[196:199], v[40:43]
	v_mfma_f32_16x16x32_bf16 v[28:31], v[152:155], v[206:209], v[28:31]
	v_mfma_f32_16x16x32_bf16 v[24:27], v[160:163], v[206:209], v[24:27]
	v_mfma_f32_16x16x32_bf16 v[12:15], v[152:155], v[214:217], v[12:15]
	v_mfma_f32_16x16x32_bf16 v[8:11], v[160:163], v[214:217], v[8:11]
	v_mfma_f32_16x16x32_bf16 v[60:63], v[156:159], v[192:195], v[60:63]
	v_mfma_f32_16x16x32_bf16 v[56:59], v[164:167], v[192:195], v[56:59]
	v_mfma_f32_16x16x32_bf16 v[44:47], v[156:159], v[202:205], v[44:47]
	v_mfma_f32_16x16x32_bf16 v[40:43], v[164:167], v[202:205], v[40:43]
	v_mfma_f32_16x16x32_bf16 v[28:31], v[156:159], v[210:213], v[28:31]
	v_mfma_f32_16x16x32_bf16 v[24:27], v[164:167], v[210:213], v[24:27]
	v_mfma_f32_16x16x32_bf16 v[12:15], v[156:159], v[218:221], v[12:15]
	v_mfma_f32_16x16x32_bf16 v[8:11], v[164:167], v[218:221], v[8:11]
	v_mfma_f32_16x16x32_bf16 v[52:55], v[168:171], v[188:191], v[52:55]
	v_mfma_f32_16x16x32_bf16 v[48:51], v[180:183], v[188:191], v[48:51]
	v_mfma_f32_16x16x32_bf16 v[36:39], v[168:171], v[196:199], v[36:39]
	v_mfma_f32_16x16x32_bf16 v[32:35], v[180:183], v[196:199], v[32:35]
	v_mfma_f32_16x16x32_bf16 v[20:23], v[168:171], v[206:209], v[20:23]
	v_mfma_f32_16x16x32_bf16 v[16:19], v[180:183], v[206:209], v[16:19]
	v_mfma_f32_16x16x32_bf16 v[4:7], v[168:171], v[214:217], v[4:7]
	v_mfma_f32_16x16x32_bf16 v[0:3], v[180:183], v[214:217], v[0:3]
	v_mfma_f32_16x16x32_bf16 v[52:55], v[172:175], v[192:195], v[52:55]
	v_mfma_f32_16x16x32_bf16 v[48:51], v[184:187], v[192:195], v[48:51]
	v_mfma_f32_16x16x32_bf16 v[36:39], v[172:175], v[202:205], v[36:39]
	v_mfma_f32_16x16x32_bf16 v[32:35], v[184:187], v[202:205], v[32:35]
	v_mfma_f32_16x16x32_bf16 v[20:23], v[172:175], v[210:213], v[20:23]
	v_mfma_f32_16x16x32_bf16 v[16:19], v[184:187], v[210:213], v[16:19]
	v_mfma_f32_16x16x32_bf16 v[4:7], v[172:175], v[218:221], v[4:7]
	v_mfma_f32_16x16x32_bf16 v[0:3], v[184:187], v[218:221], v[0:3]
	s_barrier
	s_setprio 0
	s_add_i32 s64, s64, 2
	s_add_u32 s44, s44, 0x100
	s_addc_u32 s45, s45, 0
	s_cmp_gt_u32 s64, 41
	s_cbranch_scc0 .LBB0_472
	s_and_b64 vcc, exec, s[34:35]
	s_cbranch_vccz .LBB0_475
	s_barrier

; #define PG8_STAGE(bufoff, gbase, voff) do { _Pragma("unroll") for (int _i = 0; _i < 2; ++_i) \
;         __builtin_amdgcn_global_load_lds((const unsigned*)((const char*)(gbase) + (voff)[_i]), (LAS unsigned*)(lds + (bufoff) + ldsw + _i * 8192), 16, 0, 0); } while (0)
; #define PG8_STAGEB(bufoff, gbase, perm) do { _Pragma("unroll") for (int _i = 0; _i < 2; ++_i) \
;         __builtin_amdgcn_global_load_lds((const unsigned*)((const char*)(gbase) + ((BSEL && (perm)) ? voffBp[_i] : voffB[_i])), (LAS unsigned*)(lds + (bufoff) + ldsw + _i * 8192), 16, 0, 0); } while (0)
; #define PG8_LDA(dst, b, h) do { _Pragma("unroll") for (int m = 0; m < 4; ++m) _Pragma("unroll") for (int k = 0; k < 2; ++k) dst[m][k] = *(const LAS bf16x8*)(lds + PG8_SA(b, h) + aoff + m * 2048 + k * 1024); } while (0)
; #define PG8_LDB(dst, b, h) do { _Pragma("unroll") for (int n = 0; n < 2; ++n) _Pragma("unroll") for (int k = 0; k < 2; ++k) dst[n][k] = *(const LAS bf16x8*)(lds + PG8_SB(b, h) + boff + n * 2048 + k * 1024); } while (0)
; template <class Epi, bool BSEL = false>
; __device__ __forceinline__ void gemm_phase(LAS unsigned char* lds, const Gemm g, const Order& S, const Epi& E, const int tid) {
;     ...
;         const bool has_next = S.next(ui + 1, nxt);
;         const char* nA = has_next ? nxt.a : cA; const char* nB = has_next ? nxt.b : cB;
;         const bool nP = has_next ? (BSEL && nxt.kind == 3) : cP; const size_t nhB = nP ? hstepBp : hstepBn;
;         for (int t = 0; t < nt; t += 2) {
;             const bool last = (t == nt - 2);
;             const char* a1 = cA + (size_t)(t + 1) * kstep;
;             const char* a2 = last ? nA : cA + (size_t)(t + 2) * kstep; const char* b2 = last ? nB : cB + (size_t)(t + 2) * kstep;
;             const char* a3 = a2 + kstep; const char* b3 = b2 + kstep;
;             const bool p2 = last ? nP : cP; const size_t h2 = last ? nhB : chB;
;             PG8_LDB(B0, 0, 0); PG8_LDB(B1, 0, 1); PG8_SCHED; PG8_LDA(At, 0, 0); PG8_STAGE(PG8_SA(1, 1), a1 + hstepA, voffA);
;             PG8_WAIT_V(8); PG8_WAIT_L(0); PG8_BAR; PG8_MMA(0, 0, At, B0); PG8_MMA(0, 1, At, B1); PG8_BAR; PG8_SCHED;
;             PG8_LDA(At, 0, 1); PG8_STAGEB(PG8_SB(0, 0), b2, p2); PG8_STAGEB(PG8_SB(0, 1), b2 + h2, p2); PG8_STAGE(PG8_SA(0, 0), a2, voffA);
;             PG8_WAIT_V(8); PG8_WAIT_L(0); PG8_BAR; PG8_MMA(1, 0, At, B0); PG8_MMA(1, 1, At, B1); PG8_BAR; PG8_SCHED;
.LBB0_670:
	s_add_u32 s2, s26, s62
	s_addc_u32 s3, s27, s63
	s_add_u32 s2, s2, 0x100
	s_addc_u32 s3, s3, 0
	s_add_u32 s44, s15, s62
	s_addc_u32 s45, s47, s63
	s_cmpk_eq_i32 s62, 0x700
	v_cndmask_b32_e64 v133, 0, 1, vcc
	s_cselect_b64 s[8:9], -1, 0
	v_cndmask_b32_e64 v133, v132, v133, s[8:9]
	v_and_b32_e32 v133, 1, v133
	v_cmp_eq_u32_e64 s[8:9], 1, v133
	v_add_u32_e32 v133, s94, v161
	ds_read_b128 v[134:137], v133
	ds_read_b128 v[138:141], v133 offset:1024
	ds_read_b128 v[178:181], v133 offset:2048
	ds_read_b128 v[182:185], v133 offset:3072
	v_add_u32_e32 v133, s96, v161
	ds_read_b128 v[186:189], v133
	ds_read_b128 v[190:193], v133 offset:1024
	ds_read_b128 v[194:197], v133 offset:2048
	ds_read_b128 v[202:205], v133 offset:3072
	s_cselect_b32 s3, s58, s3
	s_cselect_b32 s2, s59, s2
	s_cselect_b32 s45, s64, s45
	s_cselect_b32 s44, s65, s44
	s_cselect_b32 s93, 0, s51
	s_cselect_b32 s70, s28, s50
	v_lshl_add_u64 v[142:143], v[128:129], 0, s[62:63]
	s_add_i32 m0, s74, 0xc000
	ds_read_b128 v[206:209], v163
	ds_read_b128 v[210:213], v163 offset:1024
	ds_read_b128 v[214:217], v163 offset:2048
	ds_read_b128 v[218:221], v163 offset:3072
	ds_read_b128 v[222:225], v163 offset:4096
	ds_read_b128 v[226:229], v163 offset:5120
	ds_read_b128 v[230:233], v163 offset:6144
	ds_read_b128 v[234:237], v163 offset:7168
	global_load_lds_dwordx4 v[142:143], off
	v_lshl_add_u64 v[142:143], v[130:131], 0, s[62:63]
	s_add_i32 m0, s74, 0xe000
	s_nop 0
	global_load_lds_dwordx4 v[142:143], off
	s_waitcnt vmcnt(8)
	s_waitcnt lgkmcnt(0)
	s_setprio 1
	s_barrier
	v_mfma_f32_16x16x32_bf16 v[124:127], v[134:137], v[206:209], v[124:127]
	v_mfma_f32_16x16x32_bf16 v[120:123], v[178:181], v[206:209], v[120:123]
	v_mfma_f32_16x16x32_bf16 v[116:119], v[134:137], v[214:217], v[116:119]
	v_mfma_f32_16x16x32_bf16 v[112:115], v[178:181], v[214:217], v[112:115]
	v_mfma_f32_16x16x32_bf16 v[108:111], v[134:137], v[222:225], v[108:111]
	v_mfma_f32_16x16x32_bf16 v[104:107], v[178:181], v[222:225], v[104:107]
	v_mfma_f32_16x16x32_bf16 v[100:103], v[134:137], v[230:233], v[100:103]
	v_mfma_f32_16x16x32_bf16 v[96:99], v[178:181], v[230:233], v[96:99]
	v_mfma_f32_16x16x32_bf16 v[124:127], v[138:141], v[210:213], v[124:127]
	v_mfma_f32_16x16x32_bf16 v[120:123], v[182:185], v[210:213], v[120:123]
	v_mfma_f32_16x16x32_bf16 v[116:119], v[138:141], v[218:221], v[116:119]
	v_mfma_f32_16x16x32_bf16 v[112:115], v[182:185], v[218:221], v[112:115]
	v_mfma_f32_16x16x32_bf16 v[108:111], v[138:141], v[226:229], v[108:111]
	v_mfma_f32_16x16x32_bf16 v[104:107], v[182:185], v[226:229], v[104:107]
	v_mfma_f32_16x16x32_bf16 v[100:103], v[138:141], v[234:237], v[100:103]
	v_mfma_f32_16x16x32_bf16 v[96:99], v[182:185], v[234:237], v[96:99]
	v_mfma_f32_16x16x32_bf16 v[92:95], v[186:189], v[206:209], v[92:95]
	v_mfma_f32_16x16x32_bf16 v[88:91], v[194:197], v[206:209], v[88:91]
	v_mfma_f32_16x16x32_bf16 v[84:87], v[186:189], v[214:217], v[84:87]
	v_mfma_f32_16x16x32_bf16 v[80:83], v[194:197], v[214:217], v[80:83]
	v_mfma_f32_16x16x32_bf16 v[76:79], v[186:189], v[222:225], v[76:79]
	v_mfma_f32_16x16x32_bf16 v[72:75], v[194:197], v[222:225], v[72:75]
	v_mfma_f32_16x16x32_bf16 v[68:71], v[186:189], v[230:233], v[68:71]
	v_mfma_f32_16x16x32_bf16 v[64:67], v[194:197], v[230:233], v[64:67]
	v_mfma_f32_16x16x32_bf16 v[92:95], v[190:193], v[210:213], v[92:95]
	v_mfma_f32_16x16x32_bf16 v[88:91], v[202:205], v[210:213], v[88:91]
	v_mfma_f32_16x16x32_bf16 v[84:87], v[190:193], v[218:221], v[84:87]
	v_mfma_f32_16x16x32_bf16 v[80:83], v[202:205], v[218:221], v[80:83]
	v_mfma_f32_16x16x32_bf16 v[76:79], v[190:193], v[226:229], v[76:79]
	v_mfma_f32_16x16x32_bf16 v[72:75], v[202:205], v[226:229], v[72:75]
	v_mfma_f32_16x16x32_bf16 v[68:71], v[190:193], v[234:237], v[68:71]
	v_mfma_f32_16x16x32_bf16 v[64:67], v[202:205], v[234:237], v[64:67]
	s_barrier
	s_setprio 0
	s_add_i32 s71, s94, s25
	v_cndmask_b32_e64 v148, v151, v153, s[8:9]
	s_mov_b32 m0, s71
	ds_read_b128 v[206:209], v163 offset:16384
	ds_read_b128 v[210:213], v163 offset:17408
	ds_read_b128 v[214:217], v163 offset:18432
	ds_read_b128 v[218:221], v163 offset:19456
	ds_read_b128 v[222:225], v163 offset:20480
	ds_read_b128 v[226:229], v163 offset:21504
	ds_read_b128 v[230:233], v163 offset:22528
	ds_read_b128 v[234:237], v163 offset:23552
	global_load_lds_dwordx4 v148, s[44:45]
	s_add_i32 m0, s71, 0x2000
	v_cndmask_b32_e64 v198, v155, v157, s[8:9]
	v_mov_b32_e32 v199, v149
	s_add_u32 s8, s44, s70
	v_lshl_add_u64 v[142:143], s[44:45], 0, v[148:149]
	v_lshl_add_u64 v[238:239], s[44:45], 0, v[198:199]
	global_load_lds_dwordx4 v198, s[44:45]
	s_addc_u32 s9, s45, s93
	s_add_i32 s44, s96, s25
	s_mov_b32 m0, s44
	v_lshl_add_u64 v[242:243], s[8:9], 0, v[198:199]
	global_load_lds_dwordx4 v148, s[8:9]
	s_add_i32 m0, s44, 0x2000
	v_lshl_add_u64 v[244:245], s[2:3], 0, v[146:147]
	global_load_lds_dwordx4 v198, s[8:9]
	v_lshl_add_u64 v[198:199], s[2:3], 0, v[144:145]
	s_mov_b32 m0, s74
	v_lshl_add_u64 v[240:241], s[8:9], 0, v[148:149]
	global_load_lds_dwordx4 v[198:199], off
	s_mov_b32 m0, s76
	s_nop 0
	global_load_lds_dwordx4 v[244:245], off
	s_waitcnt vmcnt(8)
	s_waitcnt lgkmcnt(0)
	s_setprio 1
	s_barrier
; #define PG8_STAGE(bufoff, gbase, voff) do { _Pragma("unroll") for (int _i = 0; _i < 2; ++_i) \
;         __builtin_amdgcn_global_load_lds((const unsigned*)((const char*)(gbase) + (voff)[_i]), (LAS unsigned*)(lds + (bufoff) + ldsw + _i * 8192), 16, 0, 0); } while (0)
; #define PG8_LDA(dst, b, h) do { _Pragma("unroll") for (int m = 0; m < 4; ++m) _Pragma("unroll") for (int k = 0; k < 2; ++k) dst[m][k] = *(const LAS bf16x8*)(lds + PG8_SA(b, h) + aoff + m * 2048 + k * 1024); } while (0)
; #define PG8_LDB(dst, b, h) do { _Pragma("unroll") for (int n = 0; n < 2; ++n) _Pragma("unroll") for (int k = 0; k < 2; ++k) dst[n][k] = *(const LAS bf16x8*)(lds + PG8_SB(b, h) + boff + n * 2048 + k * 1024); } while (0)
; #define PG8_MMA(ai, bj, At, Bt) do { __builtin_amdgcn_s_setprio(1); _Pragma("unroll") for (int m = 0; m < 4; ++m) _Pragma("unroll") for (int n = 0; n < 2; ++n) _Pragma("unroll") for (int k = 0; k < 2; ++k) \
;         acc[ai][bj][m][n] = __builtin_amdgcn_mfma_f32_16x16x32_bf16(Bt[n][k], At[m][k], acc[ai][bj][m][n], 0, 0, 0); __builtin_amdgcn_s_setprio(0); } while (0)
; #define PG8_WAIT_V(n) asm volatile("s_waitcnt vmcnt(" #n ")" ::: "memory")
; #define PG8_WAIT_L(n) asm volatile("s_waitcnt lgkmcnt(" #n ")" ::: "memory")
; #define PG8_BAR __builtin_amdgcn_s_barrier()
; #define PG8_SCHED __builtin_amdgcn_sched_barrier(0)
; template <class Epi, bool BSEL = false>
; __device__ __forceinline__ void gemm_phase(LAS unsigned char* lds, const Gemm g, const Order& S, const Epi& E, const int tid) {
;     ...
;             PG8_WAIT_V(8); PG8_WAIT_L(0); PG8_BAR; PG8_MMA(1, 0, At, B0); PG8_MMA(1, 1, At, B1); PG8_BAR; PG8_SCHED;
;             PG8_LDB(B0, 1, 0); PG8_LDB(B1, 1, 1); PG8_SCHED; PG8_LDA(At, 1, 0); PG8_STAGE(PG8_SA(0, 1), a2 + hstepA, voffA);
;             PG8_WAIT_V(8); PG8_WAIT_L(0); PG8_BAR; PG8_MMA(0, 0, At, B0); PG8_MMA(0, 1, At, B1); PG8_BAR; PG8_SCHED;
	v_mfma_f32_16x16x32_bf16 v[60:63], v[134:137], v[206:209], v[60:63]
	v_mfma_f32_16x16x32_bf16 v[56:59], v[178:181], v[206:209], v[56:59]
	v_mfma_f32_16x16x32_bf16 v[52:55], v[134:137], v[214:217], v[52:55]
	v_mfma_f32_16x16x32_bf16 v[48:51], v[178:181], v[214:217], v[48:51]
	v_mfma_f32_16x16x32_bf16 v[44:47], v[134:137], v[222:225], v[44:47]
	v_mfma_f32_16x16x32_bf16 v[40:43], v[178:181], v[222:225], v[40:43]
	v_mfma_f32_16x16x32_bf16 v[36:39], v[134:137], v[230:233], v[36:39]
	v_mfma_f32_16x16x32_bf16 v[32:35], v[178:181], v[230:233], v[32:35]
	v_mfma_f32_16x16x32_bf16 v[60:63], v[138:141], v[210:213], v[60:63]
	v_mfma_f32_16x16x32_bf16 v[56:59], v[182:185], v[210:213], v[56:59]
	v_mfma_f32_16x16x32_bf16 v[52:55], v[138:141], v[218:221], v[52:55]
	v_mfma_f32_16x16x32_bf16 v[48:51], v[182:185], v[218:221], v[48:51]
	v_mfma_f32_16x16x32_bf16 v[44:47], v[138:141], v[226:229], v[44:47]
	v_mfma_f32_16x16x32_bf16 v[40:43], v[182:185], v[226:229], v[40:43]
	v_mfma_f32_16x16x32_bf16 v[36:39], v[138:141], v[234:237], v[36:39]
	v_mfma_f32_16x16x32_bf16 v[32:35], v[182:185], v[234:237], v[32:35]
	v_mfma_f32_16x16x32_bf16 v[28:31], v[186:189], v[206:209], v[28:31]
	v_mfma_f32_16x16x32_bf16 v[24:27], v[194:197], v[206:209], v[24:27]
	v_mfma_f32_16x16x32_bf16 v[20:23], v[186:189], v[214:217], v[20:23]
	v_mfma_f32_16x16x32_bf16 v[16:19], v[194:197], v[214:217], v[16:19]
	v_mfma_f32_16x16x32_bf16 v[12:15], v[186:189], v[222:225], v[12:15]
	v_mfma_f32_16x16x32_bf16 v[8:11], v[194:197], v[222:225], v[8:11]
	v_mfma_f32_16x16x32_bf16 v[4:7], v[186:189], v[230:233], v[4:7]
	v_mfma_f32_16x16x32_bf16 v[0:3], v[194:197], v[230:233], v[0:3]
	v_mfma_f32_16x16x32_bf16 v[28:31], v[190:193], v[210:213], v[28:31]
	v_mfma_f32_16x16x32_bf16 v[24:27], v[202:205], v[210:213], v[24:27]
	v_mfma_f32_16x16x32_bf16 v[20:23], v[190:193], v[218:221], v[20:23]
	v_mfma_f32_16x16x32_bf16 v[16:19], v[202:205], v[218:221], v[16:19]
	v_mfma_f32_16x16x32_bf16 v[12:15], v[190:193], v[226:229], v[12:15]
	v_mfma_f32_16x16x32_bf16 v[8:11], v[202:205], v[226:229], v[8:11]
	v_mfma_f32_16x16x32_bf16 v[4:7], v[190:193], v[234:237], v[4:7]
	v_mfma_f32_16x16x32_bf16 v[0:3], v[202:205], v[234:237], v[0:3]
	s_barrier
	s_setprio 0
	s_add_i32 s8, 0, 0x18000
	v_add_u32_e32 v133, s8, v161
	s_add_i32 s9, 0, 0x1c000
	ds_read_b128 v[134:137], v133
	ds_read_b128 v[138:141], v133 offset:1024
	ds_read_b128 v[178:181], v133 offset:2048
	ds_read_b128 v[182:185], v133 offset:3072
	v_add_u32_e32 v133, s9, v161
	ds_read_b128 v[186:189], v133
	ds_read_b128 v[190:193], v133 offset:1024
	ds_read_b128 v[194:197], v133 offset:2048
	ds_read_b128 v[202:205], v133 offset:3072
	s_add_u32 s2, s2, 0x40000
	s_addc_u32 s3, s3, 0
	s_mov_b32 m0, s77
	v_lshl_add_u64 v[246:247], s[2:3], 0, v[144:145]
	ds_read_b128 v[206:209], v163 offset:32768
	ds_read_b128 v[210:213], v163 offset:33792
	ds_read_b128 v[214:217], v163 offset:34816
	ds_read_b128 v[218:221], v163 offset:35840
	ds_read_b128 v[222:225], v163 offset:36864
	ds_read_b128 v[226:229], v163 offset:37888
	ds_read_b128 v[230:233], v163 offset:38912
	ds_read_b128 v[234:237], v163 offset:39936
	global_load_lds_dwordx4 v[246:247], off
	v_lshl_add_u64 v[246:247], s[2:3], 0, v[146:147]
	s_mov_b32 m0, s78
	s_nop 0
	global_load_lds_dwordx4 v[246:247], off
	s_waitcnt vmcnt(8)
	s_waitcnt lgkmcnt(0)
	s_setprio 1
	s_barrier
	v_mfma_f32_16x16x32_bf16 v[124:127], v[134:137], v[206:209], v[124:127]
	v_mfma_f32_16x16x32_bf16 v[120:123], v[178:181], v[206:209], v[120:123]
	v_mfma_f32_16x16x32_bf16 v[116:119], v[134:137], v[214:217], v[116:119]
	v_mfma_f32_16x16x32_bf16 v[112:115], v[178:181], v[214:217], v[112:115]
	v_mfma_f32_16x16x32_bf16 v[108:111], v[134:137], v[222:225], v[108:111]
	v_mfma_f32_16x16x32_bf16 v[104:107], v[178:181], v[222:225], v[104:107]
	v_mfma_f32_16x16x32_bf16 v[100:103], v[134:137], v[230:233], v[100:103]
	v_mfma_f32_16x16x32_bf16 v[96:99], v[178:181], v[230:233], v[96:99]
	v_mfma_f32_16x16x32_bf16 v[124:127], v[138:141], v[210:213], v[124:127]
	v_mfma_f32_16x16x32_bf16 v[120:123], v[182:185], v[210:213], v[120:123]
	v_mfma_f32_16x16x32_bf16 v[116:119], v[138:141], v[218:221], v[116:119]
	v_mfma_f32_16x16x32_bf16 v[112:115], v[182:185], v[218:221], v[112:115]
	v_mfma_f32_16x16x32_bf16 v[108:111], v[138:141], v[226:229], v[108:111]
	v_mfma_f32_16x16x32_bf16 v[104:107], v[182:185], v[226:229], v[104:107]
	v_mfma_f32_16x16x32_bf16 v[100:103], v[138:141], v[234:237], v[100:103]
	v_mfma_f32_16x16x32_bf16 v[96:99], v[182:185], v[234:237], v[96:99]
	v_mfma_f32_16x16x32_bf16 v[92:95], v[186:189], v[206:209], v[92:95]
	v_mfma_f32_16x16x32_bf16 v[88:91], v[194:197], v[206:209], v[88:91]
	v_mfma_f32_16x16x32_bf16 v[84:87], v[186:189], v[214:217], v[84:87]
	v_mfma_f32_16x16x32_bf16 v[80:83], v[194:197], v[214:217], v[80:83]
	v_mfma_f32_16x16x32_bf16 v[76:79], v[186:189], v[222:225], v[76:79]
	v_mfma_f32_16x16x32_bf16 v[72:75], v[194:197], v[222:225], v[72:75]
	v_mfma_f32_16x16x32_bf16 v[68:71], v[186:189], v[230:233], v[68:71]
	v_mfma_f32_16x16x32_bf16 v[64:67], v[194:197], v[230:233], v[64:67]
	v_mfma_f32_16x16x32_bf16 v[92:95], v[190:193], v[210:213], v[92:95]
	v_mfma_f32_16x16x32_bf16 v[88:91], v[202:205], v[210:213], v[88:91]
	v_mfma_f32_16x16x32_bf16 v[84:87], v[190:193], v[218:221], v[84:87]
	v_mfma_f32_16x16x32_bf16 v[80:83], v[202:205], v[218:221], v[80:83]
	v_mfma_f32_16x16x32_bf16 v[76:79], v[190:193], v[226:229], v[76:79]
	v_mfma_f32_16x16x32_bf16 v[72:75], v[202:205], v[226:229], v[72:75]
	v_mfma_f32_16x16x32_bf16 v[68:71], v[190:193], v[234:237], v[68:71]
	v_mfma_f32_16x16x32_bf16 v[64:67], v[202:205], v[234:237], v[64:67]
	s_barrier
; #define PG8_STAGE(bufoff, gbase, voff) do { _Pragma("unroll") for (int _i = 0; _i < 2; ++_i) \
;         __builtin_amdgcn_global_load_lds((const unsigned*)((const char*)(gbase) + (voff)[_i]), (LAS unsigned*)(lds + (bufoff) + ldsw + _i * 8192), 16, 0, 0); } while (0)
; #define PG8_STAGEB(bufoff, gbase, perm) do { _Pragma("unroll") for (int _i = 0; _i < 2; ++_i) \
;         __builtin_amdgcn_global_load_lds((const unsigned*)((const char*)(gbase) + ((BSEL && (perm)) ? voffBp[_i] : voffB[_i])), (LAS unsigned*)(lds + (bufoff) + ldsw + _i * 8192), 16, 0, 0); } while (0)
; #define PG8_LDA(dst, b, h) do { _Pragma("unroll") for (int m = 0; m < 4; ++m) _Pragma("unroll") for (int k = 0; k < 2; ++k) dst[m][k] = *(const LAS bf16x8*)(lds + PG8_SA(b, h) + aoff + m * 2048 + k * 1024); } while (0)
; #define PG8_MMA(ai, bj, At, Bt) do { __builtin_amdgcn_s_setprio(1); _Pragma("unroll") for (int m = 0; m < 4; ++m) _Pragma("unroll") for (int n = 0; n < 2; ++n) _Pragma("unroll") for (int k = 0; k < 2; ++k) \
;         acc[ai][bj][m][n] = __builtin_amdgcn_mfma_f32_16x16x32_bf16(Bt[n][k], At[m][k], acc[ai][bj][m][n], 0, 0, 0); __builtin_amdgcn_s_setprio(0); } while (0)
; #define PG8_WAIT_V(n) asm volatile("s_waitcnt vmcnt(" #n ")" ::: "memory")
; #define PG8_WAIT_L(n) asm volatile("s_waitcnt lgkmcnt(" #n ")" ::: "memory")
; #define PG8_BAR __builtin_amdgcn_s_barrier()
; #define PG8_SCHED __builtin_amdgcn_sched_barrier(0)
; template <class Epi, bool BSEL = false>
; __device__ __forceinline__ void gemm_phase(LAS unsigned char* lds, const Gemm g, const Order& S, const Epi& E, const int tid) {
;     ...
;             PG8_LDA(At, 1, 1); PG8_STAGEB(PG8_SB(1, 0), b3, p2); PG8_STAGEB(PG8_SB(1, 1), b3 + h2, p2); PG8_STAGE(PG8_SA(1, 0), a3, voffA);
;             PG8_WAIT_V(8); PG8_WAIT_L(0); PG8_BAR; PG8_MMA(1, 0, At, B0); PG8_MMA(1, 1, At, B1); PG8_BAR; PG8_SCHED;
;         }
;         if constexpr (ALIGN_EPI) { if (wr == 0) PG8_BAR; }
	s_setprio 0
	s_add_i32 s2, s8, s25
	v_lshl_add_u64 v[142:143], v[142:143], 0, s[36:37]
	s_mov_b32 m0, s2
	ds_read_b128 v[206:209], v163 offset:49152
	ds_read_b128 v[210:213], v163 offset:50176
	ds_read_b128 v[214:217], v163 offset:51200
	ds_read_b128 v[218:221], v163 offset:52224
	ds_read_b128 v[222:225], v163 offset:53248
	ds_read_b128 v[226:229], v163 offset:54272
	ds_read_b128 v[230:233], v163 offset:55296
	ds_read_b128 v[234:237], v163 offset:56320
	global_load_lds_dwordx4 v[142:143], off
	v_lshl_add_u64 v[142:143], v[238:239], 0, s[36:37]
	s_add_i32 m0, s2, 0x2000
	s_add_i32 s2, s9, s25
	global_load_lds_dwordx4 v[142:143], off
	v_lshl_add_u64 v[142:143], v[240:241], 0, s[36:37]
	s_mov_b32 m0, s2
	s_nop 0
	global_load_lds_dwordx4 v[142:143], off
	v_lshl_add_u64 v[142:143], v[242:243], 0, s[36:37]
	s_add_i32 m0, s2, 0x2000
	s_nop 0
	global_load_lds_dwordx4 v[142:143], off
	v_lshl_add_u64 v[142:143], v[198:199], 0, s[36:37]
	s_mov_b32 m0, s89
	s_nop 0
	global_load_lds_dwordx4 v[142:143], off
	v_lshl_add_u64 v[142:143], v[244:245], 0, s[36:37]
	s_mov_b32 m0, s90
	s_nop 0
	global_load_lds_dwordx4 v[142:143], off
	s_waitcnt vmcnt(8)
	s_waitcnt lgkmcnt(0)
	s_setprio 1
	s_barrier
	v_mfma_f32_16x16x32_bf16 v[60:63], v[134:137], v[206:209], v[60:63]
	v_mfma_f32_16x16x32_bf16 v[56:59], v[178:181], v[206:209], v[56:59]
	v_mfma_f32_16x16x32_bf16 v[52:55], v[134:137], v[214:217], v[52:55]
	v_mfma_f32_16x16x32_bf16 v[48:51], v[178:181], v[214:217], v[48:51]
	v_mfma_f32_16x16x32_bf16 v[44:47], v[134:137], v[222:225], v[44:47]
	v_mfma_f32_16x16x32_bf16 v[40:43], v[178:181], v[222:225], v[40:43]
	v_mfma_f32_16x16x32_bf16 v[36:39], v[134:137], v[230:233], v[36:39]
	v_mfma_f32_16x16x32_bf16 v[32:35], v[178:181], v[230:233], v[32:35]
	v_mfma_f32_16x16x32_bf16 v[60:63], v[138:141], v[210:213], v[60:63]
	v_mfma_f32_16x16x32_bf16 v[56:59], v[182:185], v[210:213], v[56:59]
	v_mfma_f32_16x16x32_bf16 v[52:55], v[138:141], v[218:221], v[52:55]
	v_mfma_f32_16x16x32_bf16 v[48:51], v[182:185], v[218:221], v[48:51]
	v_mfma_f32_16x16x32_bf16 v[44:47], v[138:141], v[226:229], v[44:47]
	v_mfma_f32_16x16x32_bf16 v[40:43], v[182:185], v[226:229], v[40:43]
	v_mfma_f32_16x16x32_bf16 v[36:39], v[138:141], v[234:237], v[36:39]
	v_mfma_f32_16x16x32_bf16 v[32:35], v[182:185], v[234:237], v[32:35]
	v_mfma_f32_16x16x32_bf16 v[28:31], v[186:189], v[206:209], v[28:31]
	v_mfma_f32_16x16x32_bf16 v[24:27], v[194:197], v[206:209], v[24:27]
	v_mfma_f32_16x16x32_bf16 v[20:23], v[186:189], v[214:217], v[20:23]
	v_mfma_f32_16x16x32_bf16 v[16:19], v[194:197], v[214:217], v[16:19]
	v_mfma_f32_16x16x32_bf16 v[12:15], v[186:189], v[222:225], v[12:15]
	v_mfma_f32_16x16x32_bf16 v[8:11], v[194:197], v[222:225], v[8:11]
	v_mfma_f32_16x16x32_bf16 v[4:7], v[186:189], v[230:233], v[4:7]
	v_mfma_f32_16x16x32_bf16 v[0:3], v[194:197], v[230:233], v[0:3]
	v_mfma_f32_16x16x32_bf16 v[28:31], v[190:193], v[210:213], v[28:31]
	v_mfma_f32_16x16x32_bf16 v[24:27], v[202:205], v[210:213], v[24:27]
	v_mfma_f32_16x16x32_bf16 v[20:23], v[190:193], v[218:221], v[20:23]
	v_mfma_f32_16x16x32_bf16 v[16:19], v[202:205], v[218:221], v[16:19]
	v_mfma_f32_16x16x32_bf16 v[12:15], v[190:193], v[226:229], v[12:15]
	v_mfma_f32_16x16x32_bf16 v[8:11], v[202:205], v[226:229], v[8:11]
	v_mfma_f32_16x16x32_bf16 v[4:7], v[190:193], v[234:237], v[4:7]
	v_mfma_f32_16x16x32_bf16 v[0:3], v[202:205], v[234:237], v[0:3]
	s_barrier
	s_setprio 0
	s_add_i32 s95, s95, 2
	s_add_u32 s62, s62, 0x100
	s_addc_u32 s63, s63, 0
	s_cmp_gt_u32 s95, 13
	s_cbranch_scc0 .LBB0_670
	s_and_b64 vcc, exec, s[38:39]
	s_cbranch_vccz .LBB0_696
	s_barrier
	s_cmp_gt_i32 s73, 1
	s_mov_b64 s[2:3], -1
	s_cbranch_scc1 .LBB0_697

; #define PG8_STAGE(bufoff, gbase, voff) do { _Pragma("unroll") for (int _i = 0; _i < 2; ++_i) \
;         __builtin_amdgcn_global_load_lds((const unsigned*)((const char*)(gbase) + (voff)[_i]), (LAS unsigned*)(lds + (bufoff) + ldsw + _i * 8192), 16, 0, 0); } while (0)
; #define PG8_STAGEB(bufoff, gbase, perm) do { _Pragma("unroll") for (int _i = 0; _i < 2; ++_i) \
;         __builtin_amdgcn_global_load_lds((const unsigned*)((const char*)(gbase) + ((BSEL && (perm)) ? voffBp[_i] : voffB[_i])), (LAS unsigned*)(lds + (bufoff) + ldsw + _i * 8192), 16, 0, 0); } while (0)
; #define PG8_LDA(dst, b, h) do { _Pragma("unroll") for (int m = 0; m < 4; ++m) _Pragma("unroll") for (int k = 0; k < 2; ++k) dst[m][k] = *(const LAS bf16x8*)(lds + PG8_SA(b, h) + aoff + m * 2048 + k * 1024); } while (0)
; #define PG8_LDB(dst, b, h) do { _Pragma("unroll") for (int n = 0; n < 2; ++n) _Pragma("unroll") for (int k = 0; k < 2; ++k) dst[n][k] = *(const LAS bf16x8*)(lds + PG8_SB(b, h) + boff + n * 2048 + k * 1024); } while (0)
; #define PG8_WAIT_V(n) asm volatile("s_waitcnt vmcnt(" #n ")" ::: "memory")
; #define PG8_WAIT_L(n) asm volatile("s_waitcnt lgkmcnt(" #n ")" ::: "memory")
; #define PG8_BAR __builtin_amdgcn_s_barrier()
; #define PG8_SCHED __builtin_amdgcn_sched_barrier(0)
; template <class Epi, bool BSEL = false>
; __device__ __forceinline__ void gemm_phase(LAS unsigned char* lds, const Gemm g, const Order& S, const Epi& E, const int tid) {
;     ...
;         for (int t = 0; t < nt; t += 2) {
;             const bool last = (t == nt - 2);
;             const char* a1 = cA + (size_t)(t + 1) * kstep;
;             const char* a2 = last ? nA : cA + (size_t)(t + 2) * kstep; const char* b2 = last ? nB : cB + (size_t)(t + 2) * kstep;
;             const char* a3 = a2 + kstep; const char* b3 = b2 + kstep;
;             const bool p2 = last ? nP : cP; const size_t h2 = last ? nhB : chB;
;             PG8_LDB(B0, 0, 0); PG8_LDB(B1, 0, 1); PG8_SCHED; PG8_LDA(At, 0, 0); PG8_STAGE(PG8_SA(1, 1), a1 + hstepA, voffA);
;             PG8_WAIT_V(8); PG8_WAIT_L(0); PG8_BAR; PG8_MMA(0, 0, At, B0); PG8_MMA(0, 1, At, B1); PG8_BAR; PG8_SCHED;
;             PG8_LDA(At, 0, 1); PG8_STAGEB(PG8_SB(0, 0), b2, p2); PG8_STAGEB(PG8_SB(0, 1), b2 + h2, p2); PG8_STAGE(PG8_SA(0, 0), a2, voffA);
;             PG8_WAIT_V(8); PG8_WAIT_L(0); PG8_BAR; PG8_MMA(1, 0, At, B0); PG8_MMA(1, 1, At, B1); PG8_BAR; PG8_SCHED;
.LBB0_826:
	s_xor_b64 s[38:39], s[40:41], -1
	v_add_u32_e32 v145, s53, v139
	s_and_b64 s[2:3], s[40:41], exec
	ds_read_b128 v[146:149], v145
	ds_read_b128 v[150:153], v145 offset:1024
	ds_read_b128 v[154:157], v145 offset:2048
	ds_read_b128 v[158:161], v145 offset:3072
	v_add_u32_e32 v145, s54, v139
	s_cselect_b32 s45, s1, s1
	s_cselect_b32 s44, s0, s0
	s_add_u32 s58, s0, 0x8080
	ds_read_b128 v[162:165], v145
	ds_read_b128 v[166:169], v145 offset:1024
	ds_read_b128 v[170:173], v145 offset:2048
	ds_read_b128 v[174:177], v145 offset:3072
	s_addc_u32 s59, s1, 0
	s_add_u32 s42, s44, 0x8000
	s_addc_u32 s43, s45, 0
	s_and_b64 s[2:3], s[40:41], exec
	s_cselect_b32 s2, s36, s4
	s_cselect_b32 s3, s37, s5
	s_add_u32 s60, s2, 0x8000
	s_addc_u32 s61, s3, 0
	v_lshl_add_u64 v[198:199], s[58:59], 0, v[128:129]
	s_add_i32 m0, s20, 0xc000
	ds_read_b128 v[178:181], v144
	ds_read_b128 v[182:185], v144 offset:1024
	ds_read_b128 v[186:189], v144 offset:2048
	ds_read_b128 v[190:193], v144 offset:3072
	ds_read_b128 v[194:197], v144 offset:4096
	ds_read_b128 v[202:205], v144 offset:5120
	ds_read_b128 v[206:209], v144 offset:6144
	ds_read_b128 v[210:213], v144 offset:7168
	global_load_lds_dwordx4 v[198:199], off
	v_lshl_add_u64 v[198:199], s[58:59], 0, v[132:133]
	s_add_i32 m0, s20, 0xe000
	s_nop 0
	global_load_lds_dwordx4 v[198:199], off
	s_waitcnt vmcnt(8)
	s_waitcnt lgkmcnt(0)
	s_setprio 1
	s_barrier
	v_mfma_f32_16x16x32_bf16 v[124:127], v[146:149], v[178:181], v[124:127]
	v_mfma_f32_16x16x32_bf16 v[120:123], v[154:157], v[178:181], v[120:123]
	v_mfma_f32_16x16x32_bf16 v[116:119], v[146:149], v[186:189], v[116:119]
	v_mfma_f32_16x16x32_bf16 v[112:115], v[154:157], v[186:189], v[112:115]
	v_mfma_f32_16x16x32_bf16 v[108:111], v[146:149], v[194:197], v[108:111]
	v_mfma_f32_16x16x32_bf16 v[104:107], v[154:157], v[194:197], v[104:107]
	v_mfma_f32_16x16x32_bf16 v[100:103], v[146:149], v[206:209], v[100:103]
	v_mfma_f32_16x16x32_bf16 v[96:99], v[154:157], v[206:209], v[96:99]
	v_mfma_f32_16x16x32_bf16 v[124:127], v[150:153], v[182:185], v[124:127]
	v_mfma_f32_16x16x32_bf16 v[120:123], v[158:161], v[182:185], v[120:123]
	v_mfma_f32_16x16x32_bf16 v[116:119], v[150:153], v[190:193], v[116:119]
	v_mfma_f32_16x16x32_bf16 v[112:115], v[158:161], v[190:193], v[112:115]
	v_mfma_f32_16x16x32_bf16 v[108:111], v[150:153], v[202:205], v[108:111]
	v_mfma_f32_16x16x32_bf16 v[104:107], v[158:161], v[202:205], v[104:107]
	v_mfma_f32_16x16x32_bf16 v[100:103], v[150:153], v[210:213], v[100:103]
	v_mfma_f32_16x16x32_bf16 v[96:99], v[158:161], v[210:213], v[96:99]
	v_mfma_f32_16x16x32_bf16 v[92:95], v[162:165], v[178:181], v[92:95]
	v_mfma_f32_16x16x32_bf16 v[88:91], v[170:173], v[178:181], v[88:91]
	v_mfma_f32_16x16x32_bf16 v[84:87], v[162:165], v[186:189], v[84:87]
	v_mfma_f32_16x16x32_bf16 v[80:83], v[170:173], v[186:189], v[80:83]
	v_mfma_f32_16x16x32_bf16 v[76:79], v[162:165], v[194:197], v[76:79]
	v_mfma_f32_16x16x32_bf16 v[72:75], v[170:173], v[194:197], v[72:75]
	v_mfma_f32_16x16x32_bf16 v[68:71], v[162:165], v[206:209], v[68:71]
	v_mfma_f32_16x16x32_bf16 v[64:67], v[170:173], v[206:209], v[64:67]
	v_mfma_f32_16x16x32_bf16 v[92:95], v[166:169], v[182:185], v[92:95]
	v_mfma_f32_16x16x32_bf16 v[88:91], v[174:177], v[182:185], v[88:91]
	v_mfma_f32_16x16x32_bf16 v[84:87], v[166:169], v[190:193], v[84:87]
	v_mfma_f32_16x16x32_bf16 v[80:83], v[174:177], v[190:193], v[80:83]
	v_mfma_f32_16x16x32_bf16 v[76:79], v[166:169], v[202:205], v[76:79]
	v_mfma_f32_16x16x32_bf16 v[72:75], v[174:177], v[202:205], v[72:75]
	v_mfma_f32_16x16x32_bf16 v[68:71], v[166:169], v[210:213], v[68:71]
	v_mfma_f32_16x16x32_bf16 v[64:67], v[174:177], v[210:213], v[64:67]
	s_barrier
	s_setprio 0
	s_add_i32 s35, s53, s15
	v_lshl_add_u64 v[198:199], s[2:3], 0, v[130:131]
	s_mov_b32 m0, s35
	ds_read_b128 v[178:181], v144 offset:16384
	ds_read_b128 v[182:185], v144 offset:17408
	ds_read_b128 v[186:189], v144 offset:18432
	ds_read_b128 v[190:193], v144 offset:19456
	ds_read_b128 v[194:197], v144 offset:20480
	ds_read_b128 v[202:205], v144 offset:21504
	ds_read_b128 v[206:209], v144 offset:22528
	ds_read_b128 v[210:213], v144 offset:23552
	global_load_lds_dwordx4 v[198:199], off
	v_lshl_add_u64 v[214:215], s[2:3], 0, v[134:135]
	s_add_i32 m0, s35, 0x2000
	s_add_i32 s35, s54, s15
	global_load_lds_dwordx4 v[214:215], off
	v_lshl_add_u64 v[216:217], s[60:61], 0, v[130:131]
	s_mov_b32 m0, s35
	v_lshl_add_u64 v[218:219], s[44:45], 0, v[132:133]
	global_load_lds_dwordx4 v[216:217], off
	v_lshl_add_u64 v[216:217], s[60:61], 0, v[134:135]
	s_add_i32 m0, s35, 0x2000
	s_nop 0
	global_load_lds_dwordx4 v[216:217], off
	v_lshl_add_u64 v[216:217], s[44:45], 0, v[128:129]
	s_mov_b32 m0, s20
	s_nop 0
	global_load_lds_dwordx4 v[216:217], off
	s_mov_b32 m0, s21
	s_nop 0
	global_load_lds_dwordx4 v[218:219], off
	s_waitcnt vmcnt(8)
	s_waitcnt lgkmcnt(0)
	s_setprio 1
	s_barrier
; #define PG8_STAGE(bufoff, gbase, voff) do { _Pragma("unroll") for (int _i = 0; _i < 2; ++_i) \
;         __builtin_amdgcn_global_load_lds((const unsigned*)((const char*)(gbase) + (voff)[_i]), (LAS unsigned*)(lds + (bufoff) + ldsw + _i * 8192), 16, 0, 0); } while (0)
; #define PG8_LDA(dst, b, h) do { _Pragma("unroll") for (int m = 0; m < 4; ++m) _Pragma("unroll") for (int k = 0; k < 2; ++k) dst[m][k] = *(const LAS bf16x8*)(lds + PG8_SA(b, h) + aoff + m * 2048 + k * 1024); } while (0)
; #define PG8_LDB(dst, b, h) do { _Pragma("unroll") for (int n = 0; n < 2; ++n) _Pragma("unroll") for (int k = 0; k < 2; ++k) dst[n][k] = *(const LAS bf16x8*)(lds + PG8_SB(b, h) + boff + n * 2048 + k * 1024); } while (0)
; #define PG8_MMA(ai, bj, At, Bt) do { __builtin_amdgcn_s_setprio(1); _Pragma("unroll") for (int m = 0; m < 4; ++m) _Pragma("unroll") for (int n = 0; n < 2; ++n) _Pragma("unroll") for (int k = 0; k < 2; ++k) \
;         acc[ai][bj][m][n] = __builtin_amdgcn_mfma_f32_16x16x32_bf16(Bt[n][k], At[m][k], acc[ai][bj][m][n], 0, 0, 0); __builtin_amdgcn_s_setprio(0); } while (0)
; #define PG8_WAIT_V(n) asm volatile("s_waitcnt vmcnt(" #n ")" ::: "memory")
; #define PG8_WAIT_L(n) asm volatile("s_waitcnt lgkmcnt(" #n ")" ::: "memory")
; #define PG8_BAR __builtin_amdgcn_s_barrier()
; #define PG8_SCHED __builtin_amdgcn_sched_barrier(0)
; template <class Epi, bool BSEL = false>
; __device__ __forceinline__ void gemm_phase(LAS unsigned char* lds, const Gemm g, const Order& S, const Epi& E, const int tid) {
;     ...
;             PG8_WAIT_V(8); PG8_WAIT_L(0); PG8_BAR; PG8_MMA(1, 0, At, B0); PG8_MMA(1, 1, At, B1); PG8_BAR; PG8_SCHED;
;             PG8_LDB(B0, 1, 0); PG8_LDB(B1, 1, 1); PG8_SCHED; PG8_LDA(At, 1, 0); PG8_STAGE(PG8_SA(0, 1), a2 + hstepA, voffA);
;             PG8_WAIT_V(8); PG8_WAIT_L(0); PG8_BAR; PG8_MMA(0, 0, At, B0); PG8_MMA(0, 1, At, B1); PG8_BAR; PG8_SCHED;
	v_mfma_f32_16x16x32_bf16 v[60:63], v[146:149], v[178:181], v[60:63]
	v_mfma_f32_16x16x32_bf16 v[56:59], v[154:157], v[178:181], v[56:59]
	v_mfma_f32_16x16x32_bf16 v[52:55], v[146:149], v[186:189], v[52:55]
	v_mfma_f32_16x16x32_bf16 v[48:51], v[154:157], v[186:189], v[48:51]
	v_mfma_f32_16x16x32_bf16 v[44:47], v[146:149], v[194:197], v[44:47]
	v_mfma_f32_16x16x32_bf16 v[40:43], v[154:157], v[194:197], v[40:43]
	v_mfma_f32_16x16x32_bf16 v[36:39], v[146:149], v[206:209], v[36:39]
	v_mfma_f32_16x16x32_bf16 v[32:35], v[154:157], v[206:209], v[32:35]
	v_mfma_f32_16x16x32_bf16 v[60:63], v[150:153], v[182:185], v[60:63]
	v_mfma_f32_16x16x32_bf16 v[56:59], v[158:161], v[182:185], v[56:59]
	v_mfma_f32_16x16x32_bf16 v[52:55], v[150:153], v[190:193], v[52:55]
	v_mfma_f32_16x16x32_bf16 v[48:51], v[158:161], v[190:193], v[48:51]
	v_mfma_f32_16x16x32_bf16 v[44:47], v[150:153], v[202:205], v[44:47]
	v_mfma_f32_16x16x32_bf16 v[40:43], v[158:161], v[202:205], v[40:43]
	v_mfma_f32_16x16x32_bf16 v[36:39], v[150:153], v[210:213], v[36:39]
	v_mfma_f32_16x16x32_bf16 v[32:35], v[158:161], v[210:213], v[32:35]
	v_mfma_f32_16x16x32_bf16 v[28:31], v[162:165], v[178:181], v[28:31]
	v_mfma_f32_16x16x32_bf16 v[24:27], v[170:173], v[178:181], v[24:27]
	v_mfma_f32_16x16x32_bf16 v[20:23], v[162:165], v[186:189], v[20:23]
	v_mfma_f32_16x16x32_bf16 v[16:19], v[170:173], v[186:189], v[16:19]
	v_mfma_f32_16x16x32_bf16 v[12:15], v[162:165], v[194:197], v[12:15]
	v_mfma_f32_16x16x32_bf16 v[8:11], v[170:173], v[194:197], v[8:11]
	v_mfma_f32_16x16x32_bf16 v[4:7], v[162:165], v[206:209], v[4:7]
	v_mfma_f32_16x16x32_bf16 v[0:3], v[170:173], v[206:209], v[0:3]
	v_mfma_f32_16x16x32_bf16 v[28:31], v[166:169], v[182:185], v[28:31]
	v_mfma_f32_16x16x32_bf16 v[24:27], v[174:177], v[182:185], v[24:27]
	v_mfma_f32_16x16x32_bf16 v[20:23], v[166:169], v[190:193], v[20:23]
	v_mfma_f32_16x16x32_bf16 v[16:19], v[174:177], v[190:193], v[16:19]
	v_mfma_f32_16x16x32_bf16 v[12:15], v[166:169], v[202:205], v[12:15]
	v_mfma_f32_16x16x32_bf16 v[8:11], v[174:177], v[202:205], v[8:11]
	v_mfma_f32_16x16x32_bf16 v[4:7], v[166:169], v[210:213], v[4:7]
	v_mfma_f32_16x16x32_bf16 v[0:3], v[174:177], v[210:213], v[0:3]
	s_barrier
	s_setprio 0
	s_add_i32 s35, 0, 0x18000
	v_add_u32_e32 v145, s35, v139
	s_add_i32 s44, 0, 0x1c000
	ds_read_b128 v[146:149], v145
	ds_read_b128 v[150:153], v145 offset:1024
	ds_read_b128 v[154:157], v145 offset:2048
	ds_read_b128 v[158:161], v145 offset:3072
	v_add_u32_e32 v145, s44, v139
	ds_read_b128 v[162:165], v145
	ds_read_b128 v[166:169], v145 offset:1024
	ds_read_b128 v[170:173], v145 offset:2048
	ds_read_b128 v[174:177], v145 offset:3072
	s_mov_b32 m0, s46
	v_lshl_add_u64 v[220:221], s[42:43], 0, v[128:129]
	ds_read_b128 v[178:181], v144 offset:32768
	ds_read_b128 v[182:185], v144 offset:33792
	ds_read_b128 v[186:189], v144 offset:34816
	ds_read_b128 v[190:193], v144 offset:35840
	ds_read_b128 v[194:197], v144 offset:36864
	ds_read_b128 v[202:205], v144 offset:37888
	ds_read_b128 v[206:209], v144 offset:38912
	ds_read_b128 v[210:213], v144 offset:39936
	global_load_lds_dwordx4 v[220:221], off
	v_lshl_add_u64 v[220:221], s[42:43], 0, v[132:133]
	s_mov_b32 m0, s47
	s_nop 0
	global_load_lds_dwordx4 v[220:221], off
	s_waitcnt vmcnt(8)
	s_waitcnt lgkmcnt(0)
	s_setprio 1
	s_barrier
	v_mfma_f32_16x16x32_bf16 v[124:127], v[146:149], v[178:181], v[124:127]
	v_mfma_f32_16x16x32_bf16 v[120:123], v[154:157], v[178:181], v[120:123]
	v_mfma_f32_16x16x32_bf16 v[116:119], v[146:149], v[186:189], v[116:119]
	v_mfma_f32_16x16x32_bf16 v[112:115], v[154:157], v[186:189], v[112:115]
	v_mfma_f32_16x16x32_bf16 v[108:111], v[146:149], v[194:197], v[108:111]
	v_mfma_f32_16x16x32_bf16 v[104:107], v[154:157], v[194:197], v[104:107]
	v_mfma_f32_16x16x32_bf16 v[100:103], v[146:149], v[206:209], v[100:103]
	v_mfma_f32_16x16x32_bf16 v[96:99], v[154:157], v[206:209], v[96:99]
	v_mfma_f32_16x16x32_bf16 v[124:127], v[150:153], v[182:185], v[124:127]
	v_mfma_f32_16x16x32_bf16 v[120:123], v[158:161], v[182:185], v[120:123]
	v_mfma_f32_16x16x32_bf16 v[116:119], v[150:153], v[190:193], v[116:119]
	v_mfma_f32_16x16x32_bf16 v[112:115], v[158:161], v[190:193], v[112:115]
	v_mfma_f32_16x16x32_bf16 v[108:111], v[150:153], v[202:205], v[108:111]
	v_mfma_f32_16x16x32_bf16 v[104:107], v[158:161], v[202:205], v[104:107]
	v_mfma_f32_16x16x32_bf16 v[100:103], v[150:153], v[210:213], v[100:103]
	v_mfma_f32_16x16x32_bf16 v[96:99], v[158:161], v[210:213], v[96:99]
	v_mfma_f32_16x16x32_bf16 v[92:95], v[162:165], v[178:181], v[92:95]
	v_mfma_f32_16x16x32_bf16 v[88:91], v[170:173], v[178:181], v[88:91]
	v_mfma_f32_16x16x32_bf16 v[84:87], v[162:165], v[186:189], v[84:87]
	v_mfma_f32_16x16x32_bf16 v[80:83], v[170:173], v[186:189], v[80:83]
	v_mfma_f32_16x16x32_bf16 v[76:79], v[162:165], v[194:197], v[76:79]
	v_mfma_f32_16x16x32_bf16 v[72:75], v[170:173], v[194:197], v[72:75]
	v_mfma_f32_16x16x32_bf16 v[68:71], v[162:165], v[206:209], v[68:71]
	v_mfma_f32_16x16x32_bf16 v[64:67], v[170:173], v[206:209], v[64:67]
	v_mfma_f32_16x16x32_bf16 v[92:95], v[166:169], v[182:185], v[92:95]
	v_mfma_f32_16x16x32_bf16 v[88:91], v[174:177], v[182:185], v[88:91]
	v_mfma_f32_16x16x32_bf16 v[84:87], v[166:169], v[190:193], v[84:87]
	v_mfma_f32_16x16x32_bf16 v[80:83], v[174:177], v[190:193], v[80:83]
	v_mfma_f32_16x16x32_bf16 v[76:79], v[166:169], v[202:205], v[76:79]
	v_mfma_f32_16x16x32_bf16 v[72:75], v[174:177], v[202:205], v[72:75]
	v_mfma_f32_16x16x32_bf16 v[68:71], v[166:169], v[210:213], v[68:71]
	v_mfma_f32_16x16x32_bf16 v[64:67], v[174:177], v[210:213], v[64:67]
	s_barrier
; #define PG8_STAGE(bufoff, gbase, voff) do { _Pragma("unroll") for (int _i = 0; _i < 2; ++_i) \
;         __builtin_amdgcn_global_load_lds((const unsigned*)((const char*)(gbase) + (voff)[_i]), (LAS unsigned*)(lds + (bufoff) + ldsw + _i * 8192), 16, 0, 0); } while (0)
; #define PG8_STAGEB(bufoff, gbase, perm) do { _Pragma("unroll") for (int _i = 0; _i < 2; ++_i) \
;         __builtin_amdgcn_global_load_lds((const unsigned*)((const char*)(gbase) + ((BSEL && (perm)) ? voffBp[_i] : voffB[_i])), (LAS unsigned*)(lds + (bufoff) + ldsw + _i * 8192), 16, 0, 0); } while (0)
; #define PG8_LDA(dst, b, h) do { _Pragma("unroll") for (int m = 0; m < 4; ++m) _Pragma("unroll") for (int k = 0; k < 2; ++k) dst[m][k] = *(const LAS bf16x8*)(lds + PG8_SA(b, h) + aoff + m * 2048 + k * 1024); } while (0)
; #define PG8_WAIT_V(n) asm volatile("s_waitcnt vmcnt(" #n ")" ::: "memory")
; #define PG8_WAIT_L(n) asm volatile("s_waitcnt lgkmcnt(" #n ")" ::: "memory")
; #define PG8_BAR __builtin_amdgcn_s_barrier()
; #define PG8_SCHED __builtin_amdgcn_sched_barrier(0)
; template <class Epi, bool BSEL = false>
; __device__ __forceinline__ void gemm_phase(LAS unsigned char* lds, const Gemm g, const Order& S, const Epi& E, const int tid) {
;     ...
;             PG8_LDA(At, 1, 1); PG8_STAGEB(PG8_SB(1, 0), b3, p2); PG8_STAGEB(PG8_SB(1, 1), b3 + h2, p2); PG8_STAGE(PG8_SA(1, 0), a3, voffA);
;             PG8_WAIT_V(8); PG8_WAIT_L(0); PG8_BAR; PG8_MMA(1, 0, At, B0); PG8_MMA(1, 1, At, B1); PG8_BAR; PG8_SCHED;
;         }
;         if constexpr (ALIGN_EPI) { if (wr == 0) PG8_BAR; }
;     __device__ __forceinline__ void operator()(const f32x4 (&acc)[2][2][4][2], const Unit& u, int wr, int wc, int fr, int fq) const {
;         if (wr != 0) return;
;         const __amdgpu_buffer_rsrc_t rsrc = __builtin_amdgcn_make_buffer_rsrc(YT, 0, 65536 * 128 * 2, 0x00020000);
; #pragma unroll
;         for (int m = 0; m < 4; ++m) { const int k1 = 16 * m + fr;
; #pragma unroll
;             for (int bj = 0; bj < 2; ++bj) { const int col = 4 * u.pn + 2 * bj + (wc >> 1), b = col >> 8, ch = col & 255;
;                 const int n2 = 32 * (wc & 1) + 8 * fq;
;                 const unsigned rowo = (unsigned)((((size_t)(b * 64 + k1) * 256 + ch) * 128 + n2) * 2);
;                 int kk = k1; asm volatile("" : "+v"(kk));
	s_setprio 0
	s_add_i32 s35, s35, s15
	v_lshl_add_u64 v[198:199], v[198:199], 0, s[28:29]
	s_mov_b32 m0, s35
	ds_read_b128 v[178:181], v144 offset:49152
	ds_read_b128 v[182:185], v144 offset:50176
	ds_read_b128 v[186:189], v144 offset:51200
	ds_read_b128 v[190:193], v144 offset:52224
	ds_read_b128 v[194:197], v144 offset:53248
	ds_read_b128 v[202:205], v144 offset:54272
	ds_read_b128 v[206:209], v144 offset:55296
	ds_read_b128 v[210:213], v144 offset:56320
	global_load_lds_dwordx4 v[198:199], off
	s_add_i32 m0, s35, 0x2000
	s_add_u32 s2, s2, 0x8080
	v_lshl_add_u64 v[198:199], v[214:215], 0, s[28:29]
	s_addc_u32 s3, s3, 0
	s_add_i32 s35, s44, s15
	global_load_lds_dwordx4 v[198:199], off
	v_lshl_add_u64 v[198:199], s[2:3], 0, v[130:131]
	s_mov_b32 m0, s35
	s_nop 0
	global_load_lds_dwordx4 v[198:199], off
	v_lshl_add_u64 v[198:199], s[2:3], 0, v[134:135]
	s_add_i32 m0, s35, 0x2000
	s_nop 0
	global_load_lds_dwordx4 v[198:199], off
	v_lshl_add_u64 v[198:199], v[216:217], 0, s[28:29]
	s_mov_b32 m0, s49
	s_nop 0
	global_load_lds_dwordx4 v[198:199], off
	v_lshl_add_u64 v[198:199], v[218:219], 0, s[28:29]
	s_mov_b32 m0, s51
	s_nop 0
	global_load_lds_dwordx4 v[198:199], off
	s_waitcnt vmcnt(8)
	s_waitcnt lgkmcnt(0)
	s_setprio 1
	s_barrier
	v_mfma_f32_16x16x32_bf16 v[60:63], v[146:149], v[178:181], v[60:63]
	v_mfma_f32_16x16x32_bf16 v[56:59], v[154:157], v[178:181], v[56:59]
	v_mfma_f32_16x16x32_bf16 v[52:55], v[146:149], v[186:189], v[52:55]
	v_mfma_f32_16x16x32_bf16 v[48:51], v[154:157], v[186:189], v[48:51]
	v_mfma_f32_16x16x32_bf16 v[44:47], v[146:149], v[194:197], v[44:47]
	v_mfma_f32_16x16x32_bf16 v[40:43], v[154:157], v[194:197], v[40:43]
	v_mfma_f32_16x16x32_bf16 v[36:39], v[146:149], v[206:209], v[36:39]
	v_mfma_f32_16x16x32_bf16 v[32:35], v[154:157], v[206:209], v[32:35]
	v_mfma_f32_16x16x32_bf16 v[60:63], v[150:153], v[182:185], v[60:63]
	v_mfma_f32_16x16x32_bf16 v[56:59], v[158:161], v[182:185], v[56:59]
	v_mfma_f32_16x16x32_bf16 v[52:55], v[150:153], v[190:193], v[52:55]
	v_mfma_f32_16x16x32_bf16 v[48:51], v[158:161], v[190:193], v[48:51]
	v_mfma_f32_16x16x32_bf16 v[44:47], v[150:153], v[202:205], v[44:47]
	v_mfma_f32_16x16x32_bf16 v[40:43], v[158:161], v[202:205], v[40:43]
	v_mfma_f32_16x16x32_bf16 v[36:39], v[150:153], v[210:213], v[36:39]
	v_mfma_f32_16x16x32_bf16 v[32:35], v[158:161], v[210:213], v[32:35]
	v_mfma_f32_16x16x32_bf16 v[28:31], v[162:165], v[178:181], v[28:31]
	v_mfma_f32_16x16x32_bf16 v[24:27], v[170:173], v[178:181], v[24:27]
	v_mfma_f32_16x16x32_bf16 v[20:23], v[162:165], v[186:189], v[20:23]
	v_mfma_f32_16x16x32_bf16 v[16:19], v[170:173], v[186:189], v[16:19]
	v_mfma_f32_16x16x32_bf16 v[12:15], v[162:165], v[194:197], v[12:15]
	v_mfma_f32_16x16x32_bf16 v[8:11], v[170:173], v[194:197], v[8:11]
	v_mfma_f32_16x16x32_bf16 v[4:7], v[162:165], v[206:209], v[4:7]
	v_mfma_f32_16x16x32_bf16 v[0:3], v[170:173], v[206:209], v[0:3]
	v_mfma_f32_16x16x32_bf16 v[28:31], v[166:169], v[182:185], v[28:31]
	v_mfma_f32_16x16x32_bf16 v[24:27], v[174:177], v[182:185], v[24:27]
	v_mfma_f32_16x16x32_bf16 v[20:23], v[166:169], v[190:193], v[20:23]
	v_mfma_f32_16x16x32_bf16 v[16:19], v[174:177], v[190:193], v[16:19]
	v_mfma_f32_16x16x32_bf16 v[12:15], v[166:169], v[202:205], v[12:15]
	v_mfma_f32_16x16x32_bf16 v[8:11], v[174:177], v[202:205], v[8:11]
	v_mfma_f32_16x16x32_bf16 v[4:7], v[166:169], v[210:213], v[4:7]
	v_mfma_f32_16x16x32_bf16 v[0:3], v[174:177], v[210:213], v[0:3]
	s_barrier
	s_setprio 0
	s_andn2_b64 vcc, exec, s[30:31]
	s_cbranch_vccnz .LBB0_828
	v_mov_b32_e32 v145, v138
	s_barrier
	v_mov_b32_e32 v162, v124
	v_mul_lo_u32 v146, v145, v140
	v_ashrrev_i32_e32 v147, 31, v146
	v_lshl_add_u64 v[148:149], v[146:147], 3, s[26:27]
	v_add_u32_e32 v146, v146, v145
	v_ashrrev_i32_e32 v147, 31, v146
	v_lshl_add_u64 v[150:151], v[146:147], 3, s[26:27]
	v_add_u32_e32 v146, v146, v145
	v_ashrrev_i32_e32 v147, 31, v146
	v_lshl_add_u64 v[152:153], v[146:147], 3, s[26:27]
	v_add_u32_e32 v146, v146, v145
	v_ashrrev_i32_e32 v147, 31, v146
	v_lshl_add_u64 v[154:155], v[146:147], 3, s[26:27]
	v_add_u32_e32 v146, v146, v145
	global_load_dwordx2 v[148:149], v[148:149], off
	v_ashrrev_i32_e32 v147, 31, v146
	global_load_dwordx2 v[150:151], v[150:151], off
	v_lshl_add_u64 v[156:157], v[146:147], 3, s[26:27]
	v_add_u32_e32 v146, v146, v145
	global_load_dwordx2 v[152:153], v[152:153], off
	v_ashrrev_i32_e32 v147, 31, v146
	global_load_dwordx2 v[154:155], v[154:155], off
	v_lshl_add_u64 v[158:159], v[146:147], 3, s[26:27]
	v_add_u32_e32 v146, v146, v145
	global_load_dwordx2 v[156:157], v[156:157], off
	v_ashrrev_i32_e32 v147, 31, v146
	global_load_dwordx2 v[158:159], v[158:159], off
	v_lshl_add_u64 v[160:161], v[146:147], 3, s[26:27]
	global_load_dwordx2 v[160:161], v[160:161], off
	v_add_u32_e32 v146, v146, v145
	v_ashrrev_i32_e32 v147, 31, v146
	v_lshl_add_u64 v[146:147], v[146:147], 3, s[26:27]
	global_load_dwordx2 v[146:147], v[146:147], off
	v_mov_b32_e32 v163, v60
	v_mov_b32_e32 v164, v60
	v_mov_b32_e32 v165, v124
	v_mov_b32_e32 v166, v125
	v_mov_b32_e32 v167, v61
	v_mov_b32_e32 v168, v61
	v_mov_b32_e32 v169, v125
	v_mov_b32_e32 v170, v126
	v_mov_b32_e32 v171, v62
	v_mov_b32_e32 v172, v62
	v_mov_b32_e32 v173, v126
	v_mov_b32_e32 v174, v127
	v_mov_b32_e32 v175, v63
	v_mov_b32_e32 v176, v63
	v_mov_b32_e32 v177, v127
	v_mov_b32_e32 v178, v120
	v_mov_b32_e32 v179, v56
	v_mov_b32_e32 v180, v56
	v_mov_b32_e32 v181, v120
	v_mov_b32_e32 v182, v121
	v_mov_b32_e32 v183, v57
	v_mov_b32_e32 v184, v57
	v_mov_b32_e32 v185, v121
	v_mov_b32_e32 v186, v122
	v_mov_b32_e32 v187, v58
	s_lshl_b32 s3, s48, 2
	s_and_b32 s2, s48, 0xffc0
	s_and_b32 s3, s3, 0xfc
	v_or_b32_e32 v145, s2, v138
	s_or_b32 s3, s3, s52
	v_lshl_or_b32 v145, v145, 15, v140
	s_lshl_b32 s35, s3, 7
	v_or_b32_e32 v188, s35, v145
	s_or_b32 s3, s35, 0x100
	v_or_b32_e32 v145, s3, v145
	v_lshlrev_b32_e32 v145, 1, v145
	s_waitcnt vmcnt(0)
; __device__ __forceinline__ unsigned cvt_pk_bf16(float lo, float hi) { unsigned r; asm volatile("v_cvt_pk_bf16_f32 %0, %1, %2" : "=v"(r) : "v"(lo), "v"(hi)); return r; }
;     __device__ __forceinline__ void operator()(const f32x4 (&acc)[2][2][4][2], const Unit& u, int wr, int wc, int fr, int fq) const {
;     ...
; #pragma unroll
;                 for (int n = 0; n < 2; ++n) { const f32x4 yr = acc[0][bj][m][n], yi = acc[1][bj][m][n];
; #pragma unroll
;                     for (int i = 0; i < 4; ++i) { const f32x2 cs = TW[(n2 + 4 * n + i) * kk]; pr[n][i] = yr[i] * cs.x + yi[i] * cs.y; pi[n][i] = yi[i] * cs.x - yr[i] * cs.y; } }
;                 u32x4 w; w.x = cvt_pk_bf16(pr[0][0], pr[0][1]); w.y = cvt_pk_bf16(pr[0][2], pr[0][3]); w.z = cvt_pk_bf16(pr[1][0], pr[1][1]); w.w = cvt_pk_bf16(pr[1][2], pr[1][3]);
;                 __builtin_amdgcn_raw_buffer_store_b128(w, rsrc, rowo, 0, 16);
;                 w.x = cvt_pk_bf16(pi[0][0], pi[0][1]); w.y = cvt_pk_bf16(pi[0][2], pi[0][3]); w.z = cvt_pk_bf16(pi[1][0], pi[1][1]); w.w = cvt_pk_bf16(pi[1][2], pi[1][3]);
;                 __builtin_amdgcn_raw_buffer_store_b128(w, rsrc, rowo + 128, 0, 16);
	v_pk_mul_f32 v[162:163], v[162:163], v[148:149]
	v_pk_mul_f32 v[148:149], v[164:165], v[148:149]
	v_add_f32_e32 v162, v162, v163
	v_sub_f32_e32 v163, v148, v149
	v_pk_mul_f32 v[148:149], v[166:167], v[150:151]
	v_pk_mul_f32 v[150:151], v[168:169], v[150:151]
	v_add_f32_e32 v164, v148, v149
	v_pk_mul_f32 v[148:149], v[170:171], v[152:153]
	v_sub_f32_e32 v165, v150, v151
	v_pk_mul_f32 v[150:151], v[172:173], v[152:153]
	v_add_f32_e32 v152, v148, v149
	v_pk_mul_f32 v[148:149], v[174:175], v[154:155]
	v_sub_f32_e32 v153, v150, v151
	v_pk_mul_f32 v[150:151], v[176:177], v[154:155]
	v_add_f32_e32 v154, v148, v149
	v_pk_mul_f32 v[148:149], v[178:179], v[156:157]
	v_sub_f32_e32 v155, v150, v151
	v_pk_mul_f32 v[150:151], v[180:181], v[156:157]
	v_add_f32_e32 v156, v148, v149
	v_pk_mul_f32 v[148:149], v[182:183], v[158:159]
	v_sub_f32_e32 v157, v150, v151
	v_pk_mul_f32 v[150:151], v[184:185], v[158:159]
	v_add_f32_e32 v158, v148, v149
	v_pk_mul_f32 v[148:149], v[186:187], v[160:161]
	v_sub_f32_e32 v150, v150, v151
	v_add_f32_e32 v151, v148, v149
	v_mov_b32_e32 v148, v58
	v_mov_b32_e32 v149, v122
	v_pk_mul_f32 v[148:149], v[148:149], v[160:161]
	v_lshlrev_b32_e32 v166, 1, v188
	v_sub_f32_e32 v159, v148, v149
	v_mov_b32_e32 v148, v123
	v_mov_b32_e32 v149, v59
	v_pk_mul_f32 v[148:149], v[148:149], v[146:147]
	v_mov_b32_e32 v167, v29
	v_add_f32_e32 v160, v148, v149
	v_mov_b32_e32 v148, v59
	v_mov_b32_e32 v149, v123
	v_pk_mul_f32 v[146:147], v[148:149], v[146:147]
	v_mov_b32_e32 v168, v29
	v_sub_f32_e32 v161, v146, v147
	v_cvt_pk_bf16_f32 v146, v162, v164
	v_cvt_pk_bf16_f32 v147, v152, v154
	v_cvt_pk_bf16_f32 v148, v156, v158
	v_cvt_pk_bf16_f32 v149, v151, v160
	buffer_store_dwordx4 v[146:149], v166, s[8:11], 0 offen sc1
	v_mov_b32_e32 v162, v138
	v_mov_b32_e32 v164, v28
	v_cvt_pk_bf16_f32 v146, v163, v165
	v_cvt_pk_bf16_f32 v147, v153, v155
	v_cvt_pk_bf16_f32 v148, v157, v150
	v_cvt_pk_bf16_f32 v149, v159, v161
	buffer_store_dwordx4 v[146:149], v166, s[8:11], 0 offen offset:128 sc1
	v_mov_b32_e32 v163, v28
	v_mov_b32_e32 v165, v92
	v_mul_lo_u32 v146, v162, v140
	v_ashrrev_i32_e32 v147, 31, v146
	v_lshl_add_u64 v[148:149], v[146:147], 3, s[26:27]
	v_add_u32_e32 v146, v146, v162
	v_ashrrev_i32_e32 v147, 31, v146
	v_lshl_add_u64 v[150:151], v[146:147], 3, s[26:27]
	v_add_u32_e32 v146, v146, v162
	v_ashrrev_i32_e32 v147, 31, v146
	global_load_dwordx2 v[148:149], v[148:149], off
	v_lshl_add_u64 v[152:153], v[146:147], 3, s[26:27]
	v_add_u32_e32 v146, v146, v162
	global_load_dwordx2 v[150:151], v[150:151], off
	v_ashrrev_i32_e32 v147, 31, v146
	global_load_dwordx2 v[152:153], v[152:153], off
	v_lshl_add_u64 v[154:155], v[146:147], 3, s[26:27]
	v_add_u32_e32 v146, v146, v162
	global_load_dwordx2 v[154:155], v[154:155], off
	v_ashrrev_i32_e32 v147, 31, v146
	v_lshl_add_u64 v[156:157], v[146:147], 3, s[26:27]
	global_load_dwordx2 v[156:157], v[156:157], off
	v_add_u32_e32 v146, v146, v162
	v_ashrrev_i32_e32 v147, 31, v146
	v_lshl_add_u64 v[158:159], v[146:147], 3, s[26:27]
	global_load_dwordx2 v[158:159], v[158:159], off
	v_add_u32_e32 v146, v146, v162
	v_ashrrev_i32_e32 v147, 31, v146
	v_lshl_add_u64 v[160:161], v[146:147], 3, s[26:27]
	global_load_dwordx2 v[160:161], v[160:161], off
	v_add_u32_e32 v146, v146, v162
	v_ashrrev_i32_e32 v147, 31, v146
	v_lshl_add_u64 v[146:147], v[146:147], 3, s[26:27]
	global_load_dwordx2 v[146:147], v[146:147], off
	v_mov_b32_e32 v162, v92
	v_mov_b32_e32 v166, v93
	v_mov_b32_e32 v169, v93
	v_mov_b32_e32 v170, v94
	v_mov_b32_e32 v171, v30
	v_mov_b32_e32 v172, v30
	v_mov_b32_e32 v173, v94
	v_mov_b32_e32 v174, v95
	v_mov_b32_e32 v175, v31
	v_mov_b32_e32 v176, v31
	v_mov_b32_e32 v177, v95
	s_waitcnt vmcnt(7)
	v_pk_mul_f32 v[162:163], v[162:163], v[148:149]
	v_pk_mul_f32 v[148:149], v[164:165], v[148:149]
	v_add_f32_e32 v162, v162, v163
	v_sub_f32_e32 v163, v148, v149
	s_waitcnt vmcnt(6)
	v_pk_mul_f32 v[148:149], v[166:167], v[150:151]
	v_pk_mul_f32 v[150:151], v[168:169], v[150:151]
	v_add_f32_e32 v164, v148, v149
	s_waitcnt vmcnt(5)
	v_pk_mul_f32 v[148:149], v[170:171], v[152:153]
	v_sub_f32_e32 v165, v150, v151
	v_pk_mul_f32 v[150:151], v[172:173], v[152:153]
	v_add_f32_e32 v152, v148, v149
	s_waitcnt vmcnt(4)
	v_pk_mul_f32 v[148:149], v[174:175], v[154:155]
	v_sub_f32_e32 v153, v150, v151
	v_pk_mul_f32 v[150:151], v[176:177], v[154:155]
	v_add_f32_e32 v154, v148, v149
	v_mov_b32_e32 v148, v88
	v_mov_b32_e32 v149, v24
	s_waitcnt vmcnt(3)
	v_pk_mul_f32 v[148:149], v[148:149], v[156:157]
	v_sub_f32_e32 v150, v150, v151
	v_add_f32_e32 v151, v148, v149
	v_mov_b32_e32 v148, v24
	v_mov_b32_e32 v149, v88
	v_pk_mul_f32 v[148:149], v[148:149], v[156:157]
	v_mov_b32_e32 v166, v117
	v_sub_f32_e32 v155, v148, v149
	v_mov_b32_e32 v148, v89
	v_mov_b32_e32 v149, v25
	s_waitcnt vmcnt(2)
	v_pk_mul_f32 v[148:149], v[148:149], v[158:159]
	v_mov_b32_e32 v167, v53
	v_add_f32_e32 v156, v148, v149
	v_mov_b32_e32 v148, v25
	v_mov_b32_e32 v149, v89
	v_pk_mul_f32 v[148:149], v[148:149], v[158:159]
	s_nop 0
	v_sub_f32_e32 v157, v148, v149
	v_mov_b32_e32 v148, v90
	v_mov_b32_e32 v149, v26
	s_waitcnt vmcnt(1)
	v_pk_mul_f32 v[148:149], v[148:149], v[160:161]
	s_nop 0
	v_add_f32_e32 v158, v148, v149
	v_mov_b32_e32 v148, v26
	v_mov_b32_e32 v149, v90
	v_pk_mul_f32 v[148:149], v[148:149], v[160:161]
	s_nop 0
	v_sub_f32_e32 v159, v148, v149
	v_mov_b32_e32 v148, v91
	v_mov_b32_e32 v149, v27
	s_waitcnt vmcnt(0)
; __device__ __forceinline__ unsigned cvt_pk_bf16(float lo, float hi) { unsigned r; asm volatile("v_cvt_pk_bf16_f32 %0, %1, %2" : "=v"(r) : "v"(lo), "v"(hi)); return r; }
;     __device__ __forceinline__ void operator()(const f32x4 (&acc)[2][2][4][2], const Unit& u, int wr, int wc, int fr, int fq) const {
;     ...
;         for (int m = 0; m < 4; ++m) { const int k1 = 16 * m + fr;
; #pragma unroll
;             for (int bj = 0; bj < 2; ++bj) { const int col = 4 * u.pn + 2 * bj + (wc >> 1), b = col >> 8, ch = col & 255;
;                 const int n2 = 32 * (wc & 1) + 8 * fq;
;                 const unsigned rowo = (unsigned)((((size_t)(b * 64 + k1) * 256 + ch) * 128 + n2) * 2);
;                 int kk = k1; asm volatile("" : "+v"(kk));
;     ...
; #pragma unroll
;                 for (int n = 0; n < 2; ++n) { const f32x4 yr = acc[0][bj][m][n], yi = acc[1][bj][m][n];
; #pragma unroll
;                     for (int i = 0; i < 4; ++i) { const f32x2 cs = TW[(n2 + 4 * n + i) * kk]; pr[n][i] = yr[i] * cs.x + yi[i] * cs.y; pi[n][i] = yi[i] * cs.x - yr[i] * cs.y; } }
;                 u32x4 w; w.x = cvt_pk_bf16(pr[0][0], pr[0][1]); w.y = cvt_pk_bf16(pr[0][2], pr[0][3]); w.z = cvt_pk_bf16(pr[1][0], pr[1][1]); w.w = cvt_pk_bf16(pr[1][2], pr[1][3]);
;                 __builtin_amdgcn_raw_buffer_store_b128(w, rsrc, rowo, 0, 16);
;                 w.x = cvt_pk_bf16(pi[0][0], pi[0][1]); w.y = cvt_pk_bf16(pi[0][2], pi[0][3]); w.z = cvt_pk_bf16(pi[1][0], pi[1][1]); w.w = cvt_pk_bf16(pi[1][2], pi[1][3]);
;                 __builtin_amdgcn_raw_buffer_store_b128(w, rsrc, rowo + 128, 0, 16);
	v_pk_mul_f32 v[148:149], v[148:149], v[146:147]
	s_nop 0
	v_add_f32_e32 v160, v148, v149
	v_mov_b32_e32 v148, v27
	v_mov_b32_e32 v149, v91
	v_pk_mul_f32 v[146:147], v[148:149], v[146:147]
	s_nop 0
	v_sub_f32_e32 v161, v146, v147
	v_cvt_pk_bf16_f32 v146, v162, v164
	v_cvt_pk_bf16_f32 v147, v152, v154
	v_cvt_pk_bf16_f32 v148, v151, v156
	v_cvt_pk_bf16_f32 v149, v158, v160
	buffer_store_dwordx4 v[146:149], v145, s[8:11], 0 offen sc1
	v_mov_b32_e32 v162, v116
	v_mov_b32_e32 v164, v52
	v_cvt_pk_bf16_f32 v146, v163, v165
	v_cvt_pk_bf16_f32 v147, v153, v150
	v_cvt_pk_bf16_f32 v148, v155, v157
	v_cvt_pk_bf16_f32 v149, v159, v161
	buffer_store_dwordx4 v[146:149], v145, s[8:11], 0 offen offset:128 sc1
	v_mov_b32_e32 v145, v141
	v_mov_b32_e32 v163, v52
	v_mul_lo_u32 v146, v145, v140
	v_ashrrev_i32_e32 v147, 31, v146
	v_lshl_add_u64 v[148:149], v[146:147], 3, s[26:27]
	v_add_u32_e32 v146, v146, v145
	v_ashrrev_i32_e32 v147, 31, v146
	global_load_dwordx2 v[148:149], v[148:149], off
	v_lshl_add_u64 v[150:151], v[146:147], 3, s[26:27]
	global_load_dwordx2 v[150:151], v[150:151], off
	v_add_u32_e32 v146, v146, v145
	v_ashrrev_i32_e32 v147, 31, v146
	v_lshl_add_u64 v[152:153], v[146:147], 3, s[26:27]
	global_load_dwordx2 v[152:153], v[152:153], off
	v_add_u32_e32 v146, v146, v145
	v_ashrrev_i32_e32 v147, 31, v146
	v_lshl_add_u64 v[154:155], v[146:147], 3, s[26:27]
	global_load_dwordx2 v[154:155], v[154:155], off
	v_add_u32_e32 v146, v146, v145
	v_ashrrev_i32_e32 v147, 31, v146
	v_lshl_add_u64 v[156:157], v[146:147], 3, s[26:27]
	global_load_dwordx2 v[156:157], v[156:157], off
	v_add_u32_e32 v146, v146, v145
	v_ashrrev_i32_e32 v147, 31, v146
	v_lshl_add_u64 v[158:159], v[146:147], 3, s[26:27]
	global_load_dwordx2 v[158:159], v[158:159], off
	v_add_u32_e32 v146, v146, v145
	v_ashrrev_i32_e32 v147, 31, v146
	v_lshl_add_u64 v[160:161], v[146:147], 3, s[26:27]
	global_load_dwordx2 v[160:161], v[160:161], off
	v_add_u32_e32 v146, v146, v145
	v_ashrrev_i32_e32 v147, 31, v146
	v_lshl_add_u64 v[146:147], v[146:147], 3, s[26:27]
	global_load_dwordx2 v[146:147], v[146:147], off
	v_mov_b32_e32 v165, v116
	v_or_b32_e32 v145, s2, v141
	v_lshl_or_b32 v145, v145, 15, v140
	v_or_b32_e32 v168, s35, v145
	v_or_b32_e32 v145, s3, v145
	v_lshlrev_b32_e32 v145, 1, v145
	s_waitcnt vmcnt(7)
	v_pk_mul_f32 v[162:163], v[162:163], v[148:149]
	v_pk_mul_f32 v[148:149], v[164:165], v[148:149]
	v_add_f32_e32 v162, v162, v163
	v_sub_f32_e32 v163, v148, v149
	s_waitcnt vmcnt(6)
	v_pk_mul_f32 v[148:149], v[166:167], v[150:151]
	v_lshlrev_b32_e32 v166, 1, v168
	v_add_f32_e32 v164, v148, v149
	v_mov_b32_e32 v148, v53
	v_mov_b32_e32 v149, v117
	v_pk_mul_f32 v[148:149], v[148:149], v[150:151]
	s_nop 0
	v_sub_f32_e32 v150, v148, v149
	v_mov_b32_e32 v148, v118
	v_mov_b32_e32 v149, v54
	s_waitcnt vmcnt(5)
	v_pk_mul_f32 v[148:149], v[148:149], v[152:153]
	s_nop 0
	v_add_f32_e32 v151, v148, v149
	v_mov_b32_e32 v148, v54
	v_mov_b32_e32 v149, v118
	v_pk_mul_f32 v[148:149], v[148:149], v[152:153]
	s_nop 0
	v_sub_f32_e32 v152, v148, v149
	v_mov_b32_e32 v148, v119
	v_mov_b32_e32 v149, v55
	s_waitcnt vmcnt(4)
	v_pk_mul_f32 v[148:149], v[148:149], v[154:155]
	s_nop 0
	v_add_f32_e32 v153, v148, v149
	v_mov_b32_e32 v148, v55
	v_mov_b32_e32 v149, v119
	v_pk_mul_f32 v[148:149], v[148:149], v[154:155]
	s_nop 0
	v_sub_f32_e32 v154, v148, v149
	v_mov_b32_e32 v148, v112
	v_mov_b32_e32 v149, v48
	s_waitcnt vmcnt(3)
	v_pk_mul_f32 v[148:149], v[148:149], v[156:157]
	s_nop 0
	v_add_f32_e32 v155, v148, v149
	v_mov_b32_e32 v148, v48
	v_mov_b32_e32 v149, v112
	v_pk_mul_f32 v[148:149], v[148:149], v[156:157]
	s_nop 0
	v_sub_f32_e32 v156, v148, v149
	v_mov_b32_e32 v148, v113
	v_mov_b32_e32 v149, v49
	s_waitcnt vmcnt(2)
	v_pk_mul_f32 v[148:149], v[148:149], v[158:159]
	s_nop 0
	v_add_f32_e32 v157, v148, v149
	v_mov_b32_e32 v148, v49
	v_mov_b32_e32 v149, v113
	v_pk_mul_f32 v[148:149], v[148:149], v[158:159]
	s_nop 0
	v_sub_f32_e32 v158, v148, v149
	v_mov_b32_e32 v148, v114
	v_mov_b32_e32 v149, v50
	s_waitcnt vmcnt(1)
	v_pk_mul_f32 v[148:149], v[148:149], v[160:161]
	s_nop 0
	v_add_f32_e32 v159, v148, v149
	v_mov_b32_e32 v148, v50
	v_mov_b32_e32 v149, v114
	v_pk_mul_f32 v[148:149], v[148:149], v[160:161]
	s_nop 0
	v_sub_f32_e32 v160, v148, v149
	v_mov_b32_e32 v148, v115
	v_mov_b32_e32 v149, v51
	s_waitcnt vmcnt(0)
	v_pk_mul_f32 v[148:149], v[148:149], v[146:147]
	s_nop 0
	v_add_f32_e32 v161, v148, v149
	v_mov_b32_e32 v148, v51
	v_mov_b32_e32 v149, v115
	v_pk_mul_f32 v[146:147], v[148:149], v[146:147]
	s_nop 0
	v_sub_f32_e32 v165, v146, v147
	v_cvt_pk_bf16_f32 v146, v162, v164
	v_cvt_pk_bf16_f32 v147, v151, v153
	v_cvt_pk_bf16_f32 v148, v155, v157
	v_cvt_pk_bf16_f32 v149, v159, v161
	buffer_store_dwordx4 v[146:149], v166, s[8:11], 0 offen sc1
	v_mov_b32_e32 v162, v141
	s_nop 0
	v_cvt_pk_bf16_f32 v146, v163, v150
	v_cvt_pk_bf16_f32 v147, v152, v154
	v_cvt_pk_bf16_f32 v148, v156, v158
	v_cvt_pk_bf16_f32 v149, v160, v165
	buffer_store_dwordx4 v[146:149], v166, s[8:11], 0 offen offset:128 sc1
	v_mov_b32_e32 v163, v20
	s_nop 0
	v_mul_lo_u32 v146, v162, v140
	v_ashrrev_i32_e32 v147, 31, v146
	v_lshl_add_u64 v[148:149], v[146:147], 3, s[26:27]
	global_load_dwordx2 v[148:149], v[148:149], off
	v_add_u32_e32 v146, v146, v162
	v_ashrrev_i32_e32 v147, 31, v146
	v_lshl_add_u64 v[150:151], v[146:147], 3, s[26:27]
	global_load_dwordx2 v[150:151], v[150:151], off
	v_add_u32_e32 v146, v146, v162
	v_ashrrev_i32_e32 v147, 31, v146
	v_lshl_add_u64 v[152:153], v[146:147], 3, s[26:27]
	global_load_dwordx2 v[152:153], v[152:153], off
	v_add_u32_e32 v146, v146, v162
	v_ashrrev_i32_e32 v147, 31, v146
	v_lshl_add_u64 v[154:155], v[146:147], 3, s[26:27]
	global_load_dwordx2 v[154:155], v[154:155], off
	v_add_u32_e32 v146, v146, v162
	v_ashrrev_i32_e32 v147, 31, v146
	v_lshl_add_u64 v[156:157], v[146:147], 3, s[26:27]
	global_load_dwordx2 v[156:157], v[156:157], off
	v_add_u32_e32 v146, v146, v162
	v_ashrrev_i32_e32 v147, 31, v146
	v_lshl_add_u64 v[158:159], v[146:147], 3, s[26:27]
	global_load_dwordx2 v[158:159], v[158:159], off
	v_add_u32_e32 v146, v146, v162
	v_ashrrev_i32_e32 v147, 31, v146
	v_lshl_add_u64 v[160:161], v[146:147], 3, s[26:27]
	global_load_dwordx2 v[160:161], v[160:161], off
	v_add_u32_e32 v146, v146, v162
	v_ashrrev_i32_e32 v147, 31, v146
	v_lshl_add_u64 v[146:147], v[146:147], 3, s[26:27]
	global_load_dwordx2 v[146:147], v[146:147], off
	v_mov_b32_e32 v162, v84
	s_waitcnt vmcnt(7)
; __device__ __forceinline__ unsigned cvt_pk_bf16(float lo, float hi) { unsigned r; asm volatile("v_cvt_pk_bf16_f32 %0, %1, %2" : "=v"(r) : "v"(lo), "v"(hi)); return r; }
;     __device__ __forceinline__ void operator()(const f32x4 (&acc)[2][2][4][2], const Unit& u, int wr, int wc, int fr, int fq) const {
;     ...
;         for (int m = 0; m < 4; ++m) { const int k1 = 16 * m + fr;
; #pragma unroll
;             for (int bj = 0; bj < 2; ++bj) { const int col = 4 * u.pn + 2 * bj + (wc >> 1), b = col >> 8, ch = col & 255;
;                 const int n2 = 32 * (wc & 1) + 8 * fq;
;                 const unsigned rowo = (unsigned)((((size_t)(b * 64 + k1) * 256 + ch) * 128 + n2) * 2);
;                 int kk = k1; asm volatile("" : "+v"(kk));
;     ...
; #pragma unroll
;                 for (int n = 0; n < 2; ++n) { const f32x4 yr = acc[0][bj][m][n], yi = acc[1][bj][m][n];
; #pragma unroll
;                     for (int i = 0; i < 4; ++i) { const f32x2 cs = TW[(n2 + 4 * n + i) * kk]; pr[n][i] = yr[i] * cs.x + yi[i] * cs.y; pi[n][i] = yi[i] * cs.x - yr[i] * cs.y; } }
;                 u32x4 w; w.x = cvt_pk_bf16(pr[0][0], pr[0][1]); w.y = cvt_pk_bf16(pr[0][2], pr[0][3]); w.z = cvt_pk_bf16(pr[1][0], pr[1][1]); w.w = cvt_pk_bf16(pr[1][2], pr[1][3]);
;                 __builtin_amdgcn_raw_buffer_store_b128(w, rsrc, rowo, 0, 16);
;                 w.x = cvt_pk_bf16(pi[0][0], pi[0][1]); w.y = cvt_pk_bf16(pi[0][2], pi[0][3]); w.z = cvt_pk_bf16(pi[1][0], pi[1][1]); w.w = cvt_pk_bf16(pi[1][2], pi[1][3]);
;                 __builtin_amdgcn_raw_buffer_store_b128(w, rsrc, rowo + 128, 0, 16);
	v_pk_mul_f32 v[162:163], v[162:163], v[148:149]
	s_nop 0
	v_add_f32_e32 v164, v162, v163
	v_mov_b32_e32 v162, v20
	v_mov_b32_e32 v163, v84
	v_pk_mul_f32 v[148:149], v[162:163], v[148:149]
	s_nop 0
	v_sub_f32_e32 v162, v148, v149
	v_mov_b32_e32 v148, v85
	v_mov_b32_e32 v149, v21
	s_waitcnt vmcnt(6)
	v_pk_mul_f32 v[148:149], v[148:149], v[150:151]
	s_nop 0
	v_add_f32_e32 v163, v148, v149
	v_mov_b32_e32 v148, v21
	v_mov_b32_e32 v149, v85
	v_pk_mul_f32 v[148:149], v[148:149], v[150:151]
	s_nop 0
	v_sub_f32_e32 v150, v148, v149
	v_mov_b32_e32 v148, v86
	v_mov_b32_e32 v149, v22
	s_waitcnt vmcnt(5)
	v_pk_mul_f32 v[148:149], v[148:149], v[152:153]
	s_nop 0
	v_add_f32_e32 v151, v148, v149
	v_mov_b32_e32 v148, v22
	v_mov_b32_e32 v149, v86
	v_pk_mul_f32 v[148:149], v[148:149], v[152:153]
	s_nop 0
	v_sub_f32_e32 v152, v148, v149
	v_mov_b32_e32 v148, v87
	v_mov_b32_e32 v149, v23
	s_waitcnt vmcnt(4)
	v_pk_mul_f32 v[148:149], v[148:149], v[154:155]
	s_nop 0
	v_add_f32_e32 v153, v148, v149
	v_mov_b32_e32 v148, v23
	v_mov_b32_e32 v149, v87
	v_pk_mul_f32 v[148:149], v[148:149], v[154:155]
	s_nop 0
	v_sub_f32_e32 v154, v148, v149
	v_mov_b32_e32 v148, v80
	v_mov_b32_e32 v149, v16
	s_waitcnt vmcnt(3)
	v_pk_mul_f32 v[148:149], v[148:149], v[156:157]
	s_nop 0
	v_add_f32_e32 v155, v148, v149
	v_mov_b32_e32 v148, v16
	v_mov_b32_e32 v149, v80
	v_pk_mul_f32 v[148:149], v[148:149], v[156:157]
	s_nop 0
	v_sub_f32_e32 v156, v148, v149
	v_mov_b32_e32 v148, v81
	v_mov_b32_e32 v149, v17
	s_waitcnt vmcnt(2)
	v_pk_mul_f32 v[148:149], v[148:149], v[158:159]
	s_nop 0
	v_add_f32_e32 v157, v148, v149
	v_mov_b32_e32 v148, v17
	v_mov_b32_e32 v149, v81
	v_pk_mul_f32 v[148:149], v[148:149], v[158:159]
	s_nop 0
	v_sub_f32_e32 v158, v148, v149
	v_mov_b32_e32 v148, v82
	v_mov_b32_e32 v149, v18
	s_waitcnt vmcnt(1)
	v_pk_mul_f32 v[148:149], v[148:149], v[160:161]
	s_nop 0
	v_add_f32_e32 v159, v148, v149
	v_mov_b32_e32 v148, v18
	v_mov_b32_e32 v149, v82
	v_pk_mul_f32 v[148:149], v[148:149], v[160:161]
	s_nop 0
	v_sub_f32_e32 v160, v148, v149
	v_mov_b32_e32 v148, v83
	v_mov_b32_e32 v149, v19
	s_waitcnt vmcnt(0)
	v_pk_mul_f32 v[148:149], v[148:149], v[146:147]
	s_nop 0
	v_add_f32_e32 v161, v148, v149
	v_mov_b32_e32 v148, v19
	v_mov_b32_e32 v149, v83
	v_pk_mul_f32 v[146:147], v[148:149], v[146:147]
	s_nop 0
	v_sub_f32_e32 v165, v146, v147
	v_cvt_pk_bf16_f32 v146, v164, v163
	v_cvt_pk_bf16_f32 v147, v151, v153
	v_cvt_pk_bf16_f32 v148, v155, v157
	v_cvt_pk_bf16_f32 v149, v159, v161
	buffer_store_dwordx4 v[146:149], v145, s[8:11], 0 offen sc1
	v_mov_b32_e32 v163, v44
	s_nop 0
	v_cvt_pk_bf16_f32 v146, v162, v150
	v_cvt_pk_bf16_f32 v147, v152, v154
	v_cvt_pk_bf16_f32 v148, v156, v158
	v_cvt_pk_bf16_f32 v149, v160, v165
	buffer_store_dwordx4 v[146:149], v145, s[8:11], 0 offen offset:128 sc1
	v_mov_b32_e32 v145, v142
	v_mov_b32_e32 v162, v108
	v_mul_lo_u32 v146, v145, v140
	v_ashrrev_i32_e32 v147, 31, v146
	v_lshl_add_u64 v[148:149], v[146:147], 3, s[26:27]
	global_load_dwordx2 v[148:149], v[148:149], off
	v_add_u32_e32 v146, v146, v145
	v_ashrrev_i32_e32 v147, 31, v146
	v_lshl_add_u64 v[150:151], v[146:147], 3, s[26:27]
	global_load_dwordx2 v[150:151], v[150:151], off
	v_add_u32_e32 v146, v146, v145
	v_ashrrev_i32_e32 v147, 31, v146
	v_lshl_add_u64 v[152:153], v[146:147], 3, s[26:27]
	global_load_dwordx2 v[152:153], v[152:153], off
	v_add_u32_e32 v146, v146, v145
	v_ashrrev_i32_e32 v147, 31, v146
	v_lshl_add_u64 v[154:155], v[146:147], 3, s[26:27]
	global_load_dwordx2 v[154:155], v[154:155], off
	v_add_u32_e32 v146, v146, v145
	v_ashrrev_i32_e32 v147, 31, v146
	v_lshl_add_u64 v[156:157], v[146:147], 3, s[26:27]
	global_load_dwordx2 v[156:157], v[156:157], off
	v_add_u32_e32 v146, v146, v145
	v_ashrrev_i32_e32 v147, 31, v146
	v_lshl_add_u64 v[158:159], v[146:147], 3, s[26:27]
	global_load_dwordx2 v[158:159], v[158:159], off
	v_add_u32_e32 v146, v146, v145
	v_ashrrev_i32_e32 v147, 31, v146
	v_lshl_add_u64 v[160:161], v[146:147], 3, s[26:27]
	global_load_dwordx2 v[160:161], v[160:161], off
	v_add_u32_e32 v146, v146, v145
	v_ashrrev_i32_e32 v147, 31, v146
	v_lshl_add_u64 v[146:147], v[146:147], 3, s[26:27]
	global_load_dwordx2 v[146:147], v[146:147], off
	v_or_b32_e32 v145, s2, v142
	v_lshl_or_b32 v145, v145, 15, v140
	v_or_b32_e32 v164, s35, v145
	v_lshlrev_b32_e32 v164, 1, v164
	v_or_b32_e32 v145, s3, v145
	v_lshlrev_b32_e32 v145, 1, v145
	s_waitcnt vmcnt(7)
	v_pk_mul_f32 v[162:163], v[162:163], v[148:149]
	s_nop 0
	v_add_f32_e32 v165, v162, v163
	v_mov_b32_e32 v162, v44
	v_mov_b32_e32 v163, v108
	v_pk_mul_f32 v[148:149], v[162:163], v[148:149]
	s_nop 0
	v_sub_f32_e32 v162, v148, v149
	v_mov_b32_e32 v148, v109
	v_mov_b32_e32 v149, v45
	s_waitcnt vmcnt(6)
	v_pk_mul_f32 v[148:149], v[148:149], v[150:151]
	s_nop 0
	v_add_f32_e32 v163, v148, v149
	v_mov_b32_e32 v148, v45
	v_mov_b32_e32 v149, v109
	v_pk_mul_f32 v[148:149], v[148:149], v[150:151]
	s_nop 0
	v_sub_f32_e32 v150, v148, v149
	v_mov_b32_e32 v148, v110
	v_mov_b32_e32 v149, v46
	s_waitcnt vmcnt(5)
	v_pk_mul_f32 v[148:149], v[148:149], v[152:153]
	s_nop 0
	v_add_f32_e32 v151, v148, v149
	v_mov_b32_e32 v148, v46
	v_mov_b32_e32 v149, v110
	v_pk_mul_f32 v[148:149], v[148:149], v[152:153]
	s_nop 0
	v_sub_f32_e32 v152, v148, v149
	v_mov_b32_e32 v148, v111
	v_mov_b32_e32 v149, v47
	s_waitcnt vmcnt(4)
	v_pk_mul_f32 v[148:149], v[148:149], v[154:155]
	s_nop 0
	v_add_f32_e32 v153, v148, v149
	v_mov_b32_e32 v148, v47
	v_mov_b32_e32 v149, v111
	v_pk_mul_f32 v[148:149], v[148:149], v[154:155]
	s_nop 0
	v_sub_f32_e32 v154, v148, v149
	v_mov_b32_e32 v148, v104
	v_mov_b32_e32 v149, v40
	s_waitcnt vmcnt(3)
; __device__ __forceinline__ unsigned cvt_pk_bf16(float lo, float hi) { unsigned r; asm volatile("v_cvt_pk_bf16_f32 %0, %1, %2" : "=v"(r) : "v"(lo), "v"(hi)); return r; }
;     __device__ __forceinline__ void operator()(const f32x4 (&acc)[2][2][4][2], const Unit& u, int wr, int wc, int fr, int fq) const {
;     ...
;         for (int m = 0; m < 4; ++m) { const int k1 = 16 * m + fr;
; #pragma unroll
;             for (int bj = 0; bj < 2; ++bj) { const int col = 4 * u.pn + 2 * bj + (wc >> 1), b = col >> 8, ch = col & 255;
;                 const int n2 = 32 * (wc & 1) + 8 * fq;
;                 const unsigned rowo = (unsigned)((((size_t)(b * 64 + k1) * 256 + ch) * 128 + n2) * 2);
;                 int kk = k1; asm volatile("" : "+v"(kk));
;     ...
; #pragma unroll
;                 for (int n = 0; n < 2; ++n) { const f32x4 yr = acc[0][bj][m][n], yi = acc[1][bj][m][n];
; #pragma unroll
;                     for (int i = 0; i < 4; ++i) { const f32x2 cs = TW[(n2 + 4 * n + i) * kk]; pr[n][i] = yr[i] * cs.x + yi[i] * cs.y; pi[n][i] = yi[i] * cs.x - yr[i] * cs.y; } }
;                 u32x4 w; w.x = cvt_pk_bf16(pr[0][0], pr[0][1]); w.y = cvt_pk_bf16(pr[0][2], pr[0][3]); w.z = cvt_pk_bf16(pr[1][0], pr[1][1]); w.w = cvt_pk_bf16(pr[1][2], pr[1][3]);
;                 __builtin_amdgcn_raw_buffer_store_b128(w, rsrc, rowo, 0, 16);
;                 w.x = cvt_pk_bf16(pi[0][0], pi[0][1]); w.y = cvt_pk_bf16(pi[0][2], pi[0][3]); w.z = cvt_pk_bf16(pi[1][0], pi[1][1]); w.w = cvt_pk_bf16(pi[1][2], pi[1][3]);
;                 __builtin_amdgcn_raw_buffer_store_b128(w, rsrc, rowo + 128, 0, 16);
	v_pk_mul_f32 v[148:149], v[148:149], v[156:157]
	s_nop 0
	v_add_f32_e32 v155, v148, v149
	v_mov_b32_e32 v148, v40
	v_mov_b32_e32 v149, v104
	v_pk_mul_f32 v[148:149], v[148:149], v[156:157]
	s_nop 0
	v_sub_f32_e32 v156, v148, v149
	v_mov_b32_e32 v148, v105
	v_mov_b32_e32 v149, v41
	s_waitcnt vmcnt(2)
	v_pk_mul_f32 v[148:149], v[148:149], v[158:159]
	s_nop 0
	v_add_f32_e32 v157, v148, v149
	v_mov_b32_e32 v148, v41
	v_mov_b32_e32 v149, v105
	v_pk_mul_f32 v[148:149], v[148:149], v[158:159]
	s_nop 0
	v_sub_f32_e32 v158, v148, v149
	v_mov_b32_e32 v148, v106
	v_mov_b32_e32 v149, v42
	s_waitcnt vmcnt(1)
	v_pk_mul_f32 v[148:149], v[148:149], v[160:161]
	s_nop 0
	v_add_f32_e32 v159, v148, v149
	v_mov_b32_e32 v148, v42
	v_mov_b32_e32 v149, v106
	v_pk_mul_f32 v[148:149], v[148:149], v[160:161]
	s_nop 0
	v_sub_f32_e32 v160, v148, v149
	v_mov_b32_e32 v148, v107
	v_mov_b32_e32 v149, v43
	s_waitcnt vmcnt(0)
	v_pk_mul_f32 v[148:149], v[148:149], v[146:147]
	s_nop 0
	v_add_f32_e32 v161, v148, v149
	v_mov_b32_e32 v148, v43
	v_mov_b32_e32 v149, v107
	v_pk_mul_f32 v[146:147], v[148:149], v[146:147]
	s_nop 0
	v_sub_f32_e32 v166, v146, v147
	v_cvt_pk_bf16_f32 v146, v165, v163
	v_cvt_pk_bf16_f32 v147, v151, v153
	v_cvt_pk_bf16_f32 v148, v155, v157
	v_cvt_pk_bf16_f32 v149, v159, v161
	buffer_store_dwordx4 v[146:149], v164, s[8:11], 0 offen sc1
	v_mov_b32_e32 v163, v12
	s_nop 0
	v_cvt_pk_bf16_f32 v146, v162, v150
	v_cvt_pk_bf16_f32 v147, v152, v154
	v_cvt_pk_bf16_f32 v148, v156, v158
	v_cvt_pk_bf16_f32 v149, v160, v166
	buffer_store_dwordx4 v[146:149], v164, s[8:11], 0 offen offset:128 sc1
	v_mov_b32_e32 v162, v142
	s_nop 0
	v_mul_lo_u32 v146, v162, v140
	v_ashrrev_i32_e32 v147, 31, v146
	v_lshl_add_u64 v[148:149], v[146:147], 3, s[26:27]
	global_load_dwordx2 v[148:149], v[148:149], off
	v_add_u32_e32 v146, v146, v162
	v_ashrrev_i32_e32 v147, 31, v146
	v_lshl_add_u64 v[150:151], v[146:147], 3, s[26:27]
	global_load_dwordx2 v[150:151], v[150:151], off
	v_add_u32_e32 v146, v146, v162
	v_ashrrev_i32_e32 v147, 31, v146
	v_lshl_add_u64 v[152:153], v[146:147], 3, s[26:27]
	global_load_dwordx2 v[152:153], v[152:153], off
	v_add_u32_e32 v146, v146, v162
	v_ashrrev_i32_e32 v147, 31, v146
	v_lshl_add_u64 v[154:155], v[146:147], 3, s[26:27]
	global_load_dwordx2 v[154:155], v[154:155], off
	v_add_u32_e32 v146, v146, v162
	v_ashrrev_i32_e32 v147, 31, v146
	v_lshl_add_u64 v[156:157], v[146:147], 3, s[26:27]
	global_load_dwordx2 v[156:157], v[156:157], off
	v_add_u32_e32 v146, v146, v162
	v_ashrrev_i32_e32 v147, 31, v146
	v_lshl_add_u64 v[158:159], v[146:147], 3, s[26:27]
	global_load_dwordx2 v[158:159], v[158:159], off
	v_add_u32_e32 v146, v146, v162
	v_ashrrev_i32_e32 v147, 31, v146
	v_lshl_add_u64 v[160:161], v[146:147], 3, s[26:27]
	global_load_dwordx2 v[160:161], v[160:161], off
	v_add_u32_e32 v146, v146, v162
	v_ashrrev_i32_e32 v147, 31, v146
	v_lshl_add_u64 v[146:147], v[146:147], 3, s[26:27]
	global_load_dwordx2 v[146:147], v[146:147], off
	v_mov_b32_e32 v162, v76
	s_waitcnt vmcnt(7)
	v_pk_mul_f32 v[162:163], v[162:163], v[148:149]
	s_nop 0
	v_add_f32_e32 v164, v162, v163
	v_mov_b32_e32 v162, v12
	v_mov_b32_e32 v163, v76
	v_pk_mul_f32 v[148:149], v[162:163], v[148:149]
	s_nop 0
	v_sub_f32_e32 v162, v148, v149
	v_mov_b32_e32 v148, v77
	v_mov_b32_e32 v149, v13
	s_waitcnt vmcnt(6)
	v_pk_mul_f32 v[148:149], v[148:149], v[150:151]
	s_nop 0
	v_add_f32_e32 v163, v148, v149
	v_mov_b32_e32 v148, v13
	v_mov_b32_e32 v149, v77
	v_pk_mul_f32 v[148:149], v[148:149], v[150:151]
	s_nop 0
	v_sub_f32_e32 v150, v148, v149
	v_mov_b32_e32 v148, v78
	v_mov_b32_e32 v149, v14
	s_waitcnt vmcnt(5)
	v_pk_mul_f32 v[148:149], v[148:149], v[152:153]
	s_nop 0
	v_add_f32_e32 v151, v148, v149
	v_mov_b32_e32 v148, v14
	v_mov_b32_e32 v149, v78
	v_pk_mul_f32 v[148:149], v[148:149], v[152:153]
	s_nop 0
	v_sub_f32_e32 v152, v148, v149
	v_mov_b32_e32 v148, v79
	v_mov_b32_e32 v149, v15
	s_waitcnt vmcnt(4)
	v_pk_mul_f32 v[148:149], v[148:149], v[154:155]
	s_nop 0
	v_add_f32_e32 v153, v148, v149
	v_mov_b32_e32 v148, v15
	v_mov_b32_e32 v149, v79
	v_pk_mul_f32 v[148:149], v[148:149], v[154:155]
	s_nop 0
	v_sub_f32_e32 v154, v148, v149
	v_mov_b32_e32 v148, v72
	v_mov_b32_e32 v149, v8
	s_waitcnt vmcnt(3)
	v_pk_mul_f32 v[148:149], v[148:149], v[156:157]
	s_nop 0
	v_add_f32_e32 v155, v148, v149
	v_mov_b32_e32 v148, v8
	v_mov_b32_e32 v149, v72
	v_pk_mul_f32 v[148:149], v[148:149], v[156:157]
	s_nop 0
	v_sub_f32_e32 v156, v148, v149
	v_mov_b32_e32 v148, v73
	v_mov_b32_e32 v149, v9
	s_waitcnt vmcnt(2)
	v_pk_mul_f32 v[148:149], v[148:149], v[158:159]
	s_nop 0
	v_add_f32_e32 v157, v148, v149
	v_mov_b32_e32 v148, v9
	v_mov_b32_e32 v149, v73
	v_pk_mul_f32 v[148:149], v[148:149], v[158:159]
	s_nop 0
	v_sub_f32_e32 v158, v148, v149
	v_mov_b32_e32 v148, v74
	v_mov_b32_e32 v149, v10
	s_waitcnt vmcnt(1)
	v_pk_mul_f32 v[148:149], v[148:149], v[160:161]
	s_nop 0
	v_add_f32_e32 v159, v148, v149
	v_mov_b32_e32 v148, v10
	v_mov_b32_e32 v149, v74
	v_pk_mul_f32 v[148:149], v[148:149], v[160:161]
	s_nop 0
	v_sub_f32_e32 v160, v148, v149
	v_mov_b32_e32 v148, v75
	v_mov_b32_e32 v149, v11
	s_waitcnt vmcnt(0)
; __device__ __forceinline__ unsigned cvt_pk_bf16(float lo, float hi) { unsigned r; asm volatile("v_cvt_pk_bf16_f32 %0, %1, %2" : "=v"(r) : "v"(lo), "v"(hi)); return r; }
;     __device__ __forceinline__ void operator()(const f32x4 (&acc)[2][2][4][2], const Unit& u, int wr, int wc, int fr, int fq) const {
;     ...
;         for (int m = 0; m < 4; ++m) { const int k1 = 16 * m + fr;
; #pragma unroll
;             for (int bj = 0; bj < 2; ++bj) { const int col = 4 * u.pn + 2 * bj + (wc >> 1), b = col >> 8, ch = col & 255;
;                 const int n2 = 32 * (wc & 1) + 8 * fq;
;                 const unsigned rowo = (unsigned)((((size_t)(b * 64 + k1) * 256 + ch) * 128 + n2) * 2);
;                 int kk = k1; asm volatile("" : "+v"(kk));
;     ...
; #pragma unroll
;                 for (int n = 0; n < 2; ++n) { const f32x4 yr = acc[0][bj][m][n], yi = acc[1][bj][m][n];
; #pragma unroll
;                     for (int i = 0; i < 4; ++i) { const f32x2 cs = TW[(n2 + 4 * n + i) * kk]; pr[n][i] = yr[i] * cs.x + yi[i] * cs.y; pi[n][i] = yi[i] * cs.x - yr[i] * cs.y; } }
;                 u32x4 w; w.x = cvt_pk_bf16(pr[0][0], pr[0][1]); w.y = cvt_pk_bf16(pr[0][2], pr[0][3]); w.z = cvt_pk_bf16(pr[1][0], pr[1][1]); w.w = cvt_pk_bf16(pr[1][2], pr[1][3]);
;                 __builtin_amdgcn_raw_buffer_store_b128(w, rsrc, rowo, 0, 16);
;                 w.x = cvt_pk_bf16(pi[0][0], pi[0][1]); w.y = cvt_pk_bf16(pi[0][2], pi[0][3]); w.z = cvt_pk_bf16(pi[1][0], pi[1][1]); w.w = cvt_pk_bf16(pi[1][2], pi[1][3]);
;                 __builtin_amdgcn_raw_buffer_store_b128(w, rsrc, rowo + 128, 0, 16);
	v_pk_mul_f32 v[148:149], v[148:149], v[146:147]
	s_nop 0
	v_add_f32_e32 v161, v148, v149
	v_mov_b32_e32 v148, v11
	v_mov_b32_e32 v149, v75
	v_pk_mul_f32 v[146:147], v[148:149], v[146:147]
	s_nop 0
	v_sub_f32_e32 v165, v146, v147
	v_cvt_pk_bf16_f32 v146, v164, v163
	v_cvt_pk_bf16_f32 v147, v151, v153
	v_cvt_pk_bf16_f32 v148, v155, v157
	v_cvt_pk_bf16_f32 v149, v159, v161
	buffer_store_dwordx4 v[146:149], v145, s[8:11], 0 offen sc1
	v_mov_b32_e32 v163, v36
	s_nop 0
	v_cvt_pk_bf16_f32 v146, v162, v150
	v_cvt_pk_bf16_f32 v147, v152, v154
	v_cvt_pk_bf16_f32 v148, v156, v158
	v_cvt_pk_bf16_f32 v149, v160, v165
	buffer_store_dwordx4 v[146:149], v145, s[8:11], 0 offen offset:128 sc1
	v_mov_b32_e32 v145, v143
	v_mov_b32_e32 v162, v100
	v_mul_lo_u32 v146, v145, v140
	v_ashrrev_i32_e32 v147, 31, v146
	v_lshl_add_u64 v[148:149], v[146:147], 3, s[26:27]
	global_load_dwordx2 v[148:149], v[148:149], off
	v_add_u32_e32 v146, v146, v145
	v_ashrrev_i32_e32 v147, 31, v146
	v_lshl_add_u64 v[150:151], v[146:147], 3, s[26:27]
	global_load_dwordx2 v[150:151], v[150:151], off
	v_add_u32_e32 v146, v146, v145
	v_ashrrev_i32_e32 v147, 31, v146
	v_lshl_add_u64 v[152:153], v[146:147], 3, s[26:27]
	global_load_dwordx2 v[152:153], v[152:153], off
	v_add_u32_e32 v146, v146, v145
	v_ashrrev_i32_e32 v147, 31, v146
	v_lshl_add_u64 v[154:155], v[146:147], 3, s[26:27]
	global_load_dwordx2 v[154:155], v[154:155], off
	v_add_u32_e32 v146, v146, v145
	v_ashrrev_i32_e32 v147, 31, v146
	v_lshl_add_u64 v[156:157], v[146:147], 3, s[26:27]
	global_load_dwordx2 v[156:157], v[156:157], off
	v_add_u32_e32 v146, v146, v145
	v_ashrrev_i32_e32 v147, 31, v146
	v_lshl_add_u64 v[158:159], v[146:147], 3, s[26:27]
	global_load_dwordx2 v[158:159], v[158:159], off
	v_add_u32_e32 v146, v146, v145
	v_ashrrev_i32_e32 v147, 31, v146
	v_lshl_add_u64 v[160:161], v[146:147], 3, s[26:27]
	global_load_dwordx2 v[160:161], v[160:161], off
	v_add_u32_e32 v146, v146, v145
	v_ashrrev_i32_e32 v147, 31, v146
	v_lshl_add_u64 v[146:147], v[146:147], 3, s[26:27]
	global_load_dwordx2 v[146:147], v[146:147], off
	v_or_b32_e32 v145, s2, v143
	v_lshl_or_b32 v145, v145, 15, v140
	v_or_b32_e32 v164, s35, v145
	v_lshlrev_b32_e32 v164, 1, v164
	v_or_b32_e32 v145, s3, v145
	v_lshlrev_b32_e32 v145, 1, v145
	s_waitcnt vmcnt(7)
	v_pk_mul_f32 v[162:163], v[162:163], v[148:149]
	s_nop 0
	v_add_f32_e32 v165, v162, v163
	v_mov_b32_e32 v162, v36
	v_mov_b32_e32 v163, v100
	v_pk_mul_f32 v[148:149], v[162:163], v[148:149]
	s_nop 0
	v_sub_f32_e32 v162, v148, v149
	v_mov_b32_e32 v148, v101
	v_mov_b32_e32 v149, v37
	s_waitcnt vmcnt(6)
	v_pk_mul_f32 v[148:149], v[148:149], v[150:151]
	s_nop 0
	v_add_f32_e32 v163, v148, v149
	v_mov_b32_e32 v148, v37
	v_mov_b32_e32 v149, v101
	v_pk_mul_f32 v[148:149], v[148:149], v[150:151]
	s_nop 0
	v_sub_f32_e32 v150, v148, v149
	v_mov_b32_e32 v148, v102
	v_mov_b32_e32 v149, v38
	s_waitcnt vmcnt(5)
	v_pk_mul_f32 v[148:149], v[148:149], v[152:153]
	s_nop 0
	v_add_f32_e32 v151, v148, v149
	v_mov_b32_e32 v148, v38
	v_mov_b32_e32 v149, v102
	v_pk_mul_f32 v[148:149], v[148:149], v[152:153]
	s_nop 0
	v_sub_f32_e32 v152, v148, v149
	v_mov_b32_e32 v148, v103
	v_mov_b32_e32 v149, v39
	s_waitcnt vmcnt(4)
	v_pk_mul_f32 v[148:149], v[148:149], v[154:155]
	s_nop 0
	v_add_f32_e32 v153, v148, v149
	v_mov_b32_e32 v148, v39
	v_mov_b32_e32 v149, v103
	v_pk_mul_f32 v[148:149], v[148:149], v[154:155]
	s_nop 0
	v_sub_f32_e32 v154, v148, v149
	v_mov_b32_e32 v148, v96
	v_mov_b32_e32 v149, v32
	s_waitcnt vmcnt(3)
	v_pk_mul_f32 v[148:149], v[148:149], v[156:157]
	s_nop 0
	v_add_f32_e32 v155, v148, v149
	v_mov_b32_e32 v148, v32
	v_mov_b32_e32 v149, v96
	v_pk_mul_f32 v[148:149], v[148:149], v[156:157]
	s_nop 0
	v_sub_f32_e32 v156, v148, v149
	v_mov_b32_e32 v148, v97
	v_mov_b32_e32 v149, v33
	s_waitcnt vmcnt(2)
	v_pk_mul_f32 v[148:149], v[148:149], v[158:159]
	s_nop 0
	v_add_f32_e32 v157, v148, v149
	v_mov_b32_e32 v148, v33
	v_mov_b32_e32 v149, v97
	v_pk_mul_f32 v[148:149], v[148:149], v[158:159]
	s_nop 0
	v_sub_f32_e32 v158, v148, v149
	v_mov_b32_e32 v148, v98
	v_mov_b32_e32 v149, v34
	s_waitcnt vmcnt(1)
	v_pk_mul_f32 v[148:149], v[148:149], v[160:161]
	s_nop 0
	v_add_f32_e32 v159, v148, v149
	v_mov_b32_e32 v148, v34
	v_mov_b32_e32 v149, v98
	v_pk_mul_f32 v[148:149], v[148:149], v[160:161]
	s_nop 0
	v_sub_f32_e32 v160, v148, v149
	v_mov_b32_e32 v148, v99
	v_mov_b32_e32 v149, v35
	s_waitcnt vmcnt(0)
; __device__ __forceinline__ unsigned cvt_pk_bf16(float lo, float hi) { unsigned r; asm volatile("v_cvt_pk_bf16_f32 %0, %1, %2" : "=v"(r) : "v"(lo), "v"(hi)); return r; }
;     __device__ __forceinline__ void operator()(const f32x4 (&acc)[2][2][4][2], const Unit& u, int wr, int wc, int fr, int fq) const {
;     ...
; #pragma unroll
;                 for (int n = 0; n < 2; ++n) { const f32x4 yr = acc[0][bj][m][n], yi = acc[1][bj][m][n];
; #pragma unroll
;                     for (int i = 0; i < 4; ++i) { const f32x2 cs = TW[(n2 + 4 * n + i) * kk]; pr[n][i] = yr[i] * cs.x + yi[i] * cs.y; pi[n][i] = yi[i] * cs.x - yr[i] * cs.y; } }
;                 u32x4 w; w.x = cvt_pk_bf16(pr[0][0], pr[0][1]); w.y = cvt_pk_bf16(pr[0][2], pr[0][3]); w.z = cvt_pk_bf16(pr[1][0], pr[1][1]); w.w = cvt_pk_bf16(pr[1][2], pr[1][3]);
;                 __builtin_amdgcn_raw_buffer_store_b128(w, rsrc, rowo, 0, 16);
;                 w.x = cvt_pk_bf16(pi[0][0], pi[0][1]); w.y = cvt_pk_bf16(pi[0][2], pi[0][3]); w.z = cvt_pk_bf16(pi[1][0], pi[1][1]); w.w = cvt_pk_bf16(pi[1][2], pi[1][3]);
;                 __builtin_amdgcn_raw_buffer_store_b128(w, rsrc, rowo + 128, 0, 16);
;                 asm volatile("" ::: "memory"); } }
	v_pk_mul_f32 v[148:149], v[148:149], v[146:147]
	s_nop 0
	v_add_f32_e32 v161, v148, v149
	v_mov_b32_e32 v148, v35
	v_mov_b32_e32 v149, v99
	v_pk_mul_f32 v[146:147], v[148:149], v[146:147]
	s_nop 0
	v_sub_f32_e32 v166, v146, v147
	v_cvt_pk_bf16_f32 v146, v165, v163
	v_cvt_pk_bf16_f32 v147, v151, v153
	v_cvt_pk_bf16_f32 v148, v155, v157
	v_cvt_pk_bf16_f32 v149, v159, v161
	buffer_store_dwordx4 v[146:149], v164, s[8:11], 0 offen sc1
	v_mov_b32_e32 v163, v4
	s_nop 0
	v_cvt_pk_bf16_f32 v146, v162, v150
	v_cvt_pk_bf16_f32 v147, v152, v154
	v_cvt_pk_bf16_f32 v148, v156, v158
	v_cvt_pk_bf16_f32 v149, v160, v166
	buffer_store_dwordx4 v[146:149], v164, s[8:11], 0 offen offset:128 sc1
	v_mov_b32_e32 v162, v143
	s_nop 0
	v_mul_lo_u32 v146, v162, v140
	v_ashrrev_i32_e32 v147, 31, v146
	v_lshl_add_u64 v[148:149], v[146:147], 3, s[26:27]
	global_load_dwordx2 v[148:149], v[148:149], off
	v_add_u32_e32 v146, v146, v162
	v_ashrrev_i32_e32 v147, 31, v146
	v_lshl_add_u64 v[150:151], v[146:147], 3, s[26:27]
	global_load_dwordx2 v[150:151], v[150:151], off
	v_add_u32_e32 v146, v146, v162
	v_ashrrev_i32_e32 v147, 31, v146
	v_lshl_add_u64 v[152:153], v[146:147], 3, s[26:27]
	global_load_dwordx2 v[152:153], v[152:153], off
	v_add_u32_e32 v146, v146, v162
	v_ashrrev_i32_e32 v147, 31, v146
	v_lshl_add_u64 v[154:155], v[146:147], 3, s[26:27]
	global_load_dwordx2 v[154:155], v[154:155], off
	v_add_u32_e32 v146, v146, v162
	v_ashrrev_i32_e32 v147, 31, v146
	v_lshl_add_u64 v[156:157], v[146:147], 3, s[26:27]
	global_load_dwordx2 v[156:157], v[156:157], off
	v_add_u32_e32 v146, v146, v162
	v_ashrrev_i32_e32 v147, 31, v146
	v_lshl_add_u64 v[158:159], v[146:147], 3, s[26:27]
	global_load_dwordx2 v[158:159], v[158:159], off
	v_add_u32_e32 v146, v146, v162
	v_ashrrev_i32_e32 v147, 31, v146
	v_lshl_add_u64 v[160:161], v[146:147], 3, s[26:27]
	global_load_dwordx2 v[160:161], v[160:161], off
	v_add_u32_e32 v146, v146, v162
	v_ashrrev_i32_e32 v147, 31, v146
	v_lshl_add_u64 v[146:147], v[146:147], 3, s[26:27]
	global_load_dwordx2 v[146:147], v[146:147], off
	v_mov_b32_e32 v162, v68
	s_waitcnt vmcnt(7)
	v_pk_mul_f32 v[162:163], v[162:163], v[148:149]
	s_nop 0
	v_add_f32_e32 v164, v162, v163
	v_mov_b32_e32 v162, v4
	v_mov_b32_e32 v163, v68
	v_pk_mul_f32 v[148:149], v[162:163], v[148:149]
	s_nop 0
	v_sub_f32_e32 v162, v148, v149
	v_mov_b32_e32 v148, v69
	v_mov_b32_e32 v149, v5
	s_waitcnt vmcnt(6)
	v_pk_mul_f32 v[148:149], v[148:149], v[150:151]
	s_nop 0
	v_add_f32_e32 v163, v148, v149
	v_mov_b32_e32 v148, v5
	v_mov_b32_e32 v149, v69
	v_pk_mul_f32 v[148:149], v[148:149], v[150:151]
	s_nop 0
	v_sub_f32_e32 v150, v148, v149
	v_mov_b32_e32 v148, v70
	v_mov_b32_e32 v149, v6
	s_waitcnt vmcnt(5)
	v_pk_mul_f32 v[148:149], v[148:149], v[152:153]
	s_nop 0
	v_add_f32_e32 v151, v148, v149
	v_mov_b32_e32 v148, v6
	v_mov_b32_e32 v149, v70
	v_pk_mul_f32 v[148:149], v[148:149], v[152:153]
	s_nop 0
	v_sub_f32_e32 v152, v148, v149
	v_mov_b32_e32 v148, v71
	v_mov_b32_e32 v149, v7
	s_waitcnt vmcnt(4)
	v_pk_mul_f32 v[148:149], v[148:149], v[154:155]
	s_nop 0
	v_add_f32_e32 v153, v148, v149
	v_mov_b32_e32 v148, v7
	v_mov_b32_e32 v149, v71
	v_pk_mul_f32 v[148:149], v[148:149], v[154:155]
	s_nop 0
	v_sub_f32_e32 v154, v148, v149
	v_mov_b32_e32 v148, v64
	v_mov_b32_e32 v149, v0
	s_waitcnt vmcnt(3)
	v_pk_mul_f32 v[148:149], v[148:149], v[156:157]
	s_nop 0
	v_add_f32_e32 v155, v148, v149
	v_mov_b32_e32 v148, v0
	v_mov_b32_e32 v149, v64
	v_pk_mul_f32 v[148:149], v[148:149], v[156:157]
	s_nop 0
	v_sub_f32_e32 v156, v148, v149
	v_mov_b32_e32 v148, v65
	v_mov_b32_e32 v149, v1
	s_waitcnt vmcnt(2)
	v_pk_mul_f32 v[148:149], v[148:149], v[158:159]
	s_nop 0
	v_add_f32_e32 v157, v148, v149
	v_mov_b32_e32 v148, v1
	v_mov_b32_e32 v149, v65
	v_pk_mul_f32 v[148:149], v[148:149], v[158:159]
	s_nop 0
	v_sub_f32_e32 v158, v148, v149
	v_mov_b32_e32 v148, v66
	v_mov_b32_e32 v149, v2
	s_waitcnt vmcnt(1)
	v_pk_mul_f32 v[148:149], v[148:149], v[160:161]
	s_nop 0
	v_add_f32_e32 v159, v148, v149
	v_mov_b32_e32 v148, v2
	v_mov_b32_e32 v149, v66
	v_pk_mul_f32 v[148:149], v[148:149], v[160:161]
	s_nop 0
	v_sub_f32_e32 v160, v148, v149
	v_mov_b32_e32 v148, v67
	v_mov_b32_e32 v149, v3
	s_waitcnt vmcnt(0)
	v_pk_mul_f32 v[148:149], v[148:149], v[146:147]
	s_nop 0
	v_add_f32_e32 v161, v148, v149
	v_mov_b32_e32 v148, v3
	v_mov_b32_e32 v149, v67
	v_pk_mul_f32 v[146:147], v[148:149], v[146:147]
	s_nop 0
	v_sub_f32_e32 v165, v146, v147
	v_cvt_pk_bf16_f32 v146, v164, v163
	v_cvt_pk_bf16_f32 v147, v151, v153
	v_cvt_pk_bf16_f32 v148, v155, v157
	v_cvt_pk_bf16_f32 v149, v159, v161
	buffer_store_dwordx4 v[146:149], v145, s[8:11], 0 offen sc1
	s_nop 1
	v_cvt_pk_bf16_f32 v146, v162, v150
	v_cvt_pk_bf16_f32 v147, v152, v154
	v_cvt_pk_bf16_f32 v148, v156, v158
	v_cvt_pk_bf16_f32 v149, v160, v165
	buffer_store_dwordx4 v[146:149], v145, s[8:11], 0 offen offset:128 sc1
	s_andn2_b64 vcc, exec, s[40:41]
	s_cbranch_vccnz .LBB0_820
	s_branch .LBB0_829

; #define PG8_STAGE(bufoff, gbase, voff) do { _Pragma("unroll") for (int _i = 0; _i < 2; ++_i) \
;         __builtin_amdgcn_global_load_lds((const unsigned*)((const char*)(gbase) + (voff)[_i]), (LAS unsigned*)(lds + (bufoff) + ldsw + _i * 8192), 16, 0, 0); } while (0)
; #define PG8_STAGEB(bufoff, gbase, perm) do { _Pragma("unroll") for (int _i = 0; _i < 2; ++_i) \
;         __builtin_amdgcn_global_load_lds((const unsigned*)((const char*)(gbase) + ((BSEL && (perm)) ? voffBp[_i] : voffB[_i])), (LAS unsigned*)(lds + (bufoff) + ldsw + _i * 8192), 16, 0, 0); } while (0)
; #define PG8_LDA(dst, b, h) do { _Pragma("unroll") for (int m = 0; m < 4; ++m) _Pragma("unroll") for (int k = 0; k < 2; ++k) dst[m][k] = *(const LAS bf16x8*)(lds + PG8_SA(b, h) + aoff + m * 2048 + k * 1024); } while (0)
; #define PG8_LDB(dst, b, h) do { _Pragma("unroll") for (int n = 0; n < 2; ++n) _Pragma("unroll") for (int k = 0; k < 2; ++k) dst[n][k] = *(const LAS bf16x8*)(lds + PG8_SB(b, h) + boff + n * 2048 + k * 1024); } while (0)
; template <class Epi, bool BSEL = false>
; __device__ __forceinline__ void gemm_phase(LAS unsigned char* lds, const Gemm g, const Order& S, const Epi& E, const int tid) {
;     ...
;         for (int t = 0; t < nt; t += 2) {
;             const bool last = (t == nt - 2);
;             const char* a1 = cA + (size_t)(t + 1) * kstep;
;             const char* a2 = last ? nA : cA + (size_t)(t + 2) * kstep; const char* b2 = last ? nB : cB + (size_t)(t + 2) * kstep;
;             const char* a3 = a2 + kstep; const char* b3 = b2 + kstep;
;             const bool p2 = last ? nP : cP; const size_t h2 = last ? nhB : chB;
;             PG8_LDB(B0, 0, 0); PG8_LDB(B1, 0, 1); PG8_SCHED; PG8_LDA(At, 0, 0); PG8_STAGE(PG8_SA(1, 1), a1 + hstepA, voffA);
;             PG8_WAIT_V(8); PG8_WAIT_L(0); PG8_BAR; PG8_MMA(0, 0, At, B0); PG8_MMA(0, 1, At, B1); PG8_BAR; PG8_SCHED;
;             PG8_LDA(At, 0, 1); PG8_STAGEB(PG8_SB(0, 0), b2, p2); PG8_STAGEB(PG8_SB(0, 1), b2 + h2, p2); PG8_STAGE(PG8_SA(0, 0), a2, voffA);
;             PG8_WAIT_V(8); PG8_WAIT_L(0); PG8_BAR; PG8_MMA(1, 0, At, B0); PG8_MMA(1, 1, At, B1); PG8_BAR; PG8_SCHED;
;             PG8_LDB(B0, 1, 0); PG8_LDB(B1, 1, 1); PG8_SCHED; PG8_LDA(At, 1, 0); PG8_STAGE(PG8_SA(0, 1), a2 + hstepA, voffA);
;             PG8_WAIT_V(8); PG8_WAIT_L(0); PG8_BAR; PG8_MMA(0, 0, At, B0); PG8_MMA(0, 1, At, B1); PG8_BAR; PG8_SCHED;
.LBB0_998:
	s_xor_b64 s[2:3], s[34:35], -1
	v_add_u32_e32 v79, s44, v77
	s_and_b64 s[36:37], s[34:35], exec
	ds_read_b128 v[80:83], v79
	ds_read_b128 v[84:87], v79 offset:1024
	ds_read_b128 v[88:91], v79 offset:2048
	ds_read_b128 v[92:95], v79 offset:3072
	v_add_u32_e32 v79, s45, v77
	s_cselect_b32 s41, s1, s1
	s_cselect_b32 s40, s0, s0
	s_add_u32 s48, s0, 0x8080
	ds_read_b128 v[96:99], v79
	ds_read_b128 v[100:103], v79 offset:1024
	ds_read_b128 v[104:107], v79 offset:2048
	ds_read_b128 v[108:111], v79 offset:3072
	s_addc_u32 s49, s1, 0
	s_add_u32 s38, s40, 0x8000
	s_addc_u32 s39, s41, 0
	s_and_b64 s[36:37], s[34:35], exec
	s_cselect_b32 s36, s30, s4
	s_cselect_b32 s37, s31, s5
	s_add_u32 s52, s36, 0x8000
	s_addc_u32 s53, s37, 0
	v_lshl_add_u64 v[144:145], s[48:49], 0, v[64:65]
	s_add_i32 m0, s13, 0xc000
	ds_read_b128 v[112:115], v78
	ds_read_b128 v[116:119], v78 offset:1024
	ds_read_b128 v[120:123], v78 offset:2048
	ds_read_b128 v[124:127], v78 offset:3072
	ds_read_b128 v[128:131], v78 offset:4096
	ds_read_b128 v[132:135], v78 offset:5120
	ds_read_b128 v[136:139], v78 offset:6144
	ds_read_b128 v[140:143], v78 offset:7168
	global_load_lds_dwordx4 v[144:145], off
	v_lshl_add_u64 v[144:145], s[48:49], 0, v[68:69]
	s_add_i32 m0, s13, 0xe000
	s_nop 0
	global_load_lds_dwordx4 v[144:145], off
	s_waitcnt vmcnt(8)
	s_waitcnt lgkmcnt(0)
	s_setprio 1
	s_barrier
	v_mfma_f32_16x16x32_bf16 v[60:63], v[80:83], v[112:115], v[60:63]
	v_mfma_f32_16x16x32_bf16 v[56:59], v[88:91], v[112:115], v[56:59]
	v_mfma_f32_16x16x32_bf16 v[52:55], v[80:83], v[120:123], v[52:55]
	v_mfma_f32_16x16x32_bf16 v[48:51], v[88:91], v[120:123], v[48:51]
	v_mfma_f32_16x16x32_bf16 v[44:47], v[80:83], v[128:131], v[44:47]
	v_mfma_f32_16x16x32_bf16 v[40:43], v[88:91], v[128:131], v[40:43]
	v_mfma_f32_16x16x32_bf16 v[36:39], v[80:83], v[136:139], v[36:39]
	v_mfma_f32_16x16x32_bf16 v[32:35], v[88:91], v[136:139], v[32:35]
	v_mfma_f32_16x16x32_bf16 v[60:63], v[84:87], v[116:119], v[60:63]
	v_mfma_f32_16x16x32_bf16 v[56:59], v[92:95], v[116:119], v[56:59]
	v_mfma_f32_16x16x32_bf16 v[52:55], v[84:87], v[124:127], v[52:55]
	v_mfma_f32_16x16x32_bf16 v[48:51], v[92:95], v[124:127], v[48:51]
	v_mfma_f32_16x16x32_bf16 v[44:47], v[84:87], v[132:135], v[44:47]
	v_mfma_f32_16x16x32_bf16 v[40:43], v[92:95], v[132:135], v[40:43]
	v_mfma_f32_16x16x32_bf16 v[36:39], v[84:87], v[140:143], v[36:39]
	v_mfma_f32_16x16x32_bf16 v[32:35], v[92:95], v[140:143], v[32:35]
	v_mfma_f32_16x16x32_bf16 v[28:31], v[96:99], v[112:115], v[28:31]
	v_mfma_f32_16x16x32_bf16 v[24:27], v[104:107], v[112:115], v[24:27]
	v_mfma_f32_16x16x32_bf16 v[20:23], v[96:99], v[120:123], v[20:23]
	v_mfma_f32_16x16x32_bf16 v[16:19], v[104:107], v[120:123], v[16:19]
	v_mfma_f32_16x16x32_bf16 v[12:15], v[96:99], v[128:131], v[12:15]
	v_mfma_f32_16x16x32_bf16 v[8:11], v[104:107], v[128:131], v[8:11]
	v_mfma_f32_16x16x32_bf16 v[4:7], v[96:99], v[136:139], v[4:7]
	v_mfma_f32_16x16x32_bf16 v[0:3], v[104:107], v[136:139], v[0:3]
	v_mfma_f32_16x16x32_bf16 v[28:31], v[100:103], v[116:119], v[28:31]
	v_mfma_f32_16x16x32_bf16 v[24:27], v[108:111], v[116:119], v[24:27]
	v_mfma_f32_16x16x32_bf16 v[20:23], v[100:103], v[124:127], v[20:23]
	v_mfma_f32_16x16x32_bf16 v[16:19], v[108:111], v[124:127], v[16:19]
	v_mfma_f32_16x16x32_bf16 v[12:15], v[100:103], v[132:135], v[12:15]
	v_mfma_f32_16x16x32_bf16 v[8:11], v[108:111], v[132:135], v[8:11]
	v_mfma_f32_16x16x32_bf16 v[4:7], v[100:103], v[140:143], v[4:7]
	v_mfma_f32_16x16x32_bf16 v[0:3], v[108:111], v[140:143], v[0:3]
	s_barrier
	s_setprio 0
	s_add_i32 s29, s44, s12
	v_lshl_add_u64 v[144:145], s[36:37], 0, v[66:67]
	s_mov_b32 m0, s29
	v_lshl_add_u64 v[146:147], s[36:37], 0, v[70:71]
	global_load_lds_dwordx4 v[144:145], off
	s_add_i32 m0, s29, 0x2000
	s_add_i32 s29, s45, s12
	global_load_lds_dwordx4 v[146:147], off
	v_lshl_add_u64 v[80:81], s[52:53], 0, v[66:67]
	s_mov_b32 m0, s29
	v_lshl_add_u64 v[148:149], s[40:41], 0, v[64:65]
	global_load_lds_dwordx4 v[80:81], off
	v_lshl_add_u64 v[80:81], s[52:53], 0, v[70:71]
	s_add_i32 m0, s29, 0x2000
	v_lshl_add_u64 v[150:151], s[40:41], 0, v[68:69]
	global_load_lds_dwordx4 v[80:81], off
	s_mov_b32 m0, s13
	s_nop 0
	global_load_lds_dwordx4 v[148:149], off
	s_mov_b32 m0, s14
	s_nop 0
	global_load_lds_dwordx4 v[150:151], off
	s_waitcnt vmcnt(8)
	s_waitcnt lgkmcnt(0)
	s_barrier
	s_setprio 1
	s_setprio 0
	s_setprio 1
	s_setprio 0
	s_barrier
	s_add_i32 s29, 0, 0x18000
	v_add_u32_e32 v79, s29, v77
	s_add_i32 s40, 0, 0x1c000
	ds_read_b128 v[80:83], v79
	ds_read_b128 v[84:87], v79 offset:1024
	ds_read_b128 v[88:91], v79 offset:2048
	ds_read_b128 v[92:95], v79 offset:3072
	v_add_u32_e32 v79, s40, v77
	ds_read_b128 v[96:99], v79
	ds_read_b128 v[100:103], v79 offset:1024
	ds_read_b128 v[104:107], v79 offset:2048
	ds_read_b128 v[108:111], v79 offset:3072
	s_mov_b32 m0, s15
	v_lshl_add_u64 v[152:153], s[38:39], 0, v[64:65]
	ds_read_b128 v[112:115], v78 offset:32768
	ds_read_b128 v[116:119], v78 offset:33792
	ds_read_b128 v[120:123], v78 offset:34816
	ds_read_b128 v[124:127], v78 offset:35840
	ds_read_b128 v[128:131], v78 offset:36864
	ds_read_b128 v[132:135], v78 offset:37888
	ds_read_b128 v[136:139], v78 offset:38912
	ds_read_b128 v[140:143], v78 offset:39936
	global_load_lds_dwordx4 v[152:153], off
	v_lshl_add_u64 v[152:153], s[38:39], 0, v[68:69]
	s_mov_b32 m0, s20
	s_nop 0
	global_load_lds_dwordx4 v[152:153], off
	s_waitcnt vmcnt(8)
	s_waitcnt lgkmcnt(0)
	s_setprio 1
	s_barrier
; #define PG8_STAGE(bufoff, gbase, voff) do { _Pragma("unroll") for (int _i = 0; _i < 2; ++_i) \
;         __builtin_amdgcn_global_load_lds((const unsigned*)((const char*)(gbase) + (voff)[_i]), (LAS unsigned*)(lds + (bufoff) + ldsw + _i * 8192), 16, 0, 0); } while (0)
; #define PG8_STAGEB(bufoff, gbase, perm) do { _Pragma("unroll") for (int _i = 0; _i < 2; ++_i) \
;         __builtin_amdgcn_global_load_lds((const unsigned*)((const char*)(gbase) + ((BSEL && (perm)) ? voffBp[_i] : voffB[_i])), (LAS unsigned*)(lds + (bufoff) + ldsw + _i * 8192), 16, 0, 0); } while (0)
; #define PG8_LDA(dst, b, h) do { _Pragma("unroll") for (int m = 0; m < 4; ++m) _Pragma("unroll") for (int k = 0; k < 2; ++k) dst[m][k] = *(const LAS bf16x8*)(lds + PG8_SA(b, h) + aoff + m * 2048 + k * 1024); } while (0)
; #define PG8_MMA(ai, bj, At, Bt) do { __builtin_amdgcn_s_setprio(1); _Pragma("unroll") for (int m = 0; m < 4; ++m) _Pragma("unroll") for (int n = 0; n < 2; ++n) _Pragma("unroll") for (int k = 0; k < 2; ++k) \
;         acc[ai][bj][m][n] = __builtin_amdgcn_mfma_f32_16x16x32_bf16(Bt[n][k], At[m][k], acc[ai][bj][m][n], 0, 0, 0); __builtin_amdgcn_s_setprio(0); } while (0)
; #define PG8_WAIT_V(n) asm volatile("s_waitcnt vmcnt(" #n ")" ::: "memory")
; #define PG8_WAIT_L(n) asm volatile("s_waitcnt lgkmcnt(" #n ")" ::: "memory")
; #define PG8_BAR __builtin_amdgcn_s_barrier()
; template <class Epi, bool BSEL = false>
; __device__ __forceinline__ void gemm_phase(LAS unsigned char* lds, const Gemm g, const Order& S, const Epi& E, const int tid) {
;     ...
;             PG8_LDA(At, 1, 1); PG8_STAGEB(PG8_SB(1, 0), b3, p2); PG8_STAGEB(PG8_SB(1, 1), b3 + h2, p2); PG8_STAGE(PG8_SA(1, 0), a3, voffA);
;             PG8_WAIT_V(8); PG8_WAIT_L(0); PG8_BAR; PG8_MMA(1, 0, At, B0); PG8_MMA(1, 1, At, B1); PG8_BAR; PG8_SCHED;
;         }
;         if constexpr (ALIGN_EPI) { if (wr == 0) PG8_BAR; }
;         if constexpr (!Epi::AFTER_DRAIN) E(acc, cur, wr, wc, fr, fq);
;         if (!has_next) break;
;     __device__ __forceinline__ void operator()(const f32x4 (&acc)[2][2][4][2], const Unit& u, int wr, int wc, int fr, int fq) const {
;         if (wr != 0) return;
;         const float sc = 1.0f / 512.0f; const int b = u.pn >> 6, k1 = u.pn & 63;
; #pragma unroll
;         for (int m = 0; m < 4; ++m) { const int k2 = 16 * m + fr; bf16_t* rowp = AO + (size_t)(b * SEQ + 64 * k2 + k1) * DM + DQK + wc * 32 + 8 * fq;
	v_mfma_f32_16x16x32_bf16 v[60:63], v[80:83], v[112:115], v[60:63]
	v_mfma_f32_16x16x32_bf16 v[56:59], v[88:91], v[112:115], v[56:59]
	v_mfma_f32_16x16x32_bf16 v[52:55], v[80:83], v[120:123], v[52:55]
	v_mfma_f32_16x16x32_bf16 v[48:51], v[88:91], v[120:123], v[48:51]
	v_mfma_f32_16x16x32_bf16 v[44:47], v[80:83], v[128:131], v[44:47]
	v_mfma_f32_16x16x32_bf16 v[40:43], v[88:91], v[128:131], v[40:43]
	v_mfma_f32_16x16x32_bf16 v[36:39], v[80:83], v[136:139], v[36:39]
	v_mfma_f32_16x16x32_bf16 v[32:35], v[88:91], v[136:139], v[32:35]
	v_mfma_f32_16x16x32_bf16 v[60:63], v[84:87], v[116:119], v[60:63]
	v_mfma_f32_16x16x32_bf16 v[56:59], v[92:95], v[116:119], v[56:59]
	v_mfma_f32_16x16x32_bf16 v[52:55], v[84:87], v[124:127], v[52:55]
	v_mfma_f32_16x16x32_bf16 v[48:51], v[92:95], v[124:127], v[48:51]
	v_mfma_f32_16x16x32_bf16 v[44:47], v[84:87], v[132:135], v[44:47]
	v_mfma_f32_16x16x32_bf16 v[40:43], v[92:95], v[132:135], v[40:43]
	v_mfma_f32_16x16x32_bf16 v[36:39], v[84:87], v[140:143], v[36:39]
	v_mfma_f32_16x16x32_bf16 v[32:35], v[92:95], v[140:143], v[32:35]
	v_mfma_f32_16x16x32_bf16 v[28:31], v[96:99], v[112:115], v[28:31]
	v_mfma_f32_16x16x32_bf16 v[24:27], v[104:107], v[112:115], v[24:27]
	v_mfma_f32_16x16x32_bf16 v[20:23], v[96:99], v[120:123], v[20:23]
	v_mfma_f32_16x16x32_bf16 v[16:19], v[104:107], v[120:123], v[16:19]
	v_mfma_f32_16x16x32_bf16 v[12:15], v[96:99], v[128:131], v[12:15]
	v_mfma_f32_16x16x32_bf16 v[8:11], v[104:107], v[128:131], v[8:11]
	v_mfma_f32_16x16x32_bf16 v[4:7], v[96:99], v[136:139], v[4:7]
	v_mfma_f32_16x16x32_bf16 v[0:3], v[104:107], v[136:139], v[0:3]
	v_mfma_f32_16x16x32_bf16 v[28:31], v[100:103], v[116:119], v[28:31]
	v_mfma_f32_16x16x32_bf16 v[24:27], v[108:111], v[116:119], v[24:27]
	v_mfma_f32_16x16x32_bf16 v[20:23], v[100:103], v[124:127], v[20:23]
	v_mfma_f32_16x16x32_bf16 v[16:19], v[108:111], v[124:127], v[16:19]
	v_mfma_f32_16x16x32_bf16 v[12:15], v[100:103], v[132:135], v[12:15]
	v_mfma_f32_16x16x32_bf16 v[8:11], v[108:111], v[132:135], v[8:11]
	v_mfma_f32_16x16x32_bf16 v[4:7], v[100:103], v[140:143], v[4:7]
	v_mfma_f32_16x16x32_bf16 v[0:3], v[108:111], v[140:143], v[0:3]
	s_barrier
	s_setprio 0
	s_add_i32 s29, s29, s12
	v_lshl_add_u64 v[80:81], v[144:145], 0, s[10:11]
	s_mov_b32 m0, s29
	s_nop 0
	global_load_lds_dwordx4 v[80:81], off
	s_add_i32 m0, s29, 0x2000
	s_add_u32 s36, s36, 0x8080
	v_lshl_add_u64 v[80:81], v[146:147], 0, s[10:11]
	s_addc_u32 s37, s37, 0
	s_add_i32 s29, s40, s12
	global_load_lds_dwordx4 v[80:81], off
	v_lshl_add_u64 v[80:81], s[36:37], 0, v[66:67]
	s_mov_b32 m0, s29
	s_nop 0
	global_load_lds_dwordx4 v[80:81], off
	v_lshl_add_u64 v[80:81], s[36:37], 0, v[70:71]
	s_add_i32 m0, s29, 0x2000
	s_nop 0
	global_load_lds_dwordx4 v[80:81], off
	v_lshl_add_u64 v[80:81], v[148:149], 0, s[10:11]
	s_mov_b32 m0, s27
	s_nop 0
	global_load_lds_dwordx4 v[80:81], off
	v_lshl_add_u64 v[80:81], v[150:151], 0, s[10:11]
	s_mov_b32 m0, s42
	s_nop 0
	global_load_lds_dwordx4 v[80:81], off
	s_waitcnt vmcnt(8)
	s_waitcnt lgkmcnt(0)
	s_barrier
	s_setprio 1
	s_setprio 0
	s_setprio 1
	s_setprio 0
	s_barrier
	s_andn2_b64 vcc, exec, s[24:25]
	s_cbranch_vccnz .LBB0_1000
	s_and_b32 s36, s21, 0x3ffffc0
	s_and_b32 s29, s21, 63
	v_or_b32_e32 v79, s36, v76
	v_lshl_or_b32 v84, v79, 6, s29
	v_ashrrev_i32_e32 v85, 31, v84
	v_lshlrev_b64 v[80:81], 11, v[84:85]
	v_lshl_add_u64 v[86:87], v[72:73], 0, v[80:81]
	v_pk_mul_f32 v[80:81], v[60:61], s[26:27] op_sel_hi:[1,0]
	s_barrier
; __device__ __forceinline__ unsigned cvt_pk_bf16(float lo, float hi) { unsigned r; asm volatile("v_cvt_pk_bf16_f32 %0, %1, %2" : "=v"(r) : "v"(lo), "v"(hi)); return r; }
;     __device__ __forceinline__ void operator()(const f32x4 (&acc)[2][2][4][2], const Unit& u, int wr, int wc, int fr, int fq) const {
;     ...
;         const float sc = 1.0f / 512.0f; const int b = u.pn >> 6, k1 = u.pn & 63;
; #pragma unroll
;         for (int m = 0; m < 4; ++m) { const int k2 = 16 * m + fr; bf16_t* rowp = AO + (size_t)(b * SEQ + 64 * k2 + k1) * DM + DQK + wc * 32 + 8 * fq;
; #pragma unroll
;             for (int bj = 0; bj < 2; ++bj) { const f32x4 v0 = acc[0][bj][m][0] * sc, v1 = acc[0][bj][m][1] * sc;
;                 u32x4 w; w.x = cvt_pk_bf16(v0[0], v0[1]); w.y = cvt_pk_bf16(v0[2], v0[3]); w.z = cvt_pk_bf16(v1[0], v1[1]); w.w = cvt_pk_bf16(v1[2], v1[3]);
;                 *(u32x4*)(rowp + bj * HALF) = w; } }
	v_pk_mul_f32 v[82:83], v[62:63], s[26:27] op_sel_hi:[1,0]
	v_cvt_pk_bf16_f32 v80, v80, v81
	v_pk_mul_f32 v[88:89], v[58:59], s[26:27] op_sel_hi:[1,0]
	v_cvt_pk_bf16_f32 v81, v82, v83
	v_pk_mul_f32 v[90:91], v[56:57], s[26:27] op_sel_hi:[1,0]
	s_nop 0
	v_cvt_pk_bf16_f32 v82, v90, v91
	v_cvt_pk_bf16_f32 v83, v88, v89
	global_store_dwordx4 v[86:87], v[80:83], off offset:1536
	v_pk_mul_f32 v[88:89], v[26:27], s[26:27] op_sel_hi:[1,0]
	v_pk_mul_f32 v[90:91], v[24:25], s[26:27] op_sel_hi:[1,0]
	v_pk_mul_f32 v[80:81], v[28:29], s[26:27] op_sel_hi:[1,0]
	v_pk_mul_f32 v[82:83], v[30:31], s[26:27] op_sel_hi:[1,0]
	v_cvt_pk_bf16_f32 v80, v80, v81
	s_nop 0
	v_cvt_pk_bf16_f32 v81, v82, v83
	v_cvt_pk_bf16_f32 v82, v90, v91
	v_cvt_pk_bf16_f32 v83, v88, v89
	global_store_dwordx4 v[86:87], v[80:83], off offset:1792
	v_pk_mul_f32 v[88:89], v[50:51], s[26:27] op_sel_hi:[1,0]
	v_pk_mul_f32 v[90:91], v[48:49], s[26:27] op_sel_hi:[1,0]
	v_or_b32_e32 v80, 0x400, v84
	v_ashrrev_i32_e32 v81, 31, v80
	v_lshlrev_b64 v[80:81], 11, v[80:81]
	v_lshl_add_u64 v[86:87], v[72:73], 0, v[80:81]
	v_pk_mul_f32 v[80:81], v[52:53], s[26:27] op_sel_hi:[1,0]
	v_pk_mul_f32 v[82:83], v[54:55], s[26:27] op_sel_hi:[1,0]
	v_cvt_pk_bf16_f32 v80, v80, v81
	s_nop 0
	v_cvt_pk_bf16_f32 v81, v82, v83
	v_cvt_pk_bf16_f32 v82, v90, v91
	v_cvt_pk_bf16_f32 v83, v88, v89
	global_store_dwordx4 v[86:87], v[80:83], off offset:1536
	v_pk_mul_f32 v[88:89], v[18:19], s[26:27] op_sel_hi:[1,0]
	v_pk_mul_f32 v[90:91], v[16:17], s[26:27] op_sel_hi:[1,0]
	v_pk_mul_f32 v[80:81], v[20:21], s[26:27] op_sel_hi:[1,0]
	v_pk_mul_f32 v[82:83], v[22:23], s[26:27] op_sel_hi:[1,0]
	v_cvt_pk_bf16_f32 v80, v80, v81
	s_nop 0
	v_cvt_pk_bf16_f32 v81, v82, v83
	v_cvt_pk_bf16_f32 v82, v90, v91
	v_cvt_pk_bf16_f32 v83, v88, v89
	global_store_dwordx4 v[86:87], v[80:83], off offset:1792
	v_pk_mul_f32 v[88:89], v[42:43], s[26:27] op_sel_hi:[1,0]
	v_pk_mul_f32 v[90:91], v[40:41], s[26:27] op_sel_hi:[1,0]
	v_or_b32_e32 v80, 0x800, v84
	v_ashrrev_i32_e32 v81, 31, v80
	v_lshlrev_b64 v[80:81], 11, v[80:81]
	v_lshl_add_u64 v[86:87], v[72:73], 0, v[80:81]
	v_pk_mul_f32 v[80:81], v[44:45], s[26:27] op_sel_hi:[1,0]
	v_pk_mul_f32 v[82:83], v[46:47], s[26:27] op_sel_hi:[1,0]
	v_cvt_pk_bf16_f32 v80, v80, v81
	s_nop 0
	v_cvt_pk_bf16_f32 v81, v82, v83
	v_cvt_pk_bf16_f32 v82, v90, v91
	v_cvt_pk_bf16_f32 v83, v88, v89
	global_store_dwordx4 v[86:87], v[80:83], off offset:1536
	v_pk_mul_f32 v[88:89], v[10:11], s[26:27] op_sel_hi:[1,0]
	v_pk_mul_f32 v[90:91], v[8:9], s[26:27] op_sel_hi:[1,0]
	v_pk_mul_f32 v[80:81], v[12:13], s[26:27] op_sel_hi:[1,0]
	v_pk_mul_f32 v[82:83], v[14:15], s[26:27] op_sel_hi:[1,0]
	v_cvt_pk_bf16_f32 v80, v80, v81
	s_nop 0
	v_cvt_pk_bf16_f32 v81, v82, v83
	v_cvt_pk_bf16_f32 v82, v90, v91
	v_cvt_pk_bf16_f32 v83, v88, v89
	global_store_dwordx4 v[86:87], v[80:83], off offset:1792
	v_pk_mul_f32 v[86:87], v[34:35], s[26:27] op_sel_hi:[1,0]
	v_pk_mul_f32 v[88:89], v[32:33], s[26:27] op_sel_hi:[1,0]
	v_or_b32_e32 v80, 0xc00, v84
	v_ashrrev_i32_e32 v81, 31, v80
	v_lshlrev_b64 v[80:81], 11, v[80:81]
	v_lshl_add_u64 v[84:85], v[72:73], 0, v[80:81]
	v_pk_mul_f32 v[82:83], v[38:39], s[26:27] op_sel_hi:[1,0]
	v_pk_mul_f32 v[80:81], v[36:37], s[26:27] op_sel_hi:[1,0]
	s_nop 0
	v_cvt_pk_bf16_f32 v80, v80, v81
	v_cvt_pk_bf16_f32 v81, v82, v83
	v_cvt_pk_bf16_f32 v82, v88, v89
	v_cvt_pk_bf16_f32 v83, v86, v87
	global_store_dwordx4 v[84:85], v[80:83], off offset:1536
	v_pk_mul_f32 v[86:87], v[2:3], s[26:27] op_sel_hi:[1,0]
	v_pk_mul_f32 v[88:89], v[0:1], s[26:27] op_sel_hi:[1,0]
	v_pk_mul_f32 v[82:83], v[6:7], s[26:27] op_sel_hi:[1,0]
	v_pk_mul_f32 v[80:81], v[4:5], s[26:27] op_sel_hi:[1,0]
	s_nop 0
	v_cvt_pk_bf16_f32 v80, v80, v81
	v_cvt_pk_bf16_f32 v81, v82, v83
	v_cvt_pk_bf16_f32 v82, v88, v89
	v_cvt_pk_bf16_f32 v83, v86, v87
	global_store_dwordx4 v[84:85], v[80:83], off offset:1792
	s_andn2_b64 vcc, exec, s[34:35]
	s_cbranch_vccnz .LBB0_990
	s_branch .LBB0_1001

; #define PG8_STAGE(bufoff, gbase, voff) do { _Pragma("unroll") for (int _i = 0; _i < 2; ++_i) \
;         __builtin_amdgcn_global_load_lds((const unsigned*)((const char*)(gbase) + (voff)[_i]), (LAS unsigned*)(lds + (bufoff) + ldsw + _i * 8192), 16, 0, 0); } while (0)
; #define PG8_STAGEB(bufoff, gbase, perm) do { _Pragma("unroll") for (int _i = 0; _i < 2; ++_i) \
;         __builtin_amdgcn_global_load_lds((const unsigned*)((const char*)(gbase) + ((BSEL && (perm)) ? voffBp[_i] : voffB[_i])), (LAS unsigned*)(lds + (bufoff) + ldsw + _i * 8192), 16, 0, 0); } while (0)
; #define PG8_LDA(dst, b, h) do { _Pragma("unroll") for (int m = 0; m < 4; ++m) _Pragma("unroll") for (int k = 0; k < 2; ++k) dst[m][k] = *(const LAS bf16x8*)(lds + PG8_SA(b, h) + aoff + m * 2048 + k * 1024); } while (0)
; #define PG8_LDB(dst, b, h) do { _Pragma("unroll") for (int n = 0; n < 2; ++n) _Pragma("unroll") for (int k = 0; k < 2; ++k) dst[n][k] = *(const LAS bf16x8*)(lds + PG8_SB(b, h) + boff + n * 2048 + k * 1024); } while (0)
; #define PG8_WAIT_V(n) asm volatile("s_waitcnt vmcnt(" #n ")" ::: "memory")
; #define PG8_WAIT_L(n) asm volatile("s_waitcnt lgkmcnt(" #n ")" ::: "memory")
; #define PG8_BAR __builtin_amdgcn_s_barrier()
; #define PG8_SCHED __builtin_amdgcn_sched_barrier(0)
; template <class Epi, bool BSEL = false>
; __device__ __forceinline__ void gemm_phase(LAS unsigned char* lds, const Gemm g, const Order& S, const Epi& E, const int tid) {
;     ...
;         for (int t = 0; t < nt; t += 2) {
;             const bool last = (t == nt - 2);
;             const char* a1 = cA + (size_t)(t + 1) * kstep;
;             const char* a2 = last ? nA : cA + (size_t)(t + 2) * kstep; const char* b2 = last ? nB : cB + (size_t)(t + 2) * kstep;
;             const char* a3 = a2 + kstep; const char* b3 = b2 + kstep;
;             const bool p2 = last ? nP : cP; const size_t h2 = last ? nhB : chB;
;             PG8_LDB(B0, 0, 0); PG8_LDB(B1, 0, 1); PG8_SCHED; PG8_LDA(At, 0, 0); PG8_STAGE(PG8_SA(1, 1), a1 + hstepA, voffA);
;             PG8_WAIT_V(8); PG8_WAIT_L(0); PG8_BAR; PG8_MMA(0, 0, At, B0); PG8_MMA(0, 1, At, B1); PG8_BAR; PG8_SCHED;
;             PG8_LDA(At, 0, 1); PG8_STAGEB(PG8_SB(0, 0), b2, p2); PG8_STAGEB(PG8_SB(0, 1), b2 + h2, p2); PG8_STAGE(PG8_SA(0, 0), a2, voffA);
;             PG8_WAIT_V(8); PG8_WAIT_L(0); PG8_BAR; PG8_MMA(1, 0, At, B0); PG8_MMA(1, 1, At, B1); PG8_BAR; PG8_SCHED;
.LBB0_1072:
	v_add_u32_e32 v172, s47, v145
	ds_read_b128 v[132:135], v172
	ds_read_b128 v[136:139], v172 offset:1024
	ds_read_b128 v[140:143], v172 offset:2048
	ds_read_b128 v[176:179], v172 offset:3072
	v_add_u32_e32 v172, s48, v145
	s_add_u32 s34, s6, s2
	ds_read_b128 v[180:183], v172
	ds_read_b128 v[184:187], v172 offset:1024
	ds_read_b128 v[188:191], v172 offset:2048
	ds_read_b128 v[192:195], v172 offset:3072
	s_addc_u32 s35, s7, s3
	s_add_u32 s34, s34, 0x100
	s_addc_u32 s35, s35, 0
	s_add_u32 s57, s1, s2
	s_addc_u32 s58, s25, s3
	s_cmpk_eq_i32 s2, 0x700
	s_cselect_b32 s39, s52, s35
	s_cselect_b32 s38, s53, s34
	s_cselect_b32 s35, s54, s58
	s_cselect_b32 s34, s55, s57
	v_lshl_add_u64 v[172:173], v[128:129], 0, s[2:3]
	s_add_i32 m0, s20, 0xc000
	ds_read_b128 v[196:199], v175
	ds_read_b128 v[202:205], v175 offset:1024
	ds_read_b128 v[206:209], v175 offset:2048
	ds_read_b128 v[210:213], v175 offset:3072
	ds_read_b128 v[214:217], v175 offset:4096
	ds_read_b128 v[218:221], v175 offset:5120
	ds_read_b128 v[222:225], v175 offset:6144
	ds_read_b128 v[226:229], v175 offset:7168
	global_load_lds_dwordx4 v[172:173], off
	v_lshl_add_u64 v[172:173], v[130:131], 0, s[2:3]
	s_add_i32 m0, s20, 0xe000
	s_nop 0
	global_load_lds_dwordx4 v[172:173], off
	s_waitcnt vmcnt(8)
	s_waitcnt lgkmcnt(0)
	s_setprio 1
	s_barrier
	v_mfma_f32_16x16x32_bf16 v[124:127], v[132:135], v[196:199], v[124:127]
	v_mfma_f32_16x16x32_bf16 v[120:123], v[140:143], v[196:199], v[120:123]
	v_mfma_f32_16x16x32_bf16 v[116:119], v[132:135], v[206:209], v[116:119]
	v_mfma_f32_16x16x32_bf16 v[112:115], v[140:143], v[206:209], v[112:115]
	v_mfma_f32_16x16x32_bf16 v[108:111], v[132:135], v[214:217], v[108:111]
	v_mfma_f32_16x16x32_bf16 v[104:107], v[140:143], v[214:217], v[104:107]
	v_mfma_f32_16x16x32_bf16 v[100:103], v[132:135], v[222:225], v[100:103]
	v_mfma_f32_16x16x32_bf16 v[96:99], v[140:143], v[222:225], v[96:99]
	v_mfma_f32_16x16x32_bf16 v[124:127], v[136:139], v[202:205], v[124:127]
	v_mfma_f32_16x16x32_bf16 v[120:123], v[176:179], v[202:205], v[120:123]
	v_mfma_f32_16x16x32_bf16 v[116:119], v[136:139], v[210:213], v[116:119]
	v_mfma_f32_16x16x32_bf16 v[112:115], v[176:179], v[210:213], v[112:115]
	v_mfma_f32_16x16x32_bf16 v[108:111], v[136:139], v[218:221], v[108:111]
	v_mfma_f32_16x16x32_bf16 v[104:107], v[176:179], v[218:221], v[104:107]
	v_mfma_f32_16x16x32_bf16 v[100:103], v[136:139], v[226:229], v[100:103]
	v_mfma_f32_16x16x32_bf16 v[96:99], v[176:179], v[226:229], v[96:99]
	v_mfma_f32_16x16x32_bf16 v[92:95], v[180:183], v[196:199], v[92:95]
	v_mfma_f32_16x16x32_bf16 v[88:91], v[188:191], v[196:199], v[88:91]
	v_mfma_f32_16x16x32_bf16 v[84:87], v[180:183], v[206:209], v[84:87]
	v_mfma_f32_16x16x32_bf16 v[80:83], v[188:191], v[206:209], v[80:83]
	v_mfma_f32_16x16x32_bf16 v[76:79], v[180:183], v[214:217], v[76:79]
	v_mfma_f32_16x16x32_bf16 v[72:75], v[188:191], v[214:217], v[72:75]
	v_mfma_f32_16x16x32_bf16 v[68:71], v[180:183], v[222:225], v[68:71]
	v_mfma_f32_16x16x32_bf16 v[64:67], v[188:191], v[222:225], v[64:67]
	v_mfma_f32_16x16x32_bf16 v[92:95], v[184:187], v[202:205], v[92:95]
	v_mfma_f32_16x16x32_bf16 v[88:91], v[192:195], v[202:205], v[88:91]
	v_mfma_f32_16x16x32_bf16 v[84:87], v[184:187], v[210:213], v[84:87]
	v_mfma_f32_16x16x32_bf16 v[80:83], v[192:195], v[210:213], v[80:83]
	v_mfma_f32_16x16x32_bf16 v[76:79], v[184:187], v[218:221], v[76:79]
	v_mfma_f32_16x16x32_bf16 v[72:75], v[192:195], v[218:221], v[72:75]
	v_mfma_f32_16x16x32_bf16 v[68:71], v[184:187], v[226:229], v[68:71]
	v_mfma_f32_16x16x32_bf16 v[64:67], v[192:195], v[226:229], v[64:67]
	s_barrier
	s_setprio 0
	s_add_i32 s57, s47, s15
	v_lshl_add_u64 v[172:173], s[34:35], 0, v[146:147]
	s_mov_b32 m0, s57
	ds_read_b128 v[196:199], v175 offset:16384
	ds_read_b128 v[202:205], v175 offset:17408
	ds_read_b128 v[206:209], v175 offset:18432
	ds_read_b128 v[210:213], v175 offset:19456
	ds_read_b128 v[214:217], v175 offset:20480
	ds_read_b128 v[218:221], v175 offset:21504
	ds_read_b128 v[222:225], v175 offset:22528
	ds_read_b128 v[226:229], v175 offset:23552
	global_load_lds_dwordx4 v[172:173], off
	s_add_i32 m0, s57, 0x2000
	s_add_u32 s58, s34, 0x40000
	v_lshl_add_u64 v[230:231], s[34:35], 0, v[148:149]
	s_addc_u32 s59, s35, 0
	s_add_i32 s57, s48, s15
	global_load_lds_dwordx4 v[230:231], off
	v_lshl_add_u64 v[232:233], s[58:59], 0, v[146:147]
	s_mov_b32 m0, s57
	v_lshl_add_u64 v[234:235], s[38:39], 0, v[148:149]
	global_load_lds_dwordx4 v[232:233], off
	v_lshl_add_u64 v[232:233], s[58:59], 0, v[148:149]
	s_add_i32 m0, s57, 0x2000
	s_nop 0
	global_load_lds_dwordx4 v[232:233], off
	v_lshl_add_u64 v[232:233], s[38:39], 0, v[146:147]
	s_mov_b32 m0, s20
	s_nop 0
	global_load_lds_dwordx4 v[232:233], off
	s_mov_b32 m0, s21
	s_nop 0
	global_load_lds_dwordx4 v[234:235], off
	s_waitcnt vmcnt(8)
	s_waitcnt lgkmcnt(0)
	s_setprio 1
	s_barrier
; #define PG8_STAGE(bufoff, gbase, voff) do { _Pragma("unroll") for (int _i = 0; _i < 2; ++_i) \
;         __builtin_amdgcn_global_load_lds((const unsigned*)((const char*)(gbase) + (voff)[_i]), (LAS unsigned*)(lds + (bufoff) + ldsw + _i * 8192), 16, 0, 0); } while (0)
; #define PG8_LDA(dst, b, h) do { _Pragma("unroll") for (int m = 0; m < 4; ++m) _Pragma("unroll") for (int k = 0; k < 2; ++k) dst[m][k] = *(const LAS bf16x8*)(lds + PG8_SA(b, h) + aoff + m * 2048 + k * 1024); } while (0)
; #define PG8_LDB(dst, b, h) do { _Pragma("unroll") for (int n = 0; n < 2; ++n) _Pragma("unroll") for (int k = 0; k < 2; ++k) dst[n][k] = *(const LAS bf16x8*)(lds + PG8_SB(b, h) + boff + n * 2048 + k * 1024); } while (0)
; #define PG8_MMA(ai, bj, At, Bt) do { __builtin_amdgcn_s_setprio(1); _Pragma("unroll") for (int m = 0; m < 4; ++m) _Pragma("unroll") for (int n = 0; n < 2; ++n) _Pragma("unroll") for (int k = 0; k < 2; ++k) \
;         acc[ai][bj][m][n] = __builtin_amdgcn_mfma_f32_16x16x32_bf16(Bt[n][k], At[m][k], acc[ai][bj][m][n], 0, 0, 0); __builtin_amdgcn_s_setprio(0); } while (0)
; #define PG8_WAIT_V(n) asm volatile("s_waitcnt vmcnt(" #n ")" ::: "memory")
; #define PG8_WAIT_L(n) asm volatile("s_waitcnt lgkmcnt(" #n ")" ::: "memory")
; #define PG8_BAR __builtin_amdgcn_s_barrier()
; #define PG8_SCHED __builtin_amdgcn_sched_barrier(0)
; template <class Epi, bool BSEL = false>
; __device__ __forceinline__ void gemm_phase(LAS unsigned char* lds, const Gemm g, const Order& S, const Epi& E, const int tid) {
;     ...
;             PG8_WAIT_V(8); PG8_WAIT_L(0); PG8_BAR; PG8_MMA(1, 0, At, B0); PG8_MMA(1, 1, At, B1); PG8_BAR; PG8_SCHED;
;             PG8_LDB(B0, 1, 0); PG8_LDB(B1, 1, 1); PG8_SCHED; PG8_LDA(At, 1, 0); PG8_STAGE(PG8_SA(0, 1), a2 + hstepA, voffA);
;             PG8_WAIT_V(8); PG8_WAIT_L(0); PG8_BAR; PG8_MMA(0, 0, At, B0); PG8_MMA(0, 1, At, B1); PG8_BAR; PG8_SCHED;
	v_mfma_f32_16x16x32_bf16 v[60:63], v[132:135], v[196:199], v[60:63]
	v_mfma_f32_16x16x32_bf16 v[56:59], v[140:143], v[196:199], v[56:59]
	v_mfma_f32_16x16x32_bf16 v[52:55], v[132:135], v[206:209], v[52:55]
	v_mfma_f32_16x16x32_bf16 v[48:51], v[140:143], v[206:209], v[48:51]
	v_mfma_f32_16x16x32_bf16 v[44:47], v[132:135], v[214:217], v[44:47]
	v_mfma_f32_16x16x32_bf16 v[40:43], v[140:143], v[214:217], v[40:43]
	v_mfma_f32_16x16x32_bf16 v[36:39], v[132:135], v[222:225], v[36:39]
	v_mfma_f32_16x16x32_bf16 v[32:35], v[140:143], v[222:225], v[32:35]
	v_mfma_f32_16x16x32_bf16 v[60:63], v[136:139], v[202:205], v[60:63]
	v_mfma_f32_16x16x32_bf16 v[56:59], v[176:179], v[202:205], v[56:59]
	v_mfma_f32_16x16x32_bf16 v[52:55], v[136:139], v[210:213], v[52:55]
	v_mfma_f32_16x16x32_bf16 v[48:51], v[176:179], v[210:213], v[48:51]
	v_mfma_f32_16x16x32_bf16 v[44:47], v[136:139], v[218:221], v[44:47]
	v_mfma_f32_16x16x32_bf16 v[40:43], v[176:179], v[218:221], v[40:43]
	v_mfma_f32_16x16x32_bf16 v[36:39], v[136:139], v[226:229], v[36:39]
	v_mfma_f32_16x16x32_bf16 v[32:35], v[176:179], v[226:229], v[32:35]
	v_mfma_f32_16x16x32_bf16 v[28:31], v[180:183], v[196:199], v[28:31]
	v_mfma_f32_16x16x32_bf16 v[24:27], v[188:191], v[196:199], v[24:27]
	v_mfma_f32_16x16x32_bf16 v[20:23], v[180:183], v[206:209], v[20:23]
	v_mfma_f32_16x16x32_bf16 v[16:19], v[188:191], v[206:209], v[16:19]
	v_mfma_f32_16x16x32_bf16 v[12:15], v[180:183], v[214:217], v[12:15]
	v_mfma_f32_16x16x32_bf16 v[8:11], v[188:191], v[214:217], v[8:11]
	v_mfma_f32_16x16x32_bf16 v[4:7], v[180:183], v[222:225], v[4:7]
	v_mfma_f32_16x16x32_bf16 v[0:3], v[188:191], v[222:225], v[0:3]
	v_mfma_f32_16x16x32_bf16 v[28:31], v[184:187], v[202:205], v[28:31]
	v_mfma_f32_16x16x32_bf16 v[24:27], v[192:195], v[202:205], v[24:27]
	v_mfma_f32_16x16x32_bf16 v[20:23], v[184:187], v[210:213], v[20:23]
	v_mfma_f32_16x16x32_bf16 v[16:19], v[192:195], v[210:213], v[16:19]
	v_mfma_f32_16x16x32_bf16 v[12:15], v[184:187], v[218:221], v[12:15]
	v_mfma_f32_16x16x32_bf16 v[8:11], v[192:195], v[218:221], v[8:11]
	v_mfma_f32_16x16x32_bf16 v[4:7], v[184:187], v[226:229], v[4:7]
	v_mfma_f32_16x16x32_bf16 v[0:3], v[192:195], v[226:229], v[0:3]
	s_barrier
	s_setprio 0
	s_add_i32 s57, 0, 0x18000
	s_add_i32 s58, 0, 0x1c000
	v_add_u32_e32 v176, s57, v145
	v_add_u32_e32 v192, s58, v145
	ds_read_b128 v[132:135], v176
	ds_read_b128 v[136:139], v176 offset:1024
	ds_read_b128 v[140:143], v176 offset:2048
	ds_read_b128 v[176:179], v176 offset:3072
	ds_read_b128 v[180:183], v192
	ds_read_b128 v[184:187], v192 offset:1024
	ds_read_b128 v[188:191], v192 offset:2048
	ds_read_b128 v[192:195], v192 offset:3072
	s_add_u32 s38, s38, 0x40000
	s_addc_u32 s39, s39, 0
	s_mov_b32 m0, s40
	v_lshl_add_u64 v[236:237], s[38:39], 0, v[146:147]
	ds_read_b128 v[196:199], v175 offset:32768
	ds_read_b128 v[202:205], v175 offset:33792
	ds_read_b128 v[206:209], v175 offset:34816
	ds_read_b128 v[210:213], v175 offset:35840
	ds_read_b128 v[214:217], v175 offset:36864
	ds_read_b128 v[218:221], v175 offset:37888
	ds_read_b128 v[222:225], v175 offset:38912
	ds_read_b128 v[226:229], v175 offset:39936
	global_load_lds_dwordx4 v[236:237], off
	v_lshl_add_u64 v[236:237], s[38:39], 0, v[148:149]
	s_mov_b32 m0, s41
	s_nop 0
	global_load_lds_dwordx4 v[236:237], off
	s_waitcnt vmcnt(8)
	s_waitcnt lgkmcnt(0)
	s_setprio 1
	s_barrier
	v_mfma_f32_16x16x32_bf16 v[124:127], v[132:135], v[196:199], v[124:127]
	v_mfma_f32_16x16x32_bf16 v[120:123], v[140:143], v[196:199], v[120:123]
	v_mfma_f32_16x16x32_bf16 v[116:119], v[132:135], v[206:209], v[116:119]
	v_mfma_f32_16x16x32_bf16 v[112:115], v[140:143], v[206:209], v[112:115]
	v_mfma_f32_16x16x32_bf16 v[108:111], v[132:135], v[214:217], v[108:111]
	v_mfma_f32_16x16x32_bf16 v[104:107], v[140:143], v[214:217], v[104:107]
	v_mfma_f32_16x16x32_bf16 v[100:103], v[132:135], v[222:225], v[100:103]
	v_mfma_f32_16x16x32_bf16 v[96:99], v[140:143], v[222:225], v[96:99]
	v_mfma_f32_16x16x32_bf16 v[124:127], v[136:139], v[202:205], v[124:127]
	v_mfma_f32_16x16x32_bf16 v[120:123], v[176:179], v[202:205], v[120:123]
	v_mfma_f32_16x16x32_bf16 v[116:119], v[136:139], v[210:213], v[116:119]
	v_mfma_f32_16x16x32_bf16 v[112:115], v[176:179], v[210:213], v[112:115]
	v_mfma_f32_16x16x32_bf16 v[108:111], v[136:139], v[218:221], v[108:111]
	v_mfma_f32_16x16x32_bf16 v[104:107], v[176:179], v[218:221], v[104:107]
	v_mfma_f32_16x16x32_bf16 v[100:103], v[136:139], v[226:229], v[100:103]
	v_mfma_f32_16x16x32_bf16 v[96:99], v[176:179], v[226:229], v[96:99]
	v_mfma_f32_16x16x32_bf16 v[92:95], v[180:183], v[196:199], v[92:95]
	v_mfma_f32_16x16x32_bf16 v[88:91], v[188:191], v[196:199], v[88:91]
	v_mfma_f32_16x16x32_bf16 v[84:87], v[180:183], v[206:209], v[84:87]
	v_mfma_f32_16x16x32_bf16 v[80:83], v[188:191], v[206:209], v[80:83]
	v_mfma_f32_16x16x32_bf16 v[76:79], v[180:183], v[214:217], v[76:79]
	v_mfma_f32_16x16x32_bf16 v[72:75], v[188:191], v[214:217], v[72:75]
	v_mfma_f32_16x16x32_bf16 v[68:71], v[180:183], v[222:225], v[68:71]
	v_mfma_f32_16x16x32_bf16 v[64:67], v[188:191], v[222:225], v[64:67]
	v_mfma_f32_16x16x32_bf16 v[92:95], v[184:187], v[202:205], v[92:95]
	v_mfma_f32_16x16x32_bf16 v[88:91], v[192:195], v[202:205], v[88:91]
	v_mfma_f32_16x16x32_bf16 v[84:87], v[184:187], v[210:213], v[84:87]
	v_mfma_f32_16x16x32_bf16 v[80:83], v[192:195], v[210:213], v[80:83]
	v_mfma_f32_16x16x32_bf16 v[76:79], v[184:187], v[218:221], v[76:79]
	v_mfma_f32_16x16x32_bf16 v[72:75], v[192:195], v[218:221], v[72:75]
	v_mfma_f32_16x16x32_bf16 v[68:71], v[184:187], v[226:229], v[68:71]
	v_mfma_f32_16x16x32_bf16 v[64:67], v[192:195], v[226:229], v[64:67]
	s_barrier
; #define PG8_STAGE(bufoff, gbase, voff) do { _Pragma("unroll") for (int _i = 0; _i < 2; ++_i) \
;         __builtin_amdgcn_global_load_lds((const unsigned*)((const char*)(gbase) + (voff)[_i]), (LAS unsigned*)(lds + (bufoff) + ldsw + _i * 8192), 16, 0, 0); } while (0)
; #define PG8_STAGEB(bufoff, gbase, perm) do { _Pragma("unroll") for (int _i = 0; _i < 2; ++_i) \
;         __builtin_amdgcn_global_load_lds((const unsigned*)((const char*)(gbase) + ((BSEL && (perm)) ? voffBp[_i] : voffB[_i])), (LAS unsigned*)(lds + (bufoff) + ldsw + _i * 8192), 16, 0, 0); } while (0)
; #define PG8_LDA(dst, b, h) do { _Pragma("unroll") for (int m = 0; m < 4; ++m) _Pragma("unroll") for (int k = 0; k < 2; ++k) dst[m][k] = *(const LAS bf16x8*)(lds + PG8_SA(b, h) + aoff + m * 2048 + k * 1024); } while (0)
; #define PG8_MMA(ai, bj, At, Bt) do { __builtin_amdgcn_s_setprio(1); _Pragma("unroll") for (int m = 0; m < 4; ++m) _Pragma("unroll") for (int n = 0; n < 2; ++n) _Pragma("unroll") for (int k = 0; k < 2; ++k) \
;         acc[ai][bj][m][n] = __builtin_amdgcn_mfma_f32_16x16x32_bf16(Bt[n][k], At[m][k], acc[ai][bj][m][n], 0, 0, 0); __builtin_amdgcn_s_setprio(0); } while (0)
; #define PG8_WAIT_V(n) asm volatile("s_waitcnt vmcnt(" #n ")" ::: "memory")
; #define PG8_WAIT_L(n) asm volatile("s_waitcnt lgkmcnt(" #n ")" ::: "memory")
; #define PG8_BAR __builtin_amdgcn_s_barrier()
; #define PG8_SCHED __builtin_amdgcn_sched_barrier(0)
; template <class Epi, bool BSEL = false>
; __device__ __forceinline__ void gemm_phase(LAS unsigned char* lds, const Gemm g, const Order& S, const Epi& E, const int tid) {
;     ...
;             PG8_LDA(At, 1, 1); PG8_STAGEB(PG8_SB(1, 0), b3, p2); PG8_STAGEB(PG8_SB(1, 1), b3 + h2, p2); PG8_STAGE(PG8_SA(1, 0), a3, voffA);
;             PG8_WAIT_V(8); PG8_WAIT_L(0); PG8_BAR; PG8_MMA(1, 0, At, B0); PG8_MMA(1, 1, At, B1); PG8_BAR; PG8_SCHED;
;         }
;         if constexpr (ALIGN_EPI) { if (wr == 0) PG8_BAR; }
	s_setprio 0
	s_add_i32 s38, s57, s15
	v_lshl_add_u64 v[172:173], v[172:173], 0, s[10:11]
	s_mov_b32 m0, s38
	ds_read_b128 v[196:199], v175 offset:49152
	ds_read_b128 v[202:205], v175 offset:50176
	ds_read_b128 v[206:209], v175 offset:51200
	ds_read_b128 v[210:213], v175 offset:52224
	ds_read_b128 v[214:217], v175 offset:53248
	ds_read_b128 v[218:221], v175 offset:54272
	ds_read_b128 v[222:225], v175 offset:55296
	ds_read_b128 v[226:229], v175 offset:56320
	global_load_lds_dwordx4 v[172:173], off
	s_add_i32 m0, s38, 0x2000
	s_add_u32 s34, s34, 0x40080
	v_lshl_add_u64 v[172:173], v[230:231], 0, s[10:11]
	s_addc_u32 s35, s35, 0
	s_add_i32 s38, s58, s15
	global_load_lds_dwordx4 v[172:173], off
	v_lshl_add_u64 v[172:173], s[34:35], 0, v[146:147]
	s_mov_b32 m0, s38
	s_nop 0
	global_load_lds_dwordx4 v[172:173], off
	v_lshl_add_u64 v[172:173], s[34:35], 0, v[148:149]
	s_add_i32 m0, s38, 0x2000
	s_nop 0
	global_load_lds_dwordx4 v[172:173], off
	v_lshl_add_u64 v[172:173], v[232:233], 0, s[10:11]
	s_mov_b32 m0, s45
	s_nop 0
	global_load_lds_dwordx4 v[172:173], off
	v_lshl_add_u64 v[172:173], v[234:235], 0, s[10:11]
	s_mov_b32 m0, s46
	s_nop 0
	global_load_lds_dwordx4 v[172:173], off
	s_waitcnt vmcnt(8)
	s_waitcnt lgkmcnt(0)
	s_setprio 1
	s_barrier
	v_mfma_f32_16x16x32_bf16 v[60:63], v[132:135], v[196:199], v[60:63]
	v_mfma_f32_16x16x32_bf16 v[56:59], v[140:143], v[196:199], v[56:59]
	v_mfma_f32_16x16x32_bf16 v[52:55], v[132:135], v[206:209], v[52:55]
	v_mfma_f32_16x16x32_bf16 v[48:51], v[140:143], v[206:209], v[48:51]
	v_mfma_f32_16x16x32_bf16 v[44:47], v[132:135], v[214:217], v[44:47]
	v_mfma_f32_16x16x32_bf16 v[40:43], v[140:143], v[214:217], v[40:43]
	v_mfma_f32_16x16x32_bf16 v[36:39], v[132:135], v[222:225], v[36:39]
	v_mfma_f32_16x16x32_bf16 v[32:35], v[140:143], v[222:225], v[32:35]
	v_mfma_f32_16x16x32_bf16 v[60:63], v[136:139], v[202:205], v[60:63]
	v_mfma_f32_16x16x32_bf16 v[56:59], v[176:179], v[202:205], v[56:59]
	v_mfma_f32_16x16x32_bf16 v[52:55], v[136:139], v[210:213], v[52:55]
	v_mfma_f32_16x16x32_bf16 v[48:51], v[176:179], v[210:213], v[48:51]
	v_mfma_f32_16x16x32_bf16 v[44:47], v[136:139], v[218:221], v[44:47]
	v_mfma_f32_16x16x32_bf16 v[40:43], v[176:179], v[218:221], v[40:43]
	v_mfma_f32_16x16x32_bf16 v[36:39], v[136:139], v[226:229], v[36:39]
	v_mfma_f32_16x16x32_bf16 v[32:35], v[176:179], v[226:229], v[32:35]
	v_mfma_f32_16x16x32_bf16 v[28:31], v[180:183], v[196:199], v[28:31]
	v_mfma_f32_16x16x32_bf16 v[24:27], v[188:191], v[196:199], v[24:27]
	v_mfma_f32_16x16x32_bf16 v[20:23], v[180:183], v[206:209], v[20:23]
	v_mfma_f32_16x16x32_bf16 v[16:19], v[188:191], v[206:209], v[16:19]
	v_mfma_f32_16x16x32_bf16 v[12:15], v[180:183], v[214:217], v[12:15]
	v_mfma_f32_16x16x32_bf16 v[8:11], v[188:191], v[214:217], v[8:11]
	v_mfma_f32_16x16x32_bf16 v[4:7], v[180:183], v[222:225], v[4:7]
	v_mfma_f32_16x16x32_bf16 v[0:3], v[188:191], v[222:225], v[0:3]
	v_mfma_f32_16x16x32_bf16 v[28:31], v[184:187], v[202:205], v[28:31]
	v_mfma_f32_16x16x32_bf16 v[24:27], v[192:195], v[202:205], v[24:27]
	v_mfma_f32_16x16x32_bf16 v[20:23], v[184:187], v[210:213], v[20:23]
	v_mfma_f32_16x16x32_bf16 v[16:19], v[192:195], v[210:213], v[16:19]
	v_mfma_f32_16x16x32_bf16 v[12:15], v[184:187], v[218:221], v[12:15]
	v_mfma_f32_16x16x32_bf16 v[8:11], v[192:195], v[218:221], v[8:11]
	v_mfma_f32_16x16x32_bf16 v[4:7], v[184:187], v[226:229], v[4:7]
	v_mfma_f32_16x16x32_bf16 v[0:3], v[192:195], v[226:229], v[0:3]
	s_barrier
	s_setprio 0
	s_add_i32 s56, s56, 2
	s_add_u32 s2, s2, 0x100
	s_addc_u32 s3, s3, 0
	s_cmp_gt_u32 s56, 13
	s_cbranch_scc0 .LBB0_1072
	s_and_b64 vcc, exec, s[22:23]
	s_cbranch_vccz .LBB0_1075
	s_barrier

; #define PG8_STAGE(bufoff, gbase, voff) do { _Pragma("unroll") for (int _i = 0; _i < 2; ++_i) \
;         __builtin_amdgcn_global_load_lds((const unsigned*)((const char*)(gbase) + (voff)[_i]), (LAS unsigned*)(lds + (bufoff) + ldsw + _i * 8192), 16, 0, 0); } while (0)
; #define PG8_STAGEB(bufoff, gbase, perm) do { _Pragma("unroll") for (int _i = 0; _i < 2; ++_i) \
;         __builtin_amdgcn_global_load_lds((const unsigned*)((const char*)(gbase) + ((BSEL && (perm)) ? voffBp[_i] : voffB[_i])), (LAS unsigned*)(lds + (bufoff) + ldsw + _i * 8192), 16, 0, 0); } while (0)
; #define PG8_LDA(dst, b, h) do { _Pragma("unroll") for (int m = 0; m < 4; ++m) _Pragma("unroll") for (int k = 0; k < 2; ++k) dst[m][k] = *(const LAS bf16x8*)(lds + PG8_SA(b, h) + aoff + m * 2048 + k * 1024); } while (0)
; #define PG8_LDB(dst, b, h) do { _Pragma("unroll") for (int n = 0; n < 2; ++n) _Pragma("unroll") for (int k = 0; k < 2; ++k) dst[n][k] = *(const LAS bf16x8*)(lds + PG8_SB(b, h) + boff + n * 2048 + k * 1024); } while (0)
; #define PG8_WAIT_V(n) asm volatile("s_waitcnt vmcnt(" #n ")" ::: "memory")
; #define PG8_WAIT_L(n) asm volatile("s_waitcnt lgkmcnt(" #n ")" ::: "memory")
; #define PG8_BAR __builtin_amdgcn_s_barrier()
; #define PG8_SCHED __builtin_amdgcn_sched_barrier(0)
; template <class Epi, bool BSEL = false>
; __device__ __forceinline__ void gemm_phase(LAS unsigned char* lds, const Gemm g, const Order& S, const Epi& E, const int tid) {
;     ...
;         for (int t = 0; t < nt; t += 2) {
;             const bool last = (t == nt - 2);
;             const char* a1 = cA + (size_t)(t + 1) * kstep;
;             const char* a2 = last ? nA : cA + (size_t)(t + 2) * kstep; const char* b2 = last ? nB : cB + (size_t)(t + 2) * kstep;
;             const char* a3 = a2 + kstep; const char* b3 = b2 + kstep;
;             const bool p2 = last ? nP : cP; const size_t h2 = last ? nhB : chB;
;             PG8_LDB(B0, 0, 0); PG8_LDB(B1, 0, 1); PG8_SCHED; PG8_LDA(At, 0, 0); PG8_STAGE(PG8_SA(1, 1), a1 + hstepA, voffA);
;             PG8_WAIT_V(8); PG8_WAIT_L(0); PG8_BAR; PG8_MMA(0, 0, At, B0); PG8_MMA(0, 1, At, B1); PG8_BAR; PG8_SCHED;
;             PG8_LDA(At, 0, 1); PG8_STAGEB(PG8_SB(0, 0), b2, p2); PG8_STAGEB(PG8_SB(0, 1), b2 + h2, p2); PG8_STAGE(PG8_SA(0, 0), a2, voffA);
;             PG8_WAIT_V(8); PG8_WAIT_L(0); PG8_BAR; PG8_MMA(1, 0, At, B0); PG8_MMA(1, 1, At, B1); PG8_BAR; PG8_SCHED;
.LBB0_1101:
	v_add_u32_e32 v164, s47, v129
	v_add_u32_e32 v180, s48, v129
	s_add_u32 s40, s8, s38
	ds_read_b128 v[152:155], v164
	ds_read_b128 v[156:159], v164 offset:1024
	ds_read_b128 v[160:163], v164 offset:2048
	ds_read_b128 v[164:167], v164 offset:3072
	ds_read_b128 v[168:171], v180
	ds_read_b128 v[172:175], v180 offset:1024
	ds_read_b128 v[176:179], v180 offset:2048
	ds_read_b128 v[180:183], v180 offset:3072
	s_addc_u32 s41, s9, s39
	s_add_u32 s40, s40, 0x100
	s_addc_u32 s41, s41, 0
	s_add_u32 s56, s27, s38
	s_addc_u32 s57, s35, s39
	s_cmpk_eq_i32 s38, 0x700
	s_cselect_b32 s43, s51, s41
	s_cselect_b32 s42, s52, s40
	s_cselect_b32 s41, s53, s57
	s_cselect_b32 s40, s54, s56
	v_lshl_add_u64 v[188:189], v[146:147], 0, s[38:39]
	s_add_i32 m0, s7, 0xc000
	ds_read_b128 v[184:187], v151
	ds_read_b128 v[192:195], v151 offset:1024
	ds_read_b128 v[196:199], v151 offset:2048
	ds_read_b128 v[202:205], v151 offset:3072
	ds_read_b128 v[206:209], v151 offset:4096
	ds_read_b128 v[210:213], v151 offset:5120
	ds_read_b128 v[214:217], v151 offset:6144
	ds_read_b128 v[218:221], v151 offset:7168
	global_load_lds_dwordx4 v[188:189], off
	v_lshl_add_u64 v[188:189], v[148:149], 0, s[38:39]
	s_add_i32 m0, s7, 0xe000
	s_nop 0
	global_load_lds_dwordx4 v[188:189], off
	s_waitcnt vmcnt(8)
	s_waitcnt lgkmcnt(0)
	s_setprio 1
	s_barrier
	v_mfma_f32_16x16x32_bf16 v[124:127], v[152:155], v[184:187], v[124:127]
	v_mfma_f32_16x16x32_bf16 v[120:123], v[160:163], v[184:187], v[120:123]
	v_mfma_f32_16x16x32_bf16 v[108:111], v[152:155], v[196:199], v[108:111]
	v_mfma_f32_16x16x32_bf16 v[104:107], v[160:163], v[196:199], v[104:107]
	v_mfma_f32_16x16x32_bf16 v[92:95], v[152:155], v[206:209], v[92:95]
	v_mfma_f32_16x16x32_bf16 v[88:91], v[160:163], v[206:209], v[88:91]
	v_mfma_f32_16x16x32_bf16 v[76:79], v[152:155], v[214:217], v[76:79]
	v_mfma_f32_16x16x32_bf16 v[72:75], v[160:163], v[214:217], v[72:75]
	v_mfma_f32_16x16x32_bf16 v[124:127], v[156:159], v[192:195], v[124:127]
	v_mfma_f32_16x16x32_bf16 v[120:123], v[164:167], v[192:195], v[120:123]
	v_mfma_f32_16x16x32_bf16 v[108:111], v[156:159], v[202:205], v[108:111]
	v_mfma_f32_16x16x32_bf16 v[104:107], v[164:167], v[202:205], v[104:107]
	v_mfma_f32_16x16x32_bf16 v[92:95], v[156:159], v[210:213], v[92:95]
	v_mfma_f32_16x16x32_bf16 v[88:91], v[164:167], v[210:213], v[88:91]
	v_mfma_f32_16x16x32_bf16 v[76:79], v[156:159], v[218:221], v[76:79]
	v_mfma_f32_16x16x32_bf16 v[72:75], v[164:167], v[218:221], v[72:75]
	v_mfma_f32_16x16x32_bf16 v[116:119], v[168:171], v[184:187], v[116:119]
	v_mfma_f32_16x16x32_bf16 v[112:115], v[176:179], v[184:187], v[112:115]
	v_mfma_f32_16x16x32_bf16 v[100:103], v[168:171], v[196:199], v[100:103]
	v_mfma_f32_16x16x32_bf16 v[96:99], v[176:179], v[196:199], v[96:99]
	v_mfma_f32_16x16x32_bf16 v[84:87], v[168:171], v[206:209], v[84:87]
	v_mfma_f32_16x16x32_bf16 v[80:83], v[176:179], v[206:209], v[80:83]
	v_mfma_f32_16x16x32_bf16 v[68:71], v[168:171], v[214:217], v[68:71]
	v_mfma_f32_16x16x32_bf16 v[64:67], v[176:179], v[214:217], v[64:67]
	v_mfma_f32_16x16x32_bf16 v[116:119], v[172:175], v[192:195], v[116:119]
	v_mfma_f32_16x16x32_bf16 v[112:115], v[180:183], v[192:195], v[112:115]
	v_mfma_f32_16x16x32_bf16 v[100:103], v[172:175], v[202:205], v[100:103]
	v_mfma_f32_16x16x32_bf16 v[96:99], v[180:183], v[202:205], v[96:99]
	v_mfma_f32_16x16x32_bf16 v[84:87], v[172:175], v[210:213], v[84:87]
	v_mfma_f32_16x16x32_bf16 v[80:83], v[180:183], v[210:213], v[80:83]
	v_mfma_f32_16x16x32_bf16 v[68:71], v[172:175], v[218:221], v[68:71]
	v_mfma_f32_16x16x32_bf16 v[64:67], v[180:183], v[218:221], v[64:67]
	s_barrier
	s_setprio 0
	s_add_i32 s56, s47, s15
	v_lshl_add_u64 v[188:189], s[40:41], 0, v[132:133]
	s_mov_b32 m0, s56
	ds_read_b128 v[184:187], v151 offset:16384
	ds_read_b128 v[192:195], v151 offset:17408
	ds_read_b128 v[196:199], v151 offset:18432
	ds_read_b128 v[202:205], v151 offset:19456
	ds_read_b128 v[206:209], v151 offset:20480
	ds_read_b128 v[210:213], v151 offset:21504
	ds_read_b128 v[214:217], v151 offset:22528
	ds_read_b128 v[218:221], v151 offset:23552
	global_load_lds_dwordx4 v[188:189], off
	s_add_i32 m0, s56, 0x2000
	s_add_u32 s56, s40, 0x40000
	v_lshl_add_u64 v[222:223], s[40:41], 0, v[136:137]
	s_addc_u32 s57, s41, 0
	s_add_i32 s58, s48, s15
	global_load_lds_dwordx4 v[222:223], off
	v_lshl_add_u64 v[224:225], s[56:57], 0, v[132:133]
	s_mov_b32 m0, s58
	v_lshl_add_u64 v[226:227], s[42:43], 0, v[134:135]
	global_load_lds_dwordx4 v[224:225], off
	v_lshl_add_u64 v[224:225], s[56:57], 0, v[136:137]
	s_add_i32 m0, s58, 0x2000
	s_nop 0
	global_load_lds_dwordx4 v[224:225], off
	v_lshl_add_u64 v[224:225], s[42:43], 0, v[130:131]
	s_mov_b32 m0, s7
	s_nop 0
	global_load_lds_dwordx4 v[224:225], off
	s_mov_b32 m0, s20
	s_nop 0
	global_load_lds_dwordx4 v[226:227], off
	s_waitcnt vmcnt(8)
	s_waitcnt lgkmcnt(0)
	s_setprio 1
	s_barrier
; #define PG8_STAGE(bufoff, gbase, voff) do { _Pragma("unroll") for (int _i = 0; _i < 2; ++_i) \
;         __builtin_amdgcn_global_load_lds((const unsigned*)((const char*)(gbase) + (voff)[_i]), (LAS unsigned*)(lds + (bufoff) + ldsw + _i * 8192), 16, 0, 0); } while (0)
; #define PG8_LDA(dst, b, h) do { _Pragma("unroll") for (int m = 0; m < 4; ++m) _Pragma("unroll") for (int k = 0; k < 2; ++k) dst[m][k] = *(const LAS bf16x8*)(lds + PG8_SA(b, h) + aoff + m * 2048 + k * 1024); } while (0)
; #define PG8_LDB(dst, b, h) do { _Pragma("unroll") for (int n = 0; n < 2; ++n) _Pragma("unroll") for (int k = 0; k < 2; ++k) dst[n][k] = *(const LAS bf16x8*)(lds + PG8_SB(b, h) + boff + n * 2048 + k * 1024); } while (0)
; #define PG8_MMA(ai, bj, At, Bt) do { __builtin_amdgcn_s_setprio(1); _Pragma("unroll") for (int m = 0; m < 4; ++m) _Pragma("unroll") for (int n = 0; n < 2; ++n) _Pragma("unroll") for (int k = 0; k < 2; ++k) \
;         acc[ai][bj][m][n] = __builtin_amdgcn_mfma_f32_16x16x32_bf16(Bt[n][k], At[m][k], acc[ai][bj][m][n], 0, 0, 0); __builtin_amdgcn_s_setprio(0); } while (0)
; #define PG8_WAIT_V(n) asm volatile("s_waitcnt vmcnt(" #n ")" ::: "memory")
; #define PG8_WAIT_L(n) asm volatile("s_waitcnt lgkmcnt(" #n ")" ::: "memory")
; #define PG8_BAR __builtin_amdgcn_s_barrier()
; #define PG8_SCHED __builtin_amdgcn_sched_barrier(0)
; template <class Epi, bool BSEL = false>
; __device__ __forceinline__ void gemm_phase(LAS unsigned char* lds, const Gemm g, const Order& S, const Epi& E, const int tid) {
;     ...
;             PG8_WAIT_V(8); PG8_WAIT_L(0); PG8_BAR; PG8_MMA(1, 0, At, B0); PG8_MMA(1, 1, At, B1); PG8_BAR; PG8_SCHED;
;             PG8_LDB(B0, 1, 0); PG8_LDB(B1, 1, 1); PG8_SCHED; PG8_LDA(At, 1, 0); PG8_STAGE(PG8_SA(0, 1), a2 + hstepA, voffA);
;             PG8_WAIT_V(8); PG8_WAIT_L(0); PG8_BAR; PG8_MMA(0, 0, At, B0); PG8_MMA(0, 1, At, B1); PG8_BAR; PG8_SCHED;
	v_mfma_f32_16x16x32_bf16 v[60:63], v[152:155], v[184:187], v[60:63]
	v_mfma_f32_16x16x32_bf16 v[56:59], v[160:163], v[184:187], v[56:59]
	v_mfma_f32_16x16x32_bf16 v[44:47], v[152:155], v[196:199], v[44:47]
	v_mfma_f32_16x16x32_bf16 v[40:43], v[160:163], v[196:199], v[40:43]
	v_mfma_f32_16x16x32_bf16 v[28:31], v[152:155], v[206:209], v[28:31]
	v_mfma_f32_16x16x32_bf16 v[24:27], v[160:163], v[206:209], v[24:27]
	v_mfma_f32_16x16x32_bf16 v[12:15], v[152:155], v[214:217], v[12:15]
	v_mfma_f32_16x16x32_bf16 v[8:11], v[160:163], v[214:217], v[8:11]
	v_mfma_f32_16x16x32_bf16 v[60:63], v[156:159], v[192:195], v[60:63]
	v_mfma_f32_16x16x32_bf16 v[56:59], v[164:167], v[192:195], v[56:59]
	v_mfma_f32_16x16x32_bf16 v[44:47], v[156:159], v[202:205], v[44:47]
	v_mfma_f32_16x16x32_bf16 v[40:43], v[164:167], v[202:205], v[40:43]
	v_mfma_f32_16x16x32_bf16 v[28:31], v[156:159], v[210:213], v[28:31]
	v_mfma_f32_16x16x32_bf16 v[24:27], v[164:167], v[210:213], v[24:27]
	v_mfma_f32_16x16x32_bf16 v[12:15], v[156:159], v[218:221], v[12:15]
	v_mfma_f32_16x16x32_bf16 v[8:11], v[164:167], v[218:221], v[8:11]
	v_mfma_f32_16x16x32_bf16 v[52:55], v[168:171], v[184:187], v[52:55]
	v_mfma_f32_16x16x32_bf16 v[48:51], v[176:179], v[184:187], v[48:51]
	v_mfma_f32_16x16x32_bf16 v[36:39], v[168:171], v[196:199], v[36:39]
	v_mfma_f32_16x16x32_bf16 v[32:35], v[176:179], v[196:199], v[32:35]
	v_mfma_f32_16x16x32_bf16 v[20:23], v[168:171], v[206:209], v[20:23]
	v_mfma_f32_16x16x32_bf16 v[16:19], v[176:179], v[206:209], v[16:19]
	v_mfma_f32_16x16x32_bf16 v[4:7], v[168:171], v[214:217], v[4:7]
	v_mfma_f32_16x16x32_bf16 v[0:3], v[176:179], v[214:217], v[0:3]
	v_mfma_f32_16x16x32_bf16 v[52:55], v[172:175], v[192:195], v[52:55]
	v_mfma_f32_16x16x32_bf16 v[48:51], v[180:183], v[192:195], v[48:51]
	v_mfma_f32_16x16x32_bf16 v[36:39], v[172:175], v[202:205], v[36:39]
	v_mfma_f32_16x16x32_bf16 v[32:35], v[180:183], v[202:205], v[32:35]
	v_mfma_f32_16x16x32_bf16 v[20:23], v[172:175], v[210:213], v[20:23]
	v_mfma_f32_16x16x32_bf16 v[16:19], v[180:183], v[210:213], v[16:19]
	v_mfma_f32_16x16x32_bf16 v[4:7], v[172:175], v[218:221], v[4:7]
	v_mfma_f32_16x16x32_bf16 v[0:3], v[180:183], v[218:221], v[0:3]
	s_barrier
	s_setprio 0
	s_add_i32 s56, 0, 0x18000
	s_add_i32 s57, 0, 0x1c000
	v_add_u32_e32 v164, s56, v129
	v_add_u32_e32 v180, s57, v129
	ds_read_b128 v[152:155], v164
	ds_read_b128 v[156:159], v164 offset:1024
	ds_read_b128 v[160:163], v164 offset:2048
	ds_read_b128 v[164:167], v164 offset:3072
	ds_read_b128 v[168:171], v180
	ds_read_b128 v[172:175], v180 offset:1024
	ds_read_b128 v[176:179], v180 offset:2048
	ds_read_b128 v[180:183], v180 offset:3072
	s_add_u32 s42, s42, 0x40000
	s_addc_u32 s43, s43, 0
	s_mov_b32 m0, s21
	v_lshl_add_u64 v[228:229], s[42:43], 0, v[130:131]
	ds_read_b128 v[184:187], v151 offset:32768
	ds_read_b128 v[192:195], v151 offset:33792
	ds_read_b128 v[196:199], v151 offset:34816
	ds_read_b128 v[202:205], v151 offset:35840
	ds_read_b128 v[206:209], v151 offset:36864
	ds_read_b128 v[210:213], v151 offset:37888
	ds_read_b128 v[214:217], v151 offset:38912
	ds_read_b128 v[218:221], v151 offset:39936
	global_load_lds_dwordx4 v[228:229], off
	v_lshl_add_u64 v[228:229], s[42:43], 0, v[134:135]
	s_mov_b32 m0, s44
	s_nop 0
	global_load_lds_dwordx4 v[228:229], off
	s_waitcnt vmcnt(8)
	s_waitcnt lgkmcnt(0)
	s_setprio 1
	s_barrier
	v_mfma_f32_16x16x32_bf16 v[124:127], v[152:155], v[184:187], v[124:127]
	v_mfma_f32_16x16x32_bf16 v[120:123], v[160:163], v[184:187], v[120:123]
	v_mfma_f32_16x16x32_bf16 v[108:111], v[152:155], v[196:199], v[108:111]
	v_mfma_f32_16x16x32_bf16 v[104:107], v[160:163], v[196:199], v[104:107]
	v_mfma_f32_16x16x32_bf16 v[92:95], v[152:155], v[206:209], v[92:95]
	v_mfma_f32_16x16x32_bf16 v[88:91], v[160:163], v[206:209], v[88:91]
	v_mfma_f32_16x16x32_bf16 v[76:79], v[152:155], v[214:217], v[76:79]
	v_mfma_f32_16x16x32_bf16 v[72:75], v[160:163], v[214:217], v[72:75]
	v_mfma_f32_16x16x32_bf16 v[124:127], v[156:159], v[192:195], v[124:127]
	v_mfma_f32_16x16x32_bf16 v[120:123], v[164:167], v[192:195], v[120:123]
	v_mfma_f32_16x16x32_bf16 v[108:111], v[156:159], v[202:205], v[108:111]
	v_mfma_f32_16x16x32_bf16 v[104:107], v[164:167], v[202:205], v[104:107]
	v_mfma_f32_16x16x32_bf16 v[92:95], v[156:159], v[210:213], v[92:95]
	v_mfma_f32_16x16x32_bf16 v[88:91], v[164:167], v[210:213], v[88:91]
	v_mfma_f32_16x16x32_bf16 v[76:79], v[156:159], v[218:221], v[76:79]
	v_mfma_f32_16x16x32_bf16 v[72:75], v[164:167], v[218:221], v[72:75]
	v_mfma_f32_16x16x32_bf16 v[116:119], v[168:171], v[184:187], v[116:119]
	v_mfma_f32_16x16x32_bf16 v[112:115], v[176:179], v[184:187], v[112:115]
	v_mfma_f32_16x16x32_bf16 v[100:103], v[168:171], v[196:199], v[100:103]
	v_mfma_f32_16x16x32_bf16 v[96:99], v[176:179], v[196:199], v[96:99]
	v_mfma_f32_16x16x32_bf16 v[84:87], v[168:171], v[206:209], v[84:87]
	v_mfma_f32_16x16x32_bf16 v[80:83], v[176:179], v[206:209], v[80:83]
	v_mfma_f32_16x16x32_bf16 v[68:71], v[168:171], v[214:217], v[68:71]
	v_mfma_f32_16x16x32_bf16 v[64:67], v[176:179], v[214:217], v[64:67]
	v_mfma_f32_16x16x32_bf16 v[116:119], v[172:175], v[192:195], v[116:119]
	v_mfma_f32_16x16x32_bf16 v[112:115], v[180:183], v[192:195], v[112:115]
	v_mfma_f32_16x16x32_bf16 v[100:103], v[172:175], v[202:205], v[100:103]
	v_mfma_f32_16x16x32_bf16 v[96:99], v[180:183], v[202:205], v[96:99]
	v_mfma_f32_16x16x32_bf16 v[84:87], v[172:175], v[210:213], v[84:87]
	v_mfma_f32_16x16x32_bf16 v[80:83], v[180:183], v[210:213], v[80:83]
	v_mfma_f32_16x16x32_bf16 v[68:71], v[172:175], v[218:221], v[68:71]
	v_mfma_f32_16x16x32_bf16 v[64:67], v[180:183], v[218:221], v[64:67]
	s_barrier
; #define PG8_STAGE(bufoff, gbase, voff) do { _Pragma("unroll") for (int _i = 0; _i < 2; ++_i) \
;         __builtin_amdgcn_global_load_lds((const unsigned*)((const char*)(gbase) + (voff)[_i]), (LAS unsigned*)(lds + (bufoff) + ldsw + _i * 8192), 16, 0, 0); } while (0)
; #define PG8_STAGEB(bufoff, gbase, perm) do { _Pragma("unroll") for (int _i = 0; _i < 2; ++_i) \
;         __builtin_amdgcn_global_load_lds((const unsigned*)((const char*)(gbase) + ((BSEL && (perm)) ? voffBp[_i] : voffB[_i])), (LAS unsigned*)(lds + (bufoff) + ldsw + _i * 8192), 16, 0, 0); } while (0)
; #define PG8_LDA(dst, b, h) do { _Pragma("unroll") for (int m = 0; m < 4; ++m) _Pragma("unroll") for (int k = 0; k < 2; ++k) dst[m][k] = *(const LAS bf16x8*)(lds + PG8_SA(b, h) + aoff + m * 2048 + k * 1024); } while (0)
; #define PG8_MMA(ai, bj, At, Bt) do { __builtin_amdgcn_s_setprio(1); _Pragma("unroll") for (int m = 0; m < 4; ++m) _Pragma("unroll") for (int n = 0; n < 2; ++n) _Pragma("unroll") for (int k = 0; k < 2; ++k) \
;         acc[ai][bj][m][n] = __builtin_amdgcn_mfma_f32_16x16x32_bf16(Bt[n][k], At[m][k], acc[ai][bj][m][n], 0, 0, 0); __builtin_amdgcn_s_setprio(0); } while (0)
; #define PG8_WAIT_V(n) asm volatile("s_waitcnt vmcnt(" #n ")" ::: "memory")
; #define PG8_WAIT_L(n) asm volatile("s_waitcnt lgkmcnt(" #n ")" ::: "memory")
; #define PG8_BAR __builtin_amdgcn_s_barrier()
; #define PG8_SCHED __builtin_amdgcn_sched_barrier(0)
; template <class Epi, bool BSEL = false>
; __device__ __forceinline__ void gemm_phase(LAS unsigned char* lds, const Gemm g, const Order& S, const Epi& E, const int tid) {
;     ...
;             PG8_LDA(At, 1, 1); PG8_STAGEB(PG8_SB(1, 0), b3, p2); PG8_STAGEB(PG8_SB(1, 1), b3 + h2, p2); PG8_STAGE(PG8_SA(1, 0), a3, voffA);
;             PG8_WAIT_V(8); PG8_WAIT_L(0); PG8_BAR; PG8_MMA(1, 0, At, B0); PG8_MMA(1, 1, At, B1); PG8_BAR; PG8_SCHED;
;         }
;         if constexpr (ALIGN_EPI) { if (wr == 0) PG8_BAR; }
	s_setprio 0
	s_add_i32 s42, s56, s15
	v_lshl_add_u64 v[188:189], v[188:189], 0, s[22:23]
	s_mov_b32 m0, s42
	ds_read_b128 v[184:187], v151 offset:49152
	ds_read_b128 v[192:195], v151 offset:50176
	ds_read_b128 v[196:199], v151 offset:51200
	ds_read_b128 v[202:205], v151 offset:52224
	ds_read_b128 v[206:209], v151 offset:53248
	ds_read_b128 v[210:213], v151 offset:54272
	ds_read_b128 v[214:217], v151 offset:55296
	ds_read_b128 v[218:221], v151 offset:56320
	global_load_lds_dwordx4 v[188:189], off
	s_add_i32 m0, s42, 0x2000
	s_add_u32 s40, s40, 0x40080
	v_lshl_add_u64 v[188:189], v[222:223], 0, s[22:23]
	s_addc_u32 s41, s41, 0
	s_add_i32 s42, s57, s15
	global_load_lds_dwordx4 v[188:189], off
	v_lshl_add_u64 v[188:189], s[40:41], 0, v[132:133]
	s_mov_b32 m0, s42
	s_nop 0
	global_load_lds_dwordx4 v[188:189], off
	v_lshl_add_u64 v[188:189], s[40:41], 0, v[136:137]
	s_add_i32 m0, s42, 0x2000
	s_nop 0
	global_load_lds_dwordx4 v[188:189], off
	v_lshl_add_u64 v[188:189], v[224:225], 0, s[22:23]
	s_mov_b32 m0, s45
	s_nop 0
	global_load_lds_dwordx4 v[188:189], off
	v_lshl_add_u64 v[188:189], v[226:227], 0, s[22:23]
	s_mov_b32 m0, s46
	s_nop 0
	global_load_lds_dwordx4 v[188:189], off
	s_waitcnt vmcnt(8)
	s_waitcnt lgkmcnt(0)
	s_setprio 1
	s_barrier
	v_mfma_f32_16x16x32_bf16 v[60:63], v[152:155], v[184:187], v[60:63]
	v_mfma_f32_16x16x32_bf16 v[56:59], v[160:163], v[184:187], v[56:59]
	v_mfma_f32_16x16x32_bf16 v[44:47], v[152:155], v[196:199], v[44:47]
	v_mfma_f32_16x16x32_bf16 v[40:43], v[160:163], v[196:199], v[40:43]
	v_mfma_f32_16x16x32_bf16 v[28:31], v[152:155], v[206:209], v[28:31]
	v_mfma_f32_16x16x32_bf16 v[24:27], v[160:163], v[206:209], v[24:27]
	v_mfma_f32_16x16x32_bf16 v[12:15], v[152:155], v[214:217], v[12:15]
	v_mfma_f32_16x16x32_bf16 v[8:11], v[160:163], v[214:217], v[8:11]
	v_mfma_f32_16x16x32_bf16 v[60:63], v[156:159], v[192:195], v[60:63]
	v_mfma_f32_16x16x32_bf16 v[56:59], v[164:167], v[192:195], v[56:59]
	v_mfma_f32_16x16x32_bf16 v[44:47], v[156:159], v[202:205], v[44:47]
	v_mfma_f32_16x16x32_bf16 v[40:43], v[164:167], v[202:205], v[40:43]
	v_mfma_f32_16x16x32_bf16 v[28:31], v[156:159], v[210:213], v[28:31]
	v_mfma_f32_16x16x32_bf16 v[24:27], v[164:167], v[210:213], v[24:27]
	v_mfma_f32_16x16x32_bf16 v[12:15], v[156:159], v[218:221], v[12:15]
	v_mfma_f32_16x16x32_bf16 v[8:11], v[164:167], v[218:221], v[8:11]
	v_mfma_f32_16x16x32_bf16 v[52:55], v[168:171], v[184:187], v[52:55]
	v_mfma_f32_16x16x32_bf16 v[48:51], v[176:179], v[184:187], v[48:51]
	v_mfma_f32_16x16x32_bf16 v[36:39], v[168:171], v[196:199], v[36:39]
	v_mfma_f32_16x16x32_bf16 v[32:35], v[176:179], v[196:199], v[32:35]
	v_mfma_f32_16x16x32_bf16 v[20:23], v[168:171], v[206:209], v[20:23]
	v_mfma_f32_16x16x32_bf16 v[16:19], v[176:179], v[206:209], v[16:19]
	v_mfma_f32_16x16x32_bf16 v[4:7], v[168:171], v[214:217], v[4:7]
	v_mfma_f32_16x16x32_bf16 v[0:3], v[176:179], v[214:217], v[0:3]
	v_mfma_f32_16x16x32_bf16 v[52:55], v[172:175], v[192:195], v[52:55]
	v_mfma_f32_16x16x32_bf16 v[48:51], v[180:183], v[192:195], v[48:51]
	v_mfma_f32_16x16x32_bf16 v[36:39], v[172:175], v[202:205], v[36:39]
	v_mfma_f32_16x16x32_bf16 v[32:35], v[180:183], v[202:205], v[32:35]
	v_mfma_f32_16x16x32_bf16 v[20:23], v[172:175], v[210:213], v[20:23]
	v_mfma_f32_16x16x32_bf16 v[16:19], v[180:183], v[210:213], v[16:19]
	v_mfma_f32_16x16x32_bf16 v[4:7], v[172:175], v[218:221], v[4:7]
	v_mfma_f32_16x16x32_bf16 v[0:3], v[180:183], v[218:221], v[0:3]
	s_barrier
	s_setprio 0
	s_add_i32 s55, s55, 2
	s_add_u32 s38, s38, 0x100
	s_addc_u32 s39, s39, 0
	s_cmp_gt_u32 s55, 13
	s_cbranch_scc0 .LBB0_1101
	s_and_b64 vcc, exec, s[24:25]
	s_cbranch_vccz .LBB0_1104
	s_barrier

; #define PG8_STAGE(bufoff, gbase, voff) do { _Pragma("unroll") for (int _i = 0; _i < 2; ++_i) \
;         __builtin_amdgcn_global_load_lds((const unsigned*)((const char*)(gbase) + (voff)[_i]), (LAS unsigned*)(lds + (bufoff) + ldsw + _i * 8192), 16, 0, 0); } while (0)
; #define PG8_STAGEB(bufoff, gbase, perm) do { _Pragma("unroll") for (int _i = 0; _i < 2; ++_i) \
;         __builtin_amdgcn_global_load_lds((const unsigned*)((const char*)(gbase) + ((BSEL && (perm)) ? voffBp[_i] : voffB[_i])), (LAS unsigned*)(lds + (bufoff) + ldsw + _i * 8192), 16, 0, 0); } while (0)
; #define PG8_LDA(dst, b, h) do { _Pragma("unroll") for (int m = 0; m < 4; ++m) _Pragma("unroll") for (int k = 0; k < 2; ++k) dst[m][k] = *(const LAS bf16x8*)(lds + PG8_SA(b, h) + aoff + m * 2048 + k * 1024); } while (0)
; #define PG8_LDB(dst, b, h) do { _Pragma("unroll") for (int n = 0; n < 2; ++n) _Pragma("unroll") for (int k = 0; k < 2; ++k) dst[n][k] = *(const LAS bf16x8*)(lds + PG8_SB(b, h) + boff + n * 2048 + k * 1024); } while (0)
; #define PG8_WAIT_V(n) asm volatile("s_waitcnt vmcnt(" #n ")" ::: "memory")
; #define PG8_WAIT_L(n) asm volatile("s_waitcnt lgkmcnt(" #n ")" ::: "memory")
; #define PG8_BAR __builtin_amdgcn_s_barrier()
; #define PG8_SCHED __builtin_amdgcn_sched_barrier(0)
; template <class Epi, bool BSEL = false>
; __device__ __forceinline__ void gemm_phase(LAS unsigned char* lds, const Gemm g, const Order& S, const Epi& E, const int tid) {
;     ...
;         for (int t = 0; t < nt; t += 2) {
;             const bool last = (t == nt - 2);
;             const char* a1 = cA + (size_t)(t + 1) * kstep;
;             const char* a2 = last ? nA : cA + (size_t)(t + 2) * kstep; const char* b2 = last ? nB : cB + (size_t)(t + 2) * kstep;
;             const char* a3 = a2 + kstep; const char* b3 = b2 + kstep;
;             const bool p2 = last ? nP : cP; const size_t h2 = last ? nhB : chB;
;             PG8_LDB(B0, 0, 0); PG8_LDB(B1, 0, 1); PG8_SCHED; PG8_LDA(At, 0, 0); PG8_STAGE(PG8_SA(1, 1), a1 + hstepA, voffA);
;             PG8_WAIT_V(8); PG8_WAIT_L(0); PG8_BAR; PG8_MMA(0, 0, At, B0); PG8_MMA(0, 1, At, B1); PG8_BAR; PG8_SCHED;
;             PG8_LDA(At, 0, 1); PG8_STAGEB(PG8_SB(0, 0), b2, p2); PG8_STAGEB(PG8_SB(0, 1), b2 + h2, p2); PG8_STAGE(PG8_SA(0, 0), a2, voffA);
;             PG8_WAIT_V(8); PG8_WAIT_L(0); PG8_BAR; PG8_MMA(1, 0, At, B0); PG8_MMA(1, 1, At, B1); PG8_BAR; PG8_SCHED;
.LBB0_1271:
	v_add_u32_e32 v162, s45, v147
	v_add_u32_e32 v178, s46, v147
	s_add_u32 s2, s8, s40
	ds_read_b128 v[150:153], v162
	ds_read_b128 v[154:157], v162 offset:1024
	ds_read_b128 v[158:161], v162 offset:2048
	ds_read_b128 v[162:165], v162 offset:3072
	ds_read_b128 v[166:169], v178
	ds_read_b128 v[170:173], v178 offset:1024
	ds_read_b128 v[174:177], v178 offset:2048
	ds_read_b128 v[178:181], v178 offset:3072
	s_addc_u32 s3, s9, s41
	s_add_u32 s2, s2, 0x100
	s_addc_u32 s3, s3, 0
	s_add_u32 s57, s27, s40
	s_addc_u32 s58, s51, s41
	s_cmpk_eq_i32 s40, 0x700
	s_cselect_b32 s37, s52, s3
	s_cselect_b32 s36, s53, s2
	s_cselect_b32 s3, s54, s58
	s_cselect_b32 s2, s55, s57
	v_lshl_add_u64 v[198:199], v[142:143], 0, s[40:41]
	s_add_i32 m0, s7, 0xc000
	ds_read_b128 v[182:185], v149
	ds_read_b128 v[186:189], v149 offset:1024
	ds_read_b128 v[190:193], v149 offset:2048
	ds_read_b128 v[194:197], v149 offset:3072
	ds_read_b128 v[202:205], v149 offset:4096
	ds_read_b128 v[206:209], v149 offset:5120
	ds_read_b128 v[210:213], v149 offset:6144
	ds_read_b128 v[214:217], v149 offset:7168
	global_load_lds_dwordx4 v[198:199], off
	v_lshl_add_u64 v[198:199], v[144:145], 0, s[40:41]
	s_add_i32 m0, s7, 0xe000
	s_nop 0
	global_load_lds_dwordx4 v[198:199], off
	s_waitcnt vmcnt(8)
	s_waitcnt lgkmcnt(0)
	s_setprio 1
	s_barrier
	v_mfma_f32_16x16x32_bf16 v[124:127], v[150:153], v[182:185], v[124:127]
	v_mfma_f32_16x16x32_bf16 v[120:123], v[158:161], v[182:185], v[120:123]
	v_mfma_f32_16x16x32_bf16 v[116:119], v[150:153], v[190:193], v[116:119]
	v_mfma_f32_16x16x32_bf16 v[112:115], v[158:161], v[190:193], v[112:115]
	v_mfma_f32_16x16x32_bf16 v[108:111], v[150:153], v[202:205], v[108:111]
	v_mfma_f32_16x16x32_bf16 v[104:107], v[158:161], v[202:205], v[104:107]
	v_mfma_f32_16x16x32_bf16 v[100:103], v[150:153], v[210:213], v[100:103]
	v_mfma_f32_16x16x32_bf16 v[96:99], v[158:161], v[210:213], v[96:99]
	v_mfma_f32_16x16x32_bf16 v[124:127], v[154:157], v[186:189], v[124:127]
	v_mfma_f32_16x16x32_bf16 v[120:123], v[162:165], v[186:189], v[120:123]
	v_mfma_f32_16x16x32_bf16 v[116:119], v[154:157], v[194:197], v[116:119]
	v_mfma_f32_16x16x32_bf16 v[112:115], v[162:165], v[194:197], v[112:115]
	v_mfma_f32_16x16x32_bf16 v[108:111], v[154:157], v[206:209], v[108:111]
	v_mfma_f32_16x16x32_bf16 v[104:107], v[162:165], v[206:209], v[104:107]
	v_mfma_f32_16x16x32_bf16 v[100:103], v[154:157], v[214:217], v[100:103]
	v_mfma_f32_16x16x32_bf16 v[96:99], v[162:165], v[214:217], v[96:99]
	v_mfma_f32_16x16x32_bf16 v[92:95], v[166:169], v[182:185], v[92:95]
	v_mfma_f32_16x16x32_bf16 v[88:91], v[174:177], v[182:185], v[88:91]
	v_mfma_f32_16x16x32_bf16 v[84:87], v[166:169], v[190:193], v[84:87]
	v_mfma_f32_16x16x32_bf16 v[80:83], v[174:177], v[190:193], v[80:83]
	v_mfma_f32_16x16x32_bf16 v[76:79], v[166:169], v[202:205], v[76:79]
	v_mfma_f32_16x16x32_bf16 v[72:75], v[174:177], v[202:205], v[72:75]
	v_mfma_f32_16x16x32_bf16 v[68:71], v[166:169], v[210:213], v[68:71]
	v_mfma_f32_16x16x32_bf16 v[64:67], v[174:177], v[210:213], v[64:67]
	v_mfma_f32_16x16x32_bf16 v[92:95], v[170:173], v[186:189], v[92:95]
	v_mfma_f32_16x16x32_bf16 v[88:91], v[178:181], v[186:189], v[88:91]
	v_mfma_f32_16x16x32_bf16 v[84:87], v[170:173], v[194:197], v[84:87]
	v_mfma_f32_16x16x32_bf16 v[80:83], v[178:181], v[194:197], v[80:83]
	v_mfma_f32_16x16x32_bf16 v[76:79], v[170:173], v[206:209], v[76:79]
	v_mfma_f32_16x16x32_bf16 v[72:75], v[178:181], v[206:209], v[72:75]
	v_mfma_f32_16x16x32_bf16 v[68:71], v[170:173], v[214:217], v[68:71]
	v_mfma_f32_16x16x32_bf16 v[64:67], v[178:181], v[214:217], v[64:67]
	s_barrier
	s_setprio 0
	s_add_i32 s57, s45, s12
	v_lshl_add_u64 v[198:199], s[2:3], 0, v[132:133]
	s_mov_b32 m0, s57
	ds_read_b128 v[182:185], v149 offset:16384
	ds_read_b128 v[186:189], v149 offset:17408
	ds_read_b128 v[190:193], v149 offset:18432
	ds_read_b128 v[194:197], v149 offset:19456
	ds_read_b128 v[202:205], v149 offset:20480
	ds_read_b128 v[206:209], v149 offset:21504
	ds_read_b128 v[210:213], v149 offset:22528
	ds_read_b128 v[214:217], v149 offset:23552
	global_load_lds_dwordx4 v[198:199], off
	s_add_i32 m0, s57, 0x2000
	s_add_u32 s58, s2, 0x40000
	v_lshl_add_u64 v[218:219], s[2:3], 0, v[128:129]
	s_addc_u32 s59, s3, 0
	s_add_i32 s57, s46, s12
	global_load_lds_dwordx4 v[218:219], off
	v_lshl_add_u64 v[220:221], s[58:59], 0, v[132:133]
	s_mov_b32 m0, s57
	v_lshl_add_u64 v[222:223], s[36:37], 0, v[130:131]
	global_load_lds_dwordx4 v[220:221], off
	v_lshl_add_u64 v[220:221], s[58:59], 0, v[128:129]
	s_add_i32 m0, s57, 0x2000
	s_nop 0
	global_load_lds_dwordx4 v[220:221], off
	v_lshl_add_u64 v[220:221], s[36:37], 0, v[134:135]
	s_mov_b32 m0, s7
	s_nop 0
	global_load_lds_dwordx4 v[220:221], off
	s_mov_b32 m0, s15
	s_nop 0
	global_load_lds_dwordx4 v[222:223], off
	s_waitcnt vmcnt(8)
	s_waitcnt lgkmcnt(0)
	s_setprio 1
	s_barrier
; #define PG8_STAGE(bufoff, gbase, voff) do { _Pragma("unroll") for (int _i = 0; _i < 2; ++_i) \
;         __builtin_amdgcn_global_load_lds((const unsigned*)((const char*)(gbase) + (voff)[_i]), (LAS unsigned*)(lds + (bufoff) + ldsw + _i * 8192), 16, 0, 0); } while (0)
; #define PG8_LDA(dst, b, h) do { _Pragma("unroll") for (int m = 0; m < 4; ++m) _Pragma("unroll") for (int k = 0; k < 2; ++k) dst[m][k] = *(const LAS bf16x8*)(lds + PG8_SA(b, h) + aoff + m * 2048 + k * 1024); } while (0)
; #define PG8_LDB(dst, b, h) do { _Pragma("unroll") for (int n = 0; n < 2; ++n) _Pragma("unroll") for (int k = 0; k < 2; ++k) dst[n][k] = *(const LAS bf16x8*)(lds + PG8_SB(b, h) + boff + n * 2048 + k * 1024); } while (0)
; #define PG8_MMA(ai, bj, At, Bt) do { __builtin_amdgcn_s_setprio(1); _Pragma("unroll") for (int m = 0; m < 4; ++m) _Pragma("unroll") for (int n = 0; n < 2; ++n) _Pragma("unroll") for (int k = 0; k < 2; ++k) \
;         acc[ai][bj][m][n] = __builtin_amdgcn_mfma_f32_16x16x32_bf16(Bt[n][k], At[m][k], acc[ai][bj][m][n], 0, 0, 0); __builtin_amdgcn_s_setprio(0); } while (0)
; #define PG8_WAIT_V(n) asm volatile("s_waitcnt vmcnt(" #n ")" ::: "memory")
; #define PG8_WAIT_L(n) asm volatile("s_waitcnt lgkmcnt(" #n ")" ::: "memory")
; #define PG8_BAR __builtin_amdgcn_s_barrier()
; #define PG8_SCHED __builtin_amdgcn_sched_barrier(0)
; template <class Epi, bool BSEL = false>
; __device__ __forceinline__ void gemm_phase(LAS unsigned char* lds, const Gemm g, const Order& S, const Epi& E, const int tid) {
;     ...
;             PG8_WAIT_V(8); PG8_WAIT_L(0); PG8_BAR; PG8_MMA(1, 0, At, B0); PG8_MMA(1, 1, At, B1); PG8_BAR; PG8_SCHED;
;             PG8_LDB(B0, 1, 0); PG8_LDB(B1, 1, 1); PG8_SCHED; PG8_LDA(At, 1, 0); PG8_STAGE(PG8_SA(0, 1), a2 + hstepA, voffA);
;             PG8_WAIT_V(8); PG8_WAIT_L(0); PG8_BAR; PG8_MMA(0, 0, At, B0); PG8_MMA(0, 1, At, B1); PG8_BAR; PG8_SCHED;
	v_mfma_f32_16x16x32_bf16 v[60:63], v[150:153], v[182:185], v[60:63]
	v_mfma_f32_16x16x32_bf16 v[56:59], v[158:161], v[182:185], v[56:59]
	v_mfma_f32_16x16x32_bf16 v[52:55], v[150:153], v[190:193], v[52:55]
	v_mfma_f32_16x16x32_bf16 v[48:51], v[158:161], v[190:193], v[48:51]
	v_mfma_f32_16x16x32_bf16 v[44:47], v[150:153], v[202:205], v[44:47]
	v_mfma_f32_16x16x32_bf16 v[40:43], v[158:161], v[202:205], v[40:43]
	v_mfma_f32_16x16x32_bf16 v[36:39], v[150:153], v[210:213], v[36:39]
	v_mfma_f32_16x16x32_bf16 v[32:35], v[158:161], v[210:213], v[32:35]
	v_mfma_f32_16x16x32_bf16 v[60:63], v[154:157], v[186:189], v[60:63]
	v_mfma_f32_16x16x32_bf16 v[56:59], v[162:165], v[186:189], v[56:59]
	v_mfma_f32_16x16x32_bf16 v[52:55], v[154:157], v[194:197], v[52:55]
	v_mfma_f32_16x16x32_bf16 v[48:51], v[162:165], v[194:197], v[48:51]
	v_mfma_f32_16x16x32_bf16 v[44:47], v[154:157], v[206:209], v[44:47]
	v_mfma_f32_16x16x32_bf16 v[40:43], v[162:165], v[206:209], v[40:43]
	v_mfma_f32_16x16x32_bf16 v[36:39], v[154:157], v[214:217], v[36:39]
	v_mfma_f32_16x16x32_bf16 v[32:35], v[162:165], v[214:217], v[32:35]
	v_mfma_f32_16x16x32_bf16 v[28:31], v[166:169], v[182:185], v[28:31]
	v_mfma_f32_16x16x32_bf16 v[24:27], v[174:177], v[182:185], v[24:27]
	v_mfma_f32_16x16x32_bf16 v[20:23], v[166:169], v[190:193], v[20:23]
	v_mfma_f32_16x16x32_bf16 v[16:19], v[174:177], v[190:193], v[16:19]
	v_mfma_f32_16x16x32_bf16 v[12:15], v[166:169], v[202:205], v[12:15]
	v_mfma_f32_16x16x32_bf16 v[8:11], v[174:177], v[202:205], v[8:11]
	v_mfma_f32_16x16x32_bf16 v[4:7], v[166:169], v[210:213], v[4:7]
	v_mfma_f32_16x16x32_bf16 v[0:3], v[174:177], v[210:213], v[0:3]
	v_mfma_f32_16x16x32_bf16 v[28:31], v[170:173], v[186:189], v[28:31]
	v_mfma_f32_16x16x32_bf16 v[24:27], v[178:181], v[186:189], v[24:27]
	v_mfma_f32_16x16x32_bf16 v[20:23], v[170:173], v[194:197], v[20:23]
	v_mfma_f32_16x16x32_bf16 v[16:19], v[178:181], v[194:197], v[16:19]
	v_mfma_f32_16x16x32_bf16 v[12:15], v[170:173], v[206:209], v[12:15]
	v_mfma_f32_16x16x32_bf16 v[8:11], v[178:181], v[206:209], v[8:11]
	v_mfma_f32_16x16x32_bf16 v[4:7], v[170:173], v[214:217], v[4:7]
	v_mfma_f32_16x16x32_bf16 v[0:3], v[178:181], v[214:217], v[0:3]
	s_barrier
	s_setprio 0
	s_add_i32 s57, 0, 0x18000
	s_add_i32 s58, 0, 0x1c000
	v_add_u32_e32 v162, s57, v147
	v_add_u32_e32 v178, s58, v147
	ds_read_b128 v[150:153], v162
	ds_read_b128 v[154:157], v162 offset:1024
	ds_read_b128 v[158:161], v162 offset:2048
	ds_read_b128 v[162:165], v162 offset:3072
	ds_read_b128 v[166:169], v178
	ds_read_b128 v[170:173], v178 offset:1024
	ds_read_b128 v[174:177], v178 offset:2048
	ds_read_b128 v[178:181], v178 offset:3072
	s_add_u32 s36, s36, 0x40000
	s_addc_u32 s37, s37, 0
	s_mov_b32 m0, s20
	v_lshl_add_u64 v[224:225], s[36:37], 0, v[134:135]
	ds_read_b128 v[182:185], v149 offset:32768
	ds_read_b128 v[186:189], v149 offset:33792
	ds_read_b128 v[190:193], v149 offset:34816
	ds_read_b128 v[194:197], v149 offset:35840
	ds_read_b128 v[202:205], v149 offset:36864
	ds_read_b128 v[206:209], v149 offset:37888
	ds_read_b128 v[210:213], v149 offset:38912
	ds_read_b128 v[214:217], v149 offset:39936
	global_load_lds_dwordx4 v[224:225], off
	v_lshl_add_u64 v[224:225], s[36:37], 0, v[130:131]
	s_mov_b32 m0, s21
	s_nop 0
	global_load_lds_dwordx4 v[224:225], off
	s_waitcnt vmcnt(8)
	s_waitcnt lgkmcnt(0)
	s_setprio 1
	s_barrier
	v_mfma_f32_16x16x32_bf16 v[124:127], v[150:153], v[182:185], v[124:127]
	v_mfma_f32_16x16x32_bf16 v[120:123], v[158:161], v[182:185], v[120:123]
	v_mfma_f32_16x16x32_bf16 v[116:119], v[150:153], v[190:193], v[116:119]
	v_mfma_f32_16x16x32_bf16 v[112:115], v[158:161], v[190:193], v[112:115]
	v_mfma_f32_16x16x32_bf16 v[108:111], v[150:153], v[202:205], v[108:111]
	v_mfma_f32_16x16x32_bf16 v[104:107], v[158:161], v[202:205], v[104:107]
	v_mfma_f32_16x16x32_bf16 v[100:103], v[150:153], v[210:213], v[100:103]
	v_mfma_f32_16x16x32_bf16 v[96:99], v[158:161], v[210:213], v[96:99]
	v_mfma_f32_16x16x32_bf16 v[124:127], v[154:157], v[186:189], v[124:127]
	v_mfma_f32_16x16x32_bf16 v[120:123], v[162:165], v[186:189], v[120:123]
	v_mfma_f32_16x16x32_bf16 v[116:119], v[154:157], v[194:197], v[116:119]
	v_mfma_f32_16x16x32_bf16 v[112:115], v[162:165], v[194:197], v[112:115]
	v_mfma_f32_16x16x32_bf16 v[108:111], v[154:157], v[206:209], v[108:111]
	v_mfma_f32_16x16x32_bf16 v[104:107], v[162:165], v[206:209], v[104:107]
	v_mfma_f32_16x16x32_bf16 v[100:103], v[154:157], v[214:217], v[100:103]
	v_mfma_f32_16x16x32_bf16 v[96:99], v[162:165], v[214:217], v[96:99]
	v_mfma_f32_16x16x32_bf16 v[92:95], v[166:169], v[182:185], v[92:95]
	v_mfma_f32_16x16x32_bf16 v[88:91], v[174:177], v[182:185], v[88:91]
	v_mfma_f32_16x16x32_bf16 v[84:87], v[166:169], v[190:193], v[84:87]
	v_mfma_f32_16x16x32_bf16 v[80:83], v[174:177], v[190:193], v[80:83]
	v_mfma_f32_16x16x32_bf16 v[76:79], v[166:169], v[202:205], v[76:79]
	v_mfma_f32_16x16x32_bf16 v[72:75], v[174:177], v[202:205], v[72:75]
	v_mfma_f32_16x16x32_bf16 v[68:71], v[166:169], v[210:213], v[68:71]
	v_mfma_f32_16x16x32_bf16 v[64:67], v[174:177], v[210:213], v[64:67]
	v_mfma_f32_16x16x32_bf16 v[92:95], v[170:173], v[186:189], v[92:95]
	v_mfma_f32_16x16x32_bf16 v[88:91], v[178:181], v[186:189], v[88:91]
	v_mfma_f32_16x16x32_bf16 v[84:87], v[170:173], v[194:197], v[84:87]
	v_mfma_f32_16x16x32_bf16 v[80:83], v[178:181], v[194:197], v[80:83]
	v_mfma_f32_16x16x32_bf16 v[76:79], v[170:173], v[206:209], v[76:79]
	v_mfma_f32_16x16x32_bf16 v[72:75], v[178:181], v[206:209], v[72:75]
	v_mfma_f32_16x16x32_bf16 v[68:71], v[170:173], v[214:217], v[68:71]
	v_mfma_f32_16x16x32_bf16 v[64:67], v[178:181], v[214:217], v[64:67]
	s_barrier
; #define PG8_STAGE(bufoff, gbase, voff) do { _Pragma("unroll") for (int _i = 0; _i < 2; ++_i) \
;         __builtin_amdgcn_global_load_lds((const unsigned*)((const char*)(gbase) + (voff)[_i]), (LAS unsigned*)(lds + (bufoff) + ldsw + _i * 8192), 16, 0, 0); } while (0)
; #define PG8_STAGEB(bufoff, gbase, perm) do { _Pragma("unroll") for (int _i = 0; _i < 2; ++_i) \
;         __builtin_amdgcn_global_load_lds((const unsigned*)((const char*)(gbase) + ((BSEL && (perm)) ? voffBp[_i] : voffB[_i])), (LAS unsigned*)(lds + (bufoff) + ldsw + _i * 8192), 16, 0, 0); } while (0)
; #define PG8_LDA(dst, b, h) do { _Pragma("unroll") for (int m = 0; m < 4; ++m) _Pragma("unroll") for (int k = 0; k < 2; ++k) dst[m][k] = *(const LAS bf16x8*)(lds + PG8_SA(b, h) + aoff + m * 2048 + k * 1024); } while (0)
; #define PG8_MMA(ai, bj, At, Bt) do { __builtin_amdgcn_s_setprio(1); _Pragma("unroll") for (int m = 0; m < 4; ++m) _Pragma("unroll") for (int n = 0; n < 2; ++n) _Pragma("unroll") for (int k = 0; k < 2; ++k) \
;         acc[ai][bj][m][n] = __builtin_amdgcn_mfma_f32_16x16x32_bf16(Bt[n][k], At[m][k], acc[ai][bj][m][n], 0, 0, 0); __builtin_amdgcn_s_setprio(0); } while (0)
; #define PG8_WAIT_V(n) asm volatile("s_waitcnt vmcnt(" #n ")" ::: "memory")
; #define PG8_WAIT_L(n) asm volatile("s_waitcnt lgkmcnt(" #n ")" ::: "memory")
; #define PG8_BAR __builtin_amdgcn_s_barrier()
; #define PG8_SCHED __builtin_amdgcn_sched_barrier(0)
; template <class Epi, bool BSEL = false>
; __device__ __forceinline__ void gemm_phase(LAS unsigned char* lds, const Gemm g, const Order& S, const Epi& E, const int tid) {
;     ...
;             PG8_LDA(At, 1, 1); PG8_STAGEB(PG8_SB(1, 0), b3, p2); PG8_STAGEB(PG8_SB(1, 1), b3 + h2, p2); PG8_STAGE(PG8_SA(1, 0), a3, voffA);
;             PG8_WAIT_V(8); PG8_WAIT_L(0); PG8_BAR; PG8_MMA(1, 0, At, B0); PG8_MMA(1, 1, At, B1); PG8_BAR; PG8_SCHED;
;         }
;         if constexpr (ALIGN_EPI) { if (wr == 0) PG8_BAR; }
	s_setprio 0
	s_add_i32 s36, s57, s12
	v_lshl_add_u64 v[198:199], v[198:199], 0, s[22:23]
	s_mov_b32 m0, s36
	ds_read_b128 v[182:185], v149 offset:49152
	ds_read_b128 v[186:189], v149 offset:50176
	ds_read_b128 v[190:193], v149 offset:51200
	ds_read_b128 v[194:197], v149 offset:52224
	ds_read_b128 v[202:205], v149 offset:53248
	ds_read_b128 v[206:209], v149 offset:54272
	ds_read_b128 v[210:213], v149 offset:55296
	ds_read_b128 v[214:217], v149 offset:56320
	global_load_lds_dwordx4 v[198:199], off
	s_add_i32 m0, s36, 0x2000
	s_add_u32 s2, s2, 0x40080
	v_lshl_add_u64 v[198:199], v[218:219], 0, s[22:23]
	s_addc_u32 s3, s3, 0
	s_add_i32 s36, s58, s12
	global_load_lds_dwordx4 v[198:199], off
	v_lshl_add_u64 v[198:199], s[2:3], 0, v[132:133]
	s_mov_b32 m0, s36
	s_nop 0
	global_load_lds_dwordx4 v[198:199], off
	v_lshl_add_u64 v[198:199], s[2:3], 0, v[128:129]
	s_add_i32 m0, s36, 0x2000
	s_nop 0
	global_load_lds_dwordx4 v[198:199], off
	v_lshl_add_u64 v[198:199], v[220:221], 0, s[22:23]
	s_mov_b32 m0, s43
	s_nop 0
	global_load_lds_dwordx4 v[198:199], off
	v_lshl_add_u64 v[198:199], v[222:223], 0, s[22:23]
	s_mov_b32 m0, s44
	s_nop 0
	global_load_lds_dwordx4 v[198:199], off
	s_waitcnt vmcnt(8)
	s_waitcnt lgkmcnt(0)
	s_setprio 1
	s_barrier
	v_mfma_f32_16x16x32_bf16 v[60:63], v[150:153], v[182:185], v[60:63]
	v_mfma_f32_16x16x32_bf16 v[56:59], v[158:161], v[182:185], v[56:59]
	v_mfma_f32_16x16x32_bf16 v[52:55], v[150:153], v[190:193], v[52:55]
	v_mfma_f32_16x16x32_bf16 v[48:51], v[158:161], v[190:193], v[48:51]
	v_mfma_f32_16x16x32_bf16 v[44:47], v[150:153], v[202:205], v[44:47]
	v_mfma_f32_16x16x32_bf16 v[40:43], v[158:161], v[202:205], v[40:43]
	v_mfma_f32_16x16x32_bf16 v[36:39], v[150:153], v[210:213], v[36:39]
	v_mfma_f32_16x16x32_bf16 v[32:35], v[158:161], v[210:213], v[32:35]
	v_mfma_f32_16x16x32_bf16 v[60:63], v[154:157], v[186:189], v[60:63]
	v_mfma_f32_16x16x32_bf16 v[56:59], v[162:165], v[186:189], v[56:59]
	v_mfma_f32_16x16x32_bf16 v[52:55], v[154:157], v[194:197], v[52:55]
	v_mfma_f32_16x16x32_bf16 v[48:51], v[162:165], v[194:197], v[48:51]
	v_mfma_f32_16x16x32_bf16 v[44:47], v[154:157], v[206:209], v[44:47]
	v_mfma_f32_16x16x32_bf16 v[40:43], v[162:165], v[206:209], v[40:43]
	v_mfma_f32_16x16x32_bf16 v[36:39], v[154:157], v[214:217], v[36:39]
	v_mfma_f32_16x16x32_bf16 v[32:35], v[162:165], v[214:217], v[32:35]
	v_mfma_f32_16x16x32_bf16 v[28:31], v[166:169], v[182:185], v[28:31]
	v_mfma_f32_16x16x32_bf16 v[24:27], v[174:177], v[182:185], v[24:27]
	v_mfma_f32_16x16x32_bf16 v[20:23], v[166:169], v[190:193], v[20:23]
	v_mfma_f32_16x16x32_bf16 v[16:19], v[174:177], v[190:193], v[16:19]
	v_mfma_f32_16x16x32_bf16 v[12:15], v[166:169], v[202:205], v[12:15]
	v_mfma_f32_16x16x32_bf16 v[8:11], v[174:177], v[202:205], v[8:11]
	v_mfma_f32_16x16x32_bf16 v[4:7], v[166:169], v[210:213], v[4:7]
	v_mfma_f32_16x16x32_bf16 v[0:3], v[174:177], v[210:213], v[0:3]
	v_mfma_f32_16x16x32_bf16 v[28:31], v[170:173], v[186:189], v[28:31]
	v_mfma_f32_16x16x32_bf16 v[24:27], v[178:181], v[186:189], v[24:27]
	v_mfma_f32_16x16x32_bf16 v[20:23], v[170:173], v[194:197], v[20:23]
	v_mfma_f32_16x16x32_bf16 v[16:19], v[178:181], v[194:197], v[16:19]
	v_mfma_f32_16x16x32_bf16 v[12:15], v[170:173], v[206:209], v[12:15]
	v_mfma_f32_16x16x32_bf16 v[8:11], v[178:181], v[206:209], v[8:11]
	v_mfma_f32_16x16x32_bf16 v[4:7], v[170:173], v[214:217], v[4:7]
	v_mfma_f32_16x16x32_bf16 v[0:3], v[178:181], v[214:217], v[0:3]
	s_barrier
	s_setprio 0
	s_add_i32 s56, s56, 2
	s_add_u32 s40, s40, 0x100
	s_addc_u32 s41, s41, 0
	s_cmp_gt_u32 s56, 13
	s_cbranch_scc0 .LBB0_1271
	s_and_b64 vcc, exec, s[24:25]
	s_cbranch_vccz .LBB0_1274
	s_barrier

; #define PG8_STAGE(bufoff, gbase, voff) do { _Pragma("unroll") for (int _i = 0; _i < 2; ++_i) \
;         __builtin_amdgcn_global_load_lds((const unsigned*)((const char*)(gbase) + (voff)[_i]), (LAS unsigned*)(lds + (bufoff) + ldsw + _i * 8192), 16, 0, 0); } while (0)
; #define PG8_STAGEB(bufoff, gbase, perm) do { _Pragma("unroll") for (int _i = 0; _i < 2; ++_i) \
;         __builtin_amdgcn_global_load_lds((const unsigned*)((const char*)(gbase) + ((BSEL && (perm)) ? voffBp[_i] : voffB[_i])), (LAS unsigned*)(lds + (bufoff) + ldsw + _i * 8192), 16, 0, 0); } while (0)
; #define PG8_LDA(dst, b, h) do { _Pragma("unroll") for (int m = 0; m < 4; ++m) _Pragma("unroll") for (int k = 0; k < 2; ++k) dst[m][k] = *(const LAS bf16x8*)(lds + PG8_SA(b, h) + aoff + m * 2048 + k * 1024); } while (0)
; #define PG8_LDB(dst, b, h) do { _Pragma("unroll") for (int n = 0; n < 2; ++n) _Pragma("unroll") for (int k = 0; k < 2; ++k) dst[n][k] = *(const LAS bf16x8*)(lds + PG8_SB(b, h) + boff + n * 2048 + k * 1024); } while (0)
; #define PG8_WAIT_V(n) asm volatile("s_waitcnt vmcnt(" #n ")" ::: "memory")
; #define PG8_WAIT_L(n) asm volatile("s_waitcnt lgkmcnt(" #n ")" ::: "memory")
; #define PG8_BAR __builtin_amdgcn_s_barrier()
; #define PG8_SCHED __builtin_amdgcn_sched_barrier(0)
; template <class Epi, bool BSEL = false>
; __device__ __forceinline__ void gemm_phase(LAS unsigned char* lds, const Gemm g, const Order& S, const Epi& E, const int tid) {
;     ...
;         for (int t = 0; t < nt; t += 2) {
;             const bool last = (t == nt - 2);
;             const char* a1 = cA + (size_t)(t + 1) * kstep;
;             const char* a2 = last ? nA : cA + (size_t)(t + 2) * kstep; const char* b2 = last ? nB : cB + (size_t)(t + 2) * kstep;
;             const char* a3 = a2 + kstep; const char* b3 = b2 + kstep;
;             const bool p2 = last ? nP : cP; const size_t h2 = last ? nhB : chB;
;             PG8_LDB(B0, 0, 0); PG8_LDB(B1, 0, 1); PG8_SCHED; PG8_LDA(At, 0, 0); PG8_STAGE(PG8_SA(1, 1), a1 + hstepA, voffA);
;             PG8_WAIT_V(8); PG8_WAIT_L(0); PG8_BAR; PG8_MMA(0, 0, At, B0); PG8_MMA(0, 1, At, B1); PG8_BAR; PG8_SCHED;
;             PG8_LDA(At, 0, 1); PG8_STAGEB(PG8_SB(0, 0), b2, p2); PG8_STAGEB(PG8_SB(0, 1), b2 + h2, p2); PG8_STAGE(PG8_SA(0, 0), a2, voffA);
;             PG8_WAIT_V(8); PG8_WAIT_L(0); PG8_BAR; PG8_MMA(1, 0, At, B0); PG8_MMA(1, 1, At, B1); PG8_BAR; PG8_SCHED;
.LBB0_1364:
	v_add_u32_e32 v172, s43, v129
	ds_read_b128 v[160:163], v172
	ds_read_b128 v[164:167], v172 offset:1024
	ds_read_b128 v[168:171], v172 offset:2048
	ds_read_b128 v[176:179], v172 offset:3072
	v_add_u32_e32 v172, s44, v129
	s_add_u32 s28, s6, s2
	ds_read_b128 v[180:183], v172
	ds_read_b128 v[184:187], v172 offset:1024
	ds_read_b128 v[188:191], v172 offset:2048
	ds_read_b128 v[192:195], v172 offset:3072
	s_addc_u32 s29, s7, s3
	s_add_u32 s28, s28, 0x100
	s_addc_u32 s29, s29, 0
	s_add_u32 s55, s1, s2
	s_addc_u32 s56, s49, s3
	s_cmpk_eq_i32 s2, 0x1500
	s_cselect_b32 s35, s50, s29
	s_cselect_b32 s34, s51, s28
	s_cselect_b32 s29, s52, s56
	s_cselect_b32 s28, s53, s55
	v_lshl_add_u64 v[172:173], v[156:157], 0, s[2:3]
	s_add_i32 m0, s20, 0xc000
	ds_read_b128 v[196:199], v175
	ds_read_b128 v[202:205], v175 offset:1024
	ds_read_b128 v[206:209], v175 offset:2048
	ds_read_b128 v[210:213], v175 offset:3072
	ds_read_b128 v[214:217], v175 offset:4096
	ds_read_b128 v[218:221], v175 offset:5120
	ds_read_b128 v[222:225], v175 offset:6144
	ds_read_b128 v[226:229], v175 offset:7168
	global_load_lds_dwordx4 v[172:173], off
	v_lshl_add_u64 v[172:173], v[158:159], 0, s[2:3]
	s_add_i32 m0, s20, 0xe000
	s_nop 0
	global_load_lds_dwordx4 v[172:173], off
	s_waitcnt vmcnt(8)
	s_waitcnt lgkmcnt(0)
	s_setprio 1
	s_barrier
	v_mfma_f32_16x16x32_bf16 v[124:127], v[160:163], v[196:199], v[124:127]
	v_mfma_f32_16x16x32_bf16 v[120:123], v[168:171], v[196:199], v[120:123]
	v_mfma_f32_16x16x32_bf16 v[116:119], v[160:163], v[206:209], v[116:119]
	v_mfma_f32_16x16x32_bf16 v[112:115], v[168:171], v[206:209], v[112:115]
	v_mfma_f32_16x16x32_bf16 v[108:111], v[160:163], v[214:217], v[108:111]
	v_mfma_f32_16x16x32_bf16 v[104:107], v[168:171], v[214:217], v[104:107]
	v_mfma_f32_16x16x32_bf16 v[100:103], v[160:163], v[222:225], v[100:103]
	v_mfma_f32_16x16x32_bf16 v[96:99], v[168:171], v[222:225], v[96:99]
	v_mfma_f32_16x16x32_bf16 v[124:127], v[164:167], v[202:205], v[124:127]
	v_mfma_f32_16x16x32_bf16 v[120:123], v[176:179], v[202:205], v[120:123]
	v_mfma_f32_16x16x32_bf16 v[116:119], v[164:167], v[210:213], v[116:119]
	v_mfma_f32_16x16x32_bf16 v[112:115], v[176:179], v[210:213], v[112:115]
	v_mfma_f32_16x16x32_bf16 v[108:111], v[164:167], v[218:221], v[108:111]
	v_mfma_f32_16x16x32_bf16 v[104:107], v[176:179], v[218:221], v[104:107]
	v_mfma_f32_16x16x32_bf16 v[100:103], v[164:167], v[226:229], v[100:103]
	v_mfma_f32_16x16x32_bf16 v[96:99], v[176:179], v[226:229], v[96:99]
	v_mfma_f32_16x16x32_bf16 v[92:95], v[180:183], v[196:199], v[92:95]
	v_mfma_f32_16x16x32_bf16 v[88:91], v[188:191], v[196:199], v[88:91]
	v_mfma_f32_16x16x32_bf16 v[84:87], v[180:183], v[206:209], v[84:87]
	v_mfma_f32_16x16x32_bf16 v[80:83], v[188:191], v[206:209], v[80:83]
	v_mfma_f32_16x16x32_bf16 v[76:79], v[180:183], v[214:217], v[76:79]
	v_mfma_f32_16x16x32_bf16 v[72:75], v[188:191], v[214:217], v[72:75]
	v_mfma_f32_16x16x32_bf16 v[68:71], v[180:183], v[222:225], v[68:71]
	v_mfma_f32_16x16x32_bf16 v[64:67], v[188:191], v[222:225], v[64:67]
	v_mfma_f32_16x16x32_bf16 v[92:95], v[184:187], v[202:205], v[92:95]
	v_mfma_f32_16x16x32_bf16 v[88:91], v[192:195], v[202:205], v[88:91]
	v_mfma_f32_16x16x32_bf16 v[84:87], v[184:187], v[210:213], v[84:87]
	v_mfma_f32_16x16x32_bf16 v[80:83], v[192:195], v[210:213], v[80:83]
	v_mfma_f32_16x16x32_bf16 v[76:79], v[184:187], v[218:221], v[76:79]
	v_mfma_f32_16x16x32_bf16 v[72:75], v[192:195], v[218:221], v[72:75]
	v_mfma_f32_16x16x32_bf16 v[68:71], v[184:187], v[226:229], v[68:71]
	v_mfma_f32_16x16x32_bf16 v[64:67], v[192:195], v[226:229], v[64:67]
	s_barrier
	s_setprio 0
	s_add_i32 s55, s43, s15
	v_lshl_add_u64 v[172:173], s[28:29], 0, v[130:131]
	s_mov_b32 m0, s55
	ds_read_b128 v[196:199], v175 offset:16384
	ds_read_b128 v[202:205], v175 offset:17408
	ds_read_b128 v[206:209], v175 offset:18432
	ds_read_b128 v[210:213], v175 offset:19456
	ds_read_b128 v[214:217], v175 offset:20480
	ds_read_b128 v[218:221], v175 offset:21504
	ds_read_b128 v[222:225], v175 offset:22528
	ds_read_b128 v[226:229], v175 offset:23552
	global_load_lds_dwordx4 v[172:173], off
	s_add_i32 m0, s55, 0x2000
	s_add_u32 s56, s28, 0xb0000
	v_lshl_add_u64 v[230:231], s[28:29], 0, v[132:133]
	s_addc_u32 s57, s29, 0
	s_add_i32 s55, s44, s15
	global_load_lds_dwordx4 v[230:231], off
	v_lshl_add_u64 v[232:233], s[56:57], 0, v[130:131]
	s_mov_b32 m0, s55
	v_lshl_add_u64 v[234:235], s[34:35], 0, v[132:133]
	global_load_lds_dwordx4 v[232:233], off
	v_lshl_add_u64 v[232:233], s[56:57], 0, v[132:133]
	s_add_i32 m0, s55, 0x2000
	s_nop 0
	global_load_lds_dwordx4 v[232:233], off
	v_lshl_add_u64 v[232:233], s[34:35], 0, v[130:131]
	s_mov_b32 m0, s20
	s_nop 0
	global_load_lds_dwordx4 v[232:233], off
	s_mov_b32 m0, s21
	s_nop 0
	global_load_lds_dwordx4 v[234:235], off
	s_waitcnt vmcnt(8)
	s_waitcnt lgkmcnt(0)
	s_setprio 1
	s_barrier
; #define PG8_STAGE(bufoff, gbase, voff) do { _Pragma("unroll") for (int _i = 0; _i < 2; ++_i) \
;         __builtin_amdgcn_global_load_lds((const unsigned*)((const char*)(gbase) + (voff)[_i]), (LAS unsigned*)(lds + (bufoff) + ldsw + _i * 8192), 16, 0, 0); } while (0)
; #define PG8_LDA(dst, b, h) do { _Pragma("unroll") for (int m = 0; m < 4; ++m) _Pragma("unroll") for (int k = 0; k < 2; ++k) dst[m][k] = *(const LAS bf16x8*)(lds + PG8_SA(b, h) + aoff + m * 2048 + k * 1024); } while (0)
; #define PG8_LDB(dst, b, h) do { _Pragma("unroll") for (int n = 0; n < 2; ++n) _Pragma("unroll") for (int k = 0; k < 2; ++k) dst[n][k] = *(const LAS bf16x8*)(lds + PG8_SB(b, h) + boff + n * 2048 + k * 1024); } while (0)
; #define PG8_MMA(ai, bj, At, Bt) do { __builtin_amdgcn_s_setprio(1); _Pragma("unroll") for (int m = 0; m < 4; ++m) _Pragma("unroll") for (int n = 0; n < 2; ++n) _Pragma("unroll") for (int k = 0; k < 2; ++k) \
;         acc[ai][bj][m][n] = __builtin_amdgcn_mfma_f32_16x16x32_bf16(Bt[n][k], At[m][k], acc[ai][bj][m][n], 0, 0, 0); __builtin_amdgcn_s_setprio(0); } while (0)
; #define PG8_WAIT_V(n) asm volatile("s_waitcnt vmcnt(" #n ")" ::: "memory")
; #define PG8_WAIT_L(n) asm volatile("s_waitcnt lgkmcnt(" #n ")" ::: "memory")
; #define PG8_BAR __builtin_amdgcn_s_barrier()
; #define PG8_SCHED __builtin_amdgcn_sched_barrier(0)
; template <class Epi, bool BSEL = false>
; __device__ __forceinline__ void gemm_phase(LAS unsigned char* lds, const Gemm g, const Order& S, const Epi& E, const int tid) {
;     ...
;             PG8_WAIT_V(8); PG8_WAIT_L(0); PG8_BAR; PG8_MMA(1, 0, At, B0); PG8_MMA(1, 1, At, B1); PG8_BAR; PG8_SCHED;
;             PG8_LDB(B0, 1, 0); PG8_LDB(B1, 1, 1); PG8_SCHED; PG8_LDA(At, 1, 0); PG8_STAGE(PG8_SA(0, 1), a2 + hstepA, voffA);
;             PG8_WAIT_V(8); PG8_WAIT_L(0); PG8_BAR; PG8_MMA(0, 0, At, B0); PG8_MMA(0, 1, At, B1); PG8_BAR; PG8_SCHED;
	v_mfma_f32_16x16x32_bf16 v[60:63], v[160:163], v[196:199], v[60:63]
	v_mfma_f32_16x16x32_bf16 v[56:59], v[168:171], v[196:199], v[56:59]
	v_mfma_f32_16x16x32_bf16 v[52:55], v[160:163], v[206:209], v[52:55]
	v_mfma_f32_16x16x32_bf16 v[48:51], v[168:171], v[206:209], v[48:51]
	v_mfma_f32_16x16x32_bf16 v[44:47], v[160:163], v[214:217], v[44:47]
	v_mfma_f32_16x16x32_bf16 v[40:43], v[168:171], v[214:217], v[40:43]
	v_mfma_f32_16x16x32_bf16 v[36:39], v[160:163], v[222:225], v[36:39]
	v_mfma_f32_16x16x32_bf16 v[32:35], v[168:171], v[222:225], v[32:35]
	v_mfma_f32_16x16x32_bf16 v[60:63], v[164:167], v[202:205], v[60:63]
	v_mfma_f32_16x16x32_bf16 v[56:59], v[176:179], v[202:205], v[56:59]
	v_mfma_f32_16x16x32_bf16 v[52:55], v[164:167], v[210:213], v[52:55]
	v_mfma_f32_16x16x32_bf16 v[48:51], v[176:179], v[210:213], v[48:51]
	v_mfma_f32_16x16x32_bf16 v[44:47], v[164:167], v[218:221], v[44:47]
	v_mfma_f32_16x16x32_bf16 v[40:43], v[176:179], v[218:221], v[40:43]
	v_mfma_f32_16x16x32_bf16 v[36:39], v[164:167], v[226:229], v[36:39]
	v_mfma_f32_16x16x32_bf16 v[32:35], v[176:179], v[226:229], v[32:35]
	v_mfma_f32_16x16x32_bf16 v[28:31], v[180:183], v[196:199], v[28:31]
	v_mfma_f32_16x16x32_bf16 v[24:27], v[188:191], v[196:199], v[24:27]
	v_mfma_f32_16x16x32_bf16 v[20:23], v[180:183], v[206:209], v[20:23]
	v_mfma_f32_16x16x32_bf16 v[16:19], v[188:191], v[206:209], v[16:19]
	v_mfma_f32_16x16x32_bf16 v[12:15], v[180:183], v[214:217], v[12:15]
	v_mfma_f32_16x16x32_bf16 v[8:11], v[188:191], v[214:217], v[8:11]
	v_mfma_f32_16x16x32_bf16 v[4:7], v[180:183], v[222:225], v[4:7]
	v_mfma_f32_16x16x32_bf16 v[0:3], v[188:191], v[222:225], v[0:3]
	v_mfma_f32_16x16x32_bf16 v[28:31], v[184:187], v[202:205], v[28:31]
	v_mfma_f32_16x16x32_bf16 v[24:27], v[192:195], v[202:205], v[24:27]
	v_mfma_f32_16x16x32_bf16 v[20:23], v[184:187], v[210:213], v[20:23]
	v_mfma_f32_16x16x32_bf16 v[16:19], v[192:195], v[210:213], v[16:19]
	v_mfma_f32_16x16x32_bf16 v[12:15], v[184:187], v[218:221], v[12:15]
	v_mfma_f32_16x16x32_bf16 v[8:11], v[192:195], v[218:221], v[8:11]
	v_mfma_f32_16x16x32_bf16 v[4:7], v[184:187], v[226:229], v[4:7]
	v_mfma_f32_16x16x32_bf16 v[0:3], v[192:195], v[226:229], v[0:3]
	s_barrier
	s_setprio 0
	s_add_i32 s55, 0, 0x18000
	s_add_i32 s56, 0, 0x1c000
	v_add_u32_e32 v176, s55, v129
	v_add_u32_e32 v192, s56, v129
	ds_read_b128 v[160:163], v176
	ds_read_b128 v[164:167], v176 offset:1024
	ds_read_b128 v[168:171], v176 offset:2048
	ds_read_b128 v[176:179], v176 offset:3072
	ds_read_b128 v[180:183], v192
	ds_read_b128 v[184:187], v192 offset:1024
	ds_read_b128 v[188:191], v192 offset:2048
	ds_read_b128 v[192:195], v192 offset:3072
	s_add_u32 s34, s34, 0xb0000
	s_addc_u32 s35, s35, 0
	s_mov_b32 m0, s36
	v_lshl_add_u64 v[236:237], s[34:35], 0, v[130:131]
	ds_read_b128 v[196:199], v175 offset:32768
	ds_read_b128 v[202:205], v175 offset:33792
	ds_read_b128 v[206:209], v175 offset:34816
	ds_read_b128 v[210:213], v175 offset:35840
	ds_read_b128 v[214:217], v175 offset:36864
	ds_read_b128 v[218:221], v175 offset:37888
	ds_read_b128 v[222:225], v175 offset:38912
	ds_read_b128 v[226:229], v175 offset:39936
	global_load_lds_dwordx4 v[236:237], off
	v_lshl_add_u64 v[236:237], s[34:35], 0, v[132:133]
	s_mov_b32 m0, s37
	s_nop 0
	global_load_lds_dwordx4 v[236:237], off
	s_waitcnt vmcnt(8)
	s_waitcnt lgkmcnt(0)
	s_setprio 1
	s_barrier
	v_mfma_f32_16x16x32_bf16 v[124:127], v[160:163], v[196:199], v[124:127]
	v_mfma_f32_16x16x32_bf16 v[120:123], v[168:171], v[196:199], v[120:123]
	v_mfma_f32_16x16x32_bf16 v[116:119], v[160:163], v[206:209], v[116:119]
	v_mfma_f32_16x16x32_bf16 v[112:115], v[168:171], v[206:209], v[112:115]
	v_mfma_f32_16x16x32_bf16 v[108:111], v[160:163], v[214:217], v[108:111]
	v_mfma_f32_16x16x32_bf16 v[104:107], v[168:171], v[214:217], v[104:107]
	v_mfma_f32_16x16x32_bf16 v[100:103], v[160:163], v[222:225], v[100:103]
	v_mfma_f32_16x16x32_bf16 v[96:99], v[168:171], v[222:225], v[96:99]
	v_mfma_f32_16x16x32_bf16 v[124:127], v[164:167], v[202:205], v[124:127]
	v_mfma_f32_16x16x32_bf16 v[120:123], v[176:179], v[202:205], v[120:123]
	v_mfma_f32_16x16x32_bf16 v[116:119], v[164:167], v[210:213], v[116:119]
	v_mfma_f32_16x16x32_bf16 v[112:115], v[176:179], v[210:213], v[112:115]
	v_mfma_f32_16x16x32_bf16 v[108:111], v[164:167], v[218:221], v[108:111]
	v_mfma_f32_16x16x32_bf16 v[104:107], v[176:179], v[218:221], v[104:107]
	v_mfma_f32_16x16x32_bf16 v[100:103], v[164:167], v[226:229], v[100:103]
	v_mfma_f32_16x16x32_bf16 v[96:99], v[176:179], v[226:229], v[96:99]
	v_mfma_f32_16x16x32_bf16 v[92:95], v[180:183], v[196:199], v[92:95]
	v_mfma_f32_16x16x32_bf16 v[88:91], v[188:191], v[196:199], v[88:91]
	v_mfma_f32_16x16x32_bf16 v[84:87], v[180:183], v[206:209], v[84:87]
	v_mfma_f32_16x16x32_bf16 v[80:83], v[188:191], v[206:209], v[80:83]
	v_mfma_f32_16x16x32_bf16 v[76:79], v[180:183], v[214:217], v[76:79]
	v_mfma_f32_16x16x32_bf16 v[72:75], v[188:191], v[214:217], v[72:75]
	v_mfma_f32_16x16x32_bf16 v[68:71], v[180:183], v[222:225], v[68:71]
	v_mfma_f32_16x16x32_bf16 v[64:67], v[188:191], v[222:225], v[64:67]
	v_mfma_f32_16x16x32_bf16 v[92:95], v[184:187], v[202:205], v[92:95]
	v_mfma_f32_16x16x32_bf16 v[88:91], v[192:195], v[202:205], v[88:91]
	v_mfma_f32_16x16x32_bf16 v[84:87], v[184:187], v[210:213], v[84:87]
	v_mfma_f32_16x16x32_bf16 v[80:83], v[192:195], v[210:213], v[80:83]
	v_mfma_f32_16x16x32_bf16 v[76:79], v[184:187], v[218:221], v[76:79]
	v_mfma_f32_16x16x32_bf16 v[72:75], v[192:195], v[218:221], v[72:75]
	v_mfma_f32_16x16x32_bf16 v[68:71], v[184:187], v[226:229], v[68:71]
	v_mfma_f32_16x16x32_bf16 v[64:67], v[192:195], v[226:229], v[64:67]
	s_barrier
; #define PG8_STAGE(bufoff, gbase, voff) do { _Pragma("unroll") for (int _i = 0; _i < 2; ++_i) \
;         __builtin_amdgcn_global_load_lds((const unsigned*)((const char*)(gbase) + (voff)[_i]), (LAS unsigned*)(lds + (bufoff) + ldsw + _i * 8192), 16, 0, 0); } while (0)
; #define PG8_STAGEB(bufoff, gbase, perm) do { _Pragma("unroll") for (int _i = 0; _i < 2; ++_i) \
;         __builtin_amdgcn_global_load_lds((const unsigned*)((const char*)(gbase) + ((BSEL && (perm)) ? voffBp[_i] : voffB[_i])), (LAS unsigned*)(lds + (bufoff) + ldsw + _i * 8192), 16, 0, 0); } while (0)
; #define PG8_LDA(dst, b, h) do { _Pragma("unroll") for (int m = 0; m < 4; ++m) _Pragma("unroll") for (int k = 0; k < 2; ++k) dst[m][k] = *(const LAS bf16x8*)(lds + PG8_SA(b, h) + aoff + m * 2048 + k * 1024); } while (0)
; #define PG8_MMA(ai, bj, At, Bt) do { __builtin_amdgcn_s_setprio(1); _Pragma("unroll") for (int m = 0; m < 4; ++m) _Pragma("unroll") for (int n = 0; n < 2; ++n) _Pragma("unroll") for (int k = 0; k < 2; ++k) \
;         acc[ai][bj][m][n] = __builtin_amdgcn_mfma_f32_16x16x32_bf16(Bt[n][k], At[m][k], acc[ai][bj][m][n], 0, 0, 0); __builtin_amdgcn_s_setprio(0); } while (0)
; #define PG8_WAIT_V(n) asm volatile("s_waitcnt vmcnt(" #n ")" ::: "memory")
; #define PG8_WAIT_L(n) asm volatile("s_waitcnt lgkmcnt(" #n ")" ::: "memory")
; #define PG8_BAR __builtin_amdgcn_s_barrier()
; #define PG8_SCHED __builtin_amdgcn_sched_barrier(0)
; template <class Epi, bool BSEL = false>
; __device__ __forceinline__ void gemm_phase(LAS unsigned char* lds, const Gemm g, const Order& S, const Epi& E, const int tid) {
;     ...
;             PG8_LDA(At, 1, 1); PG8_STAGEB(PG8_SB(1, 0), b3, p2); PG8_STAGEB(PG8_SB(1, 1), b3 + h2, p2); PG8_STAGE(PG8_SA(1, 0), a3, voffA);
;             PG8_WAIT_V(8); PG8_WAIT_L(0); PG8_BAR; PG8_MMA(1, 0, At, B0); PG8_MMA(1, 1, At, B1); PG8_BAR; PG8_SCHED;
;         }
;         if constexpr (ALIGN_EPI) { if (wr == 0) PG8_BAR; }
	s_setprio 0
	s_add_i32 s34, s55, s15
	v_lshl_add_u64 v[172:173], v[172:173], 0, s[10:11]
	s_mov_b32 m0, s34
	ds_read_b128 v[196:199], v175 offset:49152
	ds_read_b128 v[202:205], v175 offset:50176
	ds_read_b128 v[206:209], v175 offset:51200
	ds_read_b128 v[210:213], v175 offset:52224
	ds_read_b128 v[214:217], v175 offset:53248
	ds_read_b128 v[218:221], v175 offset:54272
	ds_read_b128 v[222:225], v175 offset:55296
	ds_read_b128 v[226:229], v175 offset:56320
	global_load_lds_dwordx4 v[172:173], off
	s_add_i32 m0, s34, 0x2000
	s_add_u32 s28, s28, 0xb0080
	v_lshl_add_u64 v[172:173], v[230:231], 0, s[10:11]
	s_addc_u32 s29, s29, 0
	s_add_i32 s34, s56, s15
	global_load_lds_dwordx4 v[172:173], off
	v_lshl_add_u64 v[172:173], s[28:29], 0, v[130:131]
	s_mov_b32 m0, s34
	s_nop 0
	global_load_lds_dwordx4 v[172:173], off
	v_lshl_add_u64 v[172:173], s[28:29], 0, v[132:133]
	s_add_i32 m0, s34, 0x2000
	s_nop 0
	global_load_lds_dwordx4 v[172:173], off
	v_lshl_add_u64 v[172:173], v[232:233], 0, s[10:11]
	s_mov_b32 m0, s41
	s_nop 0
	global_load_lds_dwordx4 v[172:173], off
	v_lshl_add_u64 v[172:173], v[234:235], 0, s[10:11]
	s_mov_b32 m0, s42
	s_nop 0
	global_load_lds_dwordx4 v[172:173], off
	s_waitcnt vmcnt(8)
	s_waitcnt lgkmcnt(0)
	s_setprio 1
	s_barrier
	v_mfma_f32_16x16x32_bf16 v[60:63], v[160:163], v[196:199], v[60:63]
	v_mfma_f32_16x16x32_bf16 v[56:59], v[168:171], v[196:199], v[56:59]
	v_mfma_f32_16x16x32_bf16 v[52:55], v[160:163], v[206:209], v[52:55]
	v_mfma_f32_16x16x32_bf16 v[48:51], v[168:171], v[206:209], v[48:51]
	v_mfma_f32_16x16x32_bf16 v[44:47], v[160:163], v[214:217], v[44:47]
	v_mfma_f32_16x16x32_bf16 v[40:43], v[168:171], v[214:217], v[40:43]
	v_mfma_f32_16x16x32_bf16 v[36:39], v[160:163], v[222:225], v[36:39]
	v_mfma_f32_16x16x32_bf16 v[32:35], v[168:171], v[222:225], v[32:35]
	v_mfma_f32_16x16x32_bf16 v[60:63], v[164:167], v[202:205], v[60:63]
	v_mfma_f32_16x16x32_bf16 v[56:59], v[176:179], v[202:205], v[56:59]
	v_mfma_f32_16x16x32_bf16 v[52:55], v[164:167], v[210:213], v[52:55]
	v_mfma_f32_16x16x32_bf16 v[48:51], v[176:179], v[210:213], v[48:51]
	v_mfma_f32_16x16x32_bf16 v[44:47], v[164:167], v[218:221], v[44:47]
	v_mfma_f32_16x16x32_bf16 v[40:43], v[176:179], v[218:221], v[40:43]
	v_mfma_f32_16x16x32_bf16 v[36:39], v[164:167], v[226:229], v[36:39]
	v_mfma_f32_16x16x32_bf16 v[32:35], v[176:179], v[226:229], v[32:35]
	v_mfma_f32_16x16x32_bf16 v[28:31], v[180:183], v[196:199], v[28:31]
	v_mfma_f32_16x16x32_bf16 v[24:27], v[188:191], v[196:199], v[24:27]
	v_mfma_f32_16x16x32_bf16 v[20:23], v[180:183], v[206:209], v[20:23]
	v_mfma_f32_16x16x32_bf16 v[16:19], v[188:191], v[206:209], v[16:19]
	v_mfma_f32_16x16x32_bf16 v[12:15], v[180:183], v[214:217], v[12:15]
	v_mfma_f32_16x16x32_bf16 v[8:11], v[188:191], v[214:217], v[8:11]
	v_mfma_f32_16x16x32_bf16 v[4:7], v[180:183], v[222:225], v[4:7]
	v_mfma_f32_16x16x32_bf16 v[0:3], v[188:191], v[222:225], v[0:3]
	v_mfma_f32_16x16x32_bf16 v[28:31], v[184:187], v[202:205], v[28:31]
	v_mfma_f32_16x16x32_bf16 v[24:27], v[192:195], v[202:205], v[24:27]
	v_mfma_f32_16x16x32_bf16 v[20:23], v[184:187], v[210:213], v[20:23]
	v_mfma_f32_16x16x32_bf16 v[16:19], v[192:195], v[210:213], v[16:19]
	v_mfma_f32_16x16x32_bf16 v[12:15], v[184:187], v[218:221], v[12:15]
	v_mfma_f32_16x16x32_bf16 v[8:11], v[192:195], v[218:221], v[8:11]
	v_mfma_f32_16x16x32_bf16 v[4:7], v[184:187], v[226:229], v[4:7]
	v_mfma_f32_16x16x32_bf16 v[0:3], v[192:195], v[226:229], v[0:3]
	s_barrier
	s_setprio 0
	s_add_i32 s54, s54, 2
	s_add_u32 s2, s2, 0x100
	s_addc_u32 s3, s3, 0
	s_cmp_gt_u32 s54, 41
	s_cbranch_scc0 .LBB0_1364
	s_and_b64 vcc, exec, s[18:19]
	s_cbranch_vccz .LBB0_1367
	s_barrier

; #define PG8_STAGE(bufoff, gbase, voff) do { _Pragma("unroll") for (int _i = 0; _i < 2; ++_i) \
;         __builtin_amdgcn_global_load_lds((const unsigned*)((const char*)(gbase) + (voff)[_i]), (LAS unsigned*)(lds + (bufoff) + ldsw + _i * 8192), 16, 0, 0); } while (0)
; #define PG8_STAGEB(bufoff, gbase, perm) do { _Pragma("unroll") for (int _i = 0; _i < 2; ++_i) \
;         __builtin_amdgcn_global_load_lds((const unsigned*)((const char*)(gbase) + ((BSEL && (perm)) ? voffBp[_i] : voffB[_i])), (LAS unsigned*)(lds + (bufoff) + ldsw + _i * 8192), 16, 0, 0); } while (0)
; #define PG8_LDA(dst, b, h) do { _Pragma("unroll") for (int m = 0; m < 4; ++m) _Pragma("unroll") for (int k = 0; k < 2; ++k) dst[m][k] = *(const LAS bf16x8*)(lds + PG8_SA(b, h) + aoff + m * 2048 + k * 1024); } while (0)
; #define PG8_LDB(dst, b, h) do { _Pragma("unroll") for (int n = 0; n < 2; ++n) _Pragma("unroll") for (int k = 0; k < 2; ++k) dst[n][k] = *(const LAS bf16x8*)(lds + PG8_SB(b, h) + boff + n * 2048 + k * 1024); } while (0)
; #define PG8_WAIT_V(n) asm volatile("s_waitcnt vmcnt(" #n ")" ::: "memory")
; #define PG8_WAIT_L(n) asm volatile("s_waitcnt lgkmcnt(" #n ")" ::: "memory")
; #define PG8_BAR __builtin_amdgcn_s_barrier()
; #define PG8_SCHED __builtin_amdgcn_sched_barrier(0)
; template <class Epi, bool BSEL = false>
; __device__ __forceinline__ void gemm_phase(LAS unsigned char* lds, const Gemm g, const Order& S, const Epi& E, const int tid) {
;     ...
;         for (int t = 0; t < nt; t += 2) {
;             const bool last = (t == nt - 2);
;             const char* a1 = cA + (size_t)(t + 1) * kstep;
;             const char* a2 = last ? nA : cA + (size_t)(t + 2) * kstep; const char* b2 = last ? nB : cB + (size_t)(t + 2) * kstep;
;             const char* a3 = a2 + kstep; const char* b3 = b2 + kstep;
;             const bool p2 = last ? nP : cP; const size_t h2 = last ? nhB : chB;
;             PG8_LDB(B0, 0, 0); PG8_LDB(B1, 0, 1); PG8_SCHED; PG8_LDA(At, 0, 0); PG8_STAGE(PG8_SA(1, 1), a1 + hstepA, voffA);
;             PG8_WAIT_V(8); PG8_WAIT_L(0); PG8_BAR; PG8_MMA(0, 0, At, B0); PG8_MMA(0, 1, At, B1); PG8_BAR; PG8_SCHED;
;             PG8_LDA(At, 0, 1); PG8_STAGEB(PG8_SB(0, 0), b2, p2); PG8_STAGEB(PG8_SB(0, 1), b2 + h2, p2); PG8_STAGE(PG8_SA(0, 0), a2, voffA);
;             PG8_WAIT_V(8); PG8_WAIT_L(0); PG8_BAR; PG8_MMA(1, 0, At, B0); PG8_MMA(1, 1, At, B1); PG8_BAR; PG8_SCHED;
.LBB0_1393:
	v_add_u32_e32 v151, s43, v131
	ds_read_b128 v[152:155], v151
	ds_read_b128 v[156:159], v151 offset:1024
	ds_read_b128 v[168:171], v151 offset:2048
	ds_read_b128 v[172:175], v151 offset:3072
	v_add_u32_e32 v151, s44, v131
	s_add_u32 s36, s8, s34
	ds_read_b128 v[176:179], v151
	ds_read_b128 v[180:183], v151 offset:1024
	ds_read_b128 v[184:187], v151 offset:2048
	ds_read_b128 v[188:191], v151 offset:3072
	s_addc_u32 s37, s9, s35
	s_add_u32 s36, s36, 0x100
	s_addc_u32 s37, s37, 0
	s_add_u32 s54, s29, s34
	s_addc_u32 s55, s48, s35
	s_cmpk_eq_i32 s34, 0x1500
	s_cselect_b32 s39, s49, s37
	s_cselect_b32 s38, s50, s36
	s_cselect_b32 s37, s51, s55
	s_cselect_b32 s36, s52, s54
	v_lshl_add_u64 v[160:161], v[146:147], 0, s[34:35]
	s_add_i32 m0, s15, 0xc000
	ds_read_b128 v[192:195], v150
	ds_read_b128 v[196:199], v150 offset:1024
	ds_read_b128 v[202:205], v150 offset:2048
	ds_read_b128 v[206:209], v150 offset:3072
	ds_read_b128 v[210:213], v150 offset:4096
	ds_read_b128 v[214:217], v150 offset:5120
	ds_read_b128 v[218:221], v150 offset:6144
	ds_read_b128 v[222:225], v150 offset:7168
	global_load_lds_dwordx4 v[160:161], off
	v_lshl_add_u64 v[160:161], v[148:149], 0, s[34:35]
	s_add_i32 m0, s15, 0xe000
	s_nop 0
	global_load_lds_dwordx4 v[160:161], off
	s_waitcnt vmcnt(8)
	s_waitcnt lgkmcnt(0)
	s_setprio 1
	s_barrier
	v_mfma_f32_16x16x32_bf16 v[124:127], v[152:155], v[192:195], v[124:127]
	v_mfma_f32_16x16x32_bf16 v[120:123], v[168:171], v[192:195], v[120:123]
	v_mfma_f32_16x16x32_bf16 v[108:111], v[152:155], v[202:205], v[108:111]
	v_mfma_f32_16x16x32_bf16 v[104:107], v[168:171], v[202:205], v[104:107]
	v_mfma_f32_16x16x32_bf16 v[92:95], v[152:155], v[210:213], v[92:95]
	v_mfma_f32_16x16x32_bf16 v[88:91], v[168:171], v[210:213], v[88:91]
	v_mfma_f32_16x16x32_bf16 v[76:79], v[152:155], v[218:221], v[76:79]
	v_mfma_f32_16x16x32_bf16 v[72:75], v[168:171], v[218:221], v[72:75]
	v_mfma_f32_16x16x32_bf16 v[124:127], v[156:159], v[196:199], v[124:127]
	v_mfma_f32_16x16x32_bf16 v[120:123], v[172:175], v[196:199], v[120:123]
	v_mfma_f32_16x16x32_bf16 v[108:111], v[156:159], v[206:209], v[108:111]
	v_mfma_f32_16x16x32_bf16 v[104:107], v[172:175], v[206:209], v[104:107]
	v_mfma_f32_16x16x32_bf16 v[92:95], v[156:159], v[214:217], v[92:95]
	v_mfma_f32_16x16x32_bf16 v[88:91], v[172:175], v[214:217], v[88:91]
	v_mfma_f32_16x16x32_bf16 v[76:79], v[156:159], v[222:225], v[76:79]
	v_mfma_f32_16x16x32_bf16 v[72:75], v[172:175], v[222:225], v[72:75]
	v_mfma_f32_16x16x32_bf16 v[116:119], v[176:179], v[192:195], v[116:119]
	v_mfma_f32_16x16x32_bf16 v[112:115], v[184:187], v[192:195], v[112:115]
	v_mfma_f32_16x16x32_bf16 v[100:103], v[176:179], v[202:205], v[100:103]
	v_mfma_f32_16x16x32_bf16 v[96:99], v[184:187], v[202:205], v[96:99]
	v_mfma_f32_16x16x32_bf16 v[84:87], v[176:179], v[210:213], v[84:87]
	v_mfma_f32_16x16x32_bf16 v[80:83], v[184:187], v[210:213], v[80:83]
	v_mfma_f32_16x16x32_bf16 v[68:71], v[176:179], v[218:221], v[68:71]
	v_mfma_f32_16x16x32_bf16 v[64:67], v[184:187], v[218:221], v[64:67]
	v_mfma_f32_16x16x32_bf16 v[116:119], v[180:183], v[196:199], v[116:119]
	v_mfma_f32_16x16x32_bf16 v[112:115], v[188:191], v[196:199], v[112:115]
	v_mfma_f32_16x16x32_bf16 v[100:103], v[180:183], v[206:209], v[100:103]
	v_mfma_f32_16x16x32_bf16 v[96:99], v[188:191], v[206:209], v[96:99]
	v_mfma_f32_16x16x32_bf16 v[84:87], v[180:183], v[214:217], v[84:87]
	v_mfma_f32_16x16x32_bf16 v[80:83], v[188:191], v[214:217], v[80:83]
	v_mfma_f32_16x16x32_bf16 v[68:71], v[180:183], v[222:225], v[68:71]
	v_mfma_f32_16x16x32_bf16 v[64:67], v[188:191], v[222:225], v[64:67]
	s_barrier
	s_setprio 0
	s_add_i32 s54, s43, s14
	v_lshl_add_u64 v[160:161], s[36:37], 0, v[134:135]
	s_mov_b32 m0, s54
	ds_read_b128 v[192:195], v150 offset:16384
	ds_read_b128 v[196:199], v150 offset:17408
	ds_read_b128 v[202:205], v150 offset:18432
	ds_read_b128 v[206:209], v150 offset:19456
	ds_read_b128 v[210:213], v150 offset:20480
	ds_read_b128 v[214:217], v150 offset:21504
	ds_read_b128 v[218:221], v150 offset:22528
	ds_read_b128 v[222:225], v150 offset:23552
	global_load_lds_dwordx4 v[160:161], off
	s_add_i32 m0, s54, 0x2000
	s_add_u32 s54, s36, 0xb0000
	v_lshl_add_u64 v[164:165], s[36:37], 0, v[138:139]
	s_addc_u32 s55, s37, 0
	s_add_i32 s56, s44, s14
	global_load_lds_dwordx4 v[164:165], off
	v_lshl_add_u64 v[226:227], s[54:55], 0, v[134:135]
	s_mov_b32 m0, s56
	v_lshl_add_u64 v[228:229], s[38:39], 0, v[136:137]
	global_load_lds_dwordx4 v[226:227], off
	v_lshl_add_u64 v[226:227], s[54:55], 0, v[138:139]
	s_add_i32 m0, s56, 0x2000
	s_nop 0
	global_load_lds_dwordx4 v[226:227], off
	v_lshl_add_u64 v[226:227], s[38:39], 0, v[132:133]
	s_mov_b32 m0, s15
	s_nop 0
	global_load_lds_dwordx4 v[226:227], off
	s_mov_b32 m0, s20
	s_nop 0
	global_load_lds_dwordx4 v[228:229], off
	s_waitcnt vmcnt(8)
	s_waitcnt lgkmcnt(0)
	s_setprio 1
	s_barrier
; #define PG8_STAGE(bufoff, gbase, voff) do { _Pragma("unroll") for (int _i = 0; _i < 2; ++_i) \
;         __builtin_amdgcn_global_load_lds((const unsigned*)((const char*)(gbase) + (voff)[_i]), (LAS unsigned*)(lds + (bufoff) + ldsw + _i * 8192), 16, 0, 0); } while (0)
; #define PG8_LDA(dst, b, h) do { _Pragma("unroll") for (int m = 0; m < 4; ++m) _Pragma("unroll") for (int k = 0; k < 2; ++k) dst[m][k] = *(const LAS bf16x8*)(lds + PG8_SA(b, h) + aoff + m * 2048 + k * 1024); } while (0)
; #define PG8_LDB(dst, b, h) do { _Pragma("unroll") for (int n = 0; n < 2; ++n) _Pragma("unroll") for (int k = 0; k < 2; ++k) dst[n][k] = *(const LAS bf16x8*)(lds + PG8_SB(b, h) + boff + n * 2048 + k * 1024); } while (0)
; #define PG8_MMA(ai, bj, At, Bt) do { __builtin_amdgcn_s_setprio(1); _Pragma("unroll") for (int m = 0; m < 4; ++m) _Pragma("unroll") for (int n = 0; n < 2; ++n) _Pragma("unroll") for (int k = 0; k < 2; ++k) \
;         acc[ai][bj][m][n] = __builtin_amdgcn_mfma_f32_16x16x32_bf16(Bt[n][k], At[m][k], acc[ai][bj][m][n], 0, 0, 0); __builtin_amdgcn_s_setprio(0); } while (0)
; #define PG8_WAIT_V(n) asm volatile("s_waitcnt vmcnt(" #n ")" ::: "memory")
; #define PG8_WAIT_L(n) asm volatile("s_waitcnt lgkmcnt(" #n ")" ::: "memory")
; #define PG8_BAR __builtin_amdgcn_s_barrier()
; #define PG8_SCHED __builtin_amdgcn_sched_barrier(0)
; template <class Epi, bool BSEL = false>
; __device__ __forceinline__ void gemm_phase(LAS unsigned char* lds, const Gemm g, const Order& S, const Epi& E, const int tid) {
;     ...
;             PG8_WAIT_V(8); PG8_WAIT_L(0); PG8_BAR; PG8_MMA(1, 0, At, B0); PG8_MMA(1, 1, At, B1); PG8_BAR; PG8_SCHED;
;             PG8_LDB(B0, 1, 0); PG8_LDB(B1, 1, 1); PG8_SCHED; PG8_LDA(At, 1, 0); PG8_STAGE(PG8_SA(0, 1), a2 + hstepA, voffA);
;             PG8_WAIT_V(8); PG8_WAIT_L(0); PG8_BAR; PG8_MMA(0, 0, At, B0); PG8_MMA(0, 1, At, B1); PG8_BAR; PG8_SCHED;
	v_mfma_f32_16x16x32_bf16 v[60:63], v[152:155], v[192:195], v[60:63]
	v_mfma_f32_16x16x32_bf16 v[56:59], v[168:171], v[192:195], v[56:59]
	v_mfma_f32_16x16x32_bf16 v[44:47], v[152:155], v[202:205], v[44:47]
	v_mfma_f32_16x16x32_bf16 v[40:43], v[168:171], v[202:205], v[40:43]
	v_mfma_f32_16x16x32_bf16 v[28:31], v[152:155], v[210:213], v[28:31]
	v_mfma_f32_16x16x32_bf16 v[24:27], v[168:171], v[210:213], v[24:27]
	v_mfma_f32_16x16x32_bf16 v[12:15], v[152:155], v[218:221], v[12:15]
	v_mfma_f32_16x16x32_bf16 v[8:11], v[168:171], v[218:221], v[8:11]
	v_mfma_f32_16x16x32_bf16 v[60:63], v[156:159], v[196:199], v[60:63]
	v_mfma_f32_16x16x32_bf16 v[56:59], v[172:175], v[196:199], v[56:59]
	v_mfma_f32_16x16x32_bf16 v[44:47], v[156:159], v[206:209], v[44:47]
	v_mfma_f32_16x16x32_bf16 v[40:43], v[172:175], v[206:209], v[40:43]
	v_mfma_f32_16x16x32_bf16 v[28:31], v[156:159], v[214:217], v[28:31]
	v_mfma_f32_16x16x32_bf16 v[24:27], v[172:175], v[214:217], v[24:27]
	v_mfma_f32_16x16x32_bf16 v[12:15], v[156:159], v[222:225], v[12:15]
	v_mfma_f32_16x16x32_bf16 v[8:11], v[172:175], v[222:225], v[8:11]
	v_mfma_f32_16x16x32_bf16 v[52:55], v[176:179], v[192:195], v[52:55]
	v_mfma_f32_16x16x32_bf16 v[48:51], v[184:187], v[192:195], v[48:51]
	v_mfma_f32_16x16x32_bf16 v[36:39], v[176:179], v[202:205], v[36:39]
	v_mfma_f32_16x16x32_bf16 v[32:35], v[184:187], v[202:205], v[32:35]
	v_mfma_f32_16x16x32_bf16 v[20:23], v[176:179], v[210:213], v[20:23]
	v_mfma_f32_16x16x32_bf16 v[16:19], v[184:187], v[210:213], v[16:19]
	v_mfma_f32_16x16x32_bf16 v[4:7], v[176:179], v[218:221], v[4:7]
	v_mfma_f32_16x16x32_bf16 v[0:3], v[184:187], v[218:221], v[0:3]
	v_mfma_f32_16x16x32_bf16 v[52:55], v[180:183], v[196:199], v[52:55]
	v_mfma_f32_16x16x32_bf16 v[48:51], v[188:191], v[196:199], v[48:51]
	v_mfma_f32_16x16x32_bf16 v[36:39], v[180:183], v[206:209], v[36:39]
	v_mfma_f32_16x16x32_bf16 v[32:35], v[188:191], v[206:209], v[32:35]
	v_mfma_f32_16x16x32_bf16 v[20:23], v[180:183], v[214:217], v[20:23]
	v_mfma_f32_16x16x32_bf16 v[16:19], v[188:191], v[214:217], v[16:19]
	v_mfma_f32_16x16x32_bf16 v[4:7], v[180:183], v[222:225], v[4:7]
	v_mfma_f32_16x16x32_bf16 v[0:3], v[188:191], v[222:225], v[0:3]
	s_barrier
	s_setprio 0
	s_add_i32 s54, 0, 0x18000
	v_add_u32_e32 v151, s54, v131
	s_add_i32 s55, 0, 0x1c000
	ds_read_b128 v[152:155], v151
	ds_read_b128 v[156:159], v151 offset:1024
	ds_read_b128 v[168:171], v151 offset:2048
	ds_read_b128 v[172:175], v151 offset:3072
	v_add_u32_e32 v151, s55, v131
	ds_read_b128 v[176:179], v151
	ds_read_b128 v[180:183], v151 offset:1024
	ds_read_b128 v[184:187], v151 offset:2048
	ds_read_b128 v[188:191], v151 offset:3072
	s_add_u32 s38, s38, 0xb0000
	s_addc_u32 s39, s39, 0
	s_mov_b32 m0, s21
	v_lshl_add_u64 v[230:231], s[38:39], 0, v[132:133]
	ds_read_b128 v[192:195], v150 offset:32768
	ds_read_b128 v[196:199], v150 offset:33792
	ds_read_b128 v[202:205], v150 offset:34816
	ds_read_b128 v[206:209], v150 offset:35840
	ds_read_b128 v[210:213], v150 offset:36864
	ds_read_b128 v[214:217], v150 offset:37888
	ds_read_b128 v[218:221], v150 offset:38912
	ds_read_b128 v[222:225], v150 offset:39936
	global_load_lds_dwordx4 v[230:231], off
	v_lshl_add_u64 v[230:231], s[38:39], 0, v[136:137]
	s_mov_b32 m0, s40
	s_nop 0
	global_load_lds_dwordx4 v[230:231], off
	s_waitcnt vmcnt(8)
	s_waitcnt lgkmcnt(0)
	s_setprio 1
	s_barrier
	v_mfma_f32_16x16x32_bf16 v[124:127], v[152:155], v[192:195], v[124:127]
	v_mfma_f32_16x16x32_bf16 v[120:123], v[168:171], v[192:195], v[120:123]
	v_mfma_f32_16x16x32_bf16 v[108:111], v[152:155], v[202:205], v[108:111]
	v_mfma_f32_16x16x32_bf16 v[104:107], v[168:171], v[202:205], v[104:107]
	v_mfma_f32_16x16x32_bf16 v[92:95], v[152:155], v[210:213], v[92:95]
	v_mfma_f32_16x16x32_bf16 v[88:91], v[168:171], v[210:213], v[88:91]
	v_mfma_f32_16x16x32_bf16 v[76:79], v[152:155], v[218:221], v[76:79]
	v_mfma_f32_16x16x32_bf16 v[72:75], v[168:171], v[218:221], v[72:75]
	v_mfma_f32_16x16x32_bf16 v[124:127], v[156:159], v[196:199], v[124:127]
	v_mfma_f32_16x16x32_bf16 v[120:123], v[172:175], v[196:199], v[120:123]
	v_mfma_f32_16x16x32_bf16 v[108:111], v[156:159], v[206:209], v[108:111]
	v_mfma_f32_16x16x32_bf16 v[104:107], v[172:175], v[206:209], v[104:107]
	v_mfma_f32_16x16x32_bf16 v[92:95], v[156:159], v[214:217], v[92:95]
	v_mfma_f32_16x16x32_bf16 v[88:91], v[172:175], v[214:217], v[88:91]
	v_mfma_f32_16x16x32_bf16 v[76:79], v[156:159], v[222:225], v[76:79]
	v_mfma_f32_16x16x32_bf16 v[72:75], v[172:175], v[222:225], v[72:75]
	v_mfma_f32_16x16x32_bf16 v[116:119], v[176:179], v[192:195], v[116:119]
	v_mfma_f32_16x16x32_bf16 v[112:115], v[184:187], v[192:195], v[112:115]
	v_mfma_f32_16x16x32_bf16 v[100:103], v[176:179], v[202:205], v[100:103]
	v_mfma_f32_16x16x32_bf16 v[96:99], v[184:187], v[202:205], v[96:99]
	v_mfma_f32_16x16x32_bf16 v[84:87], v[176:179], v[210:213], v[84:87]
	v_mfma_f32_16x16x32_bf16 v[80:83], v[184:187], v[210:213], v[80:83]
	v_mfma_f32_16x16x32_bf16 v[68:71], v[176:179], v[218:221], v[68:71]
	v_mfma_f32_16x16x32_bf16 v[64:67], v[184:187], v[218:221], v[64:67]
	v_mfma_f32_16x16x32_bf16 v[116:119], v[180:183], v[196:199], v[116:119]
	v_mfma_f32_16x16x32_bf16 v[112:115], v[188:191], v[196:199], v[112:115]
	v_mfma_f32_16x16x32_bf16 v[100:103], v[180:183], v[206:209], v[100:103]
	v_mfma_f32_16x16x32_bf16 v[96:99], v[188:191], v[206:209], v[96:99]
	v_mfma_f32_16x16x32_bf16 v[84:87], v[180:183], v[214:217], v[84:87]
	v_mfma_f32_16x16x32_bf16 v[80:83], v[188:191], v[214:217], v[80:83]
	v_mfma_f32_16x16x32_bf16 v[68:71], v[180:183], v[222:225], v[68:71]
	v_mfma_f32_16x16x32_bf16 v[64:67], v[188:191], v[222:225], v[64:67]
	s_barrier
; #define PG8_STAGE(bufoff, gbase, voff) do { _Pragma("unroll") for (int _i = 0; _i < 2; ++_i) \
;         __builtin_amdgcn_global_load_lds((const unsigned*)((const char*)(gbase) + (voff)[_i]), (LAS unsigned*)(lds + (bufoff) + ldsw + _i * 8192), 16, 0, 0); } while (0)
; #define PG8_STAGEB(bufoff, gbase, perm) do { _Pragma("unroll") for (int _i = 0; _i < 2; ++_i) \
;         __builtin_amdgcn_global_load_lds((const unsigned*)((const char*)(gbase) + ((BSEL && (perm)) ? voffBp[_i] : voffB[_i])), (LAS unsigned*)(lds + (bufoff) + ldsw + _i * 8192), 16, 0, 0); } while (0)
; #define PG8_LDA(dst, b, h) do { _Pragma("unroll") for (int m = 0; m < 4; ++m) _Pragma("unroll") for (int k = 0; k < 2; ++k) dst[m][k] = *(const LAS bf16x8*)(lds + PG8_SA(b, h) + aoff + m * 2048 + k * 1024); } while (0)
; #define PG8_MMA(ai, bj, At, Bt) do { __builtin_amdgcn_s_setprio(1); _Pragma("unroll") for (int m = 0; m < 4; ++m) _Pragma("unroll") for (int n = 0; n < 2; ++n) _Pragma("unroll") for (int k = 0; k < 2; ++k) \
;         acc[ai][bj][m][n] = __builtin_amdgcn_mfma_f32_16x16x32_bf16(Bt[n][k], At[m][k], acc[ai][bj][m][n], 0, 0, 0); __builtin_amdgcn_s_setprio(0); } while (0)
; #define PG8_WAIT_V(n) asm volatile("s_waitcnt vmcnt(" #n ")" ::: "memory")
; #define PG8_WAIT_L(n) asm volatile("s_waitcnt lgkmcnt(" #n ")" ::: "memory")
; #define PG8_BAR __builtin_amdgcn_s_barrier()
; #define PG8_SCHED __builtin_amdgcn_sched_barrier(0)
; template <class Epi, bool BSEL = false>
; __device__ __forceinline__ void gemm_phase(LAS unsigned char* lds, const Gemm g, const Order& S, const Epi& E, const int tid) {
;     ...
;             PG8_LDA(At, 1, 1); PG8_STAGEB(PG8_SB(1, 0), b3, p2); PG8_STAGEB(PG8_SB(1, 1), b3 + h2, p2); PG8_STAGE(PG8_SA(1, 0), a3, voffA);
;             PG8_WAIT_V(8); PG8_WAIT_L(0); PG8_BAR; PG8_MMA(1, 0, At, B0); PG8_MMA(1, 1, At, B1); PG8_BAR; PG8_SCHED;
;         }
;         if constexpr (ALIGN_EPI) { if (wr == 0) PG8_BAR; }
	s_setprio 0
	s_add_i32 s38, s54, s14
	v_lshl_add_u64 v[160:161], v[160:161], 0, s[18:19]
	s_mov_b32 m0, s38
	ds_read_b128 v[192:195], v150 offset:49152
	ds_read_b128 v[196:199], v150 offset:50176
	ds_read_b128 v[202:205], v150 offset:51200
	ds_read_b128 v[206:209], v150 offset:52224
	ds_read_b128 v[210:213], v150 offset:53248
	ds_read_b128 v[214:217], v150 offset:54272
	ds_read_b128 v[218:221], v150 offset:55296
	ds_read_b128 v[222:225], v150 offset:56320
	global_load_lds_dwordx4 v[160:161], off
	s_add_i32 m0, s38, 0x2000
	s_add_u32 s36, s36, 0xb0080
	v_lshl_add_u64 v[160:161], v[164:165], 0, s[18:19]
	s_addc_u32 s37, s37, 0
	s_add_i32 s38, s55, s14
	global_load_lds_dwordx4 v[160:161], off
	v_lshl_add_u64 v[160:161], s[36:37], 0, v[134:135]
	s_mov_b32 m0, s38
	s_nop 0
	global_load_lds_dwordx4 v[160:161], off
	v_lshl_add_u64 v[160:161], s[36:37], 0, v[138:139]
	s_add_i32 m0, s38, 0x2000
	s_nop 0
	global_load_lds_dwordx4 v[160:161], off
	v_lshl_add_u64 v[160:161], v[226:227], 0, s[18:19]
	s_mov_b32 m0, s41
	s_nop 0
	global_load_lds_dwordx4 v[160:161], off
	v_lshl_add_u64 v[160:161], v[228:229], 0, s[18:19]
	s_mov_b32 m0, s42
	s_nop 0
	global_load_lds_dwordx4 v[160:161], off
	s_waitcnt vmcnt(8)
	s_waitcnt lgkmcnt(0)
	s_setprio 1
	s_barrier
	v_mfma_f32_16x16x32_bf16 v[60:63], v[152:155], v[192:195], v[60:63]
	v_mfma_f32_16x16x32_bf16 v[56:59], v[168:171], v[192:195], v[56:59]
	v_mfma_f32_16x16x32_bf16 v[44:47], v[152:155], v[202:205], v[44:47]
	v_mfma_f32_16x16x32_bf16 v[40:43], v[168:171], v[202:205], v[40:43]
	v_mfma_f32_16x16x32_bf16 v[28:31], v[152:155], v[210:213], v[28:31]
	v_mfma_f32_16x16x32_bf16 v[24:27], v[168:171], v[210:213], v[24:27]
	v_mfma_f32_16x16x32_bf16 v[12:15], v[152:155], v[218:221], v[12:15]
	v_mfma_f32_16x16x32_bf16 v[8:11], v[168:171], v[218:221], v[8:11]
	v_mfma_f32_16x16x32_bf16 v[60:63], v[156:159], v[196:199], v[60:63]
	v_mfma_f32_16x16x32_bf16 v[56:59], v[172:175], v[196:199], v[56:59]
	v_mfma_f32_16x16x32_bf16 v[44:47], v[156:159], v[206:209], v[44:47]
	v_mfma_f32_16x16x32_bf16 v[40:43], v[172:175], v[206:209], v[40:43]
	v_mfma_f32_16x16x32_bf16 v[28:31], v[156:159], v[214:217], v[28:31]
	v_mfma_f32_16x16x32_bf16 v[24:27], v[172:175], v[214:217], v[24:27]
	v_mfma_f32_16x16x32_bf16 v[12:15], v[156:159], v[222:225], v[12:15]
	v_mfma_f32_16x16x32_bf16 v[8:11], v[172:175], v[222:225], v[8:11]
	v_mfma_f32_16x16x32_bf16 v[52:55], v[176:179], v[192:195], v[52:55]
	v_mfma_f32_16x16x32_bf16 v[48:51], v[184:187], v[192:195], v[48:51]
	v_mfma_f32_16x16x32_bf16 v[36:39], v[176:179], v[202:205], v[36:39]
	v_mfma_f32_16x16x32_bf16 v[32:35], v[184:187], v[202:205], v[32:35]
	v_mfma_f32_16x16x32_bf16 v[20:23], v[176:179], v[210:213], v[20:23]
	v_mfma_f32_16x16x32_bf16 v[16:19], v[184:187], v[210:213], v[16:19]
	v_mfma_f32_16x16x32_bf16 v[4:7], v[176:179], v[218:221], v[4:7]
	v_mfma_f32_16x16x32_bf16 v[0:3], v[184:187], v[218:221], v[0:3]
	v_mfma_f32_16x16x32_bf16 v[52:55], v[180:183], v[196:199], v[52:55]
	v_mfma_f32_16x16x32_bf16 v[48:51], v[188:191], v[196:199], v[48:51]
	v_mfma_f32_16x16x32_bf16 v[36:39], v[180:183], v[206:209], v[36:39]
	v_mfma_f32_16x16x32_bf16 v[32:35], v[188:191], v[206:209], v[32:35]
	v_mfma_f32_16x16x32_bf16 v[20:23], v[180:183], v[214:217], v[20:23]
	v_mfma_f32_16x16x32_bf16 v[16:19], v[188:191], v[214:217], v[16:19]
	v_mfma_f32_16x16x32_bf16 v[4:7], v[180:183], v[222:225], v[4:7]
	v_mfma_f32_16x16x32_bf16 v[0:3], v[188:191], v[222:225], v[0:3]
	s_barrier
	s_setprio 0
	s_add_i32 s53, s53, 2
	s_add_u32 s34, s34, 0x100
	s_addc_u32 s35, s35, 0
	s_cmp_gt_u32 s53, 41
	s_cbranch_scc0 .LBB0_1393
	s_and_b64 vcc, exec, s[22:23]
	s_cbranch_vccz .LBB0_1396
	s_barrier
